# GEMM K-loops: loop counter and pointer SALU run placed at the end of the last (light) load segment instead of behind the closing barrier
# speedup vs baseline: 1.0053x; 1.0053x over previous
; #define WAIT_V(n) asm volatile("s_waitcnt vmcnt(" #n ")" ::: "memory")
; #define WAIT_L(n) asm volatile("s_waitcnt lgkmcnt(" #n ")" ::: "memory")
; #define BAR __builtin_amdgcn_s_barrier()
; #define SCHED __builtin_amdgcn_sched_barrier(0)
; template <class Get, class Epi>
; DI void gemm_stream(LAS unsigned char* lds, const int K, const int ld, Get get, Epi epi) {
;     ...
;             LDB(B0, 0, 0); SCHED; LDA(At, 0, 0); STAGE(SAo(1, 1), a1 + hstep);
;             WAIT_L(8); BAR; WAIT_L(0); MMA(0, 0, At, B0); BAR; SCHED;
;             LDB(B1, 0, 1); STAGE(SBo(0, 0), b2);
;             BAR; WAIT_L(0); MMA(0, 1, At, B1); BAR;
;             LDA(At, 0, 1); STAGE(SAo(0, 0), a2);
;             BAR; WAIT_L(0); MMA(1, 0, At, B0); BAR; SCHED;
;             STAGE(SBo(0, 1), b2 + hstep);
;             WAIT_V(6); BAR; MMA(1, 1, At, B1); BAR;
;             LDB(B0, 1, 0); SCHED; LDA(At, 1, 0); STAGE(SAo(0, 1), a2 + hstep);
;             WAIT_L(8); BAR; WAIT_L(0); MMA(0, 0, At, B0); BAR; SCHED;
.LBB0_726:
	ds_read_b128 v[128:131], v167
	ds_read_b128 v[132:135], v167 offset:1024
	ds_read_b128 v[136:139], v167 offset:2048
	ds_read_b128 v[154:157], v167 offset:3072
	s_add_u32 s6, s4, 0xfff80080
	s_addc_u32 s7, s5, -1
	s_cmp_eq_u32 vcc_lo, 28
	s_cselect_b32 s63, s59, s7
	s_cselect_b32 s62, s58, s6
	s_cselect_b32 s7, s61, s55
	s_cselect_b32 s6, s60, s29
	v_lshl_add_u64 v[140:141], s[4:5], 0, v[148:149]
	s_add_i32 m0, s74, 0xc000
	ds_read_b128 v[158:161], v168
	ds_read_b128 v[162:165], v168 offset:1024
	ds_read_b128 v[170:173], v168 offset:2048
	ds_read_b128 v[174:177], v168 offset:3072
	ds_read_b128 v[178:181], v168 offset:4096
	ds_read_b128 v[182:185], v168 offset:5120
	ds_read_b128 v[186:189], v168 offset:6144
	ds_read_b128 v[190:193], v168 offset:7168
	global_load_lds_dwordx4 v[140:141], off
	v_lshl_add_u64 v[140:141], s[4:5], 0, v[150:151]
	s_add_i32 m0, s74, 0xe000
	s_nop 0
	global_load_lds_dwordx4 v[140:141], off
	s_waitcnt lgkmcnt(8)
	s_barrier
	s_waitcnt lgkmcnt(0)
	v_mfma_f32_16x16x32_bf16 v[124:127], v[128:131], v[158:161], v[124:127]
	v_mfma_f32_16x16x32_bf16 v[120:123], v[136:139], v[158:161], v[120:123]
	v_mfma_f32_16x16x32_bf16 v[112:115], v[128:131], v[170:173], v[112:115]
	v_mfma_f32_16x16x32_bf16 v[108:111], v[136:139], v[170:173], v[108:111]
	v_mfma_f32_16x16x32_bf16 v[100:103], v[128:131], v[178:181], v[100:103]
	v_mfma_f32_16x16x32_bf16 v[92:95], v[136:139], v[178:181], v[92:95]
	v_mfma_f32_16x16x32_bf16 v[84:87], v[128:131], v[186:189], v[84:87]
	v_mfma_f32_16x16x32_bf16 v[76:79], v[136:139], v[186:189], v[76:79]
	v_mfma_f32_16x16x32_bf16 v[124:127], v[132:135], v[162:165], v[124:127]
	v_mfma_f32_16x16x32_bf16 v[120:123], v[154:157], v[162:165], v[120:123]
	v_mfma_f32_16x16x32_bf16 v[112:115], v[132:135], v[174:177], v[112:115]
	v_mfma_f32_16x16x32_bf16 v[108:111], v[154:157], v[174:177], v[108:111]
	v_mfma_f32_16x16x32_bf16 v[100:103], v[132:135], v[182:185], v[100:103]
	v_mfma_f32_16x16x32_bf16 v[92:95], v[154:157], v[182:185], v[92:95]
	v_mfma_f32_16x16x32_bf16 v[84:87], v[132:135], v[190:193], v[84:87]
	v_mfma_f32_16x16x32_bf16 v[76:79], v[154:157], v[190:193], v[76:79]
	s_barrier
	s_add_i32 s86, s85, s35
	v_lshl_add_u64 v[140:141], s[6:7], 0, v[142:143]
	s_mov_b32 m0, s86
	ds_read_b128 v[194:197], v169
	ds_read_b128 v[198:201], v169 offset:1024
	ds_read_b128 v[202:205], v169 offset:2048
	ds_read_b128 v[208:211], v169 offset:3072
	global_load_lds_dwordx4 v[140:141], off
	v_lshl_add_u64 v[212:213], s[6:7], 0, v[144:145]
	s_add_i32 m0, s86, 0x2000
	s_nop 0
	global_load_lds_dwordx4 v[212:213], off
	s_barrier
	s_waitcnt lgkmcnt(0)
	v_mfma_f32_16x16x32_bf16 v[116:119], v[194:197], v[158:161], v[116:119]
	v_mfma_f32_16x16x32_bf16 v[104:107], v[202:205], v[158:161], v[104:107]
	v_mfma_f32_16x16x32_bf16 v[96:99], v[194:197], v[170:173], v[96:99]
	v_mfma_f32_16x16x32_bf16 v[88:91], v[202:205], v[170:173], v[88:91]
	v_mfma_f32_16x16x32_bf16 v[80:83], v[194:197], v[178:181], v[80:83]
	v_mfma_f32_16x16x32_bf16 v[72:75], v[202:205], v[178:181], v[72:75]
	v_mfma_f32_16x16x32_bf16 v[68:71], v[194:197], v[186:189], v[68:71]
	v_mfma_f32_16x16x32_bf16 v[64:67], v[202:205], v[186:189], v[64:67]
	v_mfma_f32_16x16x32_bf16 v[116:119], v[198:201], v[162:165], v[116:119]
	v_mfma_f32_16x16x32_bf16 v[104:107], v[208:211], v[162:165], v[104:107]
	v_mfma_f32_16x16x32_bf16 v[96:99], v[198:201], v[174:177], v[96:99]
	v_mfma_f32_16x16x32_bf16 v[88:91], v[208:211], v[174:177], v[88:91]
	v_mfma_f32_16x16x32_bf16 v[80:83], v[198:201], v[182:185], v[80:83]
	v_mfma_f32_16x16x32_bf16 v[72:75], v[208:211], v[182:185], v[72:75]
	v_mfma_f32_16x16x32_bf16 v[68:71], v[198:201], v[190:193], v[68:71]
	v_mfma_f32_16x16x32_bf16 v[64:67], v[208:211], v[190:193], v[64:67]
	s_barrier
	s_mov_b32 m0, s74
	v_lshl_add_u64 v[214:215], s[62:63], 0, v[142:143]
	ds_read_b128 v[158:161], v168 offset:16384
	ds_read_b128 v[162:165], v168 offset:17408
	ds_read_b128 v[170:173], v168 offset:18432
	ds_read_b128 v[174:177], v168 offset:19456
	ds_read_b128 v[178:181], v168 offset:20480
	ds_read_b128 v[182:185], v168 offset:21504
	ds_read_b128 v[186:189], v168 offset:22528
	ds_read_b128 v[190:193], v168 offset:23552
	global_load_lds_dwordx4 v[214:215], off
	v_lshl_add_u64 v[216:217], s[62:63], 0, v[144:145]
	s_mov_b32 m0, s75
	s_nop 0
	global_load_lds_dwordx4 v[216:217], off
	s_barrier
	s_waitcnt lgkmcnt(0)
	v_mfma_f32_16x16x32_bf16 v[60:63], v[128:131], v[158:161], v[60:63]
	v_mfma_f32_16x16x32_bf16 v[56:59], v[136:139], v[158:161], v[56:59]
	v_mfma_f32_16x16x32_bf16 v[52:55], v[128:131], v[170:173], v[52:55]
	v_mfma_f32_16x16x32_bf16 v[44:47], v[136:139], v[170:173], v[44:47]
	v_mfma_f32_16x16x32_bf16 v[36:39], v[128:131], v[178:181], v[36:39]
	v_mfma_f32_16x16x32_bf16 v[28:31], v[136:139], v[178:181], v[28:31]
	v_mfma_f32_16x16x32_bf16 v[20:23], v[128:131], v[186:189], v[20:23]
	v_mfma_f32_16x16x32_bf16 v[12:15], v[136:139], v[186:189], v[12:15]
	v_mfma_f32_16x16x32_bf16 v[60:63], v[132:135], v[162:165], v[60:63]
	v_mfma_f32_16x16x32_bf16 v[56:59], v[154:157], v[162:165], v[56:59]
	v_mfma_f32_16x16x32_bf16 v[52:55], v[132:135], v[174:177], v[52:55]
	v_mfma_f32_16x16x32_bf16 v[44:47], v[154:157], v[174:177], v[44:47]
	v_mfma_f32_16x16x32_bf16 v[36:39], v[132:135], v[182:185], v[36:39]
	v_mfma_f32_16x16x32_bf16 v[28:31], v[154:157], v[182:185], v[28:31]
	v_mfma_f32_16x16x32_bf16 v[20:23], v[132:135], v[190:193], v[20:23]
	v_mfma_f32_16x16x32_bf16 v[12:15], v[154:157], v[190:193], v[12:15]
	s_barrier
; #define WAIT_V(n) asm volatile("s_waitcnt vmcnt(" #n ")" ::: "memory")
; #define WAIT_L(n) asm volatile("s_waitcnt lgkmcnt(" #n ")" ::: "memory")
; #define BAR __builtin_amdgcn_s_barrier()
; #define SCHED __builtin_amdgcn_sched_barrier(0)
; template <class Get, class Epi>
; DI void gemm_stream(LAS unsigned char* lds, const int K, const int ld, Get get, Epi epi) {
;     ...
;             STAGE(SBo(0, 1), b2 + hstep);
;             WAIT_V(6); BAR; MMA(1, 1, At, B1); BAR;
;             LDB(B0, 1, 0); SCHED; LDA(At, 1, 0); STAGE(SAo(0, 1), a2 + hstep);
;             WAIT_L(8); BAR; WAIT_L(0); MMA(0, 0, At, B0); BAR; SCHED;
;             LDB(B1, 1, 1); STAGE(SBo(1, 0), b3);
;             BAR; WAIT_L(0); MMA(0, 1, At, B1); BAR;
	s_add_u32 s86, s6, 0x80000
	s_addc_u32 s87, s7, 0
	s_add_i32 s88, s96, s35
	v_lshl_add_u64 v[128:129], s[86:87], 0, v[142:143]
	s_mov_b32 m0, s88
	s_nop 0
	global_load_lds_dwordx4 v[128:129], off
	v_lshl_add_u64 v[128:129], s[86:87], 0, v[144:145]
	s_add_i32 m0, s88, 0x2000
	s_nop 0
	global_load_lds_dwordx4 v[128:129], off
	s_waitcnt vmcnt(6)
	s_barrier
	v_mfma_f32_16x16x32_bf16 v[48:51], v[194:197], v[158:161], v[48:51]
	v_mfma_f32_16x16x32_bf16 v[40:43], v[202:205], v[158:161], v[40:43]
	v_mfma_f32_16x16x32_bf16 v[32:35], v[194:197], v[170:173], v[32:35]
	v_mfma_f32_16x16x32_bf16 v[24:27], v[202:205], v[170:173], v[24:27]
	v_mfma_f32_16x16x32_bf16 v[16:19], v[194:197], v[178:181], v[16:19]
	v_mfma_f32_16x16x32_bf16 v[8:11], v[202:205], v[178:181], v[8:11]
	v_mfma_f32_16x16x32_bf16 v[4:7], v[194:197], v[186:189], v[4:7]
	v_mfma_f32_16x16x32_bf16 v[0:3], v[202:205], v[186:189], v[0:3]
	v_mfma_f32_16x16x32_bf16 v[48:51], v[198:201], v[162:165], v[48:51]
	v_mfma_f32_16x16x32_bf16 v[40:43], v[208:211], v[162:165], v[40:43]
	v_mfma_f32_16x16x32_bf16 v[32:35], v[198:201], v[174:177], v[32:35]
	v_mfma_f32_16x16x32_bf16 v[24:27], v[208:211], v[174:177], v[24:27]
	v_mfma_f32_16x16x32_bf16 v[16:19], v[198:201], v[182:185], v[16:19]
	v_mfma_f32_16x16x32_bf16 v[8:11], v[208:211], v[182:185], v[8:11]
	v_mfma_f32_16x16x32_bf16 v[4:7], v[198:201], v[190:193], v[4:7]
	v_mfma_f32_16x16x32_bf16 v[0:3], v[208:211], v[190:193], v[0:3]
	s_add_i32 s86, 16, 0x18000
	v_add_u32_e32 v146, s86, v166
	s_barrier
	ds_read_b128 v[128:131], v146
	ds_read_b128 v[132:135], v146 offset:1024
	ds_read_b128 v[136:139], v146 offset:2048
	ds_read_b128 v[154:157], v146 offset:3072
	s_add_u32 s62, s62, 0x80000
	s_addc_u32 s63, s63, 0
	s_mov_b32 m0, s76
	v_lshl_add_u64 v[194:195], s[62:63], 0, v[142:143]
	ds_read_b128 v[158:161], v168 offset:32768
	ds_read_b128 v[162:165], v168 offset:33792
	ds_read_b128 v[170:173], v168 offset:34816
	ds_read_b128 v[174:177], v168 offset:35840
	ds_read_b128 v[178:181], v168 offset:36864
	ds_read_b128 v[182:185], v168 offset:37888
	ds_read_b128 v[186:189], v168 offset:38912
	ds_read_b128 v[190:193], v168 offset:39936
	global_load_lds_dwordx4 v[194:195], off
	v_lshl_add_u64 v[194:195], s[62:63], 0, v[144:145]
	s_mov_b32 m0, s77
	s_nop 0
	global_load_lds_dwordx4 v[194:195], off
	s_waitcnt lgkmcnt(8)
	s_barrier
	s_waitcnt lgkmcnt(0)
	v_mfma_f32_16x16x32_bf16 v[124:127], v[128:131], v[158:161], v[124:127]
	v_mfma_f32_16x16x32_bf16 v[120:123], v[136:139], v[158:161], v[120:123]
	v_mfma_f32_16x16x32_bf16 v[112:115], v[128:131], v[170:173], v[112:115]
	v_mfma_f32_16x16x32_bf16 v[108:111], v[136:139], v[170:173], v[108:111]
	v_mfma_f32_16x16x32_bf16 v[100:103], v[128:131], v[178:181], v[100:103]
	v_mfma_f32_16x16x32_bf16 v[92:95], v[136:139], v[178:181], v[92:95]
	v_mfma_f32_16x16x32_bf16 v[84:87], v[128:131], v[186:189], v[84:87]
	v_mfma_f32_16x16x32_bf16 v[76:79], v[136:139], v[186:189], v[76:79]
	v_mfma_f32_16x16x32_bf16 v[124:127], v[132:135], v[162:165], v[124:127]
	v_mfma_f32_16x16x32_bf16 v[120:123], v[154:157], v[162:165], v[120:123]
	v_mfma_f32_16x16x32_bf16 v[112:115], v[132:135], v[174:177], v[112:115]
	v_mfma_f32_16x16x32_bf16 v[108:111], v[154:157], v[174:177], v[108:111]
	v_mfma_f32_16x16x32_bf16 v[100:103], v[132:135], v[182:185], v[100:103]
	v_mfma_f32_16x16x32_bf16 v[92:95], v[154:157], v[182:185], v[92:95]
	v_mfma_f32_16x16x32_bf16 v[84:87], v[132:135], v[190:193], v[84:87]
	v_mfma_f32_16x16x32_bf16 v[76:79], v[154:157], v[190:193], v[76:79]
	s_barrier
	s_add_i32 s62, 16, 0x1c000
	s_add_i32 s63, s86, s35
	v_add_u32_e32 v146, s62, v166
	v_lshl_add_u64 v[140:141], v[140:141], 0, s[0:1]
	s_mov_b32 m0, s63
	ds_read_b128 v[194:197], v146
	ds_read_b128 v[198:201], v146 offset:1024
	ds_read_b128 v[202:205], v146 offset:2048
	ds_read_b128 v[208:211], v146 offset:3072
	global_load_lds_dwordx4 v[140:141], off
	v_lshl_add_u64 v[140:141], v[212:213], 0, s[0:1]
	s_add_i32 m0, s63, 0x2000
	s_nop 0
	global_load_lds_dwordx4 v[140:141], off
	s_barrier
	s_waitcnt lgkmcnt(0)
	v_mfma_f32_16x16x32_bf16 v[116:119], v[194:197], v[158:161], v[116:119]
	v_mfma_f32_16x16x32_bf16 v[104:107], v[202:205], v[158:161], v[104:107]
	v_mfma_f32_16x16x32_bf16 v[96:99], v[194:197], v[170:173], v[96:99]
	v_mfma_f32_16x16x32_bf16 v[88:91], v[202:205], v[170:173], v[88:91]
	v_mfma_f32_16x16x32_bf16 v[80:83], v[194:197], v[178:181], v[80:83]
	v_mfma_f32_16x16x32_bf16 v[72:75], v[202:205], v[178:181], v[72:75]
	v_mfma_f32_16x16x32_bf16 v[68:71], v[194:197], v[186:189], v[68:71]
	v_mfma_f32_16x16x32_bf16 v[64:67], v[202:205], v[186:189], v[64:67]
	v_mfma_f32_16x16x32_bf16 v[116:119], v[198:201], v[162:165], v[116:119]
	v_mfma_f32_16x16x32_bf16 v[104:107], v[208:211], v[162:165], v[104:107]
	v_mfma_f32_16x16x32_bf16 v[96:99], v[198:201], v[174:177], v[96:99]
	v_mfma_f32_16x16x32_bf16 v[88:91], v[208:211], v[174:177], v[88:91]
	v_mfma_f32_16x16x32_bf16 v[80:83], v[198:201], v[182:185], v[80:83]
	v_mfma_f32_16x16x32_bf16 v[72:75], v[208:211], v[182:185], v[72:75]
	v_mfma_f32_16x16x32_bf16 v[68:71], v[198:201], v[190:193], v[68:71]
	v_mfma_f32_16x16x32_bf16 v[64:67], v[208:211], v[190:193], v[64:67]
	s_barrier
; #define WAIT_V(n) asm volatile("s_waitcnt vmcnt(" #n ")" ::: "memory")
; #define WAIT_L(n) asm volatile("s_waitcnt lgkmcnt(" #n ")" ::: "memory")
; #define BAR __builtin_amdgcn_s_barrier()
; #define SCHED __builtin_amdgcn_sched_barrier(0)
; template <class Get, class Epi>
; DI void gemm_stream(LAS unsigned char* lds, const int K, const int ld, Get get, Epi epi) {
;     ...
;             BAR; WAIT_L(0); MMA(0, 1, At, B1); BAR;
;             LDA(At, 1, 1); STAGE(SAo(1, 0), a3);
;             BAR; WAIT_L(0); MMA(1, 0, At, B0); BAR; SCHED;
;             STAGE(SBo(1, 1), b3 + hstep);
;             WAIT_V(6); BAR; MMA(1, 1, At, B1); BAR;
;         }
; template <int R>
; DI void epi_rope(const Acc& acc, const P& p, int brow, bf16_t* __restrict__ dst, int ld, int coff, int bstride, const float* rs, int nblk_valid) {
;     EPI_IDX
;     const float* __restrict__ cosT = (const float*)(p.ws + (R == 128 ? O_COSA : O_COSB));
;     const float* __restrict__ sinT = (const float*)(p.ws + (R == 128 ? O_SINA : O_SINB));
;     const int b = brow / PB, p0 = brow - b * PB;
;     const bool ctx = p0 < CTXL;
; #pragma unroll
;     for (int ai = 0; ai < 2; ++ai)
; #pragma unroll
;         for (int m = 0; m < 4; ++m) {
;             const int lr = ai * 128 + wr * 64 + m * 16 + fr;
;             const float s = rs ? rs[lr] : 1.f;
;             const int sq = p0 + lr - CTXL;
; #pragma unroll
;             for (int bj = 0; bj < 2; ++bj) {
;                 const int blk = R == 128 ? bj : bj * 2 + (wc >> 1);
;                 const int d0 = (R == 128 ? wc * 16 : (wc & 1) * 16) + fq * 4;
;                 if (blk < nblk_valid) {
;                     f32x4 cv = {1.f, 1.f, 1.f, 1.f}, sv = {0.f, 0.f, 0.f, 0.f};
;                     if (!ctx) { cv = *(const f32x4*)(cosT + (size_t)sq * (R / 2) + d0); sv = *(const f32x4*)(sinT + (size_t)sq * (R / 2) + d0); }
	s_mov_b32 m0, s80
	v_lshl_add_u64 v[140:141], v[214:215], 0, s[0:1]
	ds_read_b128 v[158:161], v168 offset:49152
	ds_read_b128 v[162:165], v168 offset:50176
	ds_read_b128 v[170:173], v168 offset:51200
	ds_read_b128 v[174:177], v168 offset:52224
	ds_read_b128 v[178:181], v168 offset:53248
	ds_read_b128 v[182:185], v168 offset:54272
	ds_read_b128 v[186:189], v168 offset:55296
	ds_read_b128 v[190:193], v168 offset:56320
	global_load_lds_dwordx4 v[140:141], off
	v_lshl_add_u64 v[140:141], v[216:217], 0, s[0:1]
	s_mov_b32 m0, s81
	s_nop 0
	global_load_lds_dwordx4 v[140:141], off
	s_barrier
	s_waitcnt lgkmcnt(0)
	v_mfma_f32_16x16x32_bf16 v[60:63], v[128:131], v[158:161], v[60:63]
	v_mfma_f32_16x16x32_bf16 v[56:59], v[136:139], v[158:161], v[56:59]
	v_mfma_f32_16x16x32_bf16 v[52:55], v[128:131], v[170:173], v[52:55]
	v_mfma_f32_16x16x32_bf16 v[44:47], v[136:139], v[170:173], v[44:47]
	v_mfma_f32_16x16x32_bf16 v[36:39], v[128:131], v[178:181], v[36:39]
	v_mfma_f32_16x16x32_bf16 v[28:31], v[136:139], v[178:181], v[28:31]
	v_mfma_f32_16x16x32_bf16 v[20:23], v[128:131], v[186:189], v[20:23]
	v_mfma_f32_16x16x32_bf16 v[12:15], v[136:139], v[186:189], v[12:15]
	v_mfma_f32_16x16x32_bf16 v[60:63], v[132:135], v[162:165], v[60:63]
	v_mfma_f32_16x16x32_bf16 v[56:59], v[154:157], v[162:165], v[56:59]
	v_mfma_f32_16x16x32_bf16 v[52:55], v[132:135], v[174:177], v[52:55]
	v_mfma_f32_16x16x32_bf16 v[44:47], v[154:157], v[174:177], v[44:47]
	v_mfma_f32_16x16x32_bf16 v[36:39], v[132:135], v[182:185], v[36:39]
	v_mfma_f32_16x16x32_bf16 v[28:31], v[154:157], v[182:185], v[28:31]
	v_mfma_f32_16x16x32_bf16 v[20:23], v[132:135], v[190:193], v[20:23]
	v_mfma_f32_16x16x32_bf16 v[12:15], v[154:157], v[190:193], v[12:15]
	s_barrier
	s_add_u32 s6, s6, 0x80080
	s_addc_u32 s7, s7, 0
	s_add_i32 s62, s62, s35
	v_lshl_add_u64 v[128:129], s[6:7], 0, v[142:143]
	s_mov_b32 m0, s62
	s_nop 0
	global_load_lds_dwordx4 v[128:129], off
	v_lshl_add_u64 v[128:129], s[6:7], 0, v[144:145]
	s_add_i32 m0, s62, 0x2000
	s_nop 0
	global_load_lds_dwordx4 v[128:129], off
	s_add_i32 vcc_lo, vcc_lo, 2
	s_add_u32 s4, s4, 0x100
	s_addc_u32 s5, s5, 0
	s_add_u32 s29, s29, 0x100
	s_addc_u32 s55, s55, 0
	s_cmp_gt_u32 vcc_lo, 29
	s_waitcnt vmcnt(6)
	s_barrier
	v_mfma_f32_16x16x32_bf16 v[48:51], v[194:197], v[158:161], v[48:51]
	v_mfma_f32_16x16x32_bf16 v[40:43], v[202:205], v[158:161], v[40:43]
	v_mfma_f32_16x16x32_bf16 v[32:35], v[194:197], v[170:173], v[32:35]
	v_mfma_f32_16x16x32_bf16 v[24:27], v[202:205], v[170:173], v[24:27]
	v_mfma_f32_16x16x32_bf16 v[16:19], v[194:197], v[178:181], v[16:19]
	v_mfma_f32_16x16x32_bf16 v[8:11], v[202:205], v[178:181], v[8:11]
	v_mfma_f32_16x16x32_bf16 v[4:7], v[194:197], v[186:189], v[4:7]
	v_mfma_f32_16x16x32_bf16 v[0:3], v[202:205], v[186:189], v[0:3]
	v_mfma_f32_16x16x32_bf16 v[48:51], v[198:201], v[162:165], v[48:51]
	v_mfma_f32_16x16x32_bf16 v[40:43], v[208:211], v[162:165], v[40:43]
	v_mfma_f32_16x16x32_bf16 v[32:35], v[198:201], v[174:177], v[32:35]
	v_mfma_f32_16x16x32_bf16 v[24:27], v[208:211], v[174:177], v[24:27]
	v_mfma_f32_16x16x32_bf16 v[16:19], v[198:201], v[182:185], v[16:19]
	v_mfma_f32_16x16x32_bf16 v[8:11], v[208:211], v[182:185], v[8:11]
	v_mfma_f32_16x16x32_bf16 v[4:7], v[198:201], v[190:193], v[4:7]
	v_mfma_f32_16x16x32_bf16 v[0:3], v[208:211], v[190:193], v[0:3]
	s_barrier
	s_cbranch_scc0 .LBB0_726
	s_lshl_b32 s29, s21, 8
	s_cmp_lg_u32 s28, 5
	s_mov_b64 s[4:5], -1
	s_cbranch_scc0 .LBB0_849
	s_cmp_gt_i32 s28, 3
	s_cbranch_scc0 .LBB0_814
	s_cmp_lg_u32 s28, 4
	s_cbranch_scc0 .LBB0_779
	s_cmp_gt_u32 s28, 7
	s_cbranch_scc0 .LBB0_776
	s_cmp_lg_u32 s28, 8
	s_cbranch_scc0 .LBB0_773
	s_mul_hi_i32 s4, s29, 0x78787879
	s_lshr_b32 s5, s4, 31
	s_ashr_i32 s4, s4, 11
	v_mov_b32_e32 v128, v206
	s_add_i32 s4, s4, s5
	s_mulk_i32 s4, 0x1100
	v_and_b32_e32 v129, 15, v128
	v_ashrrev_i32_e32 v130, 2, v128
	s_sub_i32 s55, s29, s4
	v_and_or_b32 v154, v130, s97, v129
	v_lshrrev_b32_e32 v129, 2, v128
	s_cmpk_gt_i32 s55, 0xff
	v_and_b32_e32 v129, 28, v129
	s_cselect_b64 s[4:5], -1, 0
	v_lshlrev_b32_e32 v146, 2, v129
	v_and_b32_e32 v128, 0x80, v128
	v_lshl_add_u64 v[138:139], s[14:15], 0, v[146:147]
	v_lshl_add_u64 v[140:141], s[12:13], 0, v[146:147]
	v_lshlrev_b32_e32 v146, 1, v129
	v_cmp_eq_u32_e64 s[6:7], 0, v128
	v_cndmask_b32_e64 v128, 0, 1, s[4:5]
	s_addk_i32 s55, 0xff00
	v_lshl_add_u64 v[136:137], s[10:11], 0, v[146:147]
	v_cmp_ne_u32_e64 s[4:5], 1, v128
	s_and_saveexec_b64 s[62:63], s[6:7]
	s_cbranch_execz .LBB0_737
	s_and_b64 vcc, exec, s[4:5]
	s_cbranch_vccnz .LBB0_735
	v_add_u32_e32 v128, s55, v154
	v_ashrrev_i32_e32 v129, 31, v128
	v_lshlrev_b64 v[128:129], 7, v[128:129]
	v_lshl_add_u64 v[132:133], v[138:139], 0, v[128:129]
	v_lshl_add_u64 v[128:129], v[140:141], 0, v[128:129]
	global_load_dwordx4 v[128:131], v[128:129], off
	s_nop 0
	global_load_dwordx4 v[132:135], v[132:133], off
	s_branch .LBB0_736

; #define WAIT_L(n) asm volatile("s_waitcnt lgkmcnt(" #n ")" ::: "memory")
; #define BAR __builtin_amdgcn_s_barrier()
; #define SCHED __builtin_amdgcn_sched_barrier(0)
; DI void gemm_tile(const bf16_t* __restrict__ A, const bf16_t* __restrict__ Bt, const int K, const int brow, const int bcol, LAS unsigned char* lds, Acc& acc) {
;     ...
;         LDB(B0, 0, 0); SCHED; LDA(At, 0, 0); STAGE(SAo(1, 1), a1 + hstep);
;         WAIT_L(8); BAR; WAIT_L(0); MMA(0, 0, At, B0); BAR; SCHED;
;         LDB(B1, 0, 1); STAGE(SBo(0, 0), b2);
;         BAR; WAIT_L(0); MMA(0, 1, At, B1); BAR;
;         LDA(At, 0, 1); STAGE(SAo(0, 0), a2);
;         BAR; WAIT_L(0); MMA(1, 0, At, B0); BAR; SCHED;
.LBB0_930:
	s_add_i32 s6, 16, 0x10000
	v_add_u32_e32 v154, s6, v149
	ds_read_b128 v[150:153], v154
	ds_read_b128 v[160:163], v154 offset:1024
	ds_read_b128 v[164:167], v154 offset:2048
	ds_read_b128 v[168:171], v154 offset:3072
	s_add_i32 s62, s62, 2
	v_lshl_add_u64 v[154:155], v[134:135], 0, s[60:61]
	s_add_i32 s81, s86, 0xc000
	v_lshl_add_u64 v[204:205], v[154:155], 0, s[36:37]
	s_mov_b32 m0, s81
	ds_read_b128 v[172:175], v148
	ds_read_b128 v[176:179], v148 offset:1024
	ds_read_b128 v[180:183], v148 offset:2048
	ds_read_b128 v[184:187], v148 offset:3072
	ds_read_b128 v[188:191], v148 offset:4096
	ds_read_b128 v[192:195], v148 offset:5120
	ds_read_b128 v[196:199], v148 offset:6144
	ds_read_b128 v[200:203], v148 offset:7168
	global_load_lds_dwordx4 v[204:205], off
	v_lshl_add_u64 v[204:205], v[136:137], 0, s[60:61]
	s_add_i32 s63, s86, 0xe000
	v_lshl_add_u64 v[208:209], v[204:205], 0, s[36:37]
	s_mov_b32 m0, s63
	s_nop 0
	global_load_lds_dwordx4 v[208:209], off
	s_waitcnt lgkmcnt(8)
	s_barrier
	s_waitcnt lgkmcnt(0)
	v_mfma_f32_16x16x32_bf16 v[124:127], v[150:153], v[172:175], v[124:127]
	v_mfma_f32_16x16x32_bf16 v[120:123], v[164:167], v[172:175], v[120:123]
	v_mfma_f32_16x16x32_bf16 v[116:119], v[150:153], v[180:183], v[116:119]
	v_mfma_f32_16x16x32_bf16 v[112:115], v[164:167], v[180:183], v[112:115]
	v_mfma_f32_16x16x32_bf16 v[108:111], v[150:153], v[188:191], v[108:111]
	v_mfma_f32_16x16x32_bf16 v[104:107], v[164:167], v[188:191], v[104:107]
	v_mfma_f32_16x16x32_bf16 v[100:103], v[150:153], v[196:199], v[100:103]
	v_mfma_f32_16x16x32_bf16 v[96:99], v[164:167], v[196:199], v[96:99]
	v_mfma_f32_16x16x32_bf16 v[124:127], v[160:163], v[176:179], v[124:127]
	v_mfma_f32_16x16x32_bf16 v[120:123], v[168:171], v[176:179], v[120:123]
	v_mfma_f32_16x16x32_bf16 v[116:119], v[160:163], v[184:187], v[116:119]
	v_mfma_f32_16x16x32_bf16 v[112:115], v[168:171], v[184:187], v[112:115]
	v_mfma_f32_16x16x32_bf16 v[108:111], v[160:163], v[192:195], v[108:111]
	v_mfma_f32_16x16x32_bf16 v[104:107], v[168:171], v[192:195], v[104:107]
	v_mfma_f32_16x16x32_bf16 v[100:103], v[160:163], v[200:203], v[100:103]
	v_mfma_f32_16x16x32_bf16 v[96:99], v[168:171], v[200:203], v[96:99]
	s_barrier
	s_add_i32 s7, 16, 0x14000
	v_lshl_add_u64 v[224:225], v[138:139], 0, s[60:61]
	s_add_i32 s6, s6, s18
	v_add_u32_e32 v159, s7, v149
	v_lshl_add_u64 v[226:227], v[224:225], 0, s[38:39]
	s_mov_b32 m0, s6
	ds_read_b128 v[208:211], v159
	ds_read_b128 v[212:215], v159 offset:1024
	ds_read_b128 v[216:219], v159 offset:2048
	ds_read_b128 v[220:223], v159 offset:3072
	global_load_lds_dwordx4 v[226:227], off
	v_lshl_add_u64 v[226:227], v[140:141], 0, s[60:61]
	v_lshl_add_u64 v[228:229], v[226:227], 0, s[38:39]
	s_add_i32 m0, s6, 0x2000
	s_nop 0
	global_load_lds_dwordx4 v[228:229], off
	s_barrier
	s_waitcnt lgkmcnt(0)
	v_mfma_f32_16x16x32_bf16 v[92:95], v[208:211], v[172:175], v[92:95]
	v_mfma_f32_16x16x32_bf16 v[88:91], v[216:219], v[172:175], v[88:91]
	v_mfma_f32_16x16x32_bf16 v[84:87], v[208:211], v[180:183], v[84:87]
	v_mfma_f32_16x16x32_bf16 v[80:83], v[216:219], v[180:183], v[80:83]
	v_mfma_f32_16x16x32_bf16 v[76:79], v[208:211], v[188:191], v[76:79]
	v_mfma_f32_16x16x32_bf16 v[72:75], v[216:219], v[188:191], v[72:75]
	v_mfma_f32_16x16x32_bf16 v[68:71], v[208:211], v[196:199], v[68:71]
	v_mfma_f32_16x16x32_bf16 v[64:67], v[216:219], v[196:199], v[64:67]
	v_mfma_f32_16x16x32_bf16 v[92:95], v[212:215], v[176:179], v[92:95]
	v_mfma_f32_16x16x32_bf16 v[88:91], v[220:223], v[176:179], v[88:91]
	v_mfma_f32_16x16x32_bf16 v[84:87], v[212:215], v[184:187], v[84:87]
	v_mfma_f32_16x16x32_bf16 v[80:83], v[220:223], v[184:187], v[80:83]
	v_mfma_f32_16x16x32_bf16 v[76:79], v[212:215], v[192:195], v[76:79]
	v_mfma_f32_16x16x32_bf16 v[72:75], v[220:223], v[192:195], v[72:75]
	v_mfma_f32_16x16x32_bf16 v[68:71], v[212:215], v[200:203], v[68:71]
	v_mfma_f32_16x16x32_bf16 v[64:67], v[220:223], v[200:203], v[64:67]
	s_barrier
	v_lshl_add_u64 v[228:229], v[130:131], 0, s[60:61]
	s_mov_b32 m0, s86
	v_lshl_add_u64 v[230:231], v[228:229], 0, s[38:39]
	ds_read_b128 v[172:175], v148 offset:16384
	ds_read_b128 v[176:179], v148 offset:17408
	ds_read_b128 v[180:183], v148 offset:18432
	ds_read_b128 v[184:187], v148 offset:19456
	ds_read_b128 v[188:191], v148 offset:20480
	ds_read_b128 v[192:195], v148 offset:21504
	ds_read_b128 v[196:199], v148 offset:22528
	ds_read_b128 v[200:203], v148 offset:23552
	global_load_lds_dwordx4 v[230:231], off
	v_lshl_add_u64 v[230:231], v[132:133], 0, s[60:61]
	v_lshl_add_u64 v[232:233], v[230:231], 0, s[38:39]
	s_mov_b32 m0, s82
	s_nop 0
	global_load_lds_dwordx4 v[232:233], off
	s_barrier
	s_waitcnt lgkmcnt(0)
	v_mfma_f32_16x16x32_bf16 v[60:63], v[150:153], v[172:175], v[60:63]
	v_mfma_f32_16x16x32_bf16 v[56:59], v[164:167], v[172:175], v[56:59]
	v_mfma_f32_16x16x32_bf16 v[52:55], v[150:153], v[180:183], v[52:55]
	v_mfma_f32_16x16x32_bf16 v[48:51], v[164:167], v[180:183], v[48:51]
	v_mfma_f32_16x16x32_bf16 v[44:47], v[150:153], v[188:191], v[44:47]
	v_mfma_f32_16x16x32_bf16 v[40:43], v[164:167], v[188:191], v[40:43]
	v_mfma_f32_16x16x32_bf16 v[36:39], v[150:153], v[196:199], v[36:39]
	v_mfma_f32_16x16x32_bf16 v[32:35], v[164:167], v[196:199], v[32:35]
	v_mfma_f32_16x16x32_bf16 v[60:63], v[160:163], v[176:179], v[60:63]
	v_mfma_f32_16x16x32_bf16 v[56:59], v[168:171], v[176:179], v[56:59]
	v_mfma_f32_16x16x32_bf16 v[52:55], v[160:163], v[184:187], v[52:55]
	v_mfma_f32_16x16x32_bf16 v[48:51], v[168:171], v[184:187], v[48:51]
	v_mfma_f32_16x16x32_bf16 v[44:47], v[160:163], v[192:195], v[44:47]
	v_mfma_f32_16x16x32_bf16 v[40:43], v[168:171], v[192:195], v[40:43]
	v_mfma_f32_16x16x32_bf16 v[36:39], v[160:163], v[200:203], v[36:39]
	v_mfma_f32_16x16x32_bf16 v[32:35], v[168:171], v[200:203], v[32:35]
	s_barrier
; #define WAIT_V(n) asm volatile("s_waitcnt vmcnt(" #n ")" ::: "memory")
; #define WAIT_L(n) asm volatile("s_waitcnt lgkmcnt(" #n ")" ::: "memory")
; #define BAR __builtin_amdgcn_s_barrier()
; #define SCHED __builtin_amdgcn_sched_barrier(0)
; DI void gemm_tile(const bf16_t* __restrict__ A, const bf16_t* __restrict__ Bt, const int K, const int brow, const int bcol, LAS unsigned char* lds, Acc& acc) {
;     ...
;         BAR; WAIT_L(0); MMA(1, 0, At, B0); BAR; SCHED;
;         STAGE(SBo(0, 1), b2 + hstep);
;         WAIT_V(6); BAR; MMA(1, 1, At, B1); BAR;
;         LDB(B0, 1, 0); SCHED; LDA(At, 1, 0); STAGE(SAo(0, 1), a2 + hstep);
;         WAIT_L(8); BAR; WAIT_L(0); MMA(0, 0, At, B0); BAR; SCHED;
;         LDB(B1, 1, 1); STAGE(SBo(1, 0), b3);
;         BAR; WAIT_L(0); MMA(0, 1, At, B1); BAR;
	v_lshl_add_u64 v[232:233], v[144:145], 0, s[60:61]
	s_add_i32 s6, s7, s18
	v_lshl_add_u64 v[150:151], v[232:233], 0, s[38:39]
	s_mov_b32 m0, s6
	v_lshl_add_u64 v[234:235], v[146:147], 0, s[60:61]
	global_load_lds_dwordx4 v[150:151], off
	v_lshl_add_u64 v[150:151], v[234:235], 0, s[38:39]
	s_add_i32 m0, s6, 0x2000
	s_nop 0
	global_load_lds_dwordx4 v[150:151], off
	s_waitcnt vmcnt(6)
	s_barrier
	v_mfma_f32_16x16x32_bf16 v[28:31], v[208:211], v[172:175], v[28:31]
	v_mfma_f32_16x16x32_bf16 v[24:27], v[216:219], v[172:175], v[24:27]
	v_mfma_f32_16x16x32_bf16 v[20:23], v[208:211], v[180:183], v[20:23]
	v_mfma_f32_16x16x32_bf16 v[16:19], v[216:219], v[180:183], v[16:19]
	v_mfma_f32_16x16x32_bf16 v[12:15], v[208:211], v[188:191], v[12:15]
	v_mfma_f32_16x16x32_bf16 v[8:11], v[216:219], v[188:191], v[8:11]
	v_mfma_f32_16x16x32_bf16 v[4:7], v[208:211], v[196:199], v[4:7]
	v_mfma_f32_16x16x32_bf16 v[0:3], v[216:219], v[196:199], v[0:3]
	v_mfma_f32_16x16x32_bf16 v[28:31], v[212:215], v[176:179], v[28:31]
	v_mfma_f32_16x16x32_bf16 v[24:27], v[220:223], v[176:179], v[24:27]
	v_mfma_f32_16x16x32_bf16 v[20:23], v[212:215], v[184:187], v[20:23]
	v_mfma_f32_16x16x32_bf16 v[16:19], v[220:223], v[184:187], v[16:19]
	v_mfma_f32_16x16x32_bf16 v[12:15], v[212:215], v[192:195], v[12:15]
	v_mfma_f32_16x16x32_bf16 v[8:11], v[220:223], v[192:195], v[8:11]
	v_mfma_f32_16x16x32_bf16 v[4:7], v[212:215], v[200:203], v[4:7]
	v_mfma_f32_16x16x32_bf16 v[0:3], v[220:223], v[200:203], v[0:3]
	s_add_i32 s6, 16, 0x18000
	v_add_u32_e32 v159, s6, v149
	s_barrier
	ds_read_b128 v[150:153], v159
	ds_read_b128 v[160:163], v159 offset:1024
	ds_read_b128 v[164:167], v159 offset:2048
	ds_read_b128 v[168:171], v159 offset:3072
	s_mov_b32 m0, s83
	v_lshl_add_u64 v[154:155], v[154:155], 0, s[38:39]
	ds_read_b128 v[172:175], v148 offset:32768
	ds_read_b128 v[176:179], v148 offset:33792
	ds_read_b128 v[180:183], v148 offset:34816
	ds_read_b128 v[184:187], v148 offset:35840
	ds_read_b128 v[188:191], v148 offset:36864
	ds_read_b128 v[192:195], v148 offset:37888
	ds_read_b128 v[196:199], v148 offset:38912
	ds_read_b128 v[200:203], v148 offset:39936
	global_load_lds_dwordx4 v[154:155], off
	v_lshl_add_u64 v[154:155], v[204:205], 0, s[38:39]
	s_mov_b32 m0, s85
	s_nop 0
	global_load_lds_dwordx4 v[154:155], off
	s_waitcnt lgkmcnt(8)
	s_barrier
	s_waitcnt lgkmcnt(0)
	v_mfma_f32_16x16x32_bf16 v[124:127], v[150:153], v[172:175], v[124:127]
	v_mfma_f32_16x16x32_bf16 v[120:123], v[164:167], v[172:175], v[120:123]
	v_mfma_f32_16x16x32_bf16 v[116:119], v[150:153], v[180:183], v[116:119]
	v_mfma_f32_16x16x32_bf16 v[112:115], v[164:167], v[180:183], v[112:115]
	v_mfma_f32_16x16x32_bf16 v[108:111], v[150:153], v[188:191], v[108:111]
	v_mfma_f32_16x16x32_bf16 v[104:107], v[164:167], v[188:191], v[104:107]
	v_mfma_f32_16x16x32_bf16 v[100:103], v[150:153], v[196:199], v[100:103]
	v_mfma_f32_16x16x32_bf16 v[96:99], v[164:167], v[196:199], v[96:99]
	v_mfma_f32_16x16x32_bf16 v[124:127], v[160:163], v[176:179], v[124:127]
	v_mfma_f32_16x16x32_bf16 v[120:123], v[168:171], v[176:179], v[120:123]
	v_mfma_f32_16x16x32_bf16 v[116:119], v[160:163], v[184:187], v[116:119]
	v_mfma_f32_16x16x32_bf16 v[112:115], v[168:171], v[184:187], v[112:115]
	v_mfma_f32_16x16x32_bf16 v[108:111], v[160:163], v[192:195], v[108:111]
	v_mfma_f32_16x16x32_bf16 v[104:107], v[168:171], v[192:195], v[104:107]
	v_mfma_f32_16x16x32_bf16 v[100:103], v[160:163], v[200:203], v[100:103]
	v_mfma_f32_16x16x32_bf16 v[96:99], v[168:171], v[200:203], v[96:99]
	s_barrier
	s_add_i32 s7, 16, 0x1c000
	v_add_u32_e32 v154, s7, v149
	s_add_i32 s6, s6, s18
	ds_read_b128 v[208:211], v154
	ds_read_b128 v[212:215], v154 offset:1024
	ds_read_b128 v[216:219], v154 offset:2048
	ds_read_b128 v[220:223], v154 offset:3072
	v_lshl_add_u64 v[154:155], v[224:225], 0, s[40:41]
	s_mov_b32 m0, s6
	s_nop 0
	global_load_lds_dwordx4 v[154:155], off
	v_lshl_add_u64 v[154:155], v[226:227], 0, s[40:41]
	s_add_i32 m0, s6, 0x2000
	s_nop 0
	global_load_lds_dwordx4 v[154:155], off
	s_barrier
	s_waitcnt lgkmcnt(0)
	v_mfma_f32_16x16x32_bf16 v[92:95], v[208:211], v[172:175], v[92:95]
	v_mfma_f32_16x16x32_bf16 v[88:91], v[216:219], v[172:175], v[88:91]
	v_mfma_f32_16x16x32_bf16 v[84:87], v[208:211], v[180:183], v[84:87]
	v_mfma_f32_16x16x32_bf16 v[80:83], v[216:219], v[180:183], v[80:83]
	v_mfma_f32_16x16x32_bf16 v[76:79], v[208:211], v[188:191], v[76:79]
	v_mfma_f32_16x16x32_bf16 v[72:75], v[216:219], v[188:191], v[72:75]
	v_mfma_f32_16x16x32_bf16 v[68:71], v[208:211], v[196:199], v[68:71]
	v_mfma_f32_16x16x32_bf16 v[64:67], v[216:219], v[196:199], v[64:67]
	v_mfma_f32_16x16x32_bf16 v[92:95], v[212:215], v[176:179], v[92:95]
	v_mfma_f32_16x16x32_bf16 v[88:91], v[220:223], v[176:179], v[88:91]
	v_mfma_f32_16x16x32_bf16 v[84:87], v[212:215], v[184:187], v[84:87]
	v_mfma_f32_16x16x32_bf16 v[80:83], v[220:223], v[184:187], v[80:83]
	v_mfma_f32_16x16x32_bf16 v[76:79], v[212:215], v[192:195], v[76:79]
	v_mfma_f32_16x16x32_bf16 v[72:75], v[220:223], v[192:195], v[72:75]
	v_mfma_f32_16x16x32_bf16 v[68:71], v[212:215], v[200:203], v[68:71]
	v_mfma_f32_16x16x32_bf16 v[64:67], v[220:223], v[200:203], v[64:67]
	s_barrier
	s_mov_b32 m0, s97
	v_lshl_add_u64 v[154:155], v[228:229], 0, s[40:41]
	ds_read_b128 v[172:175], v148 offset:49152
	ds_read_b128 v[176:179], v148 offset:50176
	ds_read_b128 v[180:183], v148 offset:51200
	ds_read_b128 v[184:187], v148 offset:52224
	ds_read_b128 v[188:191], v148 offset:53248
	ds_read_b128 v[192:195], v148 offset:54272
	ds_read_b128 v[196:199], v148 offset:55296
	ds_read_b128 v[200:203], v148 offset:56320
	global_load_lds_dwordx4 v[154:155], off
	v_lshl_add_u64 v[154:155], v[230:231], 0, s[40:41]
	s_mov_b32 m0, vcc_lo
	s_nop 0
	global_load_lds_dwordx4 v[154:155], off
	s_barrier
; #define WAIT_V(n) asm volatile("s_waitcnt vmcnt(" #n ")" ::: "memory")
; #define WAIT_L(n) asm volatile("s_waitcnt lgkmcnt(" #n ")" ::: "memory")
; #define BAR __builtin_amdgcn_s_barrier()
; #define SCHED __builtin_amdgcn_sched_barrier(0)
; DI void gemm_tile(const bf16_t* __restrict__ A, const bf16_t* __restrict__ Bt, const int K, const int brow, const int bcol, LAS unsigned char* lds, Acc& acc) {
;     ...
;         BAR; WAIT_L(0); MMA(0, 1, At, B1); BAR;
;         LDA(At, 1, 1); STAGE(SAo(1, 0), a3);
;         BAR; WAIT_L(0); MMA(1, 0, At, B0); BAR; SCHED;
;         STAGE(SBo(1, 1), b3 + hstep);
;         WAIT_V(6); BAR; MMA(1, 1, At, B1); BAR;
;     }
;     { LDB(B0, 0, 0); LDA(At, 0, 0); STAGE(SAo(1, 1), cA + (size_t)(nt - 1) * kstep + hstep);
;       BAR; WAIT_L(0); MMA(0, 0, At, B0); BAR;
;       LDB(B1, 0, 1); BAR; WAIT_L(0); MMA(0, 1, At, B1); BAR;
	s_waitcnt lgkmcnt(0)
	v_mfma_f32_16x16x32_bf16 v[60:63], v[150:153], v[172:175], v[60:63]
	v_mfma_f32_16x16x32_bf16 v[56:59], v[164:167], v[172:175], v[56:59]
	v_mfma_f32_16x16x32_bf16 v[52:55], v[150:153], v[180:183], v[52:55]
	v_mfma_f32_16x16x32_bf16 v[48:51], v[164:167], v[180:183], v[48:51]
	v_mfma_f32_16x16x32_bf16 v[44:47], v[150:153], v[188:191], v[44:47]
	v_mfma_f32_16x16x32_bf16 v[40:43], v[164:167], v[188:191], v[40:43]
	v_mfma_f32_16x16x32_bf16 v[36:39], v[150:153], v[196:199], v[36:39]
	v_mfma_f32_16x16x32_bf16 v[32:35], v[164:167], v[196:199], v[32:35]
	v_mfma_f32_16x16x32_bf16 v[60:63], v[160:163], v[176:179], v[60:63]
	v_mfma_f32_16x16x32_bf16 v[56:59], v[168:171], v[176:179], v[56:59]
	v_mfma_f32_16x16x32_bf16 v[52:55], v[160:163], v[184:187], v[52:55]
	v_mfma_f32_16x16x32_bf16 v[48:51], v[168:171], v[184:187], v[48:51]
	v_mfma_f32_16x16x32_bf16 v[44:47], v[160:163], v[192:195], v[44:47]
	v_mfma_f32_16x16x32_bf16 v[40:43], v[168:171], v[192:195], v[40:43]
	v_mfma_f32_16x16x32_bf16 v[36:39], v[160:163], v[200:203], v[36:39]
	v_mfma_f32_16x16x32_bf16 v[32:35], v[168:171], v[200:203], v[32:35]
	s_barrier
	s_add_i32 s6, s7, s18
	v_lshl_add_u64 v[150:151], v[232:233], 0, s[40:41]
	s_mov_b32 m0, s6
	s_nop 0
	global_load_lds_dwordx4 v[150:151], off
	v_lshl_add_u64 v[150:151], v[234:235], 0, s[40:41]
	s_add_i32 m0, s6, 0x2000
	s_nop 0
	global_load_lds_dwordx4 v[150:151], off
	s_add_u32 s60, s60, 0x100
	s_addc_u32 s61, s61, 0
	s_cmp_ge_u32 s62, vcc_hi
	s_waitcnt vmcnt(6)
	s_barrier
	v_mfma_f32_16x16x32_bf16 v[28:31], v[208:211], v[172:175], v[28:31]
	v_mfma_f32_16x16x32_bf16 v[24:27], v[216:219], v[172:175], v[24:27]
	v_mfma_f32_16x16x32_bf16 v[20:23], v[208:211], v[180:183], v[20:23]
	v_mfma_f32_16x16x32_bf16 v[16:19], v[216:219], v[180:183], v[16:19]
	v_mfma_f32_16x16x32_bf16 v[12:15], v[208:211], v[188:191], v[12:15]
	v_mfma_f32_16x16x32_bf16 v[8:11], v[216:219], v[188:191], v[8:11]
	v_mfma_f32_16x16x32_bf16 v[4:7], v[208:211], v[196:199], v[4:7]
	v_mfma_f32_16x16x32_bf16 v[0:3], v[216:219], v[196:199], v[0:3]
	v_mfma_f32_16x16x32_bf16 v[28:31], v[212:215], v[176:179], v[28:31]
	v_mfma_f32_16x16x32_bf16 v[24:27], v[220:223], v[176:179], v[24:27]
	v_mfma_f32_16x16x32_bf16 v[20:23], v[212:215], v[184:187], v[20:23]
	v_mfma_f32_16x16x32_bf16 v[16:19], v[220:223], v[184:187], v[16:19]
	v_mfma_f32_16x16x32_bf16 v[12:15], v[212:215], v[192:195], v[12:15]
	v_mfma_f32_16x16x32_bf16 v[8:11], v[220:223], v[192:195], v[8:11]
	v_mfma_f32_16x16x32_bf16 v[4:7], v[212:215], v[200:203], v[4:7]
	v_mfma_f32_16x16x32_bf16 v[0:3], v[220:223], v[200:203], v[0:3]
	s_barrier
	s_cbranch_scc0 .LBB0_930
	s_add_i32 s18, s96, -1
	s_lshl_b64 s[6:7], s[18:19], 7
	s_add_u32 s4, s4, s6
	s_addc_u32 s5, s5, s7
	s_add_u32 s4, s4, s55
	v_add_u32_e32 v149, 16, v149
	s_addc_u32 s5, s5, 0
	s_mov_b32 m0, s81
	v_add_u32_e32 v144, 0x10000, v149
	v_lshl_add_u64 v[154:155], s[4:5], 0, v[142:143]
	ds_read_b128 v[130:133], v144
	ds_read_b128 v[134:137], v144 offset:1024
	ds_read_b128 v[138:141], v144 offset:2048
	ds_read_b128 v[144:147], v144 offset:3072
	ds_read_b128 v[150:153], v148
	ds_read_b128 v[160:163], v148 offset:1024
	ds_read_b128 v[164:167], v148 offset:2048
	ds_read_b128 v[168:171], v148 offset:3072
	ds_read_b128 v[172:175], v148 offset:4096
	ds_read_b128 v[176:179], v148 offset:5120
	ds_read_b128 v[180:183], v148 offset:6144
	ds_read_b128 v[184:187], v148 offset:7168
	global_load_lds_dwordx4 v[154:155], off
	v_lshl_add_u64 v[128:129], s[4:5], 0, v[128:129]
	s_mov_b32 m0, s63
	s_nop 0
	global_load_lds_dwordx4 v[128:129], off
	s_barrier
	s_waitcnt lgkmcnt(0)
	v_mfma_f32_16x16x32_bf16 v[124:127], v[130:133], v[150:153], v[124:127]
	v_mfma_f32_16x16x32_bf16 v[120:123], v[138:141], v[150:153], v[120:123]
	v_mfma_f32_16x16x32_bf16 v[116:119], v[130:133], v[164:167], v[116:119]
	v_mfma_f32_16x16x32_bf16 v[112:115], v[138:141], v[164:167], v[112:115]
	v_mfma_f32_16x16x32_bf16 v[100:103], v[130:133], v[180:183], v[100:103]
	v_mfma_f32_16x16x32_bf16 v[96:99], v[138:141], v[180:183], v[96:99]
	v_mfma_f32_16x16x32_bf16 v[124:127], v[134:137], v[160:163], v[124:127]
	v_mfma_f32_16x16x32_bf16 v[120:123], v[144:147], v[160:163], v[120:123]
	v_mfma_f32_16x16x32_bf16 v[116:119], v[134:137], v[168:171], v[116:119]
	v_mfma_f32_16x16x32_bf16 v[112:115], v[144:147], v[168:171], v[112:115]
	v_mfma_f32_16x16x32_bf16 v[108:111], v[130:133], v[172:175], v[108:111]
	v_mfma_f32_16x16x32_bf16 v[104:107], v[138:141], v[172:175], v[104:107]
	v_mfma_f32_16x16x32_bf16 v[100:103], v[134:137], v[184:187], v[100:103]
	v_mfma_f32_16x16x32_bf16 v[96:99], v[144:147], v[184:187], v[96:99]
	v_mfma_f32_16x16x32_bf16 v[188:191], v[134:137], v[176:179], v[108:111]
	v_mfma_f32_16x16x32_bf16 v[192:195], v[144:147], v[176:179], v[104:107]
	v_add_u32_e32 v128, 0x14000, v149
	s_barrier
	s_nop 0
	ds_read_b128 v[104:107], v128
	ds_read_b128 v[108:111], v128 offset:1024
	ds_read_b128 v[196:199], v128 offset:2048
	ds_read_b128 v[200:203], v128 offset:3072
	s_barrier
	s_waitcnt lgkmcnt(0)
	v_mfma_f32_16x16x32_bf16 v[84:87], v[104:107], v[164:167], v[84:87]
	v_mfma_f32_16x16x32_bf16 v[80:83], v[196:199], v[164:167], v[80:83]
	v_mfma_f32_16x16x32_bf16 v[68:71], v[104:107], v[180:183], v[68:71]
	v_mfma_f32_16x16x32_bf16 v[64:67], v[196:199], v[180:183], v[64:67]
	v_mfma_f32_16x16x32_bf16 v[92:95], v[104:107], v[150:153], v[92:95]
	v_mfma_f32_16x16x32_bf16 v[88:91], v[196:199], v[150:153], v[88:91]
	v_mfma_f32_16x16x32_bf16 v[84:87], v[108:111], v[168:171], v[84:87]
	v_mfma_f32_16x16x32_bf16 v[80:83], v[200:203], v[168:171], v[80:83]
	v_mfma_f32_16x16x32_bf16 v[76:79], v[104:107], v[172:175], v[76:79]
	v_mfma_f32_16x16x32_bf16 v[72:75], v[196:199], v[172:175], v[72:75]
	v_mfma_f32_16x16x32_bf16 v[68:71], v[108:111], v[184:187], v[68:71]
	v_mfma_f32_16x16x32_bf16 v[64:67], v[200:203], v[184:187], v[64:67]
	v_mfma_f32_16x16x32_bf16 v[208:211], v[108:111], v[160:163], v[92:95]
	v_mfma_f32_16x16x32_bf16 v[150:153], v[200:203], v[160:163], v[88:91]
	v_mfma_f32_16x16x32_bf16 v[160:163], v[108:111], v[176:179], v[76:79]
	v_mfma_f32_16x16x32_bf16 v[164:167], v[200:203], v[176:179], v[72:75]
	s_barrier
; #define WAIT_V(n) asm volatile("s_waitcnt vmcnt(" #n ")" ::: "memory")
; #define WAIT_L(n) asm volatile("s_waitcnt lgkmcnt(" #n ")" ::: "memory")
; #define BAR __builtin_amdgcn_s_barrier()
; DI void gemm_tile(const bf16_t* __restrict__ A, const bf16_t* __restrict__ Bt, const int K, const int brow, const int bcol, LAS unsigned char* lds, Acc& acc) {
;     ...
;       LDB(B1, 0, 1); BAR; WAIT_L(0); MMA(0, 1, At, B1); BAR;
;       LDA(At, 0, 1); WAIT_V(4); BAR; WAIT_L(0); MMA(1, 0, At, B0); MMA(1, 1, At, B1); BAR; }
;     { LDB(B0, 1, 0); LDA(At, 1, 0); WAIT_V(2); BAR; WAIT_L(0); MMA(0, 0, At, B0); BAR;
;       LDB(B1, 1, 1); WAIT_V(0); BAR; WAIT_L(0); MMA(0, 1, At, B1); BAR;
	s_nop 0
	ds_read_b128 v[72:75], v148 offset:16384
	ds_read_b128 v[76:79], v148 offset:17408
	ds_read_b128 v[88:91], v148 offset:18432
	ds_read_b128 v[92:95], v148 offset:19456
	ds_read_b128 v[168:171], v148 offset:20480
	ds_read_b128 v[172:175], v148 offset:21504
	ds_read_b128 v[176:179], v148 offset:22528
	ds_read_b128 v[180:183], v148 offset:23552
	s_waitcnt vmcnt(4)
	s_barrier
	s_waitcnt lgkmcnt(0)
	v_mfma_f32_16x16x32_bf16 v[60:63], v[130:133], v[72:75], v[60:63]
	v_mfma_f32_16x16x32_bf16 v[56:59], v[138:141], v[72:75], v[56:59]
	v_mfma_f32_16x16x32_bf16 v[52:55], v[130:133], v[88:91], v[52:55]
	v_mfma_f32_16x16x32_bf16 v[48:51], v[138:141], v[88:91], v[48:51]
	v_mfma_f32_16x16x32_bf16 v[36:39], v[130:133], v[176:179], v[36:39]
	v_mfma_f32_16x16x32_bf16 v[32:35], v[138:141], v[176:179], v[32:35]
	v_mfma_f32_16x16x32_bf16 v[60:63], v[134:137], v[76:79], v[60:63]
	v_mfma_f32_16x16x32_bf16 v[56:59], v[144:147], v[76:79], v[56:59]
	v_mfma_f32_16x16x32_bf16 v[52:55], v[134:137], v[92:95], v[52:55]
	v_mfma_f32_16x16x32_bf16 v[48:51], v[144:147], v[92:95], v[48:51]
	v_mfma_f32_16x16x32_bf16 v[44:47], v[130:133], v[168:171], v[44:47]
	v_mfma_f32_16x16x32_bf16 v[40:43], v[138:141], v[168:171], v[40:43]
	v_mfma_f32_16x16x32_bf16 v[36:39], v[134:137], v[180:183], v[36:39]
	v_mfma_f32_16x16x32_bf16 v[32:35], v[144:147], v[180:183], v[32:35]
	v_mfma_f32_16x16x32_bf16 v[184:187], v[134:137], v[172:175], v[44:47]
	v_mfma_f32_16x16x32_bf16 v[212:215], v[144:147], v[172:175], v[40:43]
	v_mfma_f32_16x16x32_bf16 v[20:23], v[104:107], v[88:91], v[20:23]
	v_mfma_f32_16x16x32_bf16 v[16:19], v[196:199], v[88:91], v[16:19]
	v_mfma_f32_16x16x32_bf16 v[4:7], v[104:107], v[176:179], v[4:7]
	v_mfma_f32_16x16x32_bf16 v[0:3], v[196:199], v[176:179], v[0:3]
	v_mfma_f32_16x16x32_bf16 v[28:31], v[104:107], v[72:75], v[28:31]
	v_mfma_f32_16x16x32_bf16 v[24:27], v[196:199], v[72:75], v[24:27]
	v_mfma_f32_16x16x32_bf16 v[20:23], v[108:111], v[92:95], v[20:23]
	v_mfma_f32_16x16x32_bf16 v[16:19], v[200:203], v[92:95], v[16:19]
	v_mfma_f32_16x16x32_bf16 v[12:15], v[104:107], v[168:171], v[12:15]
	v_mfma_f32_16x16x32_bf16 v[8:11], v[196:199], v[168:171], v[8:11]
	v_mfma_f32_16x16x32_bf16 v[4:7], v[108:111], v[180:183], v[4:7]
	v_mfma_f32_16x16x32_bf16 v[0:3], v[200:203], v[180:183], v[0:3]
	v_mfma_f32_16x16x32_bf16 v[128:131], v[108:111], v[76:79], v[28:31]
	v_mfma_f32_16x16x32_bf16 v[132:135], v[200:203], v[76:79], v[24:27]
	v_mfma_f32_16x16x32_bf16 v[136:139], v[108:111], v[172:175], v[12:15]
	v_mfma_f32_16x16x32_bf16 v[144:147], v[200:203], v[172:175], v[8:11]
	v_add_u32_e32 v24, 0x18000, v149
	s_barrier
	ds_read_b128 v[8:11], v24
	ds_read_b128 v[12:15], v24 offset:1024
	ds_read_b128 v[168:171], v24 offset:2048
	ds_read_b128 v[172:175], v24 offset:3072
	ds_read_b128 v[24:27], v148 offset:32768
	ds_read_b128 v[28:31], v148 offset:33792
	ds_read_b128 v[40:43], v148 offset:34816
	ds_read_b128 v[44:47], v148 offset:35840
	ds_read_b128 v[176:179], v148 offset:36864
	ds_read_b128 v[180:183], v148 offset:37888
	ds_read_b128 v[196:199], v148 offset:38912
	ds_read_b128 v[200:203], v148 offset:39936
	s_waitcnt vmcnt(2)
	s_barrier
	s_waitcnt lgkmcnt(0)
	v_mfma_f32_16x16x32_bf16 v[72:75], v[8:11], v[24:27], v[124:127]
	v_mfma_f32_16x16x32_bf16 v[124:127], v[12:15], v[28:31], v[72:75]
	v_mfma_f32_16x16x32_bf16 v[72:75], v[168:171], v[24:27], v[120:123]
	v_mfma_f32_16x16x32_bf16 v[120:123], v[172:175], v[28:31], v[72:75]
	v_mfma_f32_16x16x32_bf16 v[72:75], v[8:11], v[40:43], v[116:119]
	v_mfma_f32_16x16x32_bf16 v[108:111], v[12:15], v[44:47], v[72:75]
	v_mfma_f32_16x16x32_bf16 v[72:75], v[168:171], v[40:43], v[112:115]
	v_mfma_f32_16x16x32_bf16 v[104:107], v[172:175], v[44:47], v[72:75]
	v_mfma_f32_16x16x32_bf16 v[72:75], v[8:11], v[176:179], v[188:191]
	v_mfma_f32_16x16x32_bf16 v[92:95], v[12:15], v[180:183], v[72:75]
	v_mfma_f32_16x16x32_bf16 v[72:75], v[168:171], v[176:179], v[192:195]
	v_mfma_f32_16x16x32_bf16 v[88:91], v[172:175], v[180:183], v[72:75]
	v_mfma_f32_16x16x32_bf16 v[72:75], v[8:11], v[196:199], v[100:103]
	v_mfma_f32_16x16x32_bf16 v[76:79], v[12:15], v[200:203], v[72:75]
	v_mfma_f32_16x16x32_bf16 v[72:75], v[168:171], v[196:199], v[96:99]
	v_mfma_f32_16x16x32_bf16 v[72:75], v[172:175], v[200:203], v[72:75]
	s_nop 0
	v_add_u32_e32 v96, 0x1c000, v149
	s_barrier
; #define WAIT_V(n) asm volatile("s_waitcnt vmcnt(" #n ")" ::: "memory")
; #define WAIT_L(n) asm volatile("s_waitcnt lgkmcnt(" #n ")" ::: "memory")
; #define BAR __builtin_amdgcn_s_barrier()
; DI void gemm_tile(const bf16_t* __restrict__ A, const bf16_t* __restrict__ Bt, const int K, const int brow, const int bcol, LAS unsigned char* lds, Acc& acc) {
;     ...
;       LDB(B1, 1, 1); WAIT_V(0); BAR; WAIT_L(0); MMA(0, 1, At, B1); BAR;
;       LDA(At, 1, 1); BAR; WAIT_L(0); MMA(1, 0, At, B0); MMA(1, 1, At, B1); BAR; }
;     if (wr == 0) BAR;
; DI void phase_qkvb(const P& p, char* shm) {
;     ...
;         if (isq) {
;             if (pn < 4) {
	ds_read_b128 v[188:191], v96
	ds_read_b128 v[192:195], v96 offset:1024
	ds_read_b128 v[216:219], v96 offset:2048
	ds_read_b128 v[220:223], v96 offset:3072
	s_waitcnt vmcnt(0)
	s_barrier
	s_waitcnt lgkmcnt(0)
	v_mfma_f32_16x16x32_bf16 v[96:99], v[188:191], v[24:27], v[208:211]
	v_mfma_f32_16x16x32_bf16 v[24:27], v[216:219], v[24:27], v[150:153]
	v_mfma_f32_16x16x32_bf16 v[112:115], v[220:223], v[28:31], v[24:27]
	v_mfma_f32_16x16x32_bf16 v[24:27], v[188:191], v[40:43], v[84:87]
	v_mfma_f32_16x16x32_bf16 v[100:103], v[192:195], v[44:47], v[24:27]
	v_mfma_f32_16x16x32_bf16 v[24:27], v[216:219], v[40:43], v[80:83]
	v_mfma_f32_16x16x32_bf16 v[116:119], v[192:195], v[28:31], v[96:99]
	v_mfma_f32_16x16x32_bf16 v[96:99], v[220:223], v[44:47], v[24:27]
	v_mfma_f32_16x16x32_bf16 v[24:27], v[188:191], v[176:179], v[160:163]
	v_mfma_f32_16x16x32_bf16 v[84:87], v[192:195], v[180:183], v[24:27]
	v_mfma_f32_16x16x32_bf16 v[24:27], v[216:219], v[176:179], v[164:167]
	v_mfma_f32_16x16x32_bf16 v[80:83], v[220:223], v[180:183], v[24:27]
	v_mfma_f32_16x16x32_bf16 v[24:27], v[188:191], v[196:199], v[68:71]
	v_mfma_f32_16x16x32_bf16 v[68:71], v[192:195], v[200:203], v[24:27]
	v_mfma_f32_16x16x32_bf16 v[24:27], v[216:219], v[196:199], v[64:67]
	v_mfma_f32_16x16x32_bf16 v[64:67], v[220:223], v[200:203], v[24:27]
	s_barrier
	ds_read_b128 v[150:153], v148 offset:49152
	ds_read_b128 v[160:163], v148 offset:50176
	ds_read_b128 v[164:167], v148 offset:51200
	ds_read_b128 v[176:179], v148 offset:52224
	ds_read_b128 v[180:183], v148 offset:53248
	ds_read_b128 v[196:199], v148 offset:54272
	ds_read_b128 v[200:203], v148 offset:55296
	ds_read_b128 v[208:211], v148 offset:56320
	s_barrier
	s_waitcnt lgkmcnt(0)
	v_mfma_f32_16x16x32_bf16 v[24:27], v[8:11], v[150:153], v[60:63]
	v_mfma_f32_16x16x32_bf16 v[60:63], v[12:15], v[160:163], v[24:27]
	v_mfma_f32_16x16x32_bf16 v[24:27], v[168:171], v[150:153], v[56:59]
	v_mfma_f32_16x16x32_bf16 v[56:59], v[172:175], v[160:163], v[24:27]
	v_mfma_f32_16x16x32_bf16 v[24:27], v[8:11], v[164:167], v[52:55]
	v_mfma_f32_16x16x32_bf16 v[44:47], v[12:15], v[176:179], v[24:27]
	v_mfma_f32_16x16x32_bf16 v[24:27], v[168:171], v[164:167], v[48:51]
	v_mfma_f32_16x16x32_bf16 v[40:43], v[172:175], v[176:179], v[24:27]
	v_mfma_f32_16x16x32_bf16 v[24:27], v[8:11], v[180:183], v[184:187]
	v_mfma_f32_16x16x32_bf16 v[8:11], v[8:11], v[200:203], v[36:39]
	v_mfma_f32_16x16x32_bf16 v[28:31], v[12:15], v[196:199], v[24:27]
	v_mfma_f32_16x16x32_bf16 v[24:27], v[168:171], v[180:183], v[212:215]
	v_mfma_f32_16x16x32_bf16 v[12:15], v[12:15], v[208:211], v[8:11]
	v_mfma_f32_16x16x32_bf16 v[8:11], v[168:171], v[200:203], v[32:35]
	v_mfma_f32_16x16x32_bf16 v[24:27], v[172:175], v[196:199], v[24:27]
	v_mfma_f32_16x16x32_bf16 v[8:11], v[172:175], v[208:211], v[8:11]
	v_mfma_f32_16x16x32_bf16 v[32:35], v[188:191], v[150:153], v[128:131]
	v_mfma_f32_16x16x32_bf16 v[52:55], v[192:195], v[160:163], v[32:35]
	v_mfma_f32_16x16x32_bf16 v[32:35], v[216:219], v[150:153], v[132:135]
	v_mfma_f32_16x16x32_bf16 v[16:19], v[216:219], v[164:167], v[16:19]
	v_mfma_f32_16x16x32_bf16 v[48:51], v[220:223], v[160:163], v[32:35]
	v_mfma_f32_16x16x32_bf16 v[20:23], v[188:191], v[164:167], v[20:23]
	v_mfma_f32_16x16x32_bf16 v[32:35], v[220:223], v[176:179], v[16:19]
	v_mfma_f32_16x16x32_bf16 v[16:19], v[188:191], v[180:183], v[136:139]
	v_mfma_f32_16x16x32_bf16 v[36:39], v[192:195], v[176:179], v[20:23]
	v_mfma_f32_16x16x32_bf16 v[20:23], v[192:195], v[196:199], v[16:19]
	v_mfma_f32_16x16x32_bf16 v[16:19], v[216:219], v[180:183], v[144:147]
	v_mfma_f32_16x16x32_bf16 v[4:7], v[188:191], v[200:203], v[4:7]
	v_mfma_f32_16x16x32_bf16 v[0:3], v[216:219], v[200:203], v[0:3]
	v_mfma_f32_16x16x32_bf16 v[16:19], v[220:223], v[196:199], v[16:19]
	v_mfma_f32_16x16x32_bf16 v[4:7], v[192:195], v[208:211], v[4:7]
	v_mfma_f32_16x16x32_bf16 v[0:3], v[220:223], v[208:211], v[0:3]
	s_cmpk_lt_u32 s29, 0x100
	s_mov_b32 s89, s23
	s_mov_b32 s90, s35
	s_mov_b32 s91, s8
	s_barrier
	s_cbranch_scc0 .LBB0_934
	s_barrier
	s_and_b64 vcc, exec, s[2:3]
	s_mov_b64 s[2:3], -1
	s_cbranch_vccz .LBB0_935

; #define WAIT_V(n) asm volatile("s_waitcnt vmcnt(" #n ")" ::: "memory")
; #define WAIT_L(n) asm volatile("s_waitcnt lgkmcnt(" #n ")" ::: "memory")
; #define BAR __builtin_amdgcn_s_barrier()
; #define SCHED __builtin_amdgcn_sched_barrier(0)
; template <class Get, class Epi>
; DI void gemm_stream(LAS unsigned char* lds, const int K, const int ld, Get get, Epi epi) {
;     ...
;             LDB(B0, 0, 0); SCHED; LDA(At, 0, 0); STAGE(SAo(1, 1), a1 + hstep);
;             WAIT_L(8); BAR; WAIT_L(0); MMA(0, 0, At, B0); BAR; SCHED;
;             LDB(B1, 0, 1); STAGE(SBo(0, 0), b2);
;             BAR; WAIT_L(0); MMA(0, 1, At, B1); BAR;
;             LDA(At, 0, 1); STAGE(SAo(0, 0), a2);
;             BAR; WAIT_L(0); MMA(1, 0, At, B0); BAR; SCHED;
;             STAGE(SBo(0, 1), b2 + hstep);
;             WAIT_V(6); BAR; MMA(1, 1, At, B1); BAR;
.LBB0_1238:
	ds_read_b128 v[128:131], v198
	ds_read_b128 v[132:135], v198 offset:1024
	ds_read_b128 v[136:139], v198 offset:2048
	ds_read_b128 v[140:143], v198 offset:3072
	s_add_u32 s8, s6, 0x100
	s_addc_u32 s9, s7, 0
	s_cmp_eq_u32 s18, 28
	s_cselect_b32 s13, s39, s9
	s_cselect_b32 s12, s38, s8
	s_cselect_b32 s11, s41, s17
	s_cselect_b32 s10, s40, s16
	s_mov_b32 m0, s74
	v_lshl_add_u64 v[186:187], s[6:7], 0, v[168:169]
	ds_read_b128 v[144:147], v199
	ds_read_b128 v[148:151], v199 offset:1024
	ds_read_b128 v[152:155], v199 offset:2048
	ds_read_b128 v[156:159], v199 offset:3072
	ds_read_b128 v[160:163], v199 offset:4096
	ds_read_b128 v[174:177], v199 offset:5120
	ds_read_b128 v[178:181], v199 offset:6144
	ds_read_b128 v[182:185], v199 offset:7168
	global_load_lds_dwordx4 v[186:187], off
	v_lshl_add_u64 v[186:187], s[6:7], 0, v[170:171]
	s_mov_b32 m0, s75
	s_nop 0
	global_load_lds_dwordx4 v[186:187], off
	s_waitcnt lgkmcnt(8)
	s_barrier
	s_waitcnt lgkmcnt(0)
	v_mfma_f32_16x16x32_bf16 v[124:127], v[128:131], v[144:147], v[124:127]
	v_mfma_f32_16x16x32_bf16 v[92:95], v[136:139], v[144:147], v[92:95]
	v_mfma_f32_16x16x32_bf16 v[120:123], v[128:131], v[152:155], v[120:123]
	v_mfma_f32_16x16x32_bf16 v[88:91], v[136:139], v[152:155], v[88:91]
	v_mfma_f32_16x16x32_bf16 v[116:119], v[128:131], v[160:163], v[116:119]
	v_mfma_f32_16x16x32_bf16 v[84:87], v[136:139], v[160:163], v[84:87]
	v_mfma_f32_16x16x32_bf16 v[112:115], v[128:131], v[178:181], v[112:115]
	v_mfma_f32_16x16x32_bf16 v[80:83], v[136:139], v[178:181], v[80:83]
	v_mfma_f32_16x16x32_bf16 v[124:127], v[132:135], v[148:151], v[124:127]
	v_mfma_f32_16x16x32_bf16 v[92:95], v[140:143], v[148:151], v[92:95]
	v_mfma_f32_16x16x32_bf16 v[120:123], v[132:135], v[156:159], v[120:123]
	v_mfma_f32_16x16x32_bf16 v[88:91], v[140:143], v[156:159], v[88:91]
	v_mfma_f32_16x16x32_bf16 v[116:119], v[132:135], v[174:177], v[116:119]
	v_mfma_f32_16x16x32_bf16 v[84:87], v[140:143], v[174:177], v[84:87]
	v_mfma_f32_16x16x32_bf16 v[112:115], v[132:135], v[182:185], v[112:115]
	v_mfma_f32_16x16x32_bf16 v[80:83], v[140:143], v[182:185], v[80:83]
	s_barrier
	s_mov_b32 m0, s80
	v_lshl_add_u64 v[204:205], s[10:11], 0, v[164:165]
	ds_read_b128 v[186:189], v200
	ds_read_b128 v[190:193], v200 offset:1024
	ds_read_b128 v[194:197], v200 offset:2048
	ds_read_b128 v[208:211], v200 offset:3072
	global_load_lds_dwordx4 v[204:205], off
	v_lshl_add_u64 v[212:213], s[10:11], 0, v[166:167]
	s_mov_b32 m0, s81
	s_nop 0
	global_load_lds_dwordx4 v[212:213], off
	s_barrier
	s_waitcnt lgkmcnt(0)
	v_mfma_f32_16x16x32_bf16 v[60:63], v[186:189], v[144:147], v[60:63]
	v_mfma_f32_16x16x32_bf16 v[28:31], v[194:197], v[144:147], v[28:31]
	v_mfma_f32_16x16x32_bf16 v[56:59], v[186:189], v[152:155], v[56:59]
	v_mfma_f32_16x16x32_bf16 v[24:27], v[194:197], v[152:155], v[24:27]
	v_mfma_f32_16x16x32_bf16 v[52:55], v[186:189], v[160:163], v[52:55]
	v_mfma_f32_16x16x32_bf16 v[20:23], v[194:197], v[160:163], v[20:23]
	v_mfma_f32_16x16x32_bf16 v[48:51], v[186:189], v[178:181], v[48:51]
	v_mfma_f32_16x16x32_bf16 v[16:19], v[194:197], v[178:181], v[16:19]
	v_mfma_f32_16x16x32_bf16 v[60:63], v[190:193], v[148:151], v[60:63]
	v_mfma_f32_16x16x32_bf16 v[28:31], v[208:211], v[148:151], v[28:31]
	v_mfma_f32_16x16x32_bf16 v[56:59], v[190:193], v[156:159], v[56:59]
	v_mfma_f32_16x16x32_bf16 v[24:27], v[208:211], v[156:159], v[24:27]
	v_mfma_f32_16x16x32_bf16 v[52:55], v[190:193], v[174:177], v[52:55]
	v_mfma_f32_16x16x32_bf16 v[20:23], v[208:211], v[174:177], v[20:23]
	v_mfma_f32_16x16x32_bf16 v[48:51], v[190:193], v[182:185], v[48:51]
	v_mfma_f32_16x16x32_bf16 v[16:19], v[208:211], v[182:185], v[16:19]
	s_barrier
	s_mov_b32 m0, s21
	v_lshl_add_u64 v[214:215], s[12:13], 0, v[164:165]
	ds_read_b128 v[144:147], v199 offset:16384
	ds_read_b128 v[148:151], v199 offset:17408
	ds_read_b128 v[152:155], v199 offset:18432
	ds_read_b128 v[156:159], v199 offset:19456
	ds_read_b128 v[160:163], v199 offset:20480
	ds_read_b128 v[174:177], v199 offset:21504
	ds_read_b128 v[178:181], v199 offset:22528
	ds_read_b128 v[182:185], v199 offset:23552
	global_load_lds_dwordx4 v[214:215], off
	v_lshl_add_u64 v[216:217], s[12:13], 0, v[166:167]
	s_mov_b32 m0, s58
	s_nop 0
	global_load_lds_dwordx4 v[216:217], off
	s_barrier
	s_waitcnt lgkmcnt(0)
	v_mfma_f32_16x16x32_bf16 v[108:111], v[128:131], v[144:147], v[108:111]
	v_mfma_f32_16x16x32_bf16 v[76:79], v[136:139], v[144:147], v[76:79]
	v_mfma_f32_16x16x32_bf16 v[104:107], v[128:131], v[152:155], v[104:107]
	v_mfma_f32_16x16x32_bf16 v[72:75], v[136:139], v[152:155], v[72:75]
	v_mfma_f32_16x16x32_bf16 v[100:103], v[128:131], v[160:163], v[100:103]
	v_mfma_f32_16x16x32_bf16 v[68:71], v[136:139], v[160:163], v[68:71]
	v_mfma_f32_16x16x32_bf16 v[96:99], v[128:131], v[178:181], v[96:99]
	v_mfma_f32_16x16x32_bf16 v[64:67], v[136:139], v[178:181], v[64:67]
	v_mfma_f32_16x16x32_bf16 v[108:111], v[132:135], v[148:151], v[108:111]
	v_mfma_f32_16x16x32_bf16 v[76:79], v[140:143], v[148:151], v[76:79]
	v_mfma_f32_16x16x32_bf16 v[104:107], v[132:135], v[156:159], v[104:107]
	v_mfma_f32_16x16x32_bf16 v[72:75], v[140:143], v[156:159], v[72:75]
	v_mfma_f32_16x16x32_bf16 v[100:103], v[132:135], v[174:177], v[100:103]
	v_mfma_f32_16x16x32_bf16 v[68:71], v[140:143], v[174:177], v[68:71]
	v_mfma_f32_16x16x32_bf16 v[96:99], v[132:135], v[182:185], v[96:99]
	v_mfma_f32_16x16x32_bf16 v[64:67], v[140:143], v[182:185], v[64:67]
	s_barrier
	s_add_u32 s6, s10, 0x80000
	s_addc_u32 s7, s11, 0
	s_mov_b32 m0, s82
	v_lshl_add_u64 v[128:129], s[6:7], 0, v[164:165]
	global_load_lds_dwordx4 v[128:129], off
	v_lshl_add_u64 v[128:129], s[6:7], 0, v[166:167]
	s_mov_b32 m0, s83
	s_nop 0
	global_load_lds_dwordx4 v[128:129], off
	s_waitcnt vmcnt(6)
	s_barrier
; #define WAIT_V(n) asm volatile("s_waitcnt vmcnt(" #n ")" ::: "memory")
; #define WAIT_L(n) asm volatile("s_waitcnt lgkmcnt(" #n ")" ::: "memory")
; #define BAR __builtin_amdgcn_s_barrier()
; #define SCHED __builtin_amdgcn_sched_barrier(0)
; template <class Get, class Epi>
; DI void gemm_stream(LAS unsigned char* lds, const int K, const int ld, Get get, Epi epi) {
;     ...
;             WAIT_V(6); BAR; MMA(1, 1, At, B1); BAR;
;             LDB(B0, 1, 0); SCHED; LDA(At, 1, 0); STAGE(SAo(0, 1), a2 + hstep);
;             WAIT_L(8); BAR; WAIT_L(0); MMA(0, 0, At, B0); BAR; SCHED;
;             LDB(B1, 1, 1); STAGE(SBo(1, 0), b3);
;             BAR; WAIT_L(0); MMA(0, 1, At, B1); BAR;
;             LDA(At, 1, 1); STAGE(SAo(1, 0), a3);
;             BAR; WAIT_L(0); MMA(1, 0, At, B0); BAR; SCHED;
	v_mfma_f32_16x16x32_bf16 v[44:47], v[186:189], v[144:147], v[44:47]
	v_mfma_f32_16x16x32_bf16 v[12:15], v[194:197], v[144:147], v[12:15]
	v_mfma_f32_16x16x32_bf16 v[40:43], v[186:189], v[152:155], v[40:43]
	v_mfma_f32_16x16x32_bf16 v[8:11], v[194:197], v[152:155], v[8:11]
	v_mfma_f32_16x16x32_bf16 v[36:39], v[186:189], v[160:163], v[36:39]
	v_mfma_f32_16x16x32_bf16 v[4:7], v[194:197], v[160:163], v[4:7]
	v_mfma_f32_16x16x32_bf16 v[32:35], v[186:189], v[178:181], v[32:35]
	v_mfma_f32_16x16x32_bf16 v[0:3], v[194:197], v[178:181], v[0:3]
	v_mfma_f32_16x16x32_bf16 v[44:47], v[190:193], v[148:151], v[44:47]
	v_mfma_f32_16x16x32_bf16 v[12:15], v[208:211], v[148:151], v[12:15]
	v_mfma_f32_16x16x32_bf16 v[40:43], v[190:193], v[156:159], v[40:43]
	v_mfma_f32_16x16x32_bf16 v[8:11], v[208:211], v[156:159], v[8:11]
	v_mfma_f32_16x16x32_bf16 v[36:39], v[190:193], v[174:177], v[36:39]
	v_mfma_f32_16x16x32_bf16 v[4:7], v[208:211], v[174:177], v[4:7]
	v_mfma_f32_16x16x32_bf16 v[32:35], v[190:193], v[182:185], v[32:35]
	v_mfma_f32_16x16x32_bf16 v[0:3], v[208:211], v[182:185], v[0:3]
	s_barrier
	ds_read_b128 v[128:131], v201
	ds_read_b128 v[132:135], v201 offset:1024
	ds_read_b128 v[136:139], v201 offset:2048
	ds_read_b128 v[140:143], v201 offset:3072
	s_add_u32 s6, s12, 0x80000
	s_addc_u32 s7, s13, 0
	s_mov_b32 m0, s59
	v_lshl_add_u64 v[186:187], s[6:7], 0, v[164:165]
	ds_read_b128 v[144:147], v199 offset:32768
	ds_read_b128 v[148:151], v199 offset:33792
	ds_read_b128 v[152:155], v199 offset:34816
	ds_read_b128 v[156:159], v199 offset:35840
	ds_read_b128 v[160:163], v199 offset:36864
	ds_read_b128 v[174:177], v199 offset:37888
	ds_read_b128 v[178:181], v199 offset:38912
	ds_read_b128 v[182:185], v199 offset:39936
	global_load_lds_dwordx4 v[186:187], off
	v_lshl_add_u64 v[186:187], s[6:7], 0, v[166:167]
	s_mov_b32 m0, s60
	s_nop 0
	global_load_lds_dwordx4 v[186:187], off
	s_waitcnt lgkmcnt(8)
	s_barrier
	s_waitcnt lgkmcnt(0)
	v_mfma_f32_16x16x32_bf16 v[124:127], v[128:131], v[144:147], v[124:127]
	v_mfma_f32_16x16x32_bf16 v[92:95], v[136:139], v[144:147], v[92:95]
	v_mfma_f32_16x16x32_bf16 v[120:123], v[128:131], v[152:155], v[120:123]
	v_mfma_f32_16x16x32_bf16 v[88:91], v[136:139], v[152:155], v[88:91]
	v_mfma_f32_16x16x32_bf16 v[116:119], v[128:131], v[160:163], v[116:119]
	v_mfma_f32_16x16x32_bf16 v[84:87], v[136:139], v[160:163], v[84:87]
	v_mfma_f32_16x16x32_bf16 v[112:115], v[128:131], v[178:181], v[112:115]
	v_mfma_f32_16x16x32_bf16 v[80:83], v[136:139], v[178:181], v[80:83]
	v_mfma_f32_16x16x32_bf16 v[124:127], v[132:135], v[148:151], v[124:127]
	v_mfma_f32_16x16x32_bf16 v[92:95], v[140:143], v[148:151], v[92:95]
	v_mfma_f32_16x16x32_bf16 v[120:123], v[132:135], v[156:159], v[120:123]
	v_mfma_f32_16x16x32_bf16 v[88:91], v[140:143], v[156:159], v[88:91]
	v_mfma_f32_16x16x32_bf16 v[116:119], v[132:135], v[174:177], v[116:119]
	v_mfma_f32_16x16x32_bf16 v[84:87], v[140:143], v[174:177], v[84:87]
	v_mfma_f32_16x16x32_bf16 v[112:115], v[132:135], v[182:185], v[112:115]
	v_mfma_f32_16x16x32_bf16 v[80:83], v[140:143], v[182:185], v[80:83]
	s_barrier
	s_mov_b32 m0, s85
	v_lshl_add_u64 v[204:205], v[204:205], 0, s[0:1]
	ds_read_b128 v[186:189], v202
	ds_read_b128 v[190:193], v202 offset:1024
	ds_read_b128 v[194:197], v202 offset:2048
	ds_read_b128 v[208:211], v202 offset:3072
	global_load_lds_dwordx4 v[204:205], off
	v_lshl_add_u64 v[204:205], v[212:213], 0, s[0:1]
	s_mov_b32 m0, s96
	s_nop 0
	global_load_lds_dwordx4 v[204:205], off
	s_barrier
	s_waitcnt lgkmcnt(0)
	v_mfma_f32_16x16x32_bf16 v[60:63], v[186:189], v[144:147], v[60:63]
	v_mfma_f32_16x16x32_bf16 v[28:31], v[194:197], v[144:147], v[28:31]
	v_mfma_f32_16x16x32_bf16 v[56:59], v[186:189], v[152:155], v[56:59]
	v_mfma_f32_16x16x32_bf16 v[24:27], v[194:197], v[152:155], v[24:27]
	v_mfma_f32_16x16x32_bf16 v[52:55], v[186:189], v[160:163], v[52:55]
	v_mfma_f32_16x16x32_bf16 v[20:23], v[194:197], v[160:163], v[20:23]
	v_mfma_f32_16x16x32_bf16 v[48:51], v[186:189], v[178:181], v[48:51]
	v_mfma_f32_16x16x32_bf16 v[16:19], v[194:197], v[178:181], v[16:19]
	v_mfma_f32_16x16x32_bf16 v[60:63], v[190:193], v[148:151], v[60:63]
	v_mfma_f32_16x16x32_bf16 v[28:31], v[208:211], v[148:151], v[28:31]
	v_mfma_f32_16x16x32_bf16 v[56:59], v[190:193], v[156:159], v[56:59]
	v_mfma_f32_16x16x32_bf16 v[24:27], v[208:211], v[156:159], v[24:27]
	v_mfma_f32_16x16x32_bf16 v[52:55], v[190:193], v[174:177], v[52:55]
	v_mfma_f32_16x16x32_bf16 v[20:23], v[208:211], v[174:177], v[20:23]
	v_mfma_f32_16x16x32_bf16 v[48:51], v[190:193], v[182:185], v[48:51]
	v_mfma_f32_16x16x32_bf16 v[16:19], v[208:211], v[182:185], v[16:19]
	s_barrier
	s_mov_b32 m0, s61
	v_lshl_add_u64 v[204:205], v[214:215], 0, s[0:1]
	ds_read_b128 v[144:147], v199 offset:49152
	ds_read_b128 v[148:151], v199 offset:50176
	ds_read_b128 v[152:155], v199 offset:51200
	ds_read_b128 v[156:159], v199 offset:52224
	ds_read_b128 v[160:163], v199 offset:53248
	ds_read_b128 v[174:177], v199 offset:54272
	ds_read_b128 v[178:181], v199 offset:55296
	ds_read_b128 v[182:185], v199 offset:56320
	global_load_lds_dwordx4 v[204:205], off
	v_lshl_add_u64 v[204:205], v[216:217], 0, s[0:1]
	s_mov_b32 m0, s62
	s_nop 0
	global_load_lds_dwordx4 v[204:205], off
	s_barrier
; #define WAIT_V(n) asm volatile("s_waitcnt vmcnt(" #n ")" ::: "memory")
; #define WAIT_L(n) asm volatile("s_waitcnt lgkmcnt(" #n ")" ::: "memory")
; #define BAR __builtin_amdgcn_s_barrier()
; #define SCHED __builtin_amdgcn_sched_barrier(0)
; #define EPI_DONE do { } while (0)
; template <class Get, class Epi>
; DI void gemm_stream(LAS unsigned char* lds, const int K, const int ld, Get get, Epi epi) {
;     ...
;             BAR; WAIT_L(0); MMA(1, 0, At, B0); BAR; SCHED;
;             STAGE(SBo(1, 1), b3 + hstep);
;             WAIT_V(6); BAR; MMA(1, 1, At, B1); BAR;
;         }
; DI void epi_resid(const Acc& acc, const P& p, int brow, int bcol, int layer, int gch, bool from_input) {
;     EPI_IDX
;     const float* gate = modv(p, layer, brow, gch);
; #pragma unroll
;     for (int bj = 0; bj < 2; ++bj)
; #pragma unroll
;         for (int n = 0; n < 2; ++n) {
;             const int c0 = bcol + bj * 128 + wc * 32 + n * 16 + fq * 4;
;             const f32x4 g = *(const f32x4*)(gate + c0);
;             f32x4 xv[2][4];
; #pragma unroll
;             for (int ai = 0; ai < 2; ++ai)
; #pragma unroll
;                 for (int m = 0; m < 4; ++m) {
;                     const int r = brow + ai * 128 + wr * 64 + m * 16 + fr;
;                     const float* sp = (from_input ? inrow(p, r) : xrow(p, r)) + c0;
;                     xv[ai][m] = *(const f32x4*)sp;
;                 }
;             __builtin_amdgcn_sched_barrier(0);
; #pragma unroll
;             for (int ai = 0; ai < 2; ++ai)
; #pragma unroll
;                 for (int m = 0; m < 4; ++m) {
;                     const int r = brow + ai * 128 + wr * 64 + m * 16 + fr;
;                     *(f32x4*)(xrow(p, r) + c0) = xv[ai][m] + g * acc[ai][bj][m][n];
;                 }
;             __builtin_amdgcn_sched_barrier(0);
;         }
;     EPI_DONE;
; }
	s_waitcnt lgkmcnt(0)
	v_mfma_f32_16x16x32_bf16 v[108:111], v[128:131], v[144:147], v[108:111]
	v_mfma_f32_16x16x32_bf16 v[76:79], v[136:139], v[144:147], v[76:79]
	v_mfma_f32_16x16x32_bf16 v[104:107], v[128:131], v[152:155], v[104:107]
	v_mfma_f32_16x16x32_bf16 v[72:75], v[136:139], v[152:155], v[72:75]
	v_mfma_f32_16x16x32_bf16 v[100:103], v[128:131], v[160:163], v[100:103]
	v_mfma_f32_16x16x32_bf16 v[68:71], v[136:139], v[160:163], v[68:71]
	v_mfma_f32_16x16x32_bf16 v[96:99], v[128:131], v[178:181], v[96:99]
	v_mfma_f32_16x16x32_bf16 v[64:67], v[136:139], v[178:181], v[64:67]
	v_mfma_f32_16x16x32_bf16 v[108:111], v[132:135], v[148:151], v[108:111]
	v_mfma_f32_16x16x32_bf16 v[76:79], v[140:143], v[148:151], v[76:79]
	v_mfma_f32_16x16x32_bf16 v[104:107], v[132:135], v[156:159], v[104:107]
	v_mfma_f32_16x16x32_bf16 v[72:75], v[140:143], v[156:159], v[72:75]
	v_mfma_f32_16x16x32_bf16 v[100:103], v[132:135], v[174:177], v[100:103]
	v_mfma_f32_16x16x32_bf16 v[68:71], v[140:143], v[174:177], v[68:71]
	v_mfma_f32_16x16x32_bf16 v[96:99], v[132:135], v[182:185], v[96:99]
	v_mfma_f32_16x16x32_bf16 v[64:67], v[140:143], v[182:185], v[64:67]
	s_barrier
	s_add_u32 s6, s10, 0x80080
	s_addc_u32 s7, s11, 0
	s_mov_b32 m0, s97
	v_lshl_add_u64 v[128:129], s[6:7], 0, v[164:165]
	global_load_lds_dwordx4 v[128:129], off
	v_lshl_add_u64 v[128:129], s[6:7], 0, v[166:167]
	s_add_i32 m0, s97, 0x2000
	s_nop 0
	global_load_lds_dwordx4 v[128:129], off
	s_add_i32 s18, s18, 2
	s_add_u32 s16, s16, 0x100
	s_addc_u32 s17, s17, 0
	s_cmp_gt_u32 s18, 29
	s_mov_b64 s[6:7], s[8:9]
	s_waitcnt vmcnt(6)
	s_barrier
	v_mfma_f32_16x16x32_bf16 v[44:47], v[186:189], v[144:147], v[44:47]
	v_mfma_f32_16x16x32_bf16 v[12:15], v[194:197], v[144:147], v[12:15]
	v_mfma_f32_16x16x32_bf16 v[40:43], v[186:189], v[152:155], v[40:43]
	v_mfma_f32_16x16x32_bf16 v[8:11], v[194:197], v[152:155], v[8:11]
	v_mfma_f32_16x16x32_bf16 v[36:39], v[186:189], v[160:163], v[36:39]
	v_mfma_f32_16x16x32_bf16 v[4:7], v[194:197], v[160:163], v[4:7]
	v_mfma_f32_16x16x32_bf16 v[32:35], v[186:189], v[178:181], v[32:35]
	v_mfma_f32_16x16x32_bf16 v[0:3], v[194:197], v[178:181], v[0:3]
	v_mfma_f32_16x16x32_bf16 v[44:47], v[190:193], v[148:151], v[44:47]
	v_mfma_f32_16x16x32_bf16 v[12:15], v[208:211], v[148:151], v[12:15]
	v_mfma_f32_16x16x32_bf16 v[40:43], v[190:193], v[156:159], v[40:43]
	v_mfma_f32_16x16x32_bf16 v[8:11], v[208:211], v[156:159], v[8:11]
	v_mfma_f32_16x16x32_bf16 v[36:39], v[190:193], v[174:177], v[36:39]
	v_mfma_f32_16x16x32_bf16 v[4:7], v[208:211], v[174:177], v[4:7]
	v_mfma_f32_16x16x32_bf16 v[32:35], v[190:193], v[182:185], v[32:35]
	v_mfma_f32_16x16x32_bf16 v[0:3], v[208:211], v[182:185], v[0:3]
	s_barrier
	s_cbranch_scc0 .LBB0_1238
	s_lshl_b32 s12, s15, 21
	s_lshl_b32 s13, s14, 10
	s_lshr_b32 s16, s15, 4
	s_add_u32 s12, s12, s13
	s_mul_i32 s16, s16, 6
	s_add_i32 s16, s16, 2
	s_lshl_b32 s16, s16, 13
	s_add_u32 s16, s16, s13
	s_add_u32 s10, s26, s16
	s_addc_u32 s11, s27, 0
	s_add_u32 s8, s52, s12
	s_addc_u32 s9, s53, 0
	s_add_u32 s6, s24, s12
	s_addc_u32 s7, s25, 0
	v_lshrrev_b32_e32 v224, 6, v206
	v_and_b32_e32 v225, 3, v224
	v_lshrrev_b32_e32 v224, 2, v224
	v_and_b32_e32 v205, 15, v206
	v_bfe_u32 v226, v206, 4, 2
	v_lshl_add_u32 v225, v225, 3, v226
	v_lshl_add_u32 v224, v224, 6, v205
	v_lshlrev_b32_e32 v205, 4, v225
	v_lshl_add_u32 v203, v224, 13, v205
	v_mov_b32_e32 v204, v203
	global_load_dwordx4 v[128:131], v205, s[10:11] offset:0
	global_load_dwordx4 v[132:135], v205, s[10:11] offset:64
	global_load_dwordx4 v[136:139], v205, s[10:11] offset:512
	global_load_dwordx4 v[140:143], v205, s[10:11] offset:576
	global_load_dwordx4 v[144:147], v203, s[8:9] offset:0
	global_load_dwordx4 v[148:151], v203, s[8:9] offset:64
	global_load_dwordx4 v[152:155], v203, s[8:9] offset:512
	global_load_dwordx4 v[156:159], v203, s[8:9] offset:576
	v_add_u32_e32 v203, 0x20000, v203
	global_load_dwordx4 v[160:163], v203, s[8:9] offset:0
	global_load_dwordx4 v[174:177], v203, s[8:9] offset:64
	global_load_dwordx4 v[178:181], v203, s[8:9] offset:512
	global_load_dwordx4 v[182:185], v203, s[8:9] offset:576
	v_add_u32_e32 v203, 0x20000, v203
	global_load_dwordx4 v[186:189], v203, s[8:9] offset:0
	global_load_dwordx4 v[190:193], v203, s[8:9] offset:64
	global_load_dwordx4 v[194:197], v203, s[8:9] offset:512
	global_load_dwordx4 v[208:211], v203, s[8:9] offset:576
	v_add_u32_e32 v203, 0x20000, v203
	global_load_dwordx4 v[212:215], v203, s[8:9] offset:0
	global_load_dwordx4 v[216:219], v203, s[8:9] offset:64
	global_load_dwordx4 v[220:223], v203, s[8:9] offset:512
	global_load_dwordx4 v[224:227], v203, s[8:9] offset:576
	v_add_u32_e32 v203, 0xa0000, v203
	s_waitcnt vmcnt(12)
	v_pk_fma_f32 v[124:125], v[124:125], v[128:129], v[144:145]
	v_pk_fma_f32 v[126:127], v[126:127], v[130:131], v[146:147]
	v_pk_fma_f32 v[92:93], v[92:93], v[132:133], v[148:149]
	v_pk_fma_f32 v[94:95], v[94:95], v[134:135], v[150:151]
	v_pk_fma_f32 v[60:61], v[60:61], v[136:137], v[152:153]
	v_pk_fma_f32 v[62:63], v[62:63], v[138:139], v[154:155]
	v_pk_fma_f32 v[28:29], v[28:29], v[140:141], v[156:157]
	v_pk_fma_f32 v[30:31], v[30:31], v[142:143], v[158:159]
	global_store_dwordx4 v204, v[124:127], s[6:7] offset:0
	global_store_dwordx4 v204, v[92:95], s[6:7] offset:64
	global_store_dwordx4 v204, v[60:63], s[6:7] offset:512
	global_store_dwordx4 v204, v[28:31], s[6:7] offset:576
	v_add_u32_e32 v204, 0x20000, v204
	global_load_dwordx4 v[144:147], v203, s[8:9] offset:0
	global_load_dwordx4 v[148:151], v203, s[8:9] offset:64
	global_load_dwordx4 v[152:155], v203, s[8:9] offset:512
	global_load_dwordx4 v[156:159], v203, s[8:9] offset:576
	v_add_u32_e32 v203, 0x20000, v203
	s_waitcnt vmcnt(16)
; #define EPI_DONE do { } while (0)
; DI void epi_resid(const Acc& acc, const P& p, int brow, int bcol, int layer, int gch, bool from_input) {
;     EPI_IDX
;     const float* gate = modv(p, layer, brow, gch);
; #pragma unroll
;     for (int bj = 0; bj < 2; ++bj)
; #pragma unroll
;         for (int n = 0; n < 2; ++n) {
;             const int c0 = bcol + bj * 128 + wc * 32 + n * 16 + fq * 4;
;             const f32x4 g = *(const f32x4*)(gate + c0);
;             f32x4 xv[2][4];
; #pragma unroll
;             for (int ai = 0; ai < 2; ++ai)
; #pragma unroll
;                 for (int m = 0; m < 4; ++m) {
;                     const int r = brow + ai * 128 + wr * 64 + m * 16 + fr;
;                     const float* sp = (from_input ? inrow(p, r) : xrow(p, r)) + c0;
;                     xv[ai][m] = *(const f32x4*)sp;
;                 }
;             __builtin_amdgcn_sched_barrier(0);
; #pragma unroll
;             for (int ai = 0; ai < 2; ++ai)
; #pragma unroll
;                 for (int m = 0; m < 4; ++m) {
;                     const int r = brow + ai * 128 + wr * 64 + m * 16 + fr;
;                     *(f32x4*)(xrow(p, r) + c0) = xv[ai][m] + g * acc[ai][bj][m][n];
;                 }
;             __builtin_amdgcn_sched_barrier(0);
;         }
;     EPI_DONE;
; }
	v_pk_fma_f32 v[120:121], v[120:121], v[128:129], v[160:161]
	v_pk_fma_f32 v[122:123], v[122:123], v[130:131], v[162:163]
	v_pk_fma_f32 v[88:89], v[88:89], v[132:133], v[174:175]
	v_pk_fma_f32 v[90:91], v[90:91], v[134:135], v[176:177]
	v_pk_fma_f32 v[56:57], v[56:57], v[136:137], v[178:179]
	v_pk_fma_f32 v[58:59], v[58:59], v[138:139], v[180:181]
	v_pk_fma_f32 v[24:25], v[24:25], v[140:141], v[182:183]
	v_pk_fma_f32 v[26:27], v[26:27], v[142:143], v[184:185]
	global_store_dwordx4 v204, v[120:123], s[6:7] offset:0
	global_store_dwordx4 v204, v[88:91], s[6:7] offset:64
	global_store_dwordx4 v204, v[56:59], s[6:7] offset:512
	global_store_dwordx4 v204, v[24:27], s[6:7] offset:576
	v_add_u32_e32 v204, 0x20000, v204
	global_load_dwordx4 v[160:163], v203, s[8:9] offset:0
	global_load_dwordx4 v[174:177], v203, s[8:9] offset:64
	global_load_dwordx4 v[178:181], v203, s[8:9] offset:512
	global_load_dwordx4 v[182:185], v203, s[8:9] offset:576
	v_add_u32_e32 v203, 0x20000, v203
	s_waitcnt vmcnt(20)
	v_pk_fma_f32 v[116:117], v[116:117], v[128:129], v[186:187]
	v_pk_fma_f32 v[118:119], v[118:119], v[130:131], v[188:189]
	v_pk_fma_f32 v[84:85], v[84:85], v[132:133], v[190:191]
	v_pk_fma_f32 v[86:87], v[86:87], v[134:135], v[192:193]
	v_pk_fma_f32 v[52:53], v[52:53], v[136:137], v[194:195]
	v_pk_fma_f32 v[54:55], v[54:55], v[138:139], v[196:197]
	v_pk_fma_f32 v[20:21], v[20:21], v[140:141], v[208:209]
	v_pk_fma_f32 v[22:23], v[22:23], v[142:143], v[210:211]
	global_store_dwordx4 v204, v[116:119], s[6:7] offset:0
	global_store_dwordx4 v204, v[84:87], s[6:7] offset:64
	global_store_dwordx4 v204, v[52:55], s[6:7] offset:512
	global_store_dwordx4 v204, v[20:23], s[6:7] offset:576
	v_add_u32_e32 v204, 0x20000, v204
	global_load_dwordx4 v[186:189], v203, s[8:9] offset:0
	global_load_dwordx4 v[190:193], v203, s[8:9] offset:64
	global_load_dwordx4 v[194:197], v203, s[8:9] offset:512
	global_load_dwordx4 v[208:211], v203, s[8:9] offset:576
	v_add_u32_e32 v203, 0x20000, v203
	s_waitcnt vmcnt(24)
	v_pk_fma_f32 v[112:113], v[112:113], v[128:129], v[212:213]
	v_pk_fma_f32 v[114:115], v[114:115], v[130:131], v[214:215]
	v_pk_fma_f32 v[80:81], v[80:81], v[132:133], v[216:217]
	v_pk_fma_f32 v[82:83], v[82:83], v[134:135], v[218:219]
	v_pk_fma_f32 v[48:49], v[48:49], v[136:137], v[220:221]
	v_pk_fma_f32 v[50:51], v[50:51], v[138:139], v[222:223]
	v_pk_fma_f32 v[16:17], v[16:17], v[140:141], v[224:225]
	v_pk_fma_f32 v[18:19], v[18:19], v[142:143], v[226:227]
	global_store_dwordx4 v204, v[112:115], s[6:7] offset:0
	global_store_dwordx4 v204, v[80:83], s[6:7] offset:64
	global_store_dwordx4 v204, v[48:51], s[6:7] offset:512
	global_store_dwordx4 v204, v[16:19], s[6:7] offset:576
	v_add_u32_e32 v204, 0xa0000, v204
	global_load_dwordx4 v[212:215], v203, s[8:9] offset:0
	global_load_dwordx4 v[216:219], v203, s[8:9] offset:64
	global_load_dwordx4 v[220:223], v203, s[8:9] offset:512
	global_load_dwordx4 v[224:227], v203, s[8:9] offset:576
	s_waitcnt vmcnt(24)
	v_pk_fma_f32 v[108:109], v[108:109], v[128:129], v[144:145]
	v_pk_fma_f32 v[110:111], v[110:111], v[130:131], v[146:147]
	v_pk_fma_f32 v[76:77], v[76:77], v[132:133], v[148:149]
	v_pk_fma_f32 v[78:79], v[78:79], v[134:135], v[150:151]
	v_pk_fma_f32 v[44:45], v[44:45], v[136:137], v[152:153]
	v_pk_fma_f32 v[46:47], v[46:47], v[138:139], v[154:155]
	v_pk_fma_f32 v[12:13], v[12:13], v[140:141], v[156:157]
	v_pk_fma_f32 v[14:15], v[14:15], v[142:143], v[158:159]
	global_store_dwordx4 v204, v[108:111], s[6:7] offset:0
	global_store_dwordx4 v204, v[76:79], s[6:7] offset:64
	global_store_dwordx4 v204, v[44:47], s[6:7] offset:512
	global_store_dwordx4 v204, v[12:15], s[6:7] offset:576
	v_add_u32_e32 v204, 0x20000, v204
	s_waitcnt vmcnt(20)
	v_pk_fma_f32 v[104:105], v[104:105], v[128:129], v[160:161]
	v_pk_fma_f32 v[106:107], v[106:107], v[130:131], v[162:163]
	v_pk_fma_f32 v[72:73], v[72:73], v[132:133], v[174:175]
	v_pk_fma_f32 v[74:75], v[74:75], v[134:135], v[176:177]
	v_pk_fma_f32 v[40:41], v[40:41], v[136:137], v[178:179]
	v_pk_fma_f32 v[42:43], v[42:43], v[138:139], v[180:181]
	v_pk_fma_f32 v[8:9], v[8:9], v[140:141], v[182:183]
	v_pk_fma_f32 v[10:11], v[10:11], v[142:143], v[184:185]
	global_store_dwordx4 v204, v[104:107], s[6:7] offset:0
	global_store_dwordx4 v204, v[72:75], s[6:7] offset:64
	global_store_dwordx4 v204, v[40:43], s[6:7] offset:512
	global_store_dwordx4 v204, v[8:11], s[6:7] offset:576
	v_add_u32_e32 v204, 0x20000, v204
	s_waitcnt vmcnt(16)
	v_pk_fma_f32 v[100:101], v[100:101], v[128:129], v[186:187]
	v_pk_fma_f32 v[102:103], v[102:103], v[130:131], v[188:189]
	v_pk_fma_f32 v[68:69], v[68:69], v[132:133], v[190:191]
	v_pk_fma_f32 v[70:71], v[70:71], v[134:135], v[192:193]
	v_pk_fma_f32 v[36:37], v[36:37], v[136:137], v[194:195]
	v_pk_fma_f32 v[38:39], v[38:39], v[138:139], v[196:197]
	v_pk_fma_f32 v[4:5], v[4:5], v[140:141], v[208:209]
	v_pk_fma_f32 v[6:7], v[6:7], v[142:143], v[210:211]
	global_store_dwordx4 v204, v[100:103], s[6:7] offset:0
	global_store_dwordx4 v204, v[68:71], s[6:7] offset:64
	global_store_dwordx4 v204, v[36:39], s[6:7] offset:512
	global_store_dwordx4 v204, v[4:7], s[6:7] offset:576
	v_add_u32_e32 v204, 0x20000, v204
	s_waitcnt vmcnt(12)
	v_pk_fma_f32 v[96:97], v[96:97], v[128:129], v[212:213]
	v_pk_fma_f32 v[98:99], v[98:99], v[130:131], v[214:215]
	v_pk_fma_f32 v[64:65], v[64:65], v[132:133], v[216:217]
	v_pk_fma_f32 v[66:67], v[66:67], v[134:135], v[218:219]
	v_pk_fma_f32 v[32:33], v[32:33], v[136:137], v[220:221]
	v_pk_fma_f32 v[34:35], v[34:35], v[138:139], v[222:223]
	v_pk_fma_f32 v[0:1], v[0:1], v[140:141], v[224:225]
	v_pk_fma_f32 v[2:3], v[2:3], v[142:143], v[226:227]
	global_store_dwordx4 v204, v[96:99], s[6:7] offset:0
	global_store_dwordx4 v204, v[64:67], s[6:7] offset:64
	global_store_dwordx4 v204, v[32:35], s[6:7] offset:512
	global_store_dwordx4 v204, v[0:3], s[6:7] offset:576
	s_branch .Lresid_latch_wout0

; #define WAIT_V(n) asm volatile("s_waitcnt vmcnt(" #n ")" ::: "memory")
; #define WAIT_L(n) asm volatile("s_waitcnt lgkmcnt(" #n ")" ::: "memory")
; #define BAR __builtin_amdgcn_s_barrier()
; #define SCHED __builtin_amdgcn_sched_barrier(0)
; template <class Get, class Epi>
; DI void gemm_stream(LAS unsigned char* lds, const int K, const int ld, Get get, Epi epi) {
;     ...
;             const bool last = (t == nt - 2);
;             const char* a1 = cA + (size_t)(t + 1) * kstep;
;             const char* a2 = last ? nA : cA + (size_t)(t + 2) * kstep;
;             const char* b2 = last ? nB : cB + (size_t)(t + 2) * kstep;
;             const char* a3 = a2 + kstep;
;             const char* b3 = b2 + kstep;
;             LDB(B0, 0, 0); SCHED; LDA(At, 0, 0); STAGE(SAo(1, 1), a1 + hstep);
;             WAIT_L(8); BAR; WAIT_L(0); MMA(0, 0, At, B0); BAR; SCHED;
;             LDB(B1, 0, 1); STAGE(SBo(0, 0), b2);
;             BAR; WAIT_L(0); MMA(0, 1, At, B1); BAR;
;             LDA(At, 0, 1); STAGE(SAo(0, 0), a2);
;             BAR; WAIT_L(0); MMA(1, 0, At, B0); BAR; SCHED;
;             STAGE(SBo(0, 1), b2 + hstep);
;             WAIT_V(6); BAR; MMA(1, 1, At, B1); BAR;
.LBB0_1630:
	ds_read_b128 v[148:151], v142
	ds_read_b128 v[152:155], v142 offset:1024
	ds_read_b128 v[156:159], v142 offset:2048
	ds_read_b128 v[160:163], v142 offset:3072
	s_add_u32 s12, s10, 0xfff80080
	s_addc_u32 s13, s11, -1
	s_cmp_eq_u32 s59, 28
	s_cselect_b32 s15, s7, s13
	s_cselect_b32 s14, s6, s12
	s_cselect_b32 s13, s9, s58
	s_cselect_b32 s12, s8, s57
	s_mov_b32 m0, s28
	v_lshl_add_u64 v[140:141], s[10:11], 0, v[134:135]
	ds_read_b128 v[164:167], v143
	ds_read_b128 v[168:171], v143 offset:1024
	ds_read_b128 v[172:175], v143 offset:2048
	ds_read_b128 v[176:179], v143 offset:3072
	ds_read_b128 v[180:183], v143 offset:4096
	ds_read_b128 v[184:187], v143 offset:5120
	ds_read_b128 v[188:191], v143 offset:6144
	ds_read_b128 v[192:195], v143 offset:7168
	global_load_lds_dwordx4 v[140:141], off
	v_lshl_add_u64 v[140:141], s[10:11], 0, v[136:137]
	s_mov_b32 m0, s29
	s_nop 0
	global_load_lds_dwordx4 v[140:141], off
	s_waitcnt lgkmcnt(8)
	s_barrier
	s_waitcnt lgkmcnt(0)
	v_mfma_f32_16x16x32_bf16 v[124:127], v[148:151], v[164:167], v[124:127]
	v_mfma_f32_16x16x32_bf16 v[116:119], v[156:159], v[164:167], v[116:119]
	v_mfma_f32_16x16x32_bf16 v[108:111], v[148:151], v[172:175], v[108:111]
	v_mfma_f32_16x16x32_bf16 v[100:103], v[156:159], v[172:175], v[100:103]
	v_mfma_f32_16x16x32_bf16 v[92:95], v[148:151], v[180:183], v[92:95]
	v_mfma_f32_16x16x32_bf16 v[84:87], v[156:159], v[180:183], v[84:87]
	v_mfma_f32_16x16x32_bf16 v[76:79], v[148:151], v[188:191], v[76:79]
	v_mfma_f32_16x16x32_bf16 v[68:71], v[156:159], v[188:191], v[68:71]
	v_mfma_f32_16x16x32_bf16 v[124:127], v[152:155], v[168:171], v[124:127]
	v_mfma_f32_16x16x32_bf16 v[116:119], v[160:163], v[168:171], v[116:119]
	v_mfma_f32_16x16x32_bf16 v[108:111], v[152:155], v[176:179], v[108:111]
	v_mfma_f32_16x16x32_bf16 v[100:103], v[160:163], v[176:179], v[100:103]
	v_mfma_f32_16x16x32_bf16 v[92:95], v[152:155], v[184:187], v[92:95]
	v_mfma_f32_16x16x32_bf16 v[84:87], v[160:163], v[184:187], v[84:87]
	v_mfma_f32_16x16x32_bf16 v[76:79], v[152:155], v[192:195], v[76:79]
	v_mfma_f32_16x16x32_bf16 v[68:71], v[160:163], v[192:195], v[68:71]
	s_barrier
	s_mov_b32 m0, s35
	v_lshl_add_u64 v[140:141], s[12:13], 0, v[130:131]
	ds_read_b128 v[196:199], v144
	ds_read_b128 v[200:203], v144 offset:1024
	ds_read_b128 v[208:211], v144 offset:2048
	ds_read_b128 v[212:215], v144 offset:3072
	global_load_lds_dwordx4 v[140:141], off
	v_lshl_add_u64 v[204:205], s[12:13], 0, v[128:129]
	s_mov_b32 m0, s36
	s_nop 0
	global_load_lds_dwordx4 v[204:205], off
	s_barrier
	s_waitcnt lgkmcnt(0)
	v_mfma_f32_16x16x32_bf16 v[120:123], v[196:199], v[164:167], v[120:123]
	v_mfma_f32_16x16x32_bf16 v[112:115], v[208:211], v[164:167], v[112:115]
	v_mfma_f32_16x16x32_bf16 v[104:107], v[196:199], v[172:175], v[104:107]
	v_mfma_f32_16x16x32_bf16 v[96:99], v[208:211], v[172:175], v[96:99]
	v_mfma_f32_16x16x32_bf16 v[88:91], v[196:199], v[180:183], v[88:91]
	v_mfma_f32_16x16x32_bf16 v[80:83], v[208:211], v[180:183], v[80:83]
	v_mfma_f32_16x16x32_bf16 v[72:75], v[196:199], v[188:191], v[72:75]
	v_mfma_f32_16x16x32_bf16 v[64:67], v[208:211], v[188:191], v[64:67]
	v_mfma_f32_16x16x32_bf16 v[120:123], v[200:203], v[168:171], v[120:123]
	v_mfma_f32_16x16x32_bf16 v[112:115], v[212:215], v[168:171], v[112:115]
	v_mfma_f32_16x16x32_bf16 v[104:107], v[200:203], v[176:179], v[104:107]
	v_mfma_f32_16x16x32_bf16 v[96:99], v[212:215], v[176:179], v[96:99]
	v_mfma_f32_16x16x32_bf16 v[88:91], v[200:203], v[184:187], v[88:91]
	v_mfma_f32_16x16x32_bf16 v[80:83], v[212:215], v[184:187], v[80:83]
	v_mfma_f32_16x16x32_bf16 v[72:75], v[200:203], v[192:195], v[72:75]
	v_mfma_f32_16x16x32_bf16 v[64:67], v[212:215], v[192:195], v[64:67]
	s_barrier
	s_mov_b32 m0, s3
	v_lshl_add_u64 v[216:217], s[14:15], 0, v[130:131]
	ds_read_b128 v[164:167], v143 offset:16384
	ds_read_b128 v[168:171], v143 offset:17408
	ds_read_b128 v[172:175], v143 offset:18432
	ds_read_b128 v[176:179], v143 offset:19456
	ds_read_b128 v[180:183], v143 offset:20480
	ds_read_b128 v[184:187], v143 offset:21504
	ds_read_b128 v[188:191], v143 offset:22528
	ds_read_b128 v[192:195], v143 offset:23552
	global_load_lds_dwordx4 v[216:217], off
	v_lshl_add_u64 v[218:219], s[14:15], 0, v[128:129]
	s_mov_b32 m0, s16
	s_nop 0
	global_load_lds_dwordx4 v[218:219], off
	s_barrier
	s_waitcnt lgkmcnt(0)
	v_mfma_f32_16x16x32_bf16 v[60:63], v[148:151], v[164:167], v[60:63]
	v_mfma_f32_16x16x32_bf16 v[52:55], v[156:159], v[164:167], v[52:55]
	v_mfma_f32_16x16x32_bf16 v[44:47], v[148:151], v[172:175], v[44:47]
	v_mfma_f32_16x16x32_bf16 v[36:39], v[156:159], v[172:175], v[36:39]
	v_mfma_f32_16x16x32_bf16 v[28:31], v[148:151], v[180:183], v[28:31]
	v_mfma_f32_16x16x32_bf16 v[20:23], v[156:159], v[180:183], v[20:23]
	v_mfma_f32_16x16x32_bf16 v[12:15], v[148:151], v[188:191], v[12:15]
	v_mfma_f32_16x16x32_bf16 v[4:7], v[156:159], v[188:191], v[4:7]
	v_mfma_f32_16x16x32_bf16 v[60:63], v[152:155], v[168:171], v[60:63]
	v_mfma_f32_16x16x32_bf16 v[52:55], v[160:163], v[168:171], v[52:55]
	v_mfma_f32_16x16x32_bf16 v[44:47], v[152:155], v[176:179], v[44:47]
	v_mfma_f32_16x16x32_bf16 v[36:39], v[160:163], v[176:179], v[36:39]
	v_mfma_f32_16x16x32_bf16 v[28:31], v[152:155], v[184:187], v[28:31]
	v_mfma_f32_16x16x32_bf16 v[20:23], v[160:163], v[184:187], v[20:23]
	v_mfma_f32_16x16x32_bf16 v[12:15], v[152:155], v[192:195], v[12:15]
	v_mfma_f32_16x16x32_bf16 v[4:7], v[160:163], v[192:195], v[4:7]
	s_barrier
	s_add_u32 s60, s12, 0x80000
	s_addc_u32 s61, s13, 0
	s_mov_b32 m0, s37
	v_lshl_add_u64 v[148:149], s[60:61], 0, v[130:131]
	global_load_lds_dwordx4 v[148:149], off
	v_lshl_add_u64 v[148:149], s[60:61], 0, v[128:129]
	s_mov_b32 m0, s38
	s_nop 0
	global_load_lds_dwordx4 v[148:149], off
	s_waitcnt vmcnt(6)
	s_barrier
; #define WAIT_V(n) asm volatile("s_waitcnt vmcnt(" #n ")" ::: "memory")
; #define WAIT_L(n) asm volatile("s_waitcnt lgkmcnt(" #n ")" ::: "memory")
; #define BAR __builtin_amdgcn_s_barrier()
; #define SCHED __builtin_amdgcn_sched_barrier(0)
; template <class Get, class Epi>
; DI void gemm_stream(LAS unsigned char* lds, const int K, const int ld, Get get, Epi epi) {
;     ...
;             WAIT_V(6); BAR; MMA(1, 1, At, B1); BAR;
;             LDB(B0, 1, 0); SCHED; LDA(At, 1, 0); STAGE(SAo(0, 1), a2 + hstep);
;             WAIT_L(8); BAR; WAIT_L(0); MMA(0, 0, At, B0); BAR; SCHED;
;             LDB(B1, 1, 1); STAGE(SBo(1, 0), b3);
;             BAR; WAIT_L(0); MMA(0, 1, At, B1); BAR;
;             LDA(At, 1, 1); STAGE(SAo(1, 0), a3);
;             BAR; WAIT_L(0); MMA(1, 0, At, B0); BAR; SCHED;
	v_mfma_f32_16x16x32_bf16 v[56:59], v[196:199], v[164:167], v[56:59]
	v_mfma_f32_16x16x32_bf16 v[48:51], v[208:211], v[164:167], v[48:51]
	v_mfma_f32_16x16x32_bf16 v[40:43], v[196:199], v[172:175], v[40:43]
	v_mfma_f32_16x16x32_bf16 v[32:35], v[208:211], v[172:175], v[32:35]
	v_mfma_f32_16x16x32_bf16 v[24:27], v[196:199], v[180:183], v[24:27]
	v_mfma_f32_16x16x32_bf16 v[16:19], v[208:211], v[180:183], v[16:19]
	v_mfma_f32_16x16x32_bf16 v[8:11], v[196:199], v[188:191], v[8:11]
	v_mfma_f32_16x16x32_bf16 v[0:3], v[208:211], v[188:191], v[0:3]
	v_mfma_f32_16x16x32_bf16 v[56:59], v[200:203], v[168:171], v[56:59]
	v_mfma_f32_16x16x32_bf16 v[48:51], v[212:215], v[168:171], v[48:51]
	v_mfma_f32_16x16x32_bf16 v[40:43], v[200:203], v[176:179], v[40:43]
	v_mfma_f32_16x16x32_bf16 v[32:35], v[212:215], v[176:179], v[32:35]
	v_mfma_f32_16x16x32_bf16 v[24:27], v[200:203], v[184:187], v[24:27]
	v_mfma_f32_16x16x32_bf16 v[16:19], v[212:215], v[184:187], v[16:19]
	v_mfma_f32_16x16x32_bf16 v[8:11], v[200:203], v[192:195], v[8:11]
	v_mfma_f32_16x16x32_bf16 v[0:3], v[212:215], v[192:195], v[0:3]
	s_barrier
	ds_read_b128 v[148:151], v145
	ds_read_b128 v[152:155], v145 offset:1024
	ds_read_b128 v[156:159], v145 offset:2048
	ds_read_b128 v[160:163], v145 offset:3072
	s_add_u32 s14, s14, 0x80000
	s_addc_u32 s15, s15, 0
	s_mov_b32 m0, s17
	v_lshl_add_u64 v[196:197], s[14:15], 0, v[130:131]
	ds_read_b128 v[164:167], v143 offset:32768
	ds_read_b128 v[168:171], v143 offset:33792
	ds_read_b128 v[172:175], v143 offset:34816
	ds_read_b128 v[176:179], v143 offset:35840
	ds_read_b128 v[180:183], v143 offset:36864
	ds_read_b128 v[184:187], v143 offset:37888
	ds_read_b128 v[188:191], v143 offset:38912
	ds_read_b128 v[192:195], v143 offset:39936
	global_load_lds_dwordx4 v[196:197], off
	v_lshl_add_u64 v[196:197], s[14:15], 0, v[128:129]
	s_mov_b32 m0, s18
	s_nop 0
	global_load_lds_dwordx4 v[196:197], off
	s_waitcnt lgkmcnt(8)
	s_barrier
	s_waitcnt lgkmcnt(0)
	v_mfma_f32_16x16x32_bf16 v[124:127], v[148:151], v[164:167], v[124:127]
	v_mfma_f32_16x16x32_bf16 v[116:119], v[156:159], v[164:167], v[116:119]
	v_mfma_f32_16x16x32_bf16 v[108:111], v[148:151], v[172:175], v[108:111]
	v_mfma_f32_16x16x32_bf16 v[100:103], v[156:159], v[172:175], v[100:103]
	v_mfma_f32_16x16x32_bf16 v[92:95], v[148:151], v[180:183], v[92:95]
	v_mfma_f32_16x16x32_bf16 v[84:87], v[156:159], v[180:183], v[84:87]
	v_mfma_f32_16x16x32_bf16 v[76:79], v[148:151], v[188:191], v[76:79]
	v_mfma_f32_16x16x32_bf16 v[68:71], v[156:159], v[188:191], v[68:71]
	v_mfma_f32_16x16x32_bf16 v[124:127], v[152:155], v[168:171], v[124:127]
	v_mfma_f32_16x16x32_bf16 v[116:119], v[160:163], v[168:171], v[116:119]
	v_mfma_f32_16x16x32_bf16 v[108:111], v[152:155], v[176:179], v[108:111]
	v_mfma_f32_16x16x32_bf16 v[100:103], v[160:163], v[176:179], v[100:103]
	v_mfma_f32_16x16x32_bf16 v[92:95], v[152:155], v[184:187], v[92:95]
	v_mfma_f32_16x16x32_bf16 v[84:87], v[160:163], v[184:187], v[84:87]
	v_mfma_f32_16x16x32_bf16 v[76:79], v[152:155], v[192:195], v[76:79]
	v_mfma_f32_16x16x32_bf16 v[68:71], v[160:163], v[192:195], v[68:71]
	s_barrier
	s_mov_b32 m0, s39
	v_lshl_add_u64 v[140:141], v[140:141], 0, s[0:1]
	ds_read_b128 v[196:199], v146
	ds_read_b128 v[200:203], v146 offset:1024
	ds_read_b128 v[208:211], v146 offset:2048
	ds_read_b128 v[212:215], v146 offset:3072
	global_load_lds_dwordx4 v[140:141], off
	v_lshl_add_u64 v[140:141], v[204:205], 0, s[0:1]
	s_mov_b32 m0, s40
	s_nop 0
	global_load_lds_dwordx4 v[140:141], off
	s_barrier
	s_waitcnt lgkmcnt(0)
	v_mfma_f32_16x16x32_bf16 v[120:123], v[196:199], v[164:167], v[120:123]
	v_mfma_f32_16x16x32_bf16 v[112:115], v[208:211], v[164:167], v[112:115]
	v_mfma_f32_16x16x32_bf16 v[104:107], v[196:199], v[172:175], v[104:107]
	v_mfma_f32_16x16x32_bf16 v[96:99], v[208:211], v[172:175], v[96:99]
	v_mfma_f32_16x16x32_bf16 v[88:91], v[196:199], v[180:183], v[88:91]
	v_mfma_f32_16x16x32_bf16 v[80:83], v[208:211], v[180:183], v[80:83]
	v_mfma_f32_16x16x32_bf16 v[72:75], v[196:199], v[188:191], v[72:75]
	v_mfma_f32_16x16x32_bf16 v[64:67], v[208:211], v[188:191], v[64:67]
	v_mfma_f32_16x16x32_bf16 v[120:123], v[200:203], v[168:171], v[120:123]
	v_mfma_f32_16x16x32_bf16 v[112:115], v[212:215], v[168:171], v[112:115]
	v_mfma_f32_16x16x32_bf16 v[104:107], v[200:203], v[176:179], v[104:107]
	v_mfma_f32_16x16x32_bf16 v[96:99], v[212:215], v[176:179], v[96:99]
	v_mfma_f32_16x16x32_bf16 v[88:91], v[200:203], v[184:187], v[88:91]
	v_mfma_f32_16x16x32_bf16 v[80:83], v[212:215], v[184:187], v[80:83]
	v_mfma_f32_16x16x32_bf16 v[72:75], v[200:203], v[192:195], v[72:75]
	v_mfma_f32_16x16x32_bf16 v[64:67], v[212:215], v[192:195], v[64:67]
	s_barrier
	s_mov_b32 m0, s20
	v_lshl_add_u64 v[140:141], v[216:217], 0, s[0:1]
	ds_read_b128 v[164:167], v143 offset:49152
	ds_read_b128 v[168:171], v143 offset:50176
	ds_read_b128 v[172:175], v143 offset:51200
	ds_read_b128 v[176:179], v143 offset:52224
	ds_read_b128 v[180:183], v143 offset:53248
	ds_read_b128 v[184:187], v143 offset:54272
	ds_read_b128 v[188:191], v143 offset:55296
	ds_read_b128 v[192:195], v143 offset:56320
	global_load_lds_dwordx4 v[140:141], off
	v_lshl_add_u64 v[140:141], v[218:219], 0, s[0:1]
	s_mov_b32 m0, s21
	s_nop 0
	global_load_lds_dwordx4 v[140:141], off
	s_barrier
; DI float silu_f(float g) { return g * __builtin_amdgcn_rcpf(1.f + __builtin_amdgcn_exp2f(-LOG2E * g)); }
; #define WAIT_V(n) asm volatile("s_waitcnt vmcnt(" #n ")" ::: "memory")
; #define WAIT_L(n) asm volatile("s_waitcnt lgkmcnt(" #n ")" ::: "memory")
; #define BAR __builtin_amdgcn_s_barrier()
; #define SCHED __builtin_amdgcn_sched_barrier(0)
; #define EPI_DONE do { } while (0)
; template <class Get, class Epi>
; DI void gemm_stream(LAS unsigned char* lds, const int K, const int ld, Get get, Epi epi) {
;     ...
;             BAR; WAIT_L(0); MMA(1, 0, At, B0); BAR; SCHED;
;             STAGE(SBo(1, 1), b3 + hstep);
;             WAIT_V(6); BAR; MMA(1, 1, At, B1); BAR;
;         }
;         epi(acc, cur);
; DI void epi_swiglu(const Acc& acc, int brow, int pn, bf16_t* hid) {
;     EPI_IDX
; #pragma unroll
;     for (int ai = 0; ai < 2; ++ai)
; #pragma unroll
;         for (int m = 0; m < 4; ++m) {
;             const int r = brow + ai * 128 + wr * 64 + m * 16 + fr;
;             bf16_t* rp = hid + (size_t)r * FF + pn * 128 + wc * 32 + fq * 4;
; #pragma unroll
;             for (int n = 0; n < 2; ++n) {
;                 const f32x4 g = acc[ai][0][m][n], u = acc[ai][1][m][n];
;                 float o[4];
; #pragma unroll
;                 for (int j = 0; j < 4; ++j) o[j] = silu_f(g[j]) * u[j];
;                 st4(rp + n * 16, o[0], o[1], o[2], o[3]);
;             }
;         }
;     EPI_DONE;
	s_waitcnt lgkmcnt(0)
	v_mfma_f32_16x16x32_bf16 v[60:63], v[148:151], v[164:167], v[60:63]
	v_mfma_f32_16x16x32_bf16 v[52:55], v[156:159], v[164:167], v[52:55]
	v_mfma_f32_16x16x32_bf16 v[44:47], v[148:151], v[172:175], v[44:47]
	v_mfma_f32_16x16x32_bf16 v[36:39], v[156:159], v[172:175], v[36:39]
	v_mfma_f32_16x16x32_bf16 v[28:31], v[148:151], v[180:183], v[28:31]
	v_mfma_f32_16x16x32_bf16 v[20:23], v[156:159], v[180:183], v[20:23]
	v_mfma_f32_16x16x32_bf16 v[12:15], v[148:151], v[188:191], v[12:15]
	v_mfma_f32_16x16x32_bf16 v[4:7], v[156:159], v[188:191], v[4:7]
	v_mfma_f32_16x16x32_bf16 v[60:63], v[152:155], v[168:171], v[60:63]
	v_mfma_f32_16x16x32_bf16 v[52:55], v[160:163], v[168:171], v[52:55]
	v_mfma_f32_16x16x32_bf16 v[44:47], v[152:155], v[176:179], v[44:47]
	v_mfma_f32_16x16x32_bf16 v[36:39], v[160:163], v[176:179], v[36:39]
	v_mfma_f32_16x16x32_bf16 v[28:31], v[152:155], v[184:187], v[28:31]
	v_mfma_f32_16x16x32_bf16 v[20:23], v[160:163], v[184:187], v[20:23]
	v_mfma_f32_16x16x32_bf16 v[12:15], v[152:155], v[192:195], v[12:15]
	v_mfma_f32_16x16x32_bf16 v[4:7], v[160:163], v[192:195], v[4:7]
	s_barrier
	s_add_u32 s12, s12, 0x80080
	s_addc_u32 s13, s13, 0
	s_mov_b32 m0, s41
	v_lshl_add_u64 v[140:141], s[12:13], 0, v[130:131]
	global_load_lds_dwordx4 v[140:141], off
	v_lshl_add_u64 v[140:141], s[12:13], 0, v[128:129]
	s_mov_b32 m0, s52
	s_nop 0
	global_load_lds_dwordx4 v[140:141], off
	s_add_i32 s59, s59, 2
	s_add_u32 s10, s10, 0x100
	s_addc_u32 s11, s11, 0
	s_add_u32 s57, s57, 0x100
	s_addc_u32 s58, s58, 0
	s_cmp_gt_u32 s59, 29
	s_waitcnt vmcnt(6)
	s_barrier
	v_mfma_f32_16x16x32_bf16 v[56:59], v[196:199], v[164:167], v[56:59]
	v_mfma_f32_16x16x32_bf16 v[48:51], v[208:211], v[164:167], v[48:51]
	v_mfma_f32_16x16x32_bf16 v[40:43], v[196:199], v[172:175], v[40:43]
	v_mfma_f32_16x16x32_bf16 v[32:35], v[208:211], v[172:175], v[32:35]
	v_mfma_f32_16x16x32_bf16 v[24:27], v[196:199], v[180:183], v[24:27]
	v_mfma_f32_16x16x32_bf16 v[16:19], v[208:211], v[180:183], v[16:19]
	v_mfma_f32_16x16x32_bf16 v[8:11], v[196:199], v[188:191], v[8:11]
	v_mfma_f32_16x16x32_bf16 v[0:3], v[208:211], v[188:191], v[0:3]
	v_mfma_f32_16x16x32_bf16 v[56:59], v[200:203], v[168:171], v[56:59]
	v_mfma_f32_16x16x32_bf16 v[48:51], v[212:215], v[168:171], v[48:51]
	v_mfma_f32_16x16x32_bf16 v[40:43], v[200:203], v[176:179], v[40:43]
	v_mfma_f32_16x16x32_bf16 v[32:35], v[212:215], v[176:179], v[32:35]
	v_mfma_f32_16x16x32_bf16 v[24:27], v[200:203], v[184:187], v[24:27]
	v_mfma_f32_16x16x32_bf16 v[16:19], v[212:215], v[184:187], v[16:19]
	v_mfma_f32_16x16x32_bf16 v[8:11], v[200:203], v[192:195], v[8:11]
	v_mfma_f32_16x16x32_bf16 v[0:3], v[212:215], v[192:195], v[0:3]
	s_barrier
	s_cbranch_scc0 .LBB0_1630
	s_lshl_b32 s10, s55, 8
	v_mov_b32_e32 v132, v206
	v_mul_f32_e32 v149, 0xbfb8aa3b, v125
	v_and_or_b32 v141, v132, 15, s10
	s_lshl_b32 s10, s56, 7
	s_ashr_i32 s11, s10, 31
	s_lshl_b64 s[10:11], s[10:11], 1
	v_ashrrev_i32_e32 v140, 2, v132
	s_add_u32 s10, s80, s10
	v_and_b32_e32 v140, 0xffffffc0, v140
	s_addc_u32 s11, s81, s11
	v_lshrrev_b32_e32 v148, 1, v132
	v_and_b32_e32 v132, 0xc0, v132
	v_add_u32_e32 v147, v141, v140
	v_lshl_add_u64 v[140:141], s[10:11], 0, v[132:133]
	v_and_b32_e32 v132, 24, v148
	v_mul_f32_e32 v148, 0xbfb8aa3b, v124
	v_exp_f32_e32 v148, v148
	v_exp_f32_e32 v149, v149
	v_lshl_add_u64 v[140:141], v[140:141], 0, v[132:133]
	v_mad_i64_i32 v[152:153], s[10:11], v147, s23, v[140:141]
	v_add_f32_e32 v132, 1.0, v148
	v_rcp_f32_e32 v148, v132
	v_add_f32_e32 v132, 1.0, v149
	v_mul_f32_e32 v149, 0xbfb8aa3b, v126
	v_exp_f32_e32 v150, v149
	v_mul_f32_e32 v149, 0xbfb8aa3b, v127
	v_exp_f32_e32 v151, v149
	v_rcp_f32_e32 v149, v132
	v_add_f32_e32 v132, 1.0, v150
	v_rcp_f32_e32 v150, v132
	v_add_f32_e32 v132, 1.0, v151
	v_rcp_f32_e32 v151, v132
	v_pk_mul_f32 v[124:125], v[124:125], v[148:149]
	s_and_b64 vcc, exec, s[4:5]
	v_pk_mul_f32 v[120:121], v[124:125], v[120:121]
	v_pk_mul_f32 v[124:125], v[126:127], v[150:151]
	v_cvt_pk_bf16_f32 v120, v120, v121
	v_mul_f32_e32 v121, 0xbfb8aa3b, v116
	v_pk_mul_f32 v[122:123], v[124:125], v[122:123]
	v_exp_f32_e32 v124, v121
	v_mul_f32_e32 v121, 0xbfb8aa3b, v117
	v_exp_f32_e32 v125, v121
	v_cvt_pk_bf16_f32 v121, v122, v123
	v_add_f32_e32 v122, 1.0, v124
	v_mul_f32_e32 v124, 0xbfb8aa3b, v118
	v_add_f32_e32 v123, 1.0, v125
	v_mul_f32_e32 v125, 0xbfb8aa3b, v119
	v_exp_f32_e32 v124, v124
	v_exp_f32_e32 v125, v125
	v_rcp_f32_e32 v122, v122
	v_rcp_f32_e32 v123, v123
	v_add_f32_e32 v124, 1.0, v124
	v_add_f32_e32 v125, 1.0, v125
	v_rcp_f32_e32 v124, v124
	v_rcp_f32_e32 v125, v125
	v_pk_mul_f32 v[116:117], v[116:117], v[122:123]
	s_mov_b32 s56, s53
	v_pk_mul_f32 v[112:113], v[116:117], v[112:113]
	v_pk_mul_f32 v[116:117], v[118:119], v[124:125]
	v_cvt_pk_bf16_f32 v112, v112, v113
	v_pk_mul_f32 v[114:115], v[116:117], v[114:115]
	v_or_b32_e32 v116, 16, v147
	v_cvt_pk_bf16_f32 v113, v114, v115
	global_store_dwordx2 v[152:153], v[112:113], off offset:32
	v_mul_f32_e32 v112, 0xbfb8aa3b, v108
	v_mul_f32_e32 v113, 0xbfb8aa3b, v109
	v_exp_f32_e32 v112, v112
	v_exp_f32_e32 v113, v113
	v_mul_f32_e32 v114, 0xbfb8aa3b, v110
	v_mul_f32_e32 v115, 0xbfb8aa3b, v111
	v_exp_f32_e32 v114, v114
	v_exp_f32_e32 v115, v115
	v_add_f32_e32 v112, 1.0, v112
	v_add_f32_e32 v113, 1.0, v113
	v_rcp_f32_e32 v112, v112
	v_rcp_f32_e32 v113, v113
	v_add_f32_e32 v114, 1.0, v114
	v_add_f32_e32 v115, 1.0, v115
	v_rcp_f32_e32 v114, v114
	v_rcp_f32_e32 v115, v115
	v_pk_mul_f32 v[108:109], v[108:109], v[112:113]
	v_mad_i64_i32 v[116:117], s[10:11], v116, s23, v[140:141]
	v_pk_mul_f32 v[104:105], v[108:109], v[104:105]
	v_pk_mul_f32 v[108:109], v[110:111], v[114:115]
; DI float silu_f(float g) { return g * __builtin_amdgcn_rcpf(1.f + __builtin_amdgcn_exp2f(-LOG2E * g)); }
; #define EPI_DONE do { } while (0)
; DI void epi_swiglu(const Acc& acc, int brow, int pn, bf16_t* hid) {
;     EPI_IDX
; #pragma unroll
;     for (int ai = 0; ai < 2; ++ai)
; #pragma unroll
;         for (int m = 0; m < 4; ++m) {
;             const int r = brow + ai * 128 + wr * 64 + m * 16 + fr;
;             bf16_t* rp = hid + (size_t)r * FF + pn * 128 + wc * 32 + fq * 4;
; #pragma unroll
;             for (int n = 0; n < 2; ++n) {
;                 const f32x4 g = acc[ai][0][m][n], u = acc[ai][1][m][n];
;                 float o[4];
; #pragma unroll
;                 for (int j = 0; j < 4; ++j) o[j] = silu_f(g[j]) * u[j];
;                 st4(rp + n * 16, o[0], o[1], o[2], o[3]);
;             }
;         }
;     EPI_DONE;
	v_cvt_pk_bf16_f32 v104, v104, v105
	v_mul_f32_e32 v105, 0xbfb8aa3b, v100
	v_pk_mul_f32 v[106:107], v[108:109], v[106:107]
	v_exp_f32_e32 v108, v105
	v_mul_f32_e32 v105, 0xbfb8aa3b, v101
	v_exp_f32_e32 v109, v105
	v_cvt_pk_bf16_f32 v105, v106, v107
	v_add_f32_e32 v106, 1.0, v108
	v_mul_f32_e32 v108, 0xbfb8aa3b, v102
	v_add_f32_e32 v107, 1.0, v109
	v_mul_f32_e32 v109, 0xbfb8aa3b, v103
	v_exp_f32_e32 v108, v108
	v_exp_f32_e32 v109, v109
	v_rcp_f32_e32 v106, v106
	v_rcp_f32_e32 v107, v107
	v_add_f32_e32 v108, 1.0, v108
	v_add_f32_e32 v109, 1.0, v109
	v_rcp_f32_e32 v108, v108
	v_rcp_f32_e32 v109, v109
	v_pk_mul_f32 v[100:101], v[100:101], v[106:107]
	s_mov_b32 s55, s54
	v_pk_mul_f32 v[96:97], v[100:101], v[96:97]
	v_pk_mul_f32 v[100:101], v[102:103], v[108:109]
	v_cvt_pk_bf16_f32 v96, v96, v97
	v_pk_mul_f32 v[98:99], v[100:101], v[98:99]
	v_or_b32_e32 v100, 32, v147
	v_cvt_pk_bf16_f32 v97, v98, v99
	global_store_dwordx2 v[116:117], v[96:97], off offset:32
	v_mul_f32_e32 v96, 0xbfb8aa3b, v92
	v_mul_f32_e32 v97, 0xbfb8aa3b, v93
	v_exp_f32_e32 v96, v96
	v_exp_f32_e32 v97, v97
	v_mul_f32_e32 v98, 0xbfb8aa3b, v94
	v_mul_f32_e32 v99, 0xbfb8aa3b, v95
	v_exp_f32_e32 v98, v98
	v_exp_f32_e32 v99, v99
	v_add_f32_e32 v96, 1.0, v96
	v_add_f32_e32 v97, 1.0, v97
	v_rcp_f32_e32 v96, v96
	v_rcp_f32_e32 v97, v97
	v_add_f32_e32 v98, 1.0, v98
	v_add_f32_e32 v99, 1.0, v99
	v_rcp_f32_e32 v98, v98
	v_rcp_f32_e32 v99, v99
	v_pk_mul_f32 v[92:93], v[92:93], v[96:97]
	v_mad_i64_i32 v[100:101], s[10:11], v100, s23, v[140:141]
	v_pk_mul_f32 v[88:89], v[92:93], v[88:89]
	v_pk_mul_f32 v[92:93], v[94:95], v[98:99]
	v_cvt_pk_bf16_f32 v88, v88, v89
	v_mul_f32_e32 v89, 0xbfb8aa3b, v84
	v_pk_mul_f32 v[90:91], v[92:93], v[90:91]
	v_exp_f32_e32 v92, v89
	v_mul_f32_e32 v89, 0xbfb8aa3b, v85
	v_exp_f32_e32 v93, v89
	v_cvt_pk_bf16_f32 v89, v90, v91
	v_add_f32_e32 v90, 1.0, v92
	v_mul_f32_e32 v92, 0xbfb8aa3b, v86
	v_add_f32_e32 v91, 1.0, v93
	v_mul_f32_e32 v93, 0xbfb8aa3b, v87
	v_exp_f32_e32 v92, v92
	v_exp_f32_e32 v93, v93
	v_rcp_f32_e32 v90, v90
	v_rcp_f32_e32 v91, v91
	v_add_f32_e32 v92, 1.0, v92
	v_add_f32_e32 v93, 1.0, v93
	v_rcp_f32_e32 v92, v92
	v_rcp_f32_e32 v93, v93
	v_pk_mul_f32 v[84:85], v[84:85], v[90:91]
	s_mov_b64 s[12:13], s[8:9]
	v_pk_mul_f32 v[80:81], v[84:85], v[80:81]
	v_pk_mul_f32 v[84:85], v[86:87], v[92:93]
	v_cvt_pk_bf16_f32 v80, v80, v81
	v_pk_mul_f32 v[82:83], v[84:85], v[82:83]
	v_or_b32_e32 v84, 48, v147
	v_cvt_pk_bf16_f32 v81, v82, v83
	global_store_dwordx2 v[100:101], v[80:81], off offset:32
	v_mul_f32_e32 v80, 0xbfb8aa3b, v76
	v_mul_f32_e32 v81, 0xbfb8aa3b, v77
	v_exp_f32_e32 v80, v80
	v_exp_f32_e32 v81, v81
	v_mul_f32_e32 v82, 0xbfb8aa3b, v78
	v_mul_f32_e32 v83, 0xbfb8aa3b, v79
	v_exp_f32_e32 v82, v82
	v_exp_f32_e32 v83, v83
	v_add_f32_e32 v80, 1.0, v80
	v_add_f32_e32 v81, 1.0, v81
	v_rcp_f32_e32 v80, v80
	v_rcp_f32_e32 v81, v81
	v_add_f32_e32 v82, 1.0, v82
	v_add_f32_e32 v83, 1.0, v83
	v_rcp_f32_e32 v82, v82
	v_rcp_f32_e32 v83, v83
	v_pk_mul_f32 v[76:77], v[76:77], v[80:81]
	v_mad_i64_i32 v[84:85], s[10:11], v84, s23, v[140:141]
	v_pk_mul_f32 v[72:73], v[76:77], v[72:73]
	v_pk_mul_f32 v[76:77], v[78:79], v[82:83]
	v_cvt_pk_bf16_f32 v72, v72, v73
	v_mul_f32_e32 v73, 0xbfb8aa3b, v68
	v_pk_mul_f32 v[74:75], v[76:77], v[74:75]
	v_exp_f32_e32 v76, v73
	v_mul_f32_e32 v73, 0xbfb8aa3b, v69
	v_exp_f32_e32 v77, v73
	v_cvt_pk_bf16_f32 v73, v74, v75
	v_add_f32_e32 v74, 1.0, v76
	v_mul_f32_e32 v76, 0xbfb8aa3b, v70
	v_add_f32_e32 v75, 1.0, v77
	v_mul_f32_e32 v77, 0xbfb8aa3b, v71
	v_exp_f32_e32 v76, v76
	v_exp_f32_e32 v77, v77
	v_rcp_f32_e32 v74, v74
	v_rcp_f32_e32 v75, v75
	v_add_f32_e32 v76, 1.0, v76
	v_add_f32_e32 v77, 1.0, v77
	v_rcp_f32_e32 v76, v76
	v_rcp_f32_e32 v77, v77
	v_pk_mul_f32 v[68:69], v[68:69], v[74:75]
	global_store_dwordx2 v[152:153], v[120:121], off
	v_pk_mul_f32 v[64:65], v[68:69], v[64:65]
	v_pk_mul_f32 v[68:69], v[70:71], v[76:77]
	v_cvt_pk_bf16_f32 v64, v64, v65
	v_pk_mul_f32 v[66:67], v[68:69], v[66:67]
	v_add_u32_e32 v68, 0x80, v147
	v_cvt_pk_bf16_f32 v65, v66, v67
	global_store_dwordx2 v[84:85], v[64:65], off offset:32
	v_mul_f32_e32 v64, 0xbfb8aa3b, v60
	v_mul_f32_e32 v65, 0xbfb8aa3b, v61
	v_exp_f32_e32 v64, v64
	v_exp_f32_e32 v65, v65
	v_mul_f32_e32 v66, 0xbfb8aa3b, v62
	v_mul_f32_e32 v67, 0xbfb8aa3b, v63
	v_exp_f32_e32 v66, v66
	v_exp_f32_e32 v67, v67
	v_add_f32_e32 v64, 1.0, v64
	v_add_f32_e32 v65, 1.0, v65
	v_rcp_f32_e32 v64, v64
	v_rcp_f32_e32 v65, v65
	v_add_f32_e32 v66, 1.0, v66
	v_add_f32_e32 v67, 1.0, v67
	v_rcp_f32_e32 v66, v66
	v_rcp_f32_e32 v67, v67
	v_pk_mul_f32 v[60:61], v[60:61], v[64:65]
	v_mad_i64_i32 v[68:69], s[10:11], v68, s23, v[140:141]
	v_pk_mul_f32 v[56:57], v[60:61], v[56:57]
	v_pk_mul_f32 v[60:61], v[62:63], v[66:67]
	v_cvt_pk_bf16_f32 v56, v56, v57
	v_mul_f32_e32 v57, 0xbfb8aa3b, v52
	v_pk_mul_f32 v[58:59], v[60:61], v[58:59]
	v_exp_f32_e32 v60, v57
	v_mul_f32_e32 v57, 0xbfb8aa3b, v53
	v_exp_f32_e32 v61, v57
	v_cvt_pk_bf16_f32 v57, v58, v59
	v_add_f32_e32 v58, 1.0, v60
	v_mul_f32_e32 v60, 0xbfb8aa3b, v54
	v_add_f32_e32 v59, 1.0, v61
	v_mul_f32_e32 v61, 0xbfb8aa3b, v55
	v_exp_f32_e32 v60, v60
	v_exp_f32_e32 v61, v61
	v_rcp_f32_e32 v58, v58
	v_rcp_f32_e32 v59, v59
	v_add_f32_e32 v60, 1.0, v60
	v_add_f32_e32 v61, 1.0, v61
	v_rcp_f32_e32 v60, v60
	v_rcp_f32_e32 v61, v61
; DI float silu_f(float g) { return g * __builtin_amdgcn_rcpf(1.f + __builtin_amdgcn_exp2f(-LOG2E * g)); }
; #define WAIT_V(n) asm volatile("s_waitcnt vmcnt(" #n ")" ::: "memory")
; #define BAR __builtin_amdgcn_s_barrier()
; #define EPI_DONE do { } while (0)
; template <class Get, class Epi>
; DI void gemm_stream(LAS unsigned char* lds, const int K, const int ld, Get get, Epi epi) {
;     ...
;         epi(acc, cur);
;         if (!has_next) break;
;         ZERO_ACC;
;         cur = nxt; cA = nA; cB = nB; ++ui;
;     }
;     WAIT_V(0);
;     if (wr == 0) BAR;
;     BAR;
; DI void epi_swiglu(const Acc& acc, int brow, int pn, bf16_t* hid) {
;     EPI_IDX
; #pragma unroll
;     for (int ai = 0; ai < 2; ++ai)
; #pragma unroll
;         for (int m = 0; m < 4; ++m) {
;             const int r = brow + ai * 128 + wr * 64 + m * 16 + fr;
;             bf16_t* rp = hid + (size_t)r * FF + pn * 128 + wc * 32 + fq * 4;
; #pragma unroll
;             for (int n = 0; n < 2; ++n) {
;                 const f32x4 g = acc[ai][0][m][n], u = acc[ai][1][m][n];
;                 float o[4];
; #pragma unroll
;                 for (int j = 0; j < 4; ++j) o[j] = silu_f(g[j]) * u[j];
;                 st4(rp + n * 16, o[0], o[1], o[2], o[3]);
;             }
;         }
;     EPI_DONE;
	v_pk_mul_f32 v[52:53], v[52:53], v[58:59]
	global_store_dwordx2 v[116:117], v[104:105], off
	v_pk_mul_f32 v[48:49], v[52:53], v[48:49]
	v_pk_mul_f32 v[52:53], v[54:55], v[60:61]
	v_cvt_pk_bf16_f32 v48, v48, v49
	v_pk_mul_f32 v[50:51], v[52:53], v[50:51]
	v_add_u32_e32 v52, 0x90, v147
	v_cvt_pk_bf16_f32 v49, v50, v51
	global_store_dwordx2 v[68:69], v[48:49], off offset:32
	v_mul_f32_e32 v48, 0xbfb8aa3b, v44
	v_mul_f32_e32 v49, 0xbfb8aa3b, v45
	v_exp_f32_e32 v48, v48
	v_exp_f32_e32 v49, v49
	v_mul_f32_e32 v50, 0xbfb8aa3b, v46
	v_mul_f32_e32 v51, 0xbfb8aa3b, v47
	v_exp_f32_e32 v50, v50
	v_exp_f32_e32 v51, v51
	v_add_f32_e32 v48, 1.0, v48
	v_add_f32_e32 v49, 1.0, v49
	v_rcp_f32_e32 v48, v48
	v_rcp_f32_e32 v49, v49
	v_add_f32_e32 v50, 1.0, v50
	v_add_f32_e32 v51, 1.0, v51
	v_rcp_f32_e32 v50, v50
	v_rcp_f32_e32 v51, v51
	v_pk_mul_f32 v[44:45], v[44:45], v[48:49]
	v_mad_i64_i32 v[52:53], s[10:11], v52, s23, v[140:141]
	v_pk_mul_f32 v[40:41], v[44:45], v[40:41]
	v_pk_mul_f32 v[44:45], v[46:47], v[50:51]
	v_cvt_pk_bf16_f32 v40, v40, v41
	v_mul_f32_e32 v41, 0xbfb8aa3b, v36
	v_pk_mul_f32 v[42:43], v[44:45], v[42:43]
	v_exp_f32_e32 v44, v41
	v_mul_f32_e32 v41, 0xbfb8aa3b, v37
	v_exp_f32_e32 v45, v41
	v_cvt_pk_bf16_f32 v41, v42, v43
	v_add_f32_e32 v42, 1.0, v44
	v_mul_f32_e32 v44, 0xbfb8aa3b, v38
	v_add_f32_e32 v43, 1.0, v45
	v_mul_f32_e32 v45, 0xbfb8aa3b, v39
	v_exp_f32_e32 v44, v44
	v_exp_f32_e32 v45, v45
	v_rcp_f32_e32 v42, v42
	v_rcp_f32_e32 v43, v43
	v_add_f32_e32 v44, 1.0, v44
	v_add_f32_e32 v45, 1.0, v45
	v_rcp_f32_e32 v44, v44
	v_rcp_f32_e32 v45, v45
	v_pk_mul_f32 v[36:37], v[36:37], v[42:43]
	global_store_dwordx2 v[100:101], v[88:89], off
	v_pk_mul_f32 v[32:33], v[36:37], v[32:33]
	v_pk_mul_f32 v[36:37], v[38:39], v[44:45]
	v_cvt_pk_bf16_f32 v32, v32, v33
	v_pk_mul_f32 v[34:35], v[36:37], v[34:35]
	v_add_u32_e32 v36, 0xa0, v147
	v_cvt_pk_bf16_f32 v33, v34, v35
	global_store_dwordx2 v[52:53], v[32:33], off offset:32
	v_mul_f32_e32 v32, 0xbfb8aa3b, v28
	v_mul_f32_e32 v33, 0xbfb8aa3b, v29
	v_exp_f32_e32 v32, v32
	v_exp_f32_e32 v33, v33
	v_mul_f32_e32 v34, 0xbfb8aa3b, v30
	v_mul_f32_e32 v35, 0xbfb8aa3b, v31
	v_exp_f32_e32 v34, v34
	v_exp_f32_e32 v35, v35
	v_add_f32_e32 v32, 1.0, v32
	v_add_f32_e32 v33, 1.0, v33
	v_rcp_f32_e32 v32, v32
	v_rcp_f32_e32 v33, v33
	v_add_f32_e32 v34, 1.0, v34
	v_add_f32_e32 v35, 1.0, v35
	v_rcp_f32_e32 v34, v34
	v_rcp_f32_e32 v35, v35
	v_pk_mul_f32 v[28:29], v[28:29], v[32:33]
	v_mad_i64_i32 v[36:37], s[10:11], v36, s23, v[140:141]
	v_pk_mul_f32 v[24:25], v[28:29], v[24:25]
	v_pk_mul_f32 v[28:29], v[30:31], v[34:35]
	v_cvt_pk_bf16_f32 v24, v24, v25
	v_mul_f32_e32 v25, 0xbfb8aa3b, v20
	v_pk_mul_f32 v[26:27], v[28:29], v[26:27]
	v_exp_f32_e32 v28, v25
	v_mul_f32_e32 v25, 0xbfb8aa3b, v21
	v_exp_f32_e32 v29, v25
	v_cvt_pk_bf16_f32 v25, v26, v27
	v_add_f32_e32 v26, 1.0, v28
	v_mul_f32_e32 v28, 0xbfb8aa3b, v22
	v_add_f32_e32 v27, 1.0, v29
	v_mul_f32_e32 v29, 0xbfb8aa3b, v23
	v_exp_f32_e32 v28, v28
	v_exp_f32_e32 v29, v29
	v_rcp_f32_e32 v26, v26
	v_rcp_f32_e32 v27, v27
	v_add_f32_e32 v28, 1.0, v28
	v_add_f32_e32 v29, 1.0, v29
	v_rcp_f32_e32 v28, v28
	v_rcp_f32_e32 v29, v29
	v_pk_mul_f32 v[20:21], v[20:21], v[26:27]
	global_store_dwordx2 v[84:85], v[72:73], off
	v_pk_mul_f32 v[16:17], v[20:21], v[16:17]
	v_pk_mul_f32 v[20:21], v[22:23], v[28:29]
	v_cvt_pk_bf16_f32 v16, v16, v17
	v_pk_mul_f32 v[18:19], v[20:21], v[18:19]
	v_add_u32_e32 v20, 0xb0, v147
	v_cvt_pk_bf16_f32 v17, v18, v19
	global_store_dwordx2 v[36:37], v[16:17], off offset:32
	v_mul_f32_e32 v16, 0xbfb8aa3b, v12
	v_mul_f32_e32 v17, 0xbfb8aa3b, v13
	v_exp_f32_e32 v16, v16
	v_exp_f32_e32 v17, v17
	v_mul_f32_e32 v18, 0xbfb8aa3b, v14
	v_mul_f32_e32 v19, 0xbfb8aa3b, v15
	v_exp_f32_e32 v18, v18
	v_exp_f32_e32 v19, v19
	v_add_f32_e32 v16, 1.0, v16
	v_add_f32_e32 v17, 1.0, v17
	v_rcp_f32_e32 v16, v16
	v_rcp_f32_e32 v17, v17
	v_add_f32_e32 v18, 1.0, v18
	v_add_f32_e32 v19, 1.0, v19
	v_rcp_f32_e32 v18, v18
	v_rcp_f32_e32 v19, v19
	v_pk_mul_f32 v[12:13], v[12:13], v[16:17]
	v_mad_i64_i32 v[20:21], s[10:11], v20, s23, v[140:141]
	v_pk_mul_f32 v[8:9], v[12:13], v[8:9]
	v_pk_mul_f32 v[12:13], v[14:15], v[18:19]
	v_cvt_pk_bf16_f32 v8, v8, v9
	v_mul_f32_e32 v9, 0xbfb8aa3b, v4
	v_pk_mul_f32 v[10:11], v[12:13], v[10:11]
	v_exp_f32_e32 v12, v9
	v_mul_f32_e32 v9, 0xbfb8aa3b, v5
	v_exp_f32_e32 v13, v9
	v_cvt_pk_bf16_f32 v9, v10, v11
	v_add_f32_e32 v10, 1.0, v12
	v_mul_f32_e32 v12, 0xbfb8aa3b, v6
	v_add_f32_e32 v11, 1.0, v13
	v_mul_f32_e32 v13, 0xbfb8aa3b, v7
	v_exp_f32_e32 v12, v12
	v_exp_f32_e32 v13, v13
	v_rcp_f32_e32 v10, v10
	v_rcp_f32_e32 v11, v11
	v_add_f32_e32 v12, 1.0, v12
	v_add_f32_e32 v13, 1.0, v13
	v_rcp_f32_e32 v12, v12
	v_rcp_f32_e32 v13, v13
	v_pk_mul_f32 v[4:5], v[4:5], v[10:11]
	s_mov_b64 s[10:11], s[6:7]
	v_pk_mul_f32 v[0:1], v[4:5], v[0:1]
	v_pk_mul_f32 v[4:5], v[6:7], v[12:13]
	v_cvt_pk_bf16_f32 v0, v0, v1
	v_pk_mul_f32 v[2:3], v[4:5], v[2:3]
	global_store_dwordx2 v[68:69], v[56:57], off
	v_cvt_pk_bf16_f32 v1, v2, v3
	global_store_dwordx2 v[52:53], v[40:41], off
	global_store_dwordx2 v[36:37], v[24:25], off
	global_store_dwordx2 v[20:21], v[8:9], off
	global_store_dwordx2 v[20:21], v[0:1], off offset:32
	s_cbranch_vccz .LBB0_1627
	s_waitcnt vmcnt(0)
	s_cmpk_gt_u32 s2, 0xff
	s_cbranch_scc1 .LBB0_1634
	s_barrier

; #define WAIT_V(n) asm volatile("s_waitcnt vmcnt(" #n ")" ::: "memory")
; #define WAIT_L(n) asm volatile("s_waitcnt lgkmcnt(" #n ")" ::: "memory")
; #define BAR __builtin_amdgcn_s_barrier()
; #define SCHED __builtin_amdgcn_sched_barrier(0)
; template <class Get, class Epi>
; DI void gemm_stream(LAS unsigned char* lds, const int K, const int ld, Get get, Epi epi) {
;     ...
;             const bool last = (t == nt - 2);
;             const char* a1 = cA + (size_t)(t + 1) * kstep;
;             const char* a2 = last ? nA : cA + (size_t)(t + 2) * kstep;
;             const char* b2 = last ? nB : cB + (size_t)(t + 2) * kstep;
;             const char* a3 = a2 + kstep;
;             const char* b3 = b2 + kstep;
;             LDB(B0, 0, 0); SCHED; LDA(At, 0, 0); STAGE(SAo(1, 1), a1 + hstep);
;             WAIT_L(8); BAR; WAIT_L(0); MMA(0, 0, At, B0); BAR; SCHED;
;             LDB(B1, 0, 1); STAGE(SBo(0, 0), b2);
;             BAR; WAIT_L(0); MMA(0, 1, At, B1); BAR;
;             LDA(At, 0, 1); STAGE(SAo(0, 0), a2);
;             BAR; WAIT_L(0); MMA(1, 0, At, B0); BAR; SCHED;
;             STAGE(SBo(0, 1), b2 + hstep);
;             WAIT_V(6); BAR; MMA(1, 1, At, B1); BAR;
.LBB0_1697:
	ds_read_b128 v[128:131], v199
	ds_read_b128 v[132:135], v199 offset:1024
	ds_read_b128 v[136:139], v199 offset:2048
	ds_read_b128 v[140:143], v199 offset:3072
	s_add_u32 s8, s6, 0x100
	s_addc_u32 s9, s7, 0
	s_cmpk_eq_i32 s16, 0x54
	s_cselect_b32 s13, s39, s9
	s_cselect_b32 s12, s38, s8
	s_cselect_b32 s11, s41, s15
	s_cselect_b32 s10, s40, s14
	s_mov_b32 m0, s63
	v_lshl_add_u64 v[186:187], s[6:7], 0, v[168:169]
	ds_read_b128 v[144:147], v200
	ds_read_b128 v[148:151], v200 offset:1024
	ds_read_b128 v[152:155], v200 offset:2048
	ds_read_b128 v[156:159], v200 offset:3072
	ds_read_b128 v[160:163], v200 offset:4096
	ds_read_b128 v[174:177], v200 offset:5120
	ds_read_b128 v[178:181], v200 offset:6144
	ds_read_b128 v[182:185], v200 offset:7168
	global_load_lds_dwordx4 v[186:187], off
	v_lshl_add_u64 v[186:187], s[6:7], 0, v[170:171]
	s_mov_b32 m0, s74
	s_nop 0
	global_load_lds_dwordx4 v[186:187], off
	s_waitcnt lgkmcnt(8)
	s_barrier
	s_waitcnt lgkmcnt(0)
	v_mfma_f32_16x16x32_bf16 v[124:127], v[128:131], v[144:147], v[124:127]
	v_mfma_f32_16x16x32_bf16 v[92:95], v[136:139], v[144:147], v[92:95]
	v_mfma_f32_16x16x32_bf16 v[120:123], v[128:131], v[152:155], v[120:123]
	v_mfma_f32_16x16x32_bf16 v[88:91], v[136:139], v[152:155], v[88:91]
	v_mfma_f32_16x16x32_bf16 v[116:119], v[128:131], v[160:163], v[116:119]
	v_mfma_f32_16x16x32_bf16 v[84:87], v[136:139], v[160:163], v[84:87]
	v_mfma_f32_16x16x32_bf16 v[112:115], v[128:131], v[178:181], v[112:115]
	v_mfma_f32_16x16x32_bf16 v[80:83], v[136:139], v[178:181], v[80:83]
	v_mfma_f32_16x16x32_bf16 v[124:127], v[132:135], v[148:151], v[124:127]
	v_mfma_f32_16x16x32_bf16 v[92:95], v[140:143], v[148:151], v[92:95]
	v_mfma_f32_16x16x32_bf16 v[120:123], v[132:135], v[156:159], v[120:123]
	v_mfma_f32_16x16x32_bf16 v[88:91], v[140:143], v[156:159], v[88:91]
	v_mfma_f32_16x16x32_bf16 v[116:119], v[132:135], v[174:177], v[116:119]
	v_mfma_f32_16x16x32_bf16 v[84:87], v[140:143], v[174:177], v[84:87]
	v_mfma_f32_16x16x32_bf16 v[112:115], v[132:135], v[182:185], v[112:115]
	v_mfma_f32_16x16x32_bf16 v[80:83], v[140:143], v[182:185], v[80:83]
	s_barrier
	s_mov_b32 m0, s75
	v_lshl_add_u64 v[208:209], s[10:11], 0, v[164:165]
	ds_read_b128 v[186:189], v201
	ds_read_b128 v[190:193], v201 offset:1024
	ds_read_b128 v[194:197], v201 offset:2048
	ds_read_b128 v[202:205], v201 offset:3072
	global_load_lds_dwordx4 v[208:209], off
	v_lshl_add_u64 v[210:211], s[10:11], 0, v[166:167]
	s_mov_b32 m0, s76
	s_nop 0
	global_load_lds_dwordx4 v[210:211], off
	s_barrier
	s_waitcnt lgkmcnt(0)
	v_mfma_f32_16x16x32_bf16 v[60:63], v[186:189], v[144:147], v[60:63]
	v_mfma_f32_16x16x32_bf16 v[28:31], v[194:197], v[144:147], v[28:31]
	v_mfma_f32_16x16x32_bf16 v[56:59], v[186:189], v[152:155], v[56:59]
	v_mfma_f32_16x16x32_bf16 v[24:27], v[194:197], v[152:155], v[24:27]
	v_mfma_f32_16x16x32_bf16 v[52:55], v[186:189], v[160:163], v[52:55]
	v_mfma_f32_16x16x32_bf16 v[20:23], v[194:197], v[160:163], v[20:23]
	v_mfma_f32_16x16x32_bf16 v[48:51], v[186:189], v[178:181], v[48:51]
	v_mfma_f32_16x16x32_bf16 v[16:19], v[194:197], v[178:181], v[16:19]
	v_mfma_f32_16x16x32_bf16 v[60:63], v[190:193], v[148:151], v[60:63]
	v_mfma_f32_16x16x32_bf16 v[28:31], v[202:205], v[148:151], v[28:31]
	v_mfma_f32_16x16x32_bf16 v[56:59], v[190:193], v[156:159], v[56:59]
	v_mfma_f32_16x16x32_bf16 v[24:27], v[202:205], v[156:159], v[24:27]
	v_mfma_f32_16x16x32_bf16 v[52:55], v[190:193], v[174:177], v[52:55]
	v_mfma_f32_16x16x32_bf16 v[20:23], v[202:205], v[174:177], v[20:23]
	v_mfma_f32_16x16x32_bf16 v[48:51], v[190:193], v[182:185], v[48:51]
	v_mfma_f32_16x16x32_bf16 v[16:19], v[202:205], v[182:185], v[16:19]
	s_barrier
	s_mov_b32 m0, s23
	v_lshl_add_u64 v[212:213], s[12:13], 0, v[164:165]
	ds_read_b128 v[144:147], v200 offset:16384
	ds_read_b128 v[148:151], v200 offset:17408
	ds_read_b128 v[152:155], v200 offset:18432
	ds_read_b128 v[156:159], v200 offset:19456
	ds_read_b128 v[160:163], v200 offset:20480
	ds_read_b128 v[174:177], v200 offset:21504
	ds_read_b128 v[178:181], v200 offset:22528
	ds_read_b128 v[182:185], v200 offset:23552
	global_load_lds_dwordx4 v[212:213], off
	v_lshl_add_u64 v[214:215], s[12:13], 0, v[166:167]
	s_mov_b32 m0, s35
	s_nop 0
	global_load_lds_dwordx4 v[214:215], off
	s_barrier
	s_waitcnt lgkmcnt(0)
	v_mfma_f32_16x16x32_bf16 v[108:111], v[128:131], v[144:147], v[108:111]
	v_mfma_f32_16x16x32_bf16 v[76:79], v[136:139], v[144:147], v[76:79]
	v_mfma_f32_16x16x32_bf16 v[104:107], v[128:131], v[152:155], v[104:107]
	v_mfma_f32_16x16x32_bf16 v[72:75], v[136:139], v[152:155], v[72:75]
	v_mfma_f32_16x16x32_bf16 v[100:103], v[128:131], v[160:163], v[100:103]
	v_mfma_f32_16x16x32_bf16 v[68:71], v[136:139], v[160:163], v[68:71]
	v_mfma_f32_16x16x32_bf16 v[96:99], v[128:131], v[178:181], v[96:99]
	v_mfma_f32_16x16x32_bf16 v[64:67], v[136:139], v[178:181], v[64:67]
	v_mfma_f32_16x16x32_bf16 v[108:111], v[132:135], v[148:151], v[108:111]
	v_mfma_f32_16x16x32_bf16 v[76:79], v[140:143], v[148:151], v[76:79]
	v_mfma_f32_16x16x32_bf16 v[104:107], v[132:135], v[156:159], v[104:107]
	v_mfma_f32_16x16x32_bf16 v[72:75], v[140:143], v[156:159], v[72:75]
	v_mfma_f32_16x16x32_bf16 v[100:103], v[132:135], v[174:177], v[100:103]
	v_mfma_f32_16x16x32_bf16 v[68:71], v[140:143], v[174:177], v[68:71]
	v_mfma_f32_16x16x32_bf16 v[96:99], v[132:135], v[182:185], v[96:99]
	v_mfma_f32_16x16x32_bf16 v[64:67], v[140:143], v[182:185], v[64:67]
	s_barrier
	s_add_u32 s6, s10, 0x160000
	s_addc_u32 s7, s11, 0
	s_mov_b32 m0, s77
	v_lshl_add_u64 v[128:129], s[6:7], 0, v[164:165]
	global_load_lds_dwordx4 v[128:129], off
	v_lshl_add_u64 v[128:129], s[6:7], 0, v[166:167]
	s_mov_b32 m0, s78
	s_nop 0
	global_load_lds_dwordx4 v[128:129], off
	s_waitcnt vmcnt(6)
	s_barrier
; #define WAIT_V(n) asm volatile("s_waitcnt vmcnt(" #n ")" ::: "memory")
; #define WAIT_L(n) asm volatile("s_waitcnt lgkmcnt(" #n ")" ::: "memory")
; #define BAR __builtin_amdgcn_s_barrier()
; #define SCHED __builtin_amdgcn_sched_barrier(0)
; template <class Get, class Epi>
; DI void gemm_stream(LAS unsigned char* lds, const int K, const int ld, Get get, Epi epi) {
;     ...
;             WAIT_V(6); BAR; MMA(1, 1, At, B1); BAR;
;             LDB(B0, 1, 0); SCHED; LDA(At, 1, 0); STAGE(SAo(0, 1), a2 + hstep);
;             WAIT_L(8); BAR; WAIT_L(0); MMA(0, 0, At, B0); BAR; SCHED;
;             LDB(B1, 1, 1); STAGE(SBo(1, 0), b3);
;             BAR; WAIT_L(0); MMA(0, 1, At, B1); BAR;
;             LDA(At, 1, 1); STAGE(SAo(1, 0), a3);
;             BAR; WAIT_L(0); MMA(1, 0, At, B0); BAR; SCHED;
	v_mfma_f32_16x16x32_bf16 v[44:47], v[186:189], v[144:147], v[44:47]
	v_mfma_f32_16x16x32_bf16 v[12:15], v[194:197], v[144:147], v[12:15]
	v_mfma_f32_16x16x32_bf16 v[40:43], v[186:189], v[152:155], v[40:43]
	v_mfma_f32_16x16x32_bf16 v[8:11], v[194:197], v[152:155], v[8:11]
	v_mfma_f32_16x16x32_bf16 v[36:39], v[186:189], v[160:163], v[36:39]
	v_mfma_f32_16x16x32_bf16 v[4:7], v[194:197], v[160:163], v[4:7]
	v_mfma_f32_16x16x32_bf16 v[32:35], v[186:189], v[178:181], v[32:35]
	v_mfma_f32_16x16x32_bf16 v[0:3], v[194:197], v[178:181], v[0:3]
	v_mfma_f32_16x16x32_bf16 v[44:47], v[190:193], v[148:151], v[44:47]
	v_mfma_f32_16x16x32_bf16 v[12:15], v[202:205], v[148:151], v[12:15]
	v_mfma_f32_16x16x32_bf16 v[40:43], v[190:193], v[156:159], v[40:43]
	v_mfma_f32_16x16x32_bf16 v[8:11], v[202:205], v[156:159], v[8:11]
	v_mfma_f32_16x16x32_bf16 v[36:39], v[190:193], v[174:177], v[36:39]
	v_mfma_f32_16x16x32_bf16 v[4:7], v[202:205], v[174:177], v[4:7]
	v_mfma_f32_16x16x32_bf16 v[32:35], v[190:193], v[182:185], v[32:35]
	v_mfma_f32_16x16x32_bf16 v[0:3], v[202:205], v[182:185], v[0:3]
	s_add_i32 s17, 16, 0x18000
	v_add_u32_e32 v140, s17, v198
	s_barrier
	ds_read_b128 v[128:131], v140
	ds_read_b128 v[132:135], v140 offset:1024
	ds_read_b128 v[136:139], v140 offset:2048
	ds_read_b128 v[140:143], v140 offset:3072
	s_add_u32 s6, s12, 0x160000
	s_addc_u32 s7, s13, 0
	s_mov_b32 m0, s54
	v_lshl_add_u64 v[186:187], s[6:7], 0, v[164:165]
	ds_read_b128 v[144:147], v200 offset:32768
	ds_read_b128 v[148:151], v200 offset:33792
	ds_read_b128 v[152:155], v200 offset:34816
	ds_read_b128 v[156:159], v200 offset:35840
	ds_read_b128 v[160:163], v200 offset:36864
	ds_read_b128 v[174:177], v200 offset:37888
	ds_read_b128 v[178:181], v200 offset:38912
	ds_read_b128 v[182:185], v200 offset:39936
	global_load_lds_dwordx4 v[186:187], off
	v_lshl_add_u64 v[186:187], s[6:7], 0, v[166:167]
	s_mov_b32 m0, s55
	s_nop 0
	global_load_lds_dwordx4 v[186:187], off
	s_waitcnt lgkmcnt(8)
	s_barrier
	s_waitcnt lgkmcnt(0)
	v_mfma_f32_16x16x32_bf16 v[124:127], v[128:131], v[144:147], v[124:127]
	v_mfma_f32_16x16x32_bf16 v[92:95], v[136:139], v[144:147], v[92:95]
	v_mfma_f32_16x16x32_bf16 v[120:123], v[128:131], v[152:155], v[120:123]
	v_mfma_f32_16x16x32_bf16 v[88:91], v[136:139], v[152:155], v[88:91]
	v_mfma_f32_16x16x32_bf16 v[116:119], v[128:131], v[160:163], v[116:119]
	v_mfma_f32_16x16x32_bf16 v[84:87], v[136:139], v[160:163], v[84:87]
	v_mfma_f32_16x16x32_bf16 v[112:115], v[128:131], v[178:181], v[112:115]
	v_mfma_f32_16x16x32_bf16 v[80:83], v[136:139], v[178:181], v[80:83]
	v_mfma_f32_16x16x32_bf16 v[124:127], v[132:135], v[148:151], v[124:127]
	v_mfma_f32_16x16x32_bf16 v[92:95], v[140:143], v[148:151], v[92:95]
	v_mfma_f32_16x16x32_bf16 v[120:123], v[132:135], v[156:159], v[120:123]
	v_mfma_f32_16x16x32_bf16 v[88:91], v[140:143], v[156:159], v[88:91]
	v_mfma_f32_16x16x32_bf16 v[116:119], v[132:135], v[174:177], v[116:119]
	v_mfma_f32_16x16x32_bf16 v[84:87], v[140:143], v[174:177], v[84:87]
	v_mfma_f32_16x16x32_bf16 v[112:115], v[132:135], v[182:185], v[112:115]
	v_mfma_f32_16x16x32_bf16 v[80:83], v[140:143], v[182:185], v[80:83]
	s_barrier
	s_add_i32 s12, 16, 0x1c000
	s_add_i32 s6, s17, s21
	v_add_u32_e32 v202, s12, v198
	v_lshl_add_u64 v[208:209], v[208:209], 0, s[0:1]
	s_mov_b32 m0, s6
	ds_read_b128 v[186:189], v202
	ds_read_b128 v[190:193], v202 offset:1024
	ds_read_b128 v[194:197], v202 offset:2048
	ds_read_b128 v[202:205], v202 offset:3072
	global_load_lds_dwordx4 v[208:209], off
	v_lshl_add_u64 v[208:209], v[210:211], 0, s[0:1]
	s_add_i32 m0, s6, 0x2000
	s_nop 0
	global_load_lds_dwordx4 v[208:209], off
	s_barrier
	s_waitcnt lgkmcnt(0)
	v_mfma_f32_16x16x32_bf16 v[60:63], v[186:189], v[144:147], v[60:63]
	v_mfma_f32_16x16x32_bf16 v[28:31], v[194:197], v[144:147], v[28:31]
	v_mfma_f32_16x16x32_bf16 v[56:59], v[186:189], v[152:155], v[56:59]
	v_mfma_f32_16x16x32_bf16 v[24:27], v[194:197], v[152:155], v[24:27]
	v_mfma_f32_16x16x32_bf16 v[52:55], v[186:189], v[160:163], v[52:55]
	v_mfma_f32_16x16x32_bf16 v[20:23], v[194:197], v[160:163], v[20:23]
	v_mfma_f32_16x16x32_bf16 v[48:51], v[186:189], v[178:181], v[48:51]
	v_mfma_f32_16x16x32_bf16 v[16:19], v[194:197], v[178:181], v[16:19]
	v_mfma_f32_16x16x32_bf16 v[60:63], v[190:193], v[148:151], v[60:63]
	v_mfma_f32_16x16x32_bf16 v[28:31], v[202:205], v[148:151], v[28:31]
	v_mfma_f32_16x16x32_bf16 v[56:59], v[190:193], v[156:159], v[56:59]
	v_mfma_f32_16x16x32_bf16 v[24:27], v[202:205], v[156:159], v[24:27]
	v_mfma_f32_16x16x32_bf16 v[52:55], v[190:193], v[174:177], v[52:55]
	v_mfma_f32_16x16x32_bf16 v[20:23], v[202:205], v[174:177], v[20:23]
	v_mfma_f32_16x16x32_bf16 v[48:51], v[190:193], v[182:185], v[48:51]
	v_mfma_f32_16x16x32_bf16 v[16:19], v[202:205], v[182:185], v[16:19]
	s_barrier
	s_mov_b32 m0, s56
	v_lshl_add_u64 v[208:209], v[212:213], 0, s[0:1]
	ds_read_b128 v[144:147], v200 offset:49152
	ds_read_b128 v[148:151], v200 offset:50176
	ds_read_b128 v[152:155], v200 offset:51200
	ds_read_b128 v[156:159], v200 offset:52224
	ds_read_b128 v[160:163], v200 offset:53248
	ds_read_b128 v[174:177], v200 offset:54272
	ds_read_b128 v[178:181], v200 offset:55296
	ds_read_b128 v[182:185], v200 offset:56320
	global_load_lds_dwordx4 v[208:209], off
	v_lshl_add_u64 v[208:209], v[214:215], 0, s[0:1]
	s_mov_b32 m0, s57
	s_nop 0
	global_load_lds_dwordx4 v[208:209], off
	s_barrier
; #define WAIT_V(n) asm volatile("s_waitcnt vmcnt(" #n ")" ::: "memory")
; #define WAIT_L(n) asm volatile("s_waitcnt lgkmcnt(" #n ")" ::: "memory")
; #define BAR __builtin_amdgcn_s_barrier()
; #define SCHED __builtin_amdgcn_sched_barrier(0)
; #define EPI_DONE do { } while (0)
; template <class Get, class Epi>
; DI void gemm_stream(LAS unsigned char* lds, const int K, const int ld, Get get, Epi epi) {
;     ...
;             BAR; WAIT_L(0); MMA(1, 0, At, B0); BAR; SCHED;
;             STAGE(SBo(1, 1), b3 + hstep);
;             WAIT_V(6); BAR; MMA(1, 1, At, B1); BAR;
;         }
; DI void epi_resid(const Acc& acc, const P& p, int brow, int bcol, int layer, int gch, bool from_input) {
;     EPI_IDX
;     const float* gate = modv(p, layer, brow, gch);
; #pragma unroll
;     for (int bj = 0; bj < 2; ++bj)
; #pragma unroll
;         for (int n = 0; n < 2; ++n) {
;             const int c0 = bcol + bj * 128 + wc * 32 + n * 16 + fq * 4;
;             const f32x4 g = *(const f32x4*)(gate + c0);
;             f32x4 xv[2][4];
; #pragma unroll
;             for (int ai = 0; ai < 2; ++ai)
; #pragma unroll
;                 for (int m = 0; m < 4; ++m) {
;                     const int r = brow + ai * 128 + wr * 64 + m * 16 + fr;
;                     const float* sp = (from_input ? inrow(p, r) : xrow(p, r)) + c0;
;                     xv[ai][m] = *(const f32x4*)sp;
;                 }
;             __builtin_amdgcn_sched_barrier(0);
; #pragma unroll
;             for (int ai = 0; ai < 2; ++ai)
; #pragma unroll
;                 for (int m = 0; m < 4; ++m) {
;                     const int r = brow + ai * 128 + wr * 64 + m * 16 + fr;
;                     *(f32x4*)(xrow(p, r) + c0) = xv[ai][m] + g * acc[ai][bj][m][n];
;                 }
;             __builtin_amdgcn_sched_barrier(0);
;         }
;     EPI_DONE;
; }
	s_waitcnt lgkmcnt(0)
	v_mfma_f32_16x16x32_bf16 v[108:111], v[128:131], v[144:147], v[108:111]
	v_mfma_f32_16x16x32_bf16 v[76:79], v[136:139], v[144:147], v[76:79]
	v_mfma_f32_16x16x32_bf16 v[104:107], v[128:131], v[152:155], v[104:107]
	v_mfma_f32_16x16x32_bf16 v[72:75], v[136:139], v[152:155], v[72:75]
	v_mfma_f32_16x16x32_bf16 v[100:103], v[128:131], v[160:163], v[100:103]
	v_mfma_f32_16x16x32_bf16 v[68:71], v[136:139], v[160:163], v[68:71]
	v_mfma_f32_16x16x32_bf16 v[96:99], v[128:131], v[178:181], v[96:99]
	v_mfma_f32_16x16x32_bf16 v[64:67], v[136:139], v[178:181], v[64:67]
	v_mfma_f32_16x16x32_bf16 v[108:111], v[132:135], v[148:151], v[108:111]
	v_mfma_f32_16x16x32_bf16 v[76:79], v[140:143], v[148:151], v[76:79]
	v_mfma_f32_16x16x32_bf16 v[104:107], v[132:135], v[156:159], v[104:107]
	v_mfma_f32_16x16x32_bf16 v[72:75], v[140:143], v[156:159], v[72:75]
	v_mfma_f32_16x16x32_bf16 v[100:103], v[132:135], v[174:177], v[100:103]
	v_mfma_f32_16x16x32_bf16 v[68:71], v[140:143], v[174:177], v[68:71]
	v_mfma_f32_16x16x32_bf16 v[96:99], v[132:135], v[182:185], v[96:99]
	v_mfma_f32_16x16x32_bf16 v[64:67], v[140:143], v[182:185], v[64:67]
	s_barrier
	s_add_u32 s6, s10, 0x160080
	s_addc_u32 s7, s11, 0
	s_add_i32 s10, s12, s21
	v_lshl_add_u64 v[128:129], s[6:7], 0, v[164:165]
	s_mov_b32 m0, s10
	s_nop 0
	global_load_lds_dwordx4 v[128:129], off
	v_lshl_add_u64 v[128:129], s[6:7], 0, v[166:167]
	s_add_i32 m0, s10, 0x2000
	s_nop 0
	global_load_lds_dwordx4 v[128:129], off
	s_add_i32 s16, s16, 2
	s_add_u32 s14, s14, 0x100
	s_addc_u32 s15, s15, 0
	s_cmpk_gt_u32 s16, 0x55
	s_mov_b64 s[6:7], s[8:9]
	s_waitcnt vmcnt(6)
	s_barrier
	v_mfma_f32_16x16x32_bf16 v[44:47], v[186:189], v[144:147], v[44:47]
	v_mfma_f32_16x16x32_bf16 v[12:15], v[194:197], v[144:147], v[12:15]
	v_mfma_f32_16x16x32_bf16 v[40:43], v[186:189], v[152:155], v[40:43]
	v_mfma_f32_16x16x32_bf16 v[8:11], v[194:197], v[152:155], v[8:11]
	v_mfma_f32_16x16x32_bf16 v[36:39], v[186:189], v[160:163], v[36:39]
	v_mfma_f32_16x16x32_bf16 v[4:7], v[194:197], v[160:163], v[4:7]
	v_mfma_f32_16x16x32_bf16 v[32:35], v[186:189], v[178:181], v[32:35]
	v_mfma_f32_16x16x32_bf16 v[0:3], v[194:197], v[178:181], v[0:3]
	v_mfma_f32_16x16x32_bf16 v[44:47], v[190:193], v[148:151], v[44:47]
	v_mfma_f32_16x16x32_bf16 v[12:15], v[202:205], v[148:151], v[12:15]
	v_mfma_f32_16x16x32_bf16 v[40:43], v[190:193], v[156:159], v[40:43]
	v_mfma_f32_16x16x32_bf16 v[8:11], v[202:205], v[156:159], v[8:11]
	v_mfma_f32_16x16x32_bf16 v[36:39], v[190:193], v[174:177], v[36:39]
	v_mfma_f32_16x16x32_bf16 v[4:7], v[202:205], v[174:177], v[4:7]
	v_mfma_f32_16x16x32_bf16 v[32:35], v[190:193], v[182:185], v[32:35]
	v_mfma_f32_16x16x32_bf16 v[0:3], v[202:205], v[182:185], v[0:3]
	s_barrier
	s_cbranch_scc0 .LBB0_1697
	s_lshl_b32 s12, s3, 21
	s_lshl_b32 s13, s2, 10
	s_lshr_b32 s16, s3, 4
	s_add_u32 s12, s12, s13
	s_mul_i32 s16, s16, 6
	s_add_i32 s16, s16, 5
	s_lshl_b32 s16, s16, 13
	s_add_u32 s16, s16, s13
	s_add_u32 s10, s26, s16
	s_addc_u32 s11, s27, 0
	s_add_u32 s6, s24, s12
	s_addc_u32 s7, s25, 0
	v_lshrrev_b32_e32 v224, 6, v206
	v_and_b32_e32 v225, 3, v224
	v_lshrrev_b32_e32 v224, 2, v224
	v_and_b32_e32 v205, 15, v206
	v_bfe_u32 v226, v206, 4, 2
	v_lshl_add_u32 v225, v225, 3, v226
	v_lshl_add_u32 v224, v224, 6, v205
	v_lshlrev_b32_e32 v205, 4, v225
	v_lshl_add_u32 v203, v224, 13, v205
	v_mov_b32_e32 v204, v203
	global_load_dwordx4 v[128:131], v205, s[10:11] offset:0
	global_load_dwordx4 v[132:135], v205, s[10:11] offset:64
	global_load_dwordx4 v[136:139], v205, s[10:11] offset:512
	global_load_dwordx4 v[140:143], v205, s[10:11] offset:576
	global_load_dwordx4 v[144:147], v203, s[6:7] offset:0
	global_load_dwordx4 v[148:151], v203, s[6:7] offset:64
	global_load_dwordx4 v[152:155], v203, s[6:7] offset:512
	global_load_dwordx4 v[156:159], v203, s[6:7] offset:576
	v_add_u32_e32 v203, 0x20000, v203
	global_load_dwordx4 v[160:163], v203, s[6:7] offset:0
	global_load_dwordx4 v[174:177], v203, s[6:7] offset:64
	global_load_dwordx4 v[178:181], v203, s[6:7] offset:512
	global_load_dwordx4 v[182:185], v203, s[6:7] offset:576
	v_add_u32_e32 v203, 0x20000, v203
	global_load_dwordx4 v[186:189], v203, s[6:7] offset:0
	global_load_dwordx4 v[190:193], v203, s[6:7] offset:64
	global_load_dwordx4 v[194:197], v203, s[6:7] offset:512
	global_load_dwordx4 v[208:211], v203, s[6:7] offset:576
	v_add_u32_e32 v203, 0x20000, v203
	global_load_dwordx4 v[212:215], v203, s[6:7] offset:0
	global_load_dwordx4 v[216:219], v203, s[6:7] offset:64
	global_load_dwordx4 v[220:223], v203, s[6:7] offset:512
	global_load_dwordx4 v[224:227], v203, s[6:7] offset:576
	v_add_u32_e32 v203, 0xa0000, v203
	s_waitcnt vmcnt(12)
	v_pk_fma_f32 v[124:125], v[124:125], v[128:129], v[144:145]
	v_pk_fma_f32 v[126:127], v[126:127], v[130:131], v[146:147]
	v_pk_fma_f32 v[92:93], v[92:93], v[132:133], v[148:149]
	v_pk_fma_f32 v[94:95], v[94:95], v[134:135], v[150:151]
	v_pk_fma_f32 v[60:61], v[60:61], v[136:137], v[152:153]
	v_pk_fma_f32 v[62:63], v[62:63], v[138:139], v[154:155]
	v_pk_fma_f32 v[28:29], v[28:29], v[140:141], v[156:157]
	v_pk_fma_f32 v[30:31], v[30:31], v[142:143], v[158:159]
	global_store_dwordx4 v204, v[124:127], s[6:7] offset:0
	global_store_dwordx4 v204, v[92:95], s[6:7] offset:64
	global_store_dwordx4 v204, v[60:63], s[6:7] offset:512
	global_store_dwordx4 v204, v[28:31], s[6:7] offset:576
	v_add_u32_e32 v204, 0x20000, v204
	global_load_dwordx4 v[144:147], v203, s[6:7] offset:0
	global_load_dwordx4 v[148:151], v203, s[6:7] offset:64
	global_load_dwordx4 v[152:155], v203, s[6:7] offset:512
	global_load_dwordx4 v[156:159], v203, s[6:7] offset:576
	v_add_u32_e32 v203, 0x20000, v203
	s_waitcnt vmcnt(16)
; #define EPI_DONE do { } while (0)
; DI void epi_resid(const Acc& acc, const P& p, int brow, int bcol, int layer, int gch, bool from_input) {
;     EPI_IDX
;     const float* gate = modv(p, layer, brow, gch);
; #pragma unroll
;     for (int bj = 0; bj < 2; ++bj)
; #pragma unroll
;         for (int n = 0; n < 2; ++n) {
;             const int c0 = bcol + bj * 128 + wc * 32 + n * 16 + fq * 4;
;             const f32x4 g = *(const f32x4*)(gate + c0);
;             f32x4 xv[2][4];
; #pragma unroll
;             for (int ai = 0; ai < 2; ++ai)
; #pragma unroll
;                 for (int m = 0; m < 4; ++m) {
;                     const int r = brow + ai * 128 + wr * 64 + m * 16 + fr;
;                     const float* sp = (from_input ? inrow(p, r) : xrow(p, r)) + c0;
;                     xv[ai][m] = *(const f32x4*)sp;
;                 }
;             __builtin_amdgcn_sched_barrier(0);
; #pragma unroll
;             for (int ai = 0; ai < 2; ++ai)
; #pragma unroll
;                 for (int m = 0; m < 4; ++m) {
;                     const int r = brow + ai * 128 + wr * 64 + m * 16 + fr;
;                     *(f32x4*)(xrow(p, r) + c0) = xv[ai][m] + g * acc[ai][bj][m][n];
;                 }
;             __builtin_amdgcn_sched_barrier(0);
;         }
;     EPI_DONE;
; }
	v_pk_fma_f32 v[120:121], v[120:121], v[128:129], v[160:161]
	v_pk_fma_f32 v[122:123], v[122:123], v[130:131], v[162:163]
	v_pk_fma_f32 v[88:89], v[88:89], v[132:133], v[174:175]
	v_pk_fma_f32 v[90:91], v[90:91], v[134:135], v[176:177]
	v_pk_fma_f32 v[56:57], v[56:57], v[136:137], v[178:179]
	v_pk_fma_f32 v[58:59], v[58:59], v[138:139], v[180:181]
	v_pk_fma_f32 v[24:25], v[24:25], v[140:141], v[182:183]
	v_pk_fma_f32 v[26:27], v[26:27], v[142:143], v[184:185]
	global_store_dwordx4 v204, v[120:123], s[6:7] offset:0
	global_store_dwordx4 v204, v[88:91], s[6:7] offset:64
	global_store_dwordx4 v204, v[56:59], s[6:7] offset:512
	global_store_dwordx4 v204, v[24:27], s[6:7] offset:576
	v_add_u32_e32 v204, 0x20000, v204
	global_load_dwordx4 v[160:163], v203, s[6:7] offset:0
	global_load_dwordx4 v[174:177], v203, s[6:7] offset:64
	global_load_dwordx4 v[178:181], v203, s[6:7] offset:512
	global_load_dwordx4 v[182:185], v203, s[6:7] offset:576
	v_add_u32_e32 v203, 0x20000, v203
	s_waitcnt vmcnt(20)
	v_pk_fma_f32 v[116:117], v[116:117], v[128:129], v[186:187]
	v_pk_fma_f32 v[118:119], v[118:119], v[130:131], v[188:189]
	v_pk_fma_f32 v[84:85], v[84:85], v[132:133], v[190:191]
	v_pk_fma_f32 v[86:87], v[86:87], v[134:135], v[192:193]
	v_pk_fma_f32 v[52:53], v[52:53], v[136:137], v[194:195]
	v_pk_fma_f32 v[54:55], v[54:55], v[138:139], v[196:197]
	v_pk_fma_f32 v[20:21], v[20:21], v[140:141], v[208:209]
	v_pk_fma_f32 v[22:23], v[22:23], v[142:143], v[210:211]
	global_store_dwordx4 v204, v[116:119], s[6:7] offset:0
	global_store_dwordx4 v204, v[84:87], s[6:7] offset:64
	global_store_dwordx4 v204, v[52:55], s[6:7] offset:512
	global_store_dwordx4 v204, v[20:23], s[6:7] offset:576
	v_add_u32_e32 v204, 0x20000, v204
	global_load_dwordx4 v[186:189], v203, s[6:7] offset:0
	global_load_dwordx4 v[190:193], v203, s[6:7] offset:64
	global_load_dwordx4 v[194:197], v203, s[6:7] offset:512
	global_load_dwordx4 v[208:211], v203, s[6:7] offset:576
	v_add_u32_e32 v203, 0x20000, v203
	s_waitcnt vmcnt(24)
	v_pk_fma_f32 v[112:113], v[112:113], v[128:129], v[212:213]
	v_pk_fma_f32 v[114:115], v[114:115], v[130:131], v[214:215]
	v_pk_fma_f32 v[80:81], v[80:81], v[132:133], v[216:217]
	v_pk_fma_f32 v[82:83], v[82:83], v[134:135], v[218:219]
	v_pk_fma_f32 v[48:49], v[48:49], v[136:137], v[220:221]
	v_pk_fma_f32 v[50:51], v[50:51], v[138:139], v[222:223]
	v_pk_fma_f32 v[16:17], v[16:17], v[140:141], v[224:225]
	v_pk_fma_f32 v[18:19], v[18:19], v[142:143], v[226:227]
	global_store_dwordx4 v204, v[112:115], s[6:7] offset:0
	global_store_dwordx4 v204, v[80:83], s[6:7] offset:64
	global_store_dwordx4 v204, v[48:51], s[6:7] offset:512
	global_store_dwordx4 v204, v[16:19], s[6:7] offset:576
	v_add_u32_e32 v204, 0xa0000, v204
	global_load_dwordx4 v[212:215], v203, s[6:7] offset:0
	global_load_dwordx4 v[216:219], v203, s[6:7] offset:64
	global_load_dwordx4 v[220:223], v203, s[6:7] offset:512
	global_load_dwordx4 v[224:227], v203, s[6:7] offset:576
	s_waitcnt vmcnt(24)
	v_pk_fma_f32 v[108:109], v[108:109], v[128:129], v[144:145]
	v_pk_fma_f32 v[110:111], v[110:111], v[130:131], v[146:147]
	v_pk_fma_f32 v[76:77], v[76:77], v[132:133], v[148:149]
	v_pk_fma_f32 v[78:79], v[78:79], v[134:135], v[150:151]
	v_pk_fma_f32 v[44:45], v[44:45], v[136:137], v[152:153]
	v_pk_fma_f32 v[46:47], v[46:47], v[138:139], v[154:155]
	v_pk_fma_f32 v[12:13], v[12:13], v[140:141], v[156:157]
	v_pk_fma_f32 v[14:15], v[14:15], v[142:143], v[158:159]
	global_store_dwordx4 v204, v[108:111], s[6:7] offset:0
	global_store_dwordx4 v204, v[76:79], s[6:7] offset:64
	global_store_dwordx4 v204, v[44:47], s[6:7] offset:512
	global_store_dwordx4 v204, v[12:15], s[6:7] offset:576
	v_add_u32_e32 v204, 0x20000, v204
	s_waitcnt vmcnt(20)
	v_pk_fma_f32 v[104:105], v[104:105], v[128:129], v[160:161]
	v_pk_fma_f32 v[106:107], v[106:107], v[130:131], v[162:163]
	v_pk_fma_f32 v[72:73], v[72:73], v[132:133], v[174:175]
	v_pk_fma_f32 v[74:75], v[74:75], v[134:135], v[176:177]
	v_pk_fma_f32 v[40:41], v[40:41], v[136:137], v[178:179]
	v_pk_fma_f32 v[42:43], v[42:43], v[138:139], v[180:181]
	v_pk_fma_f32 v[8:9], v[8:9], v[140:141], v[182:183]
	v_pk_fma_f32 v[10:11], v[10:11], v[142:143], v[184:185]
	global_store_dwordx4 v204, v[104:107], s[6:7] offset:0
	global_store_dwordx4 v204, v[72:75], s[6:7] offset:64
	global_store_dwordx4 v204, v[40:43], s[6:7] offset:512
	global_store_dwordx4 v204, v[8:11], s[6:7] offset:576
	v_add_u32_e32 v204, 0x20000, v204
	s_waitcnt vmcnt(16)
	v_pk_fma_f32 v[100:101], v[100:101], v[128:129], v[186:187]
	v_pk_fma_f32 v[102:103], v[102:103], v[130:131], v[188:189]
	v_pk_fma_f32 v[68:69], v[68:69], v[132:133], v[190:191]
	v_pk_fma_f32 v[70:71], v[70:71], v[134:135], v[192:193]
	v_pk_fma_f32 v[36:37], v[36:37], v[136:137], v[194:195]
	v_pk_fma_f32 v[38:39], v[38:39], v[138:139], v[196:197]
	v_pk_fma_f32 v[4:5], v[4:5], v[140:141], v[208:209]
	v_pk_fma_f32 v[6:7], v[6:7], v[142:143], v[210:211]
	global_store_dwordx4 v204, v[100:103], s[6:7] offset:0
	global_store_dwordx4 v204, v[68:71], s[6:7] offset:64
	global_store_dwordx4 v204, v[36:39], s[6:7] offset:512
	global_store_dwordx4 v204, v[4:7], s[6:7] offset:576
	v_add_u32_e32 v204, 0x20000, v204
	s_waitcnt vmcnt(12)
	v_pk_fma_f32 v[96:97], v[96:97], v[128:129], v[212:213]
	v_pk_fma_f32 v[98:99], v[98:99], v[130:131], v[214:215]
	v_pk_fma_f32 v[64:65], v[64:65], v[132:133], v[216:217]
	v_pk_fma_f32 v[66:67], v[66:67], v[134:135], v[218:219]
	v_pk_fma_f32 v[32:33], v[32:33], v[136:137], v[220:221]
	v_pk_fma_f32 v[34:35], v[34:35], v[138:139], v[222:223]
	v_pk_fma_f32 v[0:1], v[0:1], v[140:141], v[224:225]
	v_pk_fma_f32 v[2:3], v[2:3], v[142:143], v[226:227]
	global_store_dwordx4 v204, v[96:99], s[6:7] offset:0
	global_store_dwordx4 v204, v[64:67], s[6:7] offset:64
	global_store_dwordx4 v204, v[32:35], s[6:7] offset:512
	global_store_dwordx4 v204, v[0:3], s[6:7] offset:576
	s_branch .Lresid_latch_ffndL0

; #define WAIT_V(n) asm volatile("s_waitcnt vmcnt(" #n ")" ::: "memory")
; #define WAIT_L(n) asm volatile("s_waitcnt lgkmcnt(" #n ")" ::: "memory")
; #define BAR __builtin_amdgcn_s_barrier()
; #define SCHED __builtin_amdgcn_sched_barrier(0)
; template <class Get, class Epi>
; DI void gemm_stream(LAS unsigned char* lds, const int K, const int ld, Get get, Epi epi) {
;     ...
;             const bool last = (t == nt - 2);
;             const char* a1 = cA + (size_t)(t + 1) * kstep;
;             const char* a2 = last ? nA : cA + (size_t)(t + 2) * kstep;
;             const char* b2 = last ? nB : cB + (size_t)(t + 2) * kstep;
;             const char* a3 = a2 + kstep;
;             const char* b3 = b2 + kstep;
;             LDB(B0, 0, 0); SCHED; LDA(At, 0, 0); STAGE(SAo(1, 1), a1 + hstep);
;             WAIT_L(8); BAR; WAIT_L(0); MMA(0, 0, At, B0); BAR; SCHED;
;             LDB(B1, 0, 1); STAGE(SBo(0, 0), b2);
;             BAR; WAIT_L(0); MMA(0, 1, At, B1); BAR;
;             LDA(At, 0, 1); STAGE(SAo(0, 0), a2);
;             BAR; WAIT_L(0); MMA(1, 0, At, B0); BAR; SCHED;
;             STAGE(SBo(0, 1), b2 + hstep);
;             WAIT_V(6); BAR; MMA(1, 1, At, B1); BAR;
.LBB0_1964:
	ds_read_b128 v[144:147], v141
	ds_read_b128 v[148:151], v141 offset:1024
	ds_read_b128 v[152:155], v141 offset:2048
	ds_read_b128 v[156:159], v141 offset:3072
	s_add_u32 s38, s36, 0x100
	s_addc_u32 s39, s37, 0
	s_cmp_eq_u32 s77, 4
	s_cselect_b32 s53, s17, s39
	s_cselect_b32 s52, s16, s38
	s_cselect_b32 s41, s19, s76
	s_cselect_b32 s40, s18, s0
	v_lshl_add_u64 v[192:193], s[36:37], 0, v[134:135]
	s_add_i32 m0, s20, 0xc000
	ds_read_b128 v[160:163], v142
	ds_read_b128 v[164:167], v142 offset:1024
	ds_read_b128 v[168:171], v142 offset:2048
	ds_read_b128 v[172:175], v142 offset:3072
	ds_read_b128 v[176:179], v142 offset:4096
	ds_read_b128 v[180:183], v142 offset:5120
	ds_read_b128 v[184:187], v142 offset:6144
	ds_read_b128 v[188:191], v142 offset:7168
	global_load_lds_dwordx4 v[192:193], off
	v_lshl_add_u64 v[192:193], s[36:37], 0, v[136:137]
	s_add_i32 m0, s20, 0xe000
	s_nop 0
	global_load_lds_dwordx4 v[192:193], off
	s_waitcnt lgkmcnt(8)
	s_barrier
	s_waitcnt lgkmcnt(0)
	v_mfma_f32_16x16x32_bf16 v[124:127], v[144:147], v[160:163], v[124:127]
	v_mfma_f32_16x16x32_bf16 v[120:123], v[152:155], v[160:163], v[120:123]
	v_mfma_f32_16x16x32_bf16 v[116:119], v[144:147], v[168:171], v[116:119]
	v_mfma_f32_16x16x32_bf16 v[112:115], v[152:155], v[168:171], v[112:115]
	v_mfma_f32_16x16x32_bf16 v[104:107], v[144:147], v[176:179], v[104:107]
	v_mfma_f32_16x16x32_bf16 v[96:99], v[152:155], v[176:179], v[96:99]
	v_mfma_f32_16x16x32_bf16 v[88:91], v[144:147], v[184:187], v[88:91]
	v_mfma_f32_16x16x32_bf16 v[80:83], v[152:155], v[184:187], v[80:83]
	v_mfma_f32_16x16x32_bf16 v[124:127], v[148:151], v[164:167], v[124:127]
	v_mfma_f32_16x16x32_bf16 v[120:123], v[156:159], v[164:167], v[120:123]
	v_mfma_f32_16x16x32_bf16 v[116:119], v[148:151], v[172:175], v[116:119]
	v_mfma_f32_16x16x32_bf16 v[112:115], v[156:159], v[172:175], v[112:115]
	v_mfma_f32_16x16x32_bf16 v[104:107], v[148:151], v[180:183], v[104:107]
	v_mfma_f32_16x16x32_bf16 v[96:99], v[156:159], v[180:183], v[96:99]
	v_mfma_f32_16x16x32_bf16 v[88:91], v[148:151], v[188:191], v[88:91]
	v_mfma_f32_16x16x32_bf16 v[80:83], v[156:159], v[188:191], v[80:83]
	s_barrier
	s_add_i32 s36, s56, s3
	v_lshl_add_u64 v[204:205], s[40:41], 0, v[130:131]
	s_mov_b32 m0, s36
	ds_read_b128 v[192:195], v143
	ds_read_b128 v[196:199], v143 offset:1024
	ds_read_b128 v[200:203], v143 offset:2048
	ds_read_b128 v[208:211], v143 offset:3072
	global_load_lds_dwordx4 v[204:205], off
	v_lshl_add_u64 v[212:213], s[40:41], 0, v[128:129]
	s_add_i32 m0, s36, 0x2000
	s_nop 0
	global_load_lds_dwordx4 v[212:213], off
	s_barrier
	s_waitcnt lgkmcnt(0)
	v_mfma_f32_16x16x32_bf16 v[108:111], v[192:195], v[160:163], v[108:111]
	v_mfma_f32_16x16x32_bf16 v[100:103], v[200:203], v[160:163], v[100:103]
	v_mfma_f32_16x16x32_bf16 v[92:95], v[192:195], v[168:171], v[92:95]
	v_mfma_f32_16x16x32_bf16 v[84:87], v[200:203], v[168:171], v[84:87]
	v_mfma_f32_16x16x32_bf16 v[76:79], v[192:195], v[176:179], v[76:79]
	v_mfma_f32_16x16x32_bf16 v[72:75], v[200:203], v[176:179], v[72:75]
	v_mfma_f32_16x16x32_bf16 v[68:71], v[192:195], v[184:187], v[68:71]
	v_mfma_f32_16x16x32_bf16 v[64:67], v[200:203], v[184:187], v[64:67]
	v_mfma_f32_16x16x32_bf16 v[108:111], v[196:199], v[164:167], v[108:111]
	v_mfma_f32_16x16x32_bf16 v[100:103], v[208:211], v[164:167], v[100:103]
	v_mfma_f32_16x16x32_bf16 v[92:95], v[196:199], v[172:175], v[92:95]
	v_mfma_f32_16x16x32_bf16 v[84:87], v[208:211], v[172:175], v[84:87]
	v_mfma_f32_16x16x32_bf16 v[76:79], v[196:199], v[180:183], v[76:79]
	v_mfma_f32_16x16x32_bf16 v[72:75], v[208:211], v[180:183], v[72:75]
	v_mfma_f32_16x16x32_bf16 v[68:71], v[196:199], v[188:191], v[68:71]
	v_mfma_f32_16x16x32_bf16 v[64:67], v[208:211], v[188:191], v[64:67]
	s_barrier
	s_mov_b32 m0, s20
	v_lshl_add_u64 v[214:215], s[52:53], 0, v[130:131]
	ds_read_b128 v[160:163], v142 offset:16384
	ds_read_b128 v[164:167], v142 offset:17408
	ds_read_b128 v[168:171], v142 offset:18432
	ds_read_b128 v[172:175], v142 offset:19456
	ds_read_b128 v[176:179], v142 offset:20480
	ds_read_b128 v[180:183], v142 offset:21504
	ds_read_b128 v[184:187], v142 offset:22528
	ds_read_b128 v[188:191], v142 offset:23552
	global_load_lds_dwordx4 v[214:215], off
	v_lshl_add_u64 v[216:217], s[52:53], 0, v[128:129]
	s_mov_b32 m0, s21
	s_nop 0
	global_load_lds_dwordx4 v[216:217], off
	s_barrier
	s_waitcnt lgkmcnt(0)
	v_mfma_f32_16x16x32_bf16 v[60:63], v[144:147], v[160:163], v[60:63]
	v_mfma_f32_16x16x32_bf16 v[56:59], v[152:155], v[160:163], v[56:59]
	v_mfma_f32_16x16x32_bf16 v[52:55], v[144:147], v[168:171], v[52:55]
	v_mfma_f32_16x16x32_bf16 v[48:51], v[152:155], v[168:171], v[48:51]
	v_mfma_f32_16x16x32_bf16 v[40:43], v[144:147], v[176:179], v[40:43]
	v_mfma_f32_16x16x32_bf16 v[32:35], v[152:155], v[176:179], v[32:35]
	v_mfma_f32_16x16x32_bf16 v[24:27], v[144:147], v[184:187], v[24:27]
	v_mfma_f32_16x16x32_bf16 v[16:19], v[152:155], v[184:187], v[16:19]
	v_mfma_f32_16x16x32_bf16 v[60:63], v[148:151], v[164:167], v[60:63]
	v_mfma_f32_16x16x32_bf16 v[56:59], v[156:159], v[164:167], v[56:59]
	v_mfma_f32_16x16x32_bf16 v[52:55], v[148:151], v[172:175], v[52:55]
	v_mfma_f32_16x16x32_bf16 v[48:51], v[156:159], v[172:175], v[48:51]
	v_mfma_f32_16x16x32_bf16 v[40:43], v[148:151], v[180:183], v[40:43]
	v_mfma_f32_16x16x32_bf16 v[32:35], v[156:159], v[180:183], v[32:35]
	v_mfma_f32_16x16x32_bf16 v[24:27], v[148:151], v[188:191], v[24:27]
	v_mfma_f32_16x16x32_bf16 v[16:19], v[156:159], v[188:191], v[16:19]
	s_barrier
; #define WAIT_V(n) asm volatile("s_waitcnt vmcnt(" #n ")" ::: "memory")
; #define WAIT_L(n) asm volatile("s_waitcnt lgkmcnt(" #n ")" ::: "memory")
; #define BAR __builtin_amdgcn_s_barrier()
; #define SCHED __builtin_amdgcn_sched_barrier(0)
; template <class Get, class Epi>
; DI void gemm_stream(LAS unsigned char* lds, const int K, const int ld, Get get, Epi epi) {
;     ...
;             STAGE(SBo(0, 1), b2 + hstep);
;             WAIT_V(6); BAR; MMA(1, 1, At, B1); BAR;
;             LDB(B0, 1, 0); SCHED; LDA(At, 1, 0); STAGE(SAo(0, 1), a2 + hstep);
;             WAIT_L(8); BAR; WAIT_L(0); MMA(0, 0, At, B0); BAR; SCHED;
;             LDB(B1, 1, 1); STAGE(SBo(1, 0), b3);
;             BAR; WAIT_L(0); MMA(0, 1, At, B1); BAR;
;             LDA(At, 1, 1); STAGE(SAo(1, 0), a3);
;             BAR; WAIT_L(0); MMA(1, 0, At, B0); BAR; SCHED;
	s_add_u32 s36, s40, 0x160000
	s_addc_u32 s37, s41, 0
	s_add_i32 s78, s57, s3
	v_lshl_add_u64 v[144:145], s[36:37], 0, v[130:131]
	s_mov_b32 m0, s78
	s_nop 0
	global_load_lds_dwordx4 v[144:145], off
	v_lshl_add_u64 v[144:145], s[36:37], 0, v[128:129]
	s_add_i32 m0, s78, 0x2000
	s_nop 0
	global_load_lds_dwordx4 v[144:145], off
	s_waitcnt vmcnt(6)
	s_barrier
	v_mfma_f32_16x16x32_bf16 v[44:47], v[192:195], v[160:163], v[44:47]
	v_mfma_f32_16x16x32_bf16 v[36:39], v[200:203], v[160:163], v[36:39]
	v_mfma_f32_16x16x32_bf16 v[28:31], v[192:195], v[168:171], v[28:31]
	v_mfma_f32_16x16x32_bf16 v[20:23], v[200:203], v[168:171], v[20:23]
	v_mfma_f32_16x16x32_bf16 v[12:15], v[192:195], v[176:179], v[12:15]
	v_mfma_f32_16x16x32_bf16 v[8:11], v[200:203], v[176:179], v[8:11]
	v_mfma_f32_16x16x32_bf16 v[4:7], v[192:195], v[184:187], v[4:7]
	v_mfma_f32_16x16x32_bf16 v[0:3], v[200:203], v[184:187], v[0:3]
	v_mfma_f32_16x16x32_bf16 v[44:47], v[196:199], v[164:167], v[44:47]
	v_mfma_f32_16x16x32_bf16 v[36:39], v[208:211], v[164:167], v[36:39]
	v_mfma_f32_16x16x32_bf16 v[28:31], v[196:199], v[172:175], v[28:31]
	v_mfma_f32_16x16x32_bf16 v[20:23], v[208:211], v[172:175], v[20:23]
	v_mfma_f32_16x16x32_bf16 v[12:15], v[196:199], v[180:183], v[12:15]
	v_mfma_f32_16x16x32_bf16 v[8:11], v[208:211], v[180:183], v[8:11]
	v_mfma_f32_16x16x32_bf16 v[4:7], v[196:199], v[188:191], v[4:7]
	v_mfma_f32_16x16x32_bf16 v[0:3], v[208:211], v[188:191], v[0:3]
	s_add_i32 s78, 16, 0x18000
	v_add_u32_e32 v132, s78, v140
	s_barrier
	ds_read_b128 v[144:147], v132
	ds_read_b128 v[148:151], v132 offset:1024
	ds_read_b128 v[152:155], v132 offset:2048
	ds_read_b128 v[156:159], v132 offset:3072
	s_add_u32 s36, s52, 0x160000
	s_addc_u32 s37, s53, 0
	s_mov_b32 m0, s23
	v_lshl_add_u64 v[192:193], s[36:37], 0, v[130:131]
	ds_read_b128 v[160:163], v142 offset:32768
	ds_read_b128 v[164:167], v142 offset:33792
	ds_read_b128 v[168:171], v142 offset:34816
	ds_read_b128 v[172:175], v142 offset:35840
	ds_read_b128 v[176:179], v142 offset:36864
	ds_read_b128 v[180:183], v142 offset:37888
	ds_read_b128 v[184:187], v142 offset:38912
	ds_read_b128 v[188:191], v142 offset:39936
	global_load_lds_dwordx4 v[192:193], off
	v_lshl_add_u64 v[192:193], s[36:37], 0, v[128:129]
	s_mov_b32 m0, s28
	s_nop 0
	global_load_lds_dwordx4 v[192:193], off
	s_waitcnt lgkmcnt(8)
	s_barrier
	s_waitcnt lgkmcnt(0)
	v_mfma_f32_16x16x32_bf16 v[124:127], v[144:147], v[160:163], v[124:127]
	v_mfma_f32_16x16x32_bf16 v[120:123], v[152:155], v[160:163], v[120:123]
	v_mfma_f32_16x16x32_bf16 v[116:119], v[144:147], v[168:171], v[116:119]
	v_mfma_f32_16x16x32_bf16 v[112:115], v[152:155], v[168:171], v[112:115]
	v_mfma_f32_16x16x32_bf16 v[104:107], v[144:147], v[176:179], v[104:107]
	v_mfma_f32_16x16x32_bf16 v[96:99], v[152:155], v[176:179], v[96:99]
	v_mfma_f32_16x16x32_bf16 v[88:91], v[144:147], v[184:187], v[88:91]
	v_mfma_f32_16x16x32_bf16 v[80:83], v[152:155], v[184:187], v[80:83]
	v_mfma_f32_16x16x32_bf16 v[124:127], v[148:151], v[164:167], v[124:127]
	v_mfma_f32_16x16x32_bf16 v[120:123], v[156:159], v[164:167], v[120:123]
	v_mfma_f32_16x16x32_bf16 v[116:119], v[148:151], v[172:175], v[116:119]
	v_mfma_f32_16x16x32_bf16 v[112:115], v[156:159], v[172:175], v[112:115]
	v_mfma_f32_16x16x32_bf16 v[104:107], v[148:151], v[180:183], v[104:107]
	v_mfma_f32_16x16x32_bf16 v[96:99], v[156:159], v[180:183], v[96:99]
	v_mfma_f32_16x16x32_bf16 v[88:91], v[148:151], v[188:191], v[88:91]
	v_mfma_f32_16x16x32_bf16 v[80:83], v[156:159], v[188:191], v[80:83]
	s_barrier
	s_add_i32 s52, 16, 0x1c000
	s_add_i32 s36, s78, s3
	v_add_u32_e32 v132, s52, v140
	v_lshl_add_u64 v[204:205], v[204:205], 0, s[8:9]
	s_mov_b32 m0, s36
	ds_read_b128 v[192:195], v132
	ds_read_b128 v[196:199], v132 offset:1024
	ds_read_b128 v[200:203], v132 offset:2048
	ds_read_b128 v[208:211], v132 offset:3072
	global_load_lds_dwordx4 v[204:205], off
	v_lshl_add_u64 v[204:205], v[212:213], 0, s[8:9]
	s_add_i32 m0, s36, 0x2000
	s_nop 0
	global_load_lds_dwordx4 v[204:205], off
	s_barrier
	s_waitcnt lgkmcnt(0)
	v_mfma_f32_16x16x32_bf16 v[108:111], v[192:195], v[160:163], v[108:111]
	v_mfma_f32_16x16x32_bf16 v[100:103], v[200:203], v[160:163], v[100:103]
	v_mfma_f32_16x16x32_bf16 v[92:95], v[192:195], v[168:171], v[92:95]
	v_mfma_f32_16x16x32_bf16 v[84:87], v[200:203], v[168:171], v[84:87]
	v_mfma_f32_16x16x32_bf16 v[76:79], v[192:195], v[176:179], v[76:79]
	v_mfma_f32_16x16x32_bf16 v[72:75], v[200:203], v[176:179], v[72:75]
	v_mfma_f32_16x16x32_bf16 v[68:71], v[192:195], v[184:187], v[68:71]
	v_mfma_f32_16x16x32_bf16 v[64:67], v[200:203], v[184:187], v[64:67]
	v_mfma_f32_16x16x32_bf16 v[108:111], v[196:199], v[164:167], v[108:111]
	v_mfma_f32_16x16x32_bf16 v[100:103], v[208:211], v[164:167], v[100:103]
	v_mfma_f32_16x16x32_bf16 v[92:95], v[196:199], v[172:175], v[92:95]
	v_mfma_f32_16x16x32_bf16 v[84:87], v[208:211], v[172:175], v[84:87]
	v_mfma_f32_16x16x32_bf16 v[76:79], v[196:199], v[180:183], v[76:79]
	v_mfma_f32_16x16x32_bf16 v[72:75], v[208:211], v[180:183], v[72:75]
	v_mfma_f32_16x16x32_bf16 v[68:71], v[196:199], v[188:191], v[68:71]
	v_mfma_f32_16x16x32_bf16 v[64:67], v[208:211], v[188:191], v[64:67]
	s_barrier
	s_mov_b32 m0, s29
	v_lshl_add_u64 v[204:205], v[214:215], 0, s[8:9]
	ds_read_b128 v[160:163], v142 offset:49152
	ds_read_b128 v[164:167], v142 offset:50176
	ds_read_b128 v[168:171], v142 offset:51200
	ds_read_b128 v[172:175], v142 offset:52224
	ds_read_b128 v[176:179], v142 offset:53248
	ds_read_b128 v[180:183], v142 offset:54272
	ds_read_b128 v[184:187], v142 offset:55296
	ds_read_b128 v[188:191], v142 offset:56320
	global_load_lds_dwordx4 v[204:205], off
	v_lshl_add_u64 v[204:205], v[216:217], 0, s[8:9]
	s_mov_b32 m0, s35
	s_nop 0
	global_load_lds_dwordx4 v[204:205], off
	s_barrier
; #define WAIT_V(n) asm volatile("s_waitcnt vmcnt(" #n ")" ::: "memory")
; #define WAIT_L(n) asm volatile("s_waitcnt lgkmcnt(" #n ")" ::: "memory")
; #define BAR __builtin_amdgcn_s_barrier()
; #define SCHED __builtin_amdgcn_sched_barrier(0)
; #define EPI_DONE do { } while (0)
; template <class Get, class Epi>
; DI void gemm_stream(LAS unsigned char* lds, const int K, const int ld, Get get, Epi epi) {
;     ...
;             BAR; WAIT_L(0); MMA(1, 0, At, B0); BAR; SCHED;
;             STAGE(SBo(1, 1), b3 + hstep);
;             WAIT_V(6); BAR; MMA(1, 1, At, B1); BAR;
;         }
; DI void epi_part(const Acc& acc, const P& p, int brow, int bcol, int sl) {
;     EPI_IDX
;     const int b = brow / PB;
;     float* part = (float*)(p.ws + O_PART) + ((size_t)sl * (NBATCH * CTXL) + b * CTXL) * DM;
; #pragma unroll
;     for (int ai = 0; ai < 2; ++ai)
; #pragma unroll
;         for (int m = 0; m < 4; ++m) {
;             float* rp = part + (size_t)(ai * 128 + wr * 64 + m * 16 + fr) * DM + bcol + wc * 32 + fq * 4;
; #pragma unroll
;             for (int bj = 0; bj < 2; ++bj)
; #pragma unroll
;                 for (int n = 0; n < 2; ++n) *(f32x4*)(rp + bj * 128 + n * 16) = acc[ai][bj][m][n];
;         }
;     EPI_DONE;
; }
	s_waitcnt lgkmcnt(0)
	v_mfma_f32_16x16x32_bf16 v[60:63], v[144:147], v[160:163], v[60:63]
	v_mfma_f32_16x16x32_bf16 v[56:59], v[152:155], v[160:163], v[56:59]
	v_mfma_f32_16x16x32_bf16 v[52:55], v[144:147], v[168:171], v[52:55]
	v_mfma_f32_16x16x32_bf16 v[48:51], v[152:155], v[168:171], v[48:51]
	v_mfma_f32_16x16x32_bf16 v[40:43], v[144:147], v[176:179], v[40:43]
	v_mfma_f32_16x16x32_bf16 v[32:35], v[152:155], v[176:179], v[32:35]
	v_mfma_f32_16x16x32_bf16 v[24:27], v[144:147], v[184:187], v[24:27]
	v_mfma_f32_16x16x32_bf16 v[16:19], v[152:155], v[184:187], v[16:19]
	v_mfma_f32_16x16x32_bf16 v[60:63], v[148:151], v[164:167], v[60:63]
	v_mfma_f32_16x16x32_bf16 v[56:59], v[156:159], v[164:167], v[56:59]
	v_mfma_f32_16x16x32_bf16 v[52:55], v[148:151], v[172:175], v[52:55]
	v_mfma_f32_16x16x32_bf16 v[48:51], v[156:159], v[172:175], v[48:51]
	v_mfma_f32_16x16x32_bf16 v[40:43], v[148:151], v[180:183], v[40:43]
	v_mfma_f32_16x16x32_bf16 v[32:35], v[156:159], v[180:183], v[32:35]
	v_mfma_f32_16x16x32_bf16 v[24:27], v[148:151], v[188:191], v[24:27]
	v_mfma_f32_16x16x32_bf16 v[16:19], v[156:159], v[188:191], v[16:19]
	s_barrier
	s_add_u32 s36, s40, 0x160080
	s_addc_u32 s37, s41, 0
	s_add_i32 s40, s52, s3
	v_lshl_add_u64 v[144:145], s[36:37], 0, v[130:131]
	s_mov_b32 m0, s40
	s_nop 0
	global_load_lds_dwordx4 v[144:145], off
	v_lshl_add_u64 v[144:145], s[36:37], 0, v[128:129]
	s_add_i32 m0, s40, 0x2000
	s_nop 0
	global_load_lds_dwordx4 v[144:145], off
	s_add_i32 s77, s77, 2
	s_add_u32 s0, s0, 0x100
	s_addc_u32 s76, s76, 0
	s_cmp_gt_u32 s77, 5
	s_mov_b64 s[36:37], s[38:39]
	s_waitcnt vmcnt(6)
	s_barrier
	v_mfma_f32_16x16x32_bf16 v[44:47], v[192:195], v[160:163], v[44:47]
	v_mfma_f32_16x16x32_bf16 v[36:39], v[200:203], v[160:163], v[36:39]
	v_mfma_f32_16x16x32_bf16 v[28:31], v[192:195], v[168:171], v[28:31]
	v_mfma_f32_16x16x32_bf16 v[20:23], v[200:203], v[168:171], v[20:23]
	v_mfma_f32_16x16x32_bf16 v[12:15], v[192:195], v[176:179], v[12:15]
	v_mfma_f32_16x16x32_bf16 v[8:11], v[200:203], v[176:179], v[8:11]
	v_mfma_f32_16x16x32_bf16 v[4:7], v[192:195], v[184:187], v[4:7]
	v_mfma_f32_16x16x32_bf16 v[0:3], v[200:203], v[184:187], v[0:3]
	v_mfma_f32_16x16x32_bf16 v[44:47], v[196:199], v[164:167], v[44:47]
	v_mfma_f32_16x16x32_bf16 v[36:39], v[208:211], v[164:167], v[36:39]
	v_mfma_f32_16x16x32_bf16 v[28:31], v[196:199], v[172:175], v[28:31]
	v_mfma_f32_16x16x32_bf16 v[20:23], v[208:211], v[172:175], v[20:23]
	v_mfma_f32_16x16x32_bf16 v[12:15], v[196:199], v[180:183], v[12:15]
	v_mfma_f32_16x16x32_bf16 v[8:11], v[208:211], v[180:183], v[8:11]
	v_mfma_f32_16x16x32_bf16 v[4:7], v[196:199], v[188:191], v[4:7]
	v_mfma_f32_16x16x32_bf16 v[0:3], v[208:211], v[188:191], v[0:3]
	s_barrier
	s_cbranch_scc0 .LBB0_1964
	s_mul_hi_i32 s0, s75, 0x78787879
	s_lshr_b32 s37, s0, 31
	s_lshr_b32 s0, s0, 3
	s_ashr_i32 s36, s61, 4
	s_add_i32 s0, s0, s37
	s_ashr_i32 s37, s36, 31
	s_lshl_b32 s38, s0, 8
	s_ashr_i32 s39, s38, 31
	s_lshl_b64 s[36:37], s[36:37], 23
	s_add_u32 s0, s54, s36
	s_addc_u32 s40, s55, s37
	s_lshl_b64 s[36:37], s[38:39], 13
	s_add_u32 s0, s0, s36
	v_mov_b32_e32 v145, v206
	s_addc_u32 s37, s40, s37
	s_lshl_b32 s36, s61, 10
	s_and_b32 s36, s36, 0x3c00
	v_and_b32_e32 v132, 15, v145
	v_ashrrev_i32_e32 v144, 2, v145
	v_and_or_b32 v144, v144, s58, v132
	s_add_u32 s36, s0, s36
	v_lshlrev_b32_e32 v132, 1, v145
	s_addc_u32 s37, s37, 0
	v_and_b32_e32 v132, 0x180, v132
	v_lshl_add_u64 v[146:147], s[36:37], 0, v[132:133]
	v_and_b32_e32 v132, 48, v145
	v_ashrrev_i32_e32 v145, 31, v144
	v_lshl_add_u64 v[146:147], v[146:147], 0, v[132:133]
	v_lshlrev_b64 v[148:149], 13, v[144:145]
	v_lshl_add_u64 v[148:149], v[146:147], 0, v[148:149]
	global_store_dwordx4 v[148:149], v[124:127], off
	global_store_dwordx4 v[148:149], v[120:123], off offset:64
	global_store_dwordx4 v[148:149], v[108:111], off offset:512
	global_store_dwordx4 v[148:149], v[100:103], off offset:576
	s_mov_b32 s61, s74
	s_mov_b32 s75, s63
	v_or_b32_e32 v100, 16, v144
	v_ashrrev_i32_e32 v101, 31, v100
	v_lshlrev_b64 v[100:101], 13, v[100:101]
	v_lshl_add_u64 v[100:101], v[146:147], 0, v[100:101]
	global_store_dwordx4 v[100:101], v[116:119], off
	global_store_dwordx4 v[100:101], v[112:115], off offset:64
	global_store_dwordx4 v[100:101], v[92:95], off offset:512
	global_store_dwordx4 v[100:101], v[84:87], off offset:576
	s_mov_b64 s[38:39], s[18:19]
	s_mov_b64 s[36:37], s[16:17]
	v_or_b32_e32 v84, 32, v144
	v_ashrrev_i32_e32 v85, 31, v84
	v_lshlrev_b64 v[84:85], 13, v[84:85]
	v_lshl_add_u64 v[84:85], v[146:147], 0, v[84:85]
	global_store_dwordx4 v[84:85], v[104:107], off
	global_store_dwordx4 v[84:85], v[96:99], off offset:64
	global_store_dwordx4 v[84:85], v[76:79], off offset:512
	global_store_dwordx4 v[84:85], v[72:75], off offset:576
	s_nop 1
	v_or_b32_e32 v72, 48, v144
	v_ashrrev_i32_e32 v73, 31, v72
	v_lshlrev_b64 v[72:73], 13, v[72:73]
	v_lshl_add_u64 v[72:73], v[146:147], 0, v[72:73]
	global_store_dwordx4 v[72:73], v[88:91], off
	global_store_dwordx4 v[72:73], v[80:83], off offset:64
	global_store_dwordx4 v[72:73], v[68:71], off offset:512
	global_store_dwordx4 v[72:73], v[64:67], off offset:576
	s_nop 1
	v_add_co_u32_e32 v66, vcc, s59, v148
	v_lshl_add_u64 v[64:65], v[148:149], 0, s[10:11]
	s_nop 0
	v_addc_co_u32_e32 v67, vcc, 0, v149, vcc
	global_store_dwordx4 v[66:67], v[60:63], off
	global_store_dwordx4 v[64:65], v[56:59], off offset:64
	global_store_dwordx4 v[64:65], v[44:47], off offset:512
	global_store_dwordx4 v[64:65], v[36:39], off offset:576
	s_nop 1
	v_add_co_u32_e32 v38, vcc, s60, v148
	v_lshl_add_u64 v[36:37], v[148:149], 0, s[12:13]
	s_nop 0
	v_addc_co_u32_e32 v39, vcc, 0, v149, vcc
	global_store_dwordx4 v[38:39], v[52:55], off
	global_store_dwordx4 v[36:37], v[48:51], off offset:64
	global_store_dwordx4 v[36:37], v[28:31], off offset:512
	global_store_dwordx4 v[36:37], v[20:23], off offset:576
	s_nop 1
	v_add_co_u32_e32 v22, vcc, 0x140000, v148
	v_lshl_add_u64 v[20:21], v[148:149], 0, s[14:15]
	s_nop 0
	v_addc_co_u32_e32 v23, vcc, 0, v149, vcc
	global_store_dwordx4 v[22:23], v[40:43], off
	global_store_dwordx4 v[20:21], v[32:35], off offset:64
	global_store_dwordx4 v[20:21], v[12:15], off offset:512
	global_store_dwordx4 v[20:21], v[8:11], off offset:576
	s_nop 1
	v_add_co_u32_e32 v10, vcc, 0x160000, v148
	v_lshl_add_u64 v[8:9], v[148:149], 0, s[6:7]
	s_nop 0
	v_addc_co_u32_e32 v11, vcc, 0, v149, vcc
	s_and_b64 vcc, exec, s[4:5]
	global_store_dwordx4 v[10:11], v[24:27], off
	global_store_dwordx4 v[8:9], v[16:19], off offset:64
	global_store_dwordx4 v[8:9], v[4:7], off offset:512
	global_store_dwordx4 v[8:9], v[0:3], off offset:576
	s_cbranch_vccz .LBB0_1961
	s_waitcnt vmcnt(0)
	s_cmpk_gt_u32 s2, 0xff
	s_cbranch_scc1 .LBB0_1968
	s_barrier

; #define WAIT_V(n) asm volatile("s_waitcnt vmcnt(" #n ")" ::: "memory")
; #define WAIT_L(n) asm volatile("s_waitcnt lgkmcnt(" #n ")" ::: "memory")
; #define BAR __builtin_amdgcn_s_barrier()
; #define SCHED __builtin_amdgcn_sched_barrier(0)
; template <class Get, class Epi>
; DI void gemm_stream(LAS unsigned char* lds, const int K, const int ld, Get get, Epi epi) {
;     ...
;             const bool last = (t == nt - 2);
;             const char* a1 = cA + (size_t)(t + 1) * kstep;
;             const char* a2 = last ? nA : cA + (size_t)(t + 2) * kstep;
;             const char* b2 = last ? nB : cB + (size_t)(t + 2) * kstep;
;             const char* a3 = a2 + kstep;
;             const char* b3 = b2 + kstep;
;             LDB(B0, 0, 0); SCHED; LDA(At, 0, 0); STAGE(SAo(1, 1), a1 + hstep);
;             WAIT_L(8); BAR; WAIT_L(0); MMA(0, 0, At, B0); BAR; SCHED;
;             LDB(B1, 0, 1); STAGE(SBo(0, 0), b2);
;             BAR; WAIT_L(0); MMA(0, 1, At, B1); BAR;
;             LDA(At, 0, 1); STAGE(SAo(0, 0), a2);
;             BAR; WAIT_L(0); MMA(1, 0, At, B0); BAR; SCHED;
;             STAGE(SBo(0, 1), b2 + hstep);
;             WAIT_V(6); BAR; MMA(1, 1, At, B1); BAR;
.LBB0_2102:
	ds_read_b128 v[128:131], v209
	ds_read_b128 v[132:135], v209 offset:1024
	ds_read_b128 v[136:139], v209 offset:2048
	ds_read_b128 v[156:159], v209 offset:3072
	s_add_u32 s28, s64, 0xfff80080
	s_addc_u32 s29, s65, -1
	s_cmp_eq_u32 s7, 28
	s_cselect_b32 s77, s59, s29
	s_cselect_b32 s76, s58, s28
	s_cselect_b32 s75, s61, s3
	s_cselect_b32 s74, s60, s2
	v_lshl_add_u64 v[140:141], s[64:65], 0, v[148:149]
	s_add_i32 m0, s23, 0xc000
	ds_read_b128 v[160:163], v210
	ds_read_b128 v[164:167], v210 offset:1024
	ds_read_b128 v[168:171], v210 offset:2048
	ds_read_b128 v[172:175], v210 offset:3072
	ds_read_b128 v[176:179], v210 offset:4096
	ds_read_b128 v[180:183], v210 offset:5120
	ds_read_b128 v[184:187], v210 offset:6144
	ds_read_b128 v[188:191], v210 offset:7168
	global_load_lds_dwordx4 v[140:141], off
	v_lshl_add_u64 v[140:141], s[64:65], 0, v[150:151]
	s_add_i32 m0, s23, 0xe000
	s_nop 0
	global_load_lds_dwordx4 v[140:141], off
	s_waitcnt lgkmcnt(8)
	s_barrier
	s_waitcnt lgkmcnt(0)
	v_mfma_f32_16x16x32_bf16 v[124:127], v[128:131], v[160:163], v[124:127]
	v_mfma_f32_16x16x32_bf16 v[116:119], v[136:139], v[160:163], v[116:119]
	v_mfma_f32_16x16x32_bf16 v[108:111], v[128:131], v[168:171], v[108:111]
	v_mfma_f32_16x16x32_bf16 v[100:103], v[136:139], v[168:171], v[100:103]
	v_mfma_f32_16x16x32_bf16 v[92:95], v[128:131], v[176:179], v[92:95]
	v_mfma_f32_16x16x32_bf16 v[84:87], v[136:139], v[176:179], v[84:87]
	v_mfma_f32_16x16x32_bf16 v[76:79], v[128:131], v[184:187], v[76:79]
	v_mfma_f32_16x16x32_bf16 v[68:71], v[136:139], v[184:187], v[68:71]
	v_mfma_f32_16x16x32_bf16 v[124:127], v[132:135], v[164:167], v[124:127]
	v_mfma_f32_16x16x32_bf16 v[116:119], v[156:159], v[164:167], v[116:119]
	v_mfma_f32_16x16x32_bf16 v[108:111], v[132:135], v[172:175], v[108:111]
	v_mfma_f32_16x16x32_bf16 v[100:103], v[156:159], v[172:175], v[100:103]
	v_mfma_f32_16x16x32_bf16 v[92:95], v[132:135], v[180:183], v[92:95]
	v_mfma_f32_16x16x32_bf16 v[84:87], v[156:159], v[180:183], v[84:87]
	v_mfma_f32_16x16x32_bf16 v[76:79], v[132:135], v[188:191], v[76:79]
	v_mfma_f32_16x16x32_bf16 v[68:71], v[156:159], v[188:191], v[68:71]
	s_barrier
	s_add_i32 s28, s90, s21
	v_lshl_add_u64 v[140:141], s[74:75], 0, v[142:143]
	s_mov_b32 m0, s28
	ds_read_b128 v[192:195], v211
	ds_read_b128 v[196:199], v211 offset:1024
	ds_read_b128 v[200:203], v211 offset:2048
	ds_read_b128 v[212:215], v211 offset:3072
	global_load_lds_dwordx4 v[140:141], off
	v_lshl_add_u64 v[204:205], s[74:75], 0, v[144:145]
	s_add_i32 m0, s28, 0x2000
	s_nop 0
	global_load_lds_dwordx4 v[204:205], off
	s_barrier
	s_waitcnt lgkmcnt(0)
	v_mfma_f32_16x16x32_bf16 v[120:123], v[192:195], v[160:163], v[120:123]
	v_mfma_f32_16x16x32_bf16 v[112:115], v[200:203], v[160:163], v[112:115]
	v_mfma_f32_16x16x32_bf16 v[104:107], v[192:195], v[168:171], v[104:107]
	v_mfma_f32_16x16x32_bf16 v[96:99], v[200:203], v[168:171], v[96:99]
	v_mfma_f32_16x16x32_bf16 v[88:91], v[192:195], v[176:179], v[88:91]
	v_mfma_f32_16x16x32_bf16 v[80:83], v[200:203], v[176:179], v[80:83]
	v_mfma_f32_16x16x32_bf16 v[72:75], v[192:195], v[184:187], v[72:75]
	v_mfma_f32_16x16x32_bf16 v[64:67], v[200:203], v[184:187], v[64:67]
	v_mfma_f32_16x16x32_bf16 v[120:123], v[196:199], v[164:167], v[120:123]
	v_mfma_f32_16x16x32_bf16 v[112:115], v[212:215], v[164:167], v[112:115]
	v_mfma_f32_16x16x32_bf16 v[104:107], v[196:199], v[172:175], v[104:107]
	v_mfma_f32_16x16x32_bf16 v[96:99], v[212:215], v[172:175], v[96:99]
	v_mfma_f32_16x16x32_bf16 v[88:91], v[196:199], v[180:183], v[88:91]
	v_mfma_f32_16x16x32_bf16 v[80:83], v[212:215], v[180:183], v[80:83]
	v_mfma_f32_16x16x32_bf16 v[72:75], v[196:199], v[188:191], v[72:75]
	v_mfma_f32_16x16x32_bf16 v[64:67], v[212:215], v[188:191], v[64:67]
	s_barrier
	s_mov_b32 m0, s23
	v_lshl_add_u64 v[216:217], s[76:77], 0, v[142:143]
	ds_read_b128 v[160:163], v210 offset:16384
	ds_read_b128 v[164:167], v210 offset:17408
	ds_read_b128 v[168:171], v210 offset:18432
	ds_read_b128 v[172:175], v210 offset:19456
	ds_read_b128 v[176:179], v210 offset:20480
	ds_read_b128 v[180:183], v210 offset:21504
	ds_read_b128 v[184:187], v210 offset:22528
	ds_read_b128 v[188:191], v210 offset:23552
	global_load_lds_dwordx4 v[216:217], off
	v_lshl_add_u64 v[218:219], s[76:77], 0, v[144:145]
	s_mov_b32 m0, s35
	s_nop 0
	global_load_lds_dwordx4 v[218:219], off
	s_barrier
	s_waitcnt lgkmcnt(0)
	v_mfma_f32_16x16x32_bf16 v[60:63], v[128:131], v[160:163], v[60:63]
	v_mfma_f32_16x16x32_bf16 v[52:55], v[136:139], v[160:163], v[52:55]
	v_mfma_f32_16x16x32_bf16 v[44:47], v[128:131], v[168:171], v[44:47]
	v_mfma_f32_16x16x32_bf16 v[36:39], v[136:139], v[168:171], v[36:39]
	v_mfma_f32_16x16x32_bf16 v[28:31], v[128:131], v[176:179], v[28:31]
	v_mfma_f32_16x16x32_bf16 v[20:23], v[136:139], v[176:179], v[20:23]
	v_mfma_f32_16x16x32_bf16 v[12:15], v[128:131], v[184:187], v[12:15]
	v_mfma_f32_16x16x32_bf16 v[4:7], v[136:139], v[184:187], v[4:7]
	v_mfma_f32_16x16x32_bf16 v[60:63], v[132:135], v[164:167], v[60:63]
	v_mfma_f32_16x16x32_bf16 v[52:55], v[156:159], v[164:167], v[52:55]
	v_mfma_f32_16x16x32_bf16 v[44:47], v[132:135], v[172:175], v[44:47]
	v_mfma_f32_16x16x32_bf16 v[36:39], v[156:159], v[172:175], v[36:39]
	v_mfma_f32_16x16x32_bf16 v[28:31], v[132:135], v[180:183], v[28:31]
	v_mfma_f32_16x16x32_bf16 v[20:23], v[156:159], v[180:183], v[20:23]
	v_mfma_f32_16x16x32_bf16 v[12:15], v[132:135], v[188:191], v[12:15]
	v_mfma_f32_16x16x32_bf16 v[4:7], v[156:159], v[188:191], v[4:7]
	s_barrier
; #define WAIT_V(n) asm volatile("s_waitcnt vmcnt(" #n ")" ::: "memory")
; #define WAIT_L(n) asm volatile("s_waitcnt lgkmcnt(" #n ")" ::: "memory")
; #define BAR __builtin_amdgcn_s_barrier()
; #define SCHED __builtin_amdgcn_sched_barrier(0)
; template <class Get, class Epi>
; DI void gemm_stream(LAS unsigned char* lds, const int K, const int ld, Get get, Epi epi) {
;     ...
;             STAGE(SBo(0, 1), b2 + hstep);
;             WAIT_V(6); BAR; MMA(1, 1, At, B1); BAR;
;             LDB(B0, 1, 0); SCHED; LDA(At, 1, 0); STAGE(SAo(0, 1), a2 + hstep);
;             WAIT_L(8); BAR; WAIT_L(0); MMA(0, 0, At, B0); BAR; SCHED;
;             LDB(B1, 1, 1); STAGE(SBo(1, 0), b3);
;             BAR; WAIT_L(0); MMA(0, 1, At, B1); BAR;
;             LDA(At, 1, 1); STAGE(SAo(1, 0), a3);
;             BAR; WAIT_L(0); MMA(1, 0, At, B0); BAR; SCHED;
	s_add_u32 s28, s74, 0x80000
	s_addc_u32 s29, s75, 0
	s_add_i32 s57, s91, s21
	v_lshl_add_u64 v[128:129], s[28:29], 0, v[142:143]
	s_mov_b32 m0, s57
	s_nop 0
	global_load_lds_dwordx4 v[128:129], off
	v_lshl_add_u64 v[128:129], s[28:29], 0, v[144:145]
	s_add_i32 m0, s57, 0x2000
	s_nop 0
	global_load_lds_dwordx4 v[128:129], off
	s_waitcnt vmcnt(6)
	s_barrier
	v_mfma_f32_16x16x32_bf16 v[56:59], v[192:195], v[160:163], v[56:59]
	v_mfma_f32_16x16x32_bf16 v[48:51], v[200:203], v[160:163], v[48:51]
	v_mfma_f32_16x16x32_bf16 v[40:43], v[192:195], v[168:171], v[40:43]
	v_mfma_f32_16x16x32_bf16 v[32:35], v[200:203], v[168:171], v[32:35]
	v_mfma_f32_16x16x32_bf16 v[24:27], v[192:195], v[176:179], v[24:27]
	v_mfma_f32_16x16x32_bf16 v[16:19], v[200:203], v[176:179], v[16:19]
	v_mfma_f32_16x16x32_bf16 v[8:11], v[192:195], v[184:187], v[8:11]
	v_mfma_f32_16x16x32_bf16 v[0:3], v[200:203], v[184:187], v[0:3]
	v_mfma_f32_16x16x32_bf16 v[56:59], v[196:199], v[164:167], v[56:59]
	v_mfma_f32_16x16x32_bf16 v[48:51], v[212:215], v[164:167], v[48:51]
	v_mfma_f32_16x16x32_bf16 v[40:43], v[196:199], v[172:175], v[40:43]
	v_mfma_f32_16x16x32_bf16 v[32:35], v[212:215], v[172:175], v[32:35]
	v_mfma_f32_16x16x32_bf16 v[24:27], v[196:199], v[180:183], v[24:27]
	v_mfma_f32_16x16x32_bf16 v[16:19], v[212:215], v[180:183], v[16:19]
	v_mfma_f32_16x16x32_bf16 v[8:11], v[196:199], v[188:191], v[8:11]
	v_mfma_f32_16x16x32_bf16 v[0:3], v[212:215], v[188:191], v[0:3]
	s_add_i32 s57, 16, 0x18000
	v_add_u32_e32 v146, s57, v208
	s_barrier
	ds_read_b128 v[128:131], v146
	ds_read_b128 v[132:135], v146 offset:1024
	ds_read_b128 v[136:139], v146 offset:2048
	ds_read_b128 v[156:159], v146 offset:3072
	s_add_u32 s28, s76, 0x80000
	s_addc_u32 s29, s77, 0
	s_mov_b32 m0, s55
	v_lshl_add_u64 v[192:193], s[28:29], 0, v[142:143]
	ds_read_b128 v[160:163], v210 offset:32768
	ds_read_b128 v[164:167], v210 offset:33792
	ds_read_b128 v[168:171], v210 offset:34816
	ds_read_b128 v[172:175], v210 offset:35840
	ds_read_b128 v[176:179], v210 offset:36864
	ds_read_b128 v[180:183], v210 offset:37888
	ds_read_b128 v[184:187], v210 offset:38912
	ds_read_b128 v[188:191], v210 offset:39936
	global_load_lds_dwordx4 v[192:193], off
	v_lshl_add_u64 v[192:193], s[28:29], 0, v[144:145]
	s_mov_b32 m0, s82
	s_nop 0
	global_load_lds_dwordx4 v[192:193], off
	s_waitcnt lgkmcnt(8)
	s_barrier
	s_waitcnt lgkmcnt(0)
	v_mfma_f32_16x16x32_bf16 v[124:127], v[128:131], v[160:163], v[124:127]
	v_mfma_f32_16x16x32_bf16 v[116:119], v[136:139], v[160:163], v[116:119]
	v_mfma_f32_16x16x32_bf16 v[108:111], v[128:131], v[168:171], v[108:111]
	v_mfma_f32_16x16x32_bf16 v[100:103], v[136:139], v[168:171], v[100:103]
	v_mfma_f32_16x16x32_bf16 v[92:95], v[128:131], v[176:179], v[92:95]
	v_mfma_f32_16x16x32_bf16 v[84:87], v[136:139], v[176:179], v[84:87]
	v_mfma_f32_16x16x32_bf16 v[76:79], v[128:131], v[184:187], v[76:79]
	v_mfma_f32_16x16x32_bf16 v[68:71], v[136:139], v[184:187], v[68:71]
	v_mfma_f32_16x16x32_bf16 v[124:127], v[132:135], v[164:167], v[124:127]
	v_mfma_f32_16x16x32_bf16 v[116:119], v[156:159], v[164:167], v[116:119]
	v_mfma_f32_16x16x32_bf16 v[108:111], v[132:135], v[172:175], v[108:111]
	v_mfma_f32_16x16x32_bf16 v[100:103], v[156:159], v[172:175], v[100:103]
	v_mfma_f32_16x16x32_bf16 v[92:95], v[132:135], v[180:183], v[92:95]
	v_mfma_f32_16x16x32_bf16 v[84:87], v[156:159], v[180:183], v[84:87]
	v_mfma_f32_16x16x32_bf16 v[76:79], v[132:135], v[188:191], v[76:79]
	v_mfma_f32_16x16x32_bf16 v[68:71], v[156:159], v[188:191], v[68:71]
	s_barrier
	s_add_i32 s63, 16, 0x1c000
	s_add_i32 s28, s57, s21
	v_add_u32_e32 v146, s63, v208
	v_lshl_add_u64 v[140:141], v[140:141], 0, s[0:1]
	s_mov_b32 m0, s28
	ds_read_b128 v[192:195], v146
	ds_read_b128 v[196:199], v146 offset:1024
	ds_read_b128 v[200:203], v146 offset:2048
	ds_read_b128 v[212:215], v146 offset:3072
	global_load_lds_dwordx4 v[140:141], off
	v_lshl_add_u64 v[140:141], v[204:205], 0, s[0:1]
	s_add_i32 m0, s28, 0x2000
	s_nop 0
	global_load_lds_dwordx4 v[140:141], off
	s_barrier
	s_waitcnt lgkmcnt(0)
	v_mfma_f32_16x16x32_bf16 v[120:123], v[192:195], v[160:163], v[120:123]
	v_mfma_f32_16x16x32_bf16 v[112:115], v[200:203], v[160:163], v[112:115]
	v_mfma_f32_16x16x32_bf16 v[104:107], v[192:195], v[168:171], v[104:107]
	v_mfma_f32_16x16x32_bf16 v[96:99], v[200:203], v[168:171], v[96:99]
	v_mfma_f32_16x16x32_bf16 v[88:91], v[192:195], v[176:179], v[88:91]
	v_mfma_f32_16x16x32_bf16 v[80:83], v[200:203], v[176:179], v[80:83]
	v_mfma_f32_16x16x32_bf16 v[72:75], v[192:195], v[184:187], v[72:75]
	v_mfma_f32_16x16x32_bf16 v[64:67], v[200:203], v[184:187], v[64:67]
	v_mfma_f32_16x16x32_bf16 v[120:123], v[196:199], v[164:167], v[120:123]
	v_mfma_f32_16x16x32_bf16 v[112:115], v[212:215], v[164:167], v[112:115]
	v_mfma_f32_16x16x32_bf16 v[104:107], v[196:199], v[172:175], v[104:107]
	v_mfma_f32_16x16x32_bf16 v[96:99], v[212:215], v[172:175], v[96:99]
	v_mfma_f32_16x16x32_bf16 v[88:91], v[196:199], v[180:183], v[88:91]
	v_mfma_f32_16x16x32_bf16 v[80:83], v[212:215], v[180:183], v[80:83]
	v_mfma_f32_16x16x32_bf16 v[72:75], v[196:199], v[188:191], v[72:75]
	v_mfma_f32_16x16x32_bf16 v[64:67], v[212:215], v[188:191], v[64:67]
	s_barrier
	s_mov_b32 m0, s83
	v_lshl_add_u64 v[140:141], v[216:217], 0, s[0:1]
	ds_read_b128 v[160:163], v210 offset:49152
	ds_read_b128 v[164:167], v210 offset:50176
	ds_read_b128 v[168:171], v210 offset:51200
	ds_read_b128 v[172:175], v210 offset:52224
	ds_read_b128 v[176:179], v210 offset:53248
	ds_read_b128 v[180:183], v210 offset:54272
	ds_read_b128 v[184:187], v210 offset:55296
	ds_read_b128 v[188:191], v210 offset:56320
	global_load_lds_dwordx4 v[140:141], off
	v_lshl_add_u64 v[140:141], v[218:219], 0, s[0:1]
	s_mov_b32 m0, s85
	s_nop 0
	global_load_lds_dwordx4 v[140:141], off
	s_barrier
; #define WAIT_V(n) asm volatile("s_waitcnt vmcnt(" #n ")" ::: "memory")
; #define WAIT_L(n) asm volatile("s_waitcnt lgkmcnt(" #n ")" ::: "memory")
; #define BAR __builtin_amdgcn_s_barrier()
; #define SCHED __builtin_amdgcn_sched_barrier(0)
; template <class Get, class Epi>
; DI void gemm_stream(LAS unsigned char* lds, const int K, const int ld, Get get, Epi epi) {
;     ...
;             BAR; WAIT_L(0); MMA(1, 0, At, B0); BAR; SCHED;
;             STAGE(SBo(1, 1), b3 + hstep);
;             WAIT_V(6); BAR; MMA(1, 1, At, B1); BAR;
;         }
; DI void epi_plain(const Acc& acc, int brow, bf16_t* dst, int ld, int coff, const float* rs) {
;     EPI_IDX
; #pragma unroll
;     for (int ai = 0; ai < 2; ++ai)
; #pragma unroll
;         for (int m = 0; m < 4; ++m) {
;             const int lr = ai * 128 + wr * 64 + m * 16 + fr;
;             const float s = rs ? rs[lr] : 1.f;
;             bf16_t* rp = dst + (size_t)(brow + lr) * ld + coff + wc * 32 + fq * 4;
; #pragma unroll
;             for (int bj = 0; bj < 2; ++bj)
; #pragma unroll
;                 for (int n = 0; n < 2; ++n) { const f32x4 v = acc[ai][bj][m][n]; st4(rp + bj * 128 + n * 16, v[0] * s, v[1] * s, v[2] * s, v[3] * s); }
;         }
	s_waitcnt lgkmcnt(0)
	v_mfma_f32_16x16x32_bf16 v[60:63], v[128:131], v[160:163], v[60:63]
	v_mfma_f32_16x16x32_bf16 v[52:55], v[136:139], v[160:163], v[52:55]
	v_mfma_f32_16x16x32_bf16 v[44:47], v[128:131], v[168:171], v[44:47]
	v_mfma_f32_16x16x32_bf16 v[36:39], v[136:139], v[168:171], v[36:39]
	v_mfma_f32_16x16x32_bf16 v[28:31], v[128:131], v[176:179], v[28:31]
	v_mfma_f32_16x16x32_bf16 v[20:23], v[136:139], v[176:179], v[20:23]
	v_mfma_f32_16x16x32_bf16 v[12:15], v[128:131], v[184:187], v[12:15]
	v_mfma_f32_16x16x32_bf16 v[4:7], v[136:139], v[184:187], v[4:7]
	v_mfma_f32_16x16x32_bf16 v[60:63], v[132:135], v[164:167], v[60:63]
	v_mfma_f32_16x16x32_bf16 v[52:55], v[156:159], v[164:167], v[52:55]
	v_mfma_f32_16x16x32_bf16 v[44:47], v[132:135], v[172:175], v[44:47]
	v_mfma_f32_16x16x32_bf16 v[36:39], v[156:159], v[172:175], v[36:39]
	v_mfma_f32_16x16x32_bf16 v[28:31], v[132:135], v[180:183], v[28:31]
	v_mfma_f32_16x16x32_bf16 v[20:23], v[156:159], v[180:183], v[20:23]
	v_mfma_f32_16x16x32_bf16 v[12:15], v[132:135], v[188:191], v[12:15]
	v_mfma_f32_16x16x32_bf16 v[4:7], v[156:159], v[188:191], v[4:7]
	s_barrier
	s_add_u32 s28, s74, 0x80080
	s_addc_u32 s29, s75, 0
	s_add_i32 s57, s63, s21
	v_lshl_add_u64 v[128:129], s[28:29], 0, v[142:143]
	s_mov_b32 m0, s57
	s_nop 0
	global_load_lds_dwordx4 v[128:129], off
	v_lshl_add_u64 v[128:129], s[28:29], 0, v[144:145]
	s_add_i32 m0, s57, 0x2000
	s_nop 0
	global_load_lds_dwordx4 v[128:129], off
	s_add_i32 s7, s7, 2
	s_add_u32 s64, s64, 0x100
	s_addc_u32 s65, s65, 0
	s_add_u32 s2, s2, 0x100
	s_addc_u32 s3, s3, 0
	s_cmp_gt_u32 s7, 29
	s_waitcnt vmcnt(6)
	s_barrier
	v_mfma_f32_16x16x32_bf16 v[56:59], v[192:195], v[160:163], v[56:59]
	v_mfma_f32_16x16x32_bf16 v[48:51], v[200:203], v[160:163], v[48:51]
	v_mfma_f32_16x16x32_bf16 v[40:43], v[192:195], v[168:171], v[40:43]
	v_mfma_f32_16x16x32_bf16 v[32:35], v[200:203], v[168:171], v[32:35]
	v_mfma_f32_16x16x32_bf16 v[24:27], v[192:195], v[176:179], v[24:27]
	v_mfma_f32_16x16x32_bf16 v[16:19], v[200:203], v[176:179], v[16:19]
	v_mfma_f32_16x16x32_bf16 v[8:11], v[192:195], v[184:187], v[8:11]
	v_mfma_f32_16x16x32_bf16 v[0:3], v[200:203], v[184:187], v[0:3]
	v_mfma_f32_16x16x32_bf16 v[56:59], v[196:199], v[164:167], v[56:59]
	v_mfma_f32_16x16x32_bf16 v[48:51], v[212:215], v[164:167], v[48:51]
	v_mfma_f32_16x16x32_bf16 v[40:43], v[196:199], v[172:175], v[40:43]
	v_mfma_f32_16x16x32_bf16 v[32:35], v[212:215], v[172:175], v[32:35]
	v_mfma_f32_16x16x32_bf16 v[24:27], v[196:199], v[180:183], v[24:27]
	v_mfma_f32_16x16x32_bf16 v[16:19], v[212:215], v[180:183], v[16:19]
	v_mfma_f32_16x16x32_bf16 v[8:11], v[196:199], v[188:191], v[8:11]
	v_mfma_f32_16x16x32_bf16 v[0:3], v[212:215], v[188:191], v[0:3]
	s_barrier
	s_cbranch_scc0 .LBB0_2102
	s_mul_hi_i32 s2, s6, 0x78787879
	s_lshr_b32 s3, s2, 31
	s_ashr_i32 s2, s2, 3
	s_add_i32 s76, s2, s3
	s_mul_i32 s2, s76, 17
	s_lshl_b32 s74, s6, 8
	s_sub_i32 s6, s6, s2
	s_lshl_b32 s6, s6, 8
	s_ashr_i32 s77, s76, 31
	s_addk_i32 s6, 0xff00
	s_lshl_b64 s[2:3], s[76:77], 12
	s_ashr_i32 s7, s6, 31
	s_add_u32 s64, s2, s6
	s_addc_u32 s65, s3, s7
	s_cmp_gt_i32 s62, 7
	s_mov_b64 s[6:7], -1
	s_cbranch_scc0 .LBB0_2145
	s_cmp_gt_u32 s62, 15
	s_cbranch_scc0 .LBB0_2110
	s_cmp_gt_u32 s62, 31
	v_cvt_pk_bf16_f32 v204, v124, v125
	v_cvt_pk_bf16_f32 v205, v126, v127
	v_cvt_pk_bf16_f32 v202, v116, v117
	v_cvt_pk_bf16_f32 v203, v118, v119
	v_cvt_pk_bf16_f32 v200, v120, v121
	v_cvt_pk_bf16_f32 v201, v122, v123
	v_cvt_pk_bf16_f32 v198, v112, v113
	v_cvt_pk_bf16_f32 v199, v114, v115
	v_cvt_pk_bf16_f32 v196, v108, v109
	v_cvt_pk_bf16_f32 v197, v110, v111
	v_cvt_pk_bf16_f32 v194, v100, v101
	v_cvt_pk_bf16_f32 v195, v102, v103
	v_cvt_pk_bf16_f32 v192, v104, v105
	v_cvt_pk_bf16_f32 v193, v106, v107
	v_cvt_pk_bf16_f32 v190, v96, v97
	v_cvt_pk_bf16_f32 v191, v98, v99
	v_cvt_pk_bf16_f32 v188, v92, v93
	v_cvt_pk_bf16_f32 v189, v94, v95
	v_cvt_pk_bf16_f32 v186, v84, v85
	v_cvt_pk_bf16_f32 v187, v86, v87
	v_cvt_pk_bf16_f32 v184, v88, v89
	v_cvt_pk_bf16_f32 v185, v90, v91
	v_cvt_pk_bf16_f32 v182, v80, v81
	v_cvt_pk_bf16_f32 v183, v82, v83
	v_cvt_pk_bf16_f32 v180, v76, v77
	v_cvt_pk_bf16_f32 v181, v78, v79
	v_cvt_pk_bf16_f32 v178, v68, v69
	v_cvt_pk_bf16_f32 v179, v70, v71
	v_cvt_pk_bf16_f32 v176, v72, v73
	v_cvt_pk_bf16_f32 v177, v74, v75
	v_cvt_pk_bf16_f32 v174, v64, v65
	v_cvt_pk_bf16_f32 v175, v66, v67
	v_cvt_pk_bf16_f32 v172, v60, v61
	v_cvt_pk_bf16_f32 v173, v62, v63
	v_cvt_pk_bf16_f32 v170, v52, v53
	v_cvt_pk_bf16_f32 v171, v54, v55
	v_cvt_pk_bf16_f32 v168, v56, v57
	v_cvt_pk_bf16_f32 v169, v58, v59
	v_cvt_pk_bf16_f32 v166, v48, v49
	v_cvt_pk_bf16_f32 v167, v50, v51
	v_cvt_pk_bf16_f32 v164, v44, v45
	v_cvt_pk_bf16_f32 v165, v46, v47
	v_cvt_pk_bf16_f32 v162, v36, v37
	v_cvt_pk_bf16_f32 v163, v38, v39
	v_cvt_pk_bf16_f32 v160, v40, v41
	v_cvt_pk_bf16_f32 v161, v42, v43
	v_cvt_pk_bf16_f32 v158, v32, v33
	v_cvt_pk_bf16_f32 v159, v34, v35
	v_cvt_pk_bf16_f32 v156, v28, v29
	v_cvt_pk_bf16_f32 v157, v30, v31
	v_cvt_pk_bf16_f32 v140, v20, v21
	v_cvt_pk_bf16_f32 v141, v22, v23
	v_cvt_pk_bf16_f32 v138, v24, v25
	v_cvt_pk_bf16_f32 v139, v26, v27
	v_cvt_pk_bf16_f32 v136, v16, v17
	v_cvt_pk_bf16_f32 v137, v18, v19
	v_cvt_pk_bf16_f32 v134, v12, v13
	v_cvt_pk_bf16_f32 v135, v14, v15
	v_cvt_pk_bf16_f32 v132, v4, v5
	v_cvt_pk_bf16_f32 v133, v6, v7
	v_cvt_pk_bf16_f32 v130, v8, v9
	v_cvt_pk_bf16_f32 v131, v10, v11
	v_cvt_pk_bf16_f32 v128, v0, v1
	v_cvt_pk_bf16_f32 v129, v2, v3
	s_cbranch_scc0 .LBB0_2107
; DI void epi_plain(const Acc& acc, int brow, bf16_t* dst, int ld, int coff, const float* rs) {
;     EPI_IDX
; #pragma unroll
;     for (int ai = 0; ai < 2; ++ai)
; #pragma unroll
;         for (int m = 0; m < 4; ++m) {
;             const int lr = ai * 128 + wr * 64 + m * 16 + fr;
;             const float s = rs ? rs[lr] : 1.f;
;             bf16_t* rp = dst + (size_t)(brow + lr) * ld + coff + wc * 32 + fq * 4;
; #pragma unroll
;             for (int bj = 0; bj < 2; ++bj)
; #pragma unroll
;                 for (int n = 0; n < 2; ++n) { const f32x4 v = acc[ai][bj][m][n]; st4(rp + bj * 128 + n * 16, v[0] * s, v[1] * s, v[2] * s, v[3] * s); }
;         }
	s_lshl_b64 s[2:3], s[64:65], 13
	s_add_u32 s2, s26, s2
	s_addc_u32 s3, s27, s3
	v_mov_b32_e32 v146, v206
	s_lshl_b32 s6, s62, 9
	s_add_u32 s2, s2, s6
	v_and_b32_e32 v212, 15, v146
	v_ashrrev_i32_e32 v213, 2, v146
	v_and_or_b32 v212, v213, s92, v212
	s_addc_u32 s3, s3, 0
	v_lshrrev_b32_e32 v213, 1, v146
	v_and_b32_e32 v146, 0xc0, v146
	v_lshl_add_u64 v[214:215], s[2:3], 0, v[146:147]
	v_and_b32_e32 v146, 24, v213
	v_or_b32_e32 v218, 16, v212
	v_lshl_add_u64 v[214:215], v[214:215], 0, v[146:147]
	s_mov_b64 s[2:3], 0x1a3fc000
	v_ashrrev_i32_e32 v213, 31, v212
	v_ashrrev_i32_e32 v219, 31, v218
	v_lshl_add_u64 v[214:215], v[214:215], 0, s[2:3]
	v_lshlrev_b64 v[216:217], 13, v[212:213]
	v_lshlrev_b64 v[218:219], 13, v[218:219]
	v_lshl_add_u64 v[216:217], v[214:215], 0, v[216:217]
	v_lshl_add_u64 v[218:219], v[214:215], 0, v[218:219]
	global_store_dwordx2 v[216:217], v[204:205], off
	global_store_dwordx2 v[216:217], v[202:203], off offset:32
	global_store_dwordx2 v[216:217], v[200:201], off offset:256
	global_store_dwordx2 v[216:217], v[198:199], off offset:288
	global_store_dwordx2 v[218:219], v[196:197], off
	global_store_dwordx2 v[218:219], v[194:195], off offset:32
	global_store_dwordx2 v[218:219], v[192:193], off offset:256
	global_store_dwordx2 v[218:219], v[190:191], off offset:288
	v_or_b32_e32 v218, 32, v212
	v_or_b32_e32 v212, 48, v212
	v_ashrrev_i32_e32 v219, 31, v218
	v_ashrrev_i32_e32 v213, 31, v212
	v_lshlrev_b64 v[218:219], 13, v[218:219]
	v_lshlrev_b64 v[212:213], 13, v[212:213]
	v_lshl_add_u64 v[218:219], v[214:215], 0, v[218:219]
	v_lshl_add_u64 v[212:213], v[214:215], 0, v[212:213]
	s_mov_b64 s[2:3], 0x100000
	global_store_dwordx2 v[218:219], v[188:189], off
	global_store_dwordx2 v[218:219], v[186:187], off offset:32
	global_store_dwordx2 v[218:219], v[184:185], off offset:256
	global_store_dwordx2 v[218:219], v[182:183], off offset:288
	global_store_dwordx2 v[212:213], v[180:181], off
	global_store_dwordx2 v[212:213], v[178:179], off offset:32
	global_store_dwordx2 v[212:213], v[176:177], off offset:256
	global_store_dwordx2 v[212:213], v[174:175], off offset:288
	v_lshl_add_u64 v[212:213], v[216:217], 0, s[2:3]
	s_mov_b32 s2, 0x100000
	v_add_co_u32_e32 v214, vcc, s2, v216
	s_mov_b64 s[2:3], 0x120000
	s_nop 0
	v_addc_co_u32_e32 v215, vcc, 0, v217, vcc
	global_store_dwordx2 v[214:215], v[172:173], off
	global_store_dwordx2 v[212:213], v[170:171], off offset:32
	global_store_dwordx2 v[212:213], v[168:169], off offset:256
	global_store_dwordx2 v[212:213], v[166:167], off offset:288
	v_add_co_u32_e32 v214, vcc, s93, v216
	v_lshl_add_u64 v[212:213], v[216:217], 0, s[2:3]
	s_nop 0
	v_addc_co_u32_e32 v215, vcc, 0, v217, vcc
	global_store_dwordx2 v[214:215], v[164:165], off
	global_store_dwordx2 v[212:213], v[162:163], off offset:32
	global_store_dwordx2 v[212:213], v[160:161], off offset:256
	global_store_dwordx2 v[212:213], v[158:159], off offset:288
	v_add_co_u32_e32 v214, vcc, s94, v216
	v_lshl_add_u64 v[212:213], v[216:217], 0, s[16:17]
	s_nop 0
	v_addc_co_u32_e32 v215, vcc, 0, v217, vcc
	global_store_dwordx2 v[214:215], v[156:157], off
	global_store_dwordx2 v[212:213], v[140:141], off offset:32
	global_store_dwordx2 v[212:213], v[138:139], off offset:256
	global_store_dwordx2 v[212:213], v[136:137], off offset:288
	v_add_co_u32_e32 v214, vcc, s95, v216
	v_lshl_add_u64 v[212:213], v[216:217], 0, s[18:19]
	s_nop 0
	v_addc_co_u32_e32 v215, vcc, 0, v217, vcc
	global_store_dwordx2 v[214:215], v[134:135], off
	global_store_dwordx2 v[212:213], v[132:133], off offset:32
	global_store_dwordx2 v[212:213], v[130:131], off offset:256
	global_store_dwordx2 v[212:213], v[128:129], off offset:288
	s_mov_b64 s[6:7], 0

; #define WAIT_V(n) asm volatile("s_waitcnt vmcnt(" #n ")" ::: "memory")
; #define WAIT_L(n) asm volatile("s_waitcnt lgkmcnt(" #n ")" ::: "memory")
; #define BAR __builtin_amdgcn_s_barrier()
; #define SCHED __builtin_amdgcn_sched_barrier(0)
; template <class Get, class Epi>
; DI void gemm_stream(LAS unsigned char* lds, const int K, const int ld, Get get, Epi epi) {
;     ...
;             const bool last = (t == nt - 2);
;             const char* a1 = cA + (size_t)(t + 1) * kstep;
;             const char* a2 = last ? nA : cA + (size_t)(t + 2) * kstep;
;             const char* b2 = last ? nB : cB + (size_t)(t + 2) * kstep;
;             const char* a3 = a2 + kstep;
;             const char* b3 = b2 + kstep;
;             LDB(B0, 0, 0); SCHED; LDA(At, 0, 0); STAGE(SAo(1, 1), a1 + hstep);
;             WAIT_L(8); BAR; WAIT_L(0); MMA(0, 0, At, B0); BAR; SCHED;
;             LDB(B1, 0, 1); STAGE(SBo(0, 0), b2);
;             BAR; WAIT_L(0); MMA(0, 1, At, B1); BAR;
;             LDA(At, 0, 1); STAGE(SAo(0, 0), a2);
;             BAR; WAIT_L(0); MMA(1, 0, At, B0); BAR; SCHED;
;             STAGE(SBo(0, 1), b2 + hstep);
;             WAIT_V(6); BAR; MMA(1, 1, At, B1); BAR;
.LBB0_2670:
	ds_read_b128 v[128:131], v198
	ds_read_b128 v[132:135], v198 offset:1024
	ds_read_b128 v[136:139], v198 offset:2048
	ds_read_b128 v[140:143], v198 offset:3072
	s_add_u32 s8, s6, 0x100
	s_addc_u32 s9, s7, 0
	s_cmp_eq_u32 s16, 60
	s_cselect_b32 s13, s39, s9
	s_cselect_b32 s12, s38, s8
	s_cselect_b32 s11, s41, s15
	s_cselect_b32 s10, s40, s14
	s_mov_b32 m0, s52
	v_lshl_add_u64 v[186:187], s[6:7], 0, v[168:169]
	ds_read_b128 v[144:147], v199
	ds_read_b128 v[148:151], v199 offset:1024
	ds_read_b128 v[152:155], v199 offset:2048
	ds_read_b128 v[156:159], v199 offset:3072
	ds_read_b128 v[160:163], v199 offset:4096
	ds_read_b128 v[174:177], v199 offset:5120
	ds_read_b128 v[178:181], v199 offset:6144
	ds_read_b128 v[182:185], v199 offset:7168
	global_load_lds_dwordx4 v[186:187], off
	v_lshl_add_u64 v[186:187], s[6:7], 0, v[170:171]
	s_mov_b32 m0, s53
	s_nop 0
	global_load_lds_dwordx4 v[186:187], off
	s_waitcnt lgkmcnt(8)
	s_barrier
	s_waitcnt lgkmcnt(0)
	v_mfma_f32_16x16x32_bf16 v[124:127], v[128:131], v[144:147], v[124:127]
	v_mfma_f32_16x16x32_bf16 v[92:95], v[136:139], v[144:147], v[92:95]
	v_mfma_f32_16x16x32_bf16 v[120:123], v[128:131], v[152:155], v[120:123]
	v_mfma_f32_16x16x32_bf16 v[88:91], v[136:139], v[152:155], v[88:91]
	v_mfma_f32_16x16x32_bf16 v[116:119], v[128:131], v[160:163], v[116:119]
	v_mfma_f32_16x16x32_bf16 v[84:87], v[136:139], v[160:163], v[84:87]
	v_mfma_f32_16x16x32_bf16 v[112:115], v[128:131], v[178:181], v[112:115]
	v_mfma_f32_16x16x32_bf16 v[80:83], v[136:139], v[178:181], v[80:83]
	v_mfma_f32_16x16x32_bf16 v[124:127], v[132:135], v[148:151], v[124:127]
	v_mfma_f32_16x16x32_bf16 v[92:95], v[140:143], v[148:151], v[92:95]
	v_mfma_f32_16x16x32_bf16 v[120:123], v[132:135], v[156:159], v[120:123]
	v_mfma_f32_16x16x32_bf16 v[88:91], v[140:143], v[156:159], v[88:91]
	v_mfma_f32_16x16x32_bf16 v[116:119], v[132:135], v[174:177], v[116:119]
	v_mfma_f32_16x16x32_bf16 v[84:87], v[140:143], v[174:177], v[84:87]
	v_mfma_f32_16x16x32_bf16 v[112:115], v[132:135], v[182:185], v[112:115]
	v_mfma_f32_16x16x32_bf16 v[80:83], v[140:143], v[182:185], v[80:83]
	s_barrier
	s_mov_b32 m0, s58
	v_lshl_add_u64 v[204:205], s[10:11], 0, v[164:165]
	ds_read_b128 v[186:189], v200
	ds_read_b128 v[190:193], v200 offset:1024
	ds_read_b128 v[194:197], v200 offset:2048
	ds_read_b128 v[208:211], v200 offset:3072
	global_load_lds_dwordx4 v[204:205], off
	v_lshl_add_u64 v[212:213], s[10:11], 0, v[166:167]
	s_mov_b32 m0, s59
	s_nop 0
	global_load_lds_dwordx4 v[212:213], off
	s_barrier
	s_waitcnt lgkmcnt(0)
	v_mfma_f32_16x16x32_bf16 v[60:63], v[186:189], v[144:147], v[60:63]
	v_mfma_f32_16x16x32_bf16 v[28:31], v[194:197], v[144:147], v[28:31]
	v_mfma_f32_16x16x32_bf16 v[56:59], v[186:189], v[152:155], v[56:59]
	v_mfma_f32_16x16x32_bf16 v[24:27], v[194:197], v[152:155], v[24:27]
	v_mfma_f32_16x16x32_bf16 v[52:55], v[186:189], v[160:163], v[52:55]
	v_mfma_f32_16x16x32_bf16 v[20:23], v[194:197], v[160:163], v[20:23]
	v_mfma_f32_16x16x32_bf16 v[48:51], v[186:189], v[178:181], v[48:51]
	v_mfma_f32_16x16x32_bf16 v[16:19], v[194:197], v[178:181], v[16:19]
	v_mfma_f32_16x16x32_bf16 v[60:63], v[190:193], v[148:151], v[60:63]
	v_mfma_f32_16x16x32_bf16 v[28:31], v[208:211], v[148:151], v[28:31]
	v_mfma_f32_16x16x32_bf16 v[56:59], v[190:193], v[156:159], v[56:59]
	v_mfma_f32_16x16x32_bf16 v[24:27], v[208:211], v[156:159], v[24:27]
	v_mfma_f32_16x16x32_bf16 v[52:55], v[190:193], v[174:177], v[52:55]
	v_mfma_f32_16x16x32_bf16 v[20:23], v[208:211], v[174:177], v[20:23]
	v_mfma_f32_16x16x32_bf16 v[48:51], v[190:193], v[182:185], v[48:51]
	v_mfma_f32_16x16x32_bf16 v[16:19], v[208:211], v[182:185], v[16:19]
	s_barrier
	s_mov_b32 m0, s35
	v_lshl_add_u64 v[214:215], s[12:13], 0, v[164:165]
	ds_read_b128 v[144:147], v199 offset:16384
	ds_read_b128 v[148:151], v199 offset:17408
	ds_read_b128 v[152:155], v199 offset:18432
	ds_read_b128 v[156:159], v199 offset:19456
	ds_read_b128 v[160:163], v199 offset:20480
	ds_read_b128 v[174:177], v199 offset:21504
	ds_read_b128 v[178:181], v199 offset:22528
	ds_read_b128 v[182:185], v199 offset:23552
	global_load_lds_dwordx4 v[214:215], off
	v_lshl_add_u64 v[216:217], s[12:13], 0, v[166:167]
	s_mov_b32 m0, s44
	s_nop 0
	global_load_lds_dwordx4 v[216:217], off
	s_barrier
	s_waitcnt lgkmcnt(0)
	v_mfma_f32_16x16x32_bf16 v[108:111], v[128:131], v[144:147], v[108:111]
	v_mfma_f32_16x16x32_bf16 v[76:79], v[136:139], v[144:147], v[76:79]
	v_mfma_f32_16x16x32_bf16 v[104:107], v[128:131], v[152:155], v[104:107]
	v_mfma_f32_16x16x32_bf16 v[72:75], v[136:139], v[152:155], v[72:75]
	v_mfma_f32_16x16x32_bf16 v[100:103], v[128:131], v[160:163], v[100:103]
	v_mfma_f32_16x16x32_bf16 v[68:71], v[136:139], v[160:163], v[68:71]
	v_mfma_f32_16x16x32_bf16 v[96:99], v[128:131], v[178:181], v[96:99]
	v_mfma_f32_16x16x32_bf16 v[64:67], v[136:139], v[178:181], v[64:67]
	v_mfma_f32_16x16x32_bf16 v[108:111], v[132:135], v[148:151], v[108:111]
	v_mfma_f32_16x16x32_bf16 v[76:79], v[140:143], v[148:151], v[76:79]
	v_mfma_f32_16x16x32_bf16 v[104:107], v[132:135], v[156:159], v[104:107]
	v_mfma_f32_16x16x32_bf16 v[72:75], v[140:143], v[156:159], v[72:75]
	v_mfma_f32_16x16x32_bf16 v[100:103], v[132:135], v[174:177], v[100:103]
	v_mfma_f32_16x16x32_bf16 v[68:71], v[140:143], v[174:177], v[68:71]
	v_mfma_f32_16x16x32_bf16 v[96:99], v[132:135], v[182:185], v[96:99]
	v_mfma_f32_16x16x32_bf16 v[64:67], v[140:143], v[182:185], v[64:67]
	s_barrier
	s_add_u32 s6, s10, 0x100000
	s_addc_u32 s7, s11, 0
	s_mov_b32 m0, s60
	v_lshl_add_u64 v[128:129], s[6:7], 0, v[164:165]
	global_load_lds_dwordx4 v[128:129], off
	v_lshl_add_u64 v[128:129], s[6:7], 0, v[166:167]
	s_mov_b32 m0, s61
	s_nop 0
	global_load_lds_dwordx4 v[128:129], off
	s_waitcnt vmcnt(6)
	s_barrier
; #define WAIT_V(n) asm volatile("s_waitcnt vmcnt(" #n ")" ::: "memory")
; #define WAIT_L(n) asm volatile("s_waitcnt lgkmcnt(" #n ")" ::: "memory")
; #define BAR __builtin_amdgcn_s_barrier()
; #define SCHED __builtin_amdgcn_sched_barrier(0)
; template <class Get, class Epi>
; DI void gemm_stream(LAS unsigned char* lds, const int K, const int ld, Get get, Epi epi) {
;     ...
;             WAIT_V(6); BAR; MMA(1, 1, At, B1); BAR;
;             LDB(B0, 1, 0); SCHED; LDA(At, 1, 0); STAGE(SAo(0, 1), a2 + hstep);
;             WAIT_L(8); BAR; WAIT_L(0); MMA(0, 0, At, B0); BAR; SCHED;
;             LDB(B1, 1, 1); STAGE(SBo(1, 0), b3);
;             BAR; WAIT_L(0); MMA(0, 1, At, B1); BAR;
;             LDA(At, 1, 1); STAGE(SAo(1, 0), a3);
;             BAR; WAIT_L(0); MMA(1, 0, At, B0); BAR; SCHED;
	v_mfma_f32_16x16x32_bf16 v[44:47], v[186:189], v[144:147], v[44:47]
	v_mfma_f32_16x16x32_bf16 v[12:15], v[194:197], v[144:147], v[12:15]
	v_mfma_f32_16x16x32_bf16 v[40:43], v[186:189], v[152:155], v[40:43]
	v_mfma_f32_16x16x32_bf16 v[8:11], v[194:197], v[152:155], v[8:11]
	v_mfma_f32_16x16x32_bf16 v[36:39], v[186:189], v[160:163], v[36:39]
	v_mfma_f32_16x16x32_bf16 v[4:7], v[194:197], v[160:163], v[4:7]
	v_mfma_f32_16x16x32_bf16 v[32:35], v[186:189], v[178:181], v[32:35]
	v_mfma_f32_16x16x32_bf16 v[0:3], v[194:197], v[178:181], v[0:3]
	v_mfma_f32_16x16x32_bf16 v[44:47], v[190:193], v[148:151], v[44:47]
	v_mfma_f32_16x16x32_bf16 v[12:15], v[208:211], v[148:151], v[12:15]
	v_mfma_f32_16x16x32_bf16 v[40:43], v[190:193], v[156:159], v[40:43]
	v_mfma_f32_16x16x32_bf16 v[8:11], v[208:211], v[156:159], v[8:11]
	v_mfma_f32_16x16x32_bf16 v[36:39], v[190:193], v[174:177], v[36:39]
	v_mfma_f32_16x16x32_bf16 v[4:7], v[208:211], v[174:177], v[4:7]
	v_mfma_f32_16x16x32_bf16 v[32:35], v[190:193], v[182:185], v[32:35]
	v_mfma_f32_16x16x32_bf16 v[0:3], v[208:211], v[182:185], v[0:3]
	s_barrier
	ds_read_b128 v[128:131], v201
	ds_read_b128 v[132:135], v201 offset:1024
	ds_read_b128 v[136:139], v201 offset:2048
	ds_read_b128 v[140:143], v201 offset:3072
	s_add_u32 s6, s12, 0x100000
	s_addc_u32 s7, s13, 0
	s_mov_b32 m0, s45
	v_lshl_add_u64 v[186:187], s[6:7], 0, v[164:165]
	ds_read_b128 v[144:147], v199 offset:32768
	ds_read_b128 v[148:151], v199 offset:33792
	ds_read_b128 v[152:155], v199 offset:34816
	ds_read_b128 v[156:159], v199 offset:35840
	ds_read_b128 v[160:163], v199 offset:36864
	ds_read_b128 v[174:177], v199 offset:37888
	ds_read_b128 v[178:181], v199 offset:38912
	ds_read_b128 v[182:185], v199 offset:39936
	global_load_lds_dwordx4 v[186:187], off
	v_lshl_add_u64 v[186:187], s[6:7], 0, v[166:167]
	s_mov_b32 m0, s46
	s_nop 0
	global_load_lds_dwordx4 v[186:187], off
	s_waitcnt lgkmcnt(8)
	s_barrier
	s_waitcnt lgkmcnt(0)
	v_mfma_f32_16x16x32_bf16 v[124:127], v[128:131], v[144:147], v[124:127]
	v_mfma_f32_16x16x32_bf16 v[92:95], v[136:139], v[144:147], v[92:95]
	v_mfma_f32_16x16x32_bf16 v[120:123], v[128:131], v[152:155], v[120:123]
	v_mfma_f32_16x16x32_bf16 v[88:91], v[136:139], v[152:155], v[88:91]
	v_mfma_f32_16x16x32_bf16 v[116:119], v[128:131], v[160:163], v[116:119]
	v_mfma_f32_16x16x32_bf16 v[84:87], v[136:139], v[160:163], v[84:87]
	v_mfma_f32_16x16x32_bf16 v[112:115], v[128:131], v[178:181], v[112:115]
	v_mfma_f32_16x16x32_bf16 v[80:83], v[136:139], v[178:181], v[80:83]
	v_mfma_f32_16x16x32_bf16 v[124:127], v[132:135], v[148:151], v[124:127]
	v_mfma_f32_16x16x32_bf16 v[92:95], v[140:143], v[148:151], v[92:95]
	v_mfma_f32_16x16x32_bf16 v[120:123], v[132:135], v[156:159], v[120:123]
	v_mfma_f32_16x16x32_bf16 v[88:91], v[140:143], v[156:159], v[88:91]
	v_mfma_f32_16x16x32_bf16 v[116:119], v[132:135], v[174:177], v[116:119]
	v_mfma_f32_16x16x32_bf16 v[84:87], v[140:143], v[174:177], v[84:87]
	v_mfma_f32_16x16x32_bf16 v[112:115], v[132:135], v[182:185], v[112:115]
	v_mfma_f32_16x16x32_bf16 v[80:83], v[140:143], v[182:185], v[80:83]
	s_barrier
	s_mov_b32 m0, s64
	v_lshl_add_u64 v[204:205], v[204:205], 0, s[0:1]
	ds_read_b128 v[186:189], v202
	ds_read_b128 v[190:193], v202 offset:1024
	ds_read_b128 v[194:197], v202 offset:2048
	ds_read_b128 v[208:211], v202 offset:3072
	global_load_lds_dwordx4 v[204:205], off
	v_lshl_add_u64 v[204:205], v[212:213], 0, s[0:1]
	s_mov_b32 m0, s65
	s_nop 0
	global_load_lds_dwordx4 v[204:205], off
	s_barrier
	s_waitcnt lgkmcnt(0)
	v_mfma_f32_16x16x32_bf16 v[60:63], v[186:189], v[144:147], v[60:63]
	v_mfma_f32_16x16x32_bf16 v[28:31], v[194:197], v[144:147], v[28:31]
	v_mfma_f32_16x16x32_bf16 v[56:59], v[186:189], v[152:155], v[56:59]
	v_mfma_f32_16x16x32_bf16 v[24:27], v[194:197], v[152:155], v[24:27]
	v_mfma_f32_16x16x32_bf16 v[52:55], v[186:189], v[160:163], v[52:55]
	v_mfma_f32_16x16x32_bf16 v[20:23], v[194:197], v[160:163], v[20:23]
	v_mfma_f32_16x16x32_bf16 v[48:51], v[186:189], v[178:181], v[48:51]
	v_mfma_f32_16x16x32_bf16 v[16:19], v[194:197], v[178:181], v[16:19]
	v_mfma_f32_16x16x32_bf16 v[60:63], v[190:193], v[148:151], v[60:63]
	v_mfma_f32_16x16x32_bf16 v[28:31], v[208:211], v[148:151], v[28:31]
	v_mfma_f32_16x16x32_bf16 v[56:59], v[190:193], v[156:159], v[56:59]
	v_mfma_f32_16x16x32_bf16 v[24:27], v[208:211], v[156:159], v[24:27]
	v_mfma_f32_16x16x32_bf16 v[52:55], v[190:193], v[174:177], v[52:55]
	v_mfma_f32_16x16x32_bf16 v[20:23], v[208:211], v[174:177], v[20:23]
	v_mfma_f32_16x16x32_bf16 v[48:51], v[190:193], v[182:185], v[48:51]
	v_mfma_f32_16x16x32_bf16 v[16:19], v[208:211], v[182:185], v[16:19]
	s_barrier
	s_mov_b32 m0, s47
	v_lshl_add_u64 v[204:205], v[214:215], 0, s[0:1]
	ds_read_b128 v[144:147], v199 offset:49152
	ds_read_b128 v[148:151], v199 offset:50176
	ds_read_b128 v[152:155], v199 offset:51200
	ds_read_b128 v[156:159], v199 offset:52224
	ds_read_b128 v[160:163], v199 offset:53248
	ds_read_b128 v[174:177], v199 offset:54272
	ds_read_b128 v[178:181], v199 offset:55296
	ds_read_b128 v[182:185], v199 offset:56320
	global_load_lds_dwordx4 v[204:205], off
	v_lshl_add_u64 v[204:205], v[216:217], 0, s[0:1]
	s_mov_b32 m0, s48
	s_nop 0
	global_load_lds_dwordx4 v[204:205], off
	s_barrier
; #define WAIT_V(n) asm volatile("s_waitcnt vmcnt(" #n ")" ::: "memory")
; #define WAIT_L(n) asm volatile("s_waitcnt lgkmcnt(" #n ")" ::: "memory")
; #define BAR __builtin_amdgcn_s_barrier()
; #define SCHED __builtin_amdgcn_sched_barrier(0)
; #define EPI_DONE do { } while (0)
; template <class Get, class Epi>
; DI void gemm_stream(LAS unsigned char* lds, const int K, const int ld, Get get, Epi epi) {
;     ...
;             BAR; WAIT_L(0); MMA(1, 0, At, B0); BAR; SCHED;
;             STAGE(SBo(1, 1), b3 + hstep);
;             WAIT_V(6); BAR; MMA(1, 1, At, B1); BAR;
;         }
; DI void epi_resid(const Acc& acc, const P& p, int brow, int bcol, int layer, int gch, bool from_input) {
;     EPI_IDX
;     const float* gate = modv(p, layer, brow, gch);
; #pragma unroll
;     for (int bj = 0; bj < 2; ++bj)
; #pragma unroll
;         for (int n = 0; n < 2; ++n) {
;             const int c0 = bcol + bj * 128 + wc * 32 + n * 16 + fq * 4;
;             const f32x4 g = *(const f32x4*)(gate + c0);
;             f32x4 xv[2][4];
; #pragma unroll
;             for (int ai = 0; ai < 2; ++ai)
; #pragma unroll
;                 for (int m = 0; m < 4; ++m) {
;                     const int r = brow + ai * 128 + wr * 64 + m * 16 + fr;
;                     const float* sp = (from_input ? inrow(p, r) : xrow(p, r)) + c0;
;                     xv[ai][m] = *(const f32x4*)sp;
;                 }
;             __builtin_amdgcn_sched_barrier(0);
; #pragma unroll
;             for (int ai = 0; ai < 2; ++ai)
; #pragma unroll
;                 for (int m = 0; m < 4; ++m) {
;                     const int r = brow + ai * 128 + wr * 64 + m * 16 + fr;
;                     *(f32x4*)(xrow(p, r) + c0) = xv[ai][m] + g * acc[ai][bj][m][n];
;                 }
;             __builtin_amdgcn_sched_barrier(0);
;         }
;     EPI_DONE;
; }
	s_waitcnt lgkmcnt(0)
	v_mfma_f32_16x16x32_bf16 v[108:111], v[128:131], v[144:147], v[108:111]
	v_mfma_f32_16x16x32_bf16 v[76:79], v[136:139], v[144:147], v[76:79]
	v_mfma_f32_16x16x32_bf16 v[104:107], v[128:131], v[152:155], v[104:107]
	v_mfma_f32_16x16x32_bf16 v[72:75], v[136:139], v[152:155], v[72:75]
	v_mfma_f32_16x16x32_bf16 v[100:103], v[128:131], v[160:163], v[100:103]
	v_mfma_f32_16x16x32_bf16 v[68:71], v[136:139], v[160:163], v[68:71]
	v_mfma_f32_16x16x32_bf16 v[96:99], v[128:131], v[178:181], v[96:99]
	v_mfma_f32_16x16x32_bf16 v[64:67], v[136:139], v[178:181], v[64:67]
	v_mfma_f32_16x16x32_bf16 v[108:111], v[132:135], v[148:151], v[108:111]
	v_mfma_f32_16x16x32_bf16 v[76:79], v[140:143], v[148:151], v[76:79]
	v_mfma_f32_16x16x32_bf16 v[104:107], v[132:135], v[156:159], v[104:107]
	v_mfma_f32_16x16x32_bf16 v[72:75], v[140:143], v[156:159], v[72:75]
	v_mfma_f32_16x16x32_bf16 v[100:103], v[132:135], v[174:177], v[100:103]
	v_mfma_f32_16x16x32_bf16 v[68:71], v[140:143], v[174:177], v[68:71]
	v_mfma_f32_16x16x32_bf16 v[96:99], v[132:135], v[182:185], v[96:99]
	v_mfma_f32_16x16x32_bf16 v[64:67], v[140:143], v[182:185], v[64:67]
	s_barrier
	s_add_u32 s6, s10, 0x100080
	s_addc_u32 s7, s11, 0
	s_mov_b32 m0, s68
	v_lshl_add_u64 v[128:129], s[6:7], 0, v[164:165]
	global_load_lds_dwordx4 v[128:129], off
	v_lshl_add_u64 v[128:129], s[6:7], 0, v[166:167]
	s_mov_b32 m0, s69
	s_nop 0
	global_load_lds_dwordx4 v[128:129], off
	s_add_i32 s16, s16, 2
	s_add_u32 s14, s14, 0x100
	s_addc_u32 s15, s15, 0
	s_cmp_gt_u32 s16, 61
	s_mov_b64 s[6:7], s[8:9]
	s_waitcnt vmcnt(6)
	s_barrier
	v_mfma_f32_16x16x32_bf16 v[44:47], v[186:189], v[144:147], v[44:47]
	v_mfma_f32_16x16x32_bf16 v[12:15], v[194:197], v[144:147], v[12:15]
	v_mfma_f32_16x16x32_bf16 v[40:43], v[186:189], v[152:155], v[40:43]
	v_mfma_f32_16x16x32_bf16 v[8:11], v[194:197], v[152:155], v[8:11]
	v_mfma_f32_16x16x32_bf16 v[36:39], v[186:189], v[160:163], v[36:39]
	v_mfma_f32_16x16x32_bf16 v[4:7], v[194:197], v[160:163], v[4:7]
	v_mfma_f32_16x16x32_bf16 v[32:35], v[186:189], v[178:181], v[32:35]
	v_mfma_f32_16x16x32_bf16 v[0:3], v[194:197], v[178:181], v[0:3]
	v_mfma_f32_16x16x32_bf16 v[44:47], v[190:193], v[148:151], v[44:47]
	v_mfma_f32_16x16x32_bf16 v[12:15], v[208:211], v[148:151], v[12:15]
	v_mfma_f32_16x16x32_bf16 v[40:43], v[190:193], v[156:159], v[40:43]
	v_mfma_f32_16x16x32_bf16 v[8:11], v[208:211], v[156:159], v[8:11]
	v_mfma_f32_16x16x32_bf16 v[36:39], v[190:193], v[174:177], v[36:39]
	v_mfma_f32_16x16x32_bf16 v[4:7], v[208:211], v[174:177], v[4:7]
	v_mfma_f32_16x16x32_bf16 v[32:35], v[190:193], v[182:185], v[32:35]
	v_mfma_f32_16x16x32_bf16 v[0:3], v[208:211], v[182:185], v[0:3]
	s_barrier
	s_cbranch_scc0 .LBB0_2670
	s_lshl_b32 s12, s3, 21
	s_lshl_b32 s13, s2, 10
	s_lshr_b32 s16, s3, 4
	s_add_u32 s12, s12, s13
	s_mul_i32 s16, s16, 6
	s_add_i32 s16, s16, 32
	s_lshl_b32 s16, s16, 13
	s_add_u32 s16, s16, s13
	s_add_u32 s10, s26, s16
	s_addc_u32 s11, s27, 0
	s_add_u32 s6, s24, s12
	s_addc_u32 s7, s25, 0
	v_lshrrev_b32_e32 v224, 6, v206
	v_and_b32_e32 v225, 3, v224
	v_lshrrev_b32_e32 v224, 2, v224
	v_and_b32_e32 v205, 15, v206
	v_bfe_u32 v226, v206, 4, 2
	v_lshl_add_u32 v225, v225, 3, v226
	v_lshl_add_u32 v224, v224, 6, v205
	v_lshlrev_b32_e32 v205, 4, v225
	v_lshl_add_u32 v203, v224, 13, v205
	v_mov_b32_e32 v204, v203
	global_load_dwordx4 v[128:131], v205, s[10:11] offset:0
	global_load_dwordx4 v[132:135], v205, s[10:11] offset:64
	global_load_dwordx4 v[136:139], v205, s[10:11] offset:512
	global_load_dwordx4 v[140:143], v205, s[10:11] offset:576
	global_load_dwordx4 v[144:147], v203, s[6:7] offset:0
	global_load_dwordx4 v[148:151], v203, s[6:7] offset:64
	global_load_dwordx4 v[152:155], v203, s[6:7] offset:512
	global_load_dwordx4 v[156:159], v203, s[6:7] offset:576
	v_add_u32_e32 v203, 0x20000, v203
	global_load_dwordx4 v[160:163], v203, s[6:7] offset:0
	global_load_dwordx4 v[174:177], v203, s[6:7] offset:64
	global_load_dwordx4 v[178:181], v203, s[6:7] offset:512
	global_load_dwordx4 v[182:185], v203, s[6:7] offset:576
	v_add_u32_e32 v203, 0x20000, v203
	global_load_dwordx4 v[186:189], v203, s[6:7] offset:0
	global_load_dwordx4 v[190:193], v203, s[6:7] offset:64
	global_load_dwordx4 v[194:197], v203, s[6:7] offset:512
	global_load_dwordx4 v[208:211], v203, s[6:7] offset:576
	v_add_u32_e32 v203, 0x20000, v203
	global_load_dwordx4 v[212:215], v203, s[6:7] offset:0
	global_load_dwordx4 v[216:219], v203, s[6:7] offset:64
	global_load_dwordx4 v[220:223], v203, s[6:7] offset:512
	global_load_dwordx4 v[224:227], v203, s[6:7] offset:576
	v_add_u32_e32 v203, 0xa0000, v203
	s_waitcnt vmcnt(12)
	v_pk_fma_f32 v[124:125], v[124:125], v[128:129], v[144:145]
	v_pk_fma_f32 v[126:127], v[126:127], v[130:131], v[146:147]
	v_pk_fma_f32 v[92:93], v[92:93], v[132:133], v[148:149]
	v_pk_fma_f32 v[94:95], v[94:95], v[134:135], v[150:151]
	v_pk_fma_f32 v[60:61], v[60:61], v[136:137], v[152:153]
	v_pk_fma_f32 v[62:63], v[62:63], v[138:139], v[154:155]
	v_pk_fma_f32 v[28:29], v[28:29], v[140:141], v[156:157]
	v_pk_fma_f32 v[30:31], v[30:31], v[142:143], v[158:159]
	global_store_dwordx4 v204, v[124:127], s[6:7] offset:0
	global_store_dwordx4 v204, v[92:95], s[6:7] offset:64
	global_store_dwordx4 v204, v[60:63], s[6:7] offset:512
	global_store_dwordx4 v204, v[28:31], s[6:7] offset:576
	v_add_u32_e32 v204, 0x20000, v204
	global_load_dwordx4 v[144:147], v203, s[6:7] offset:0
	global_load_dwordx4 v[148:151], v203, s[6:7] offset:64
	global_load_dwordx4 v[152:155], v203, s[6:7] offset:512
	global_load_dwordx4 v[156:159], v203, s[6:7] offset:576
	v_add_u32_e32 v203, 0x20000, v203
	s_waitcnt vmcnt(16)
; DI void epi_resid(const Acc& acc, const P& p, int brow, int bcol, int layer, int gch, bool from_input) {
;     ...
; #pragma unroll
;     for (int bj = 0; bj < 2; ++bj)
; #pragma unroll
;         for (int n = 0; n < 2; ++n) {
;             const int c0 = bcol + bj * 128 + wc * 32 + n * 16 + fq * 4;
;             const f32x4 g = *(const f32x4*)(gate + c0);
;             f32x4 xv[2][4];
; #pragma unroll
;             for (int ai = 0; ai < 2; ++ai)
; #pragma unroll
;                 for (int m = 0; m < 4; ++m) {
;                     const int r = brow + ai * 128 + wr * 64 + m * 16 + fr;
;                     const float* sp = (from_input ? inrow(p, r) : xrow(p, r)) + c0;
;                     xv[ai][m] = *(const f32x4*)sp;
;                 }
;             __builtin_amdgcn_sched_barrier(0);
; #pragma unroll
;             for (int ai = 0; ai < 2; ++ai)
; #pragma unroll
;                 for (int m = 0; m < 4; ++m) {
;                     const int r = brow + ai * 128 + wr * 64 + m * 16 + fr;
;                     *(f32x4*)(xrow(p, r) + c0) = xv[ai][m] + g * acc[ai][bj][m][n];
;                 }
;             __builtin_amdgcn_sched_barrier(0);
;         }
	v_pk_fma_f32 v[120:121], v[120:121], v[128:129], v[160:161]
	v_pk_fma_f32 v[122:123], v[122:123], v[130:131], v[162:163]
	v_pk_fma_f32 v[88:89], v[88:89], v[132:133], v[174:175]
	v_pk_fma_f32 v[90:91], v[90:91], v[134:135], v[176:177]
	v_pk_fma_f32 v[56:57], v[56:57], v[136:137], v[178:179]
	v_pk_fma_f32 v[58:59], v[58:59], v[138:139], v[180:181]
	v_pk_fma_f32 v[24:25], v[24:25], v[140:141], v[182:183]
	v_pk_fma_f32 v[26:27], v[26:27], v[142:143], v[184:185]
	global_store_dwordx4 v204, v[120:123], s[6:7] offset:0
	global_store_dwordx4 v204, v[88:91], s[6:7] offset:64
	global_store_dwordx4 v204, v[56:59], s[6:7] offset:512
	global_store_dwordx4 v204, v[24:27], s[6:7] offset:576
	v_add_u32_e32 v204, 0x20000, v204
	global_load_dwordx4 v[160:163], v203, s[6:7] offset:0
	global_load_dwordx4 v[174:177], v203, s[6:7] offset:64
	global_load_dwordx4 v[178:181], v203, s[6:7] offset:512
	global_load_dwordx4 v[182:185], v203, s[6:7] offset:576
	v_add_u32_e32 v203, 0x20000, v203
	s_waitcnt vmcnt(20)
	v_pk_fma_f32 v[116:117], v[116:117], v[128:129], v[186:187]
	v_pk_fma_f32 v[118:119], v[118:119], v[130:131], v[188:189]
	v_pk_fma_f32 v[84:85], v[84:85], v[132:133], v[190:191]
	v_pk_fma_f32 v[86:87], v[86:87], v[134:135], v[192:193]
	v_pk_fma_f32 v[52:53], v[52:53], v[136:137], v[194:195]
	v_pk_fma_f32 v[54:55], v[54:55], v[138:139], v[196:197]
	v_pk_fma_f32 v[20:21], v[20:21], v[140:141], v[208:209]
	v_pk_fma_f32 v[22:23], v[22:23], v[142:143], v[210:211]
	global_store_dwordx4 v204, v[116:119], s[6:7] offset:0
	global_store_dwordx4 v204, v[84:87], s[6:7] offset:64
	global_store_dwordx4 v204, v[52:55], s[6:7] offset:512
	global_store_dwordx4 v204, v[20:23], s[6:7] offset:576
	v_add_u32_e32 v204, 0x20000, v204
	global_load_dwordx4 v[186:189], v203, s[6:7] offset:0
	global_load_dwordx4 v[190:193], v203, s[6:7] offset:64
	global_load_dwordx4 v[194:197], v203, s[6:7] offset:512
	global_load_dwordx4 v[208:211], v203, s[6:7] offset:576
	v_add_u32_e32 v203, 0x20000, v203
	s_waitcnt vmcnt(24)
	v_pk_fma_f32 v[112:113], v[112:113], v[128:129], v[212:213]
	v_pk_fma_f32 v[114:115], v[114:115], v[130:131], v[214:215]
	v_pk_fma_f32 v[80:81], v[80:81], v[132:133], v[216:217]
	v_pk_fma_f32 v[82:83], v[82:83], v[134:135], v[218:219]
	v_pk_fma_f32 v[48:49], v[48:49], v[136:137], v[220:221]
	v_pk_fma_f32 v[50:51], v[50:51], v[138:139], v[222:223]
	v_pk_fma_f32 v[16:17], v[16:17], v[140:141], v[224:225]
	v_pk_fma_f32 v[18:19], v[18:19], v[142:143], v[226:227]
	global_store_dwordx4 v204, v[112:115], s[6:7] offset:0
	global_store_dwordx4 v204, v[80:83], s[6:7] offset:64
	global_store_dwordx4 v204, v[48:51], s[6:7] offset:512
	global_store_dwordx4 v204, v[16:19], s[6:7] offset:576
	v_add_u32_e32 v204, 0xa0000, v204
	global_load_dwordx4 v[212:215], v203, s[6:7] offset:0
	global_load_dwordx4 v[216:219], v203, s[6:7] offset:64
	global_load_dwordx4 v[220:223], v203, s[6:7] offset:512
	global_load_dwordx4 v[224:227], v203, s[6:7] offset:576
	s_waitcnt vmcnt(24)
	v_pk_fma_f32 v[108:109], v[108:109], v[128:129], v[144:145]
	v_pk_fma_f32 v[110:111], v[110:111], v[130:131], v[146:147]
	v_pk_fma_f32 v[76:77], v[76:77], v[132:133], v[148:149]
	v_pk_fma_f32 v[78:79], v[78:79], v[134:135], v[150:151]
	v_pk_fma_f32 v[44:45], v[44:45], v[136:137], v[152:153]
	v_pk_fma_f32 v[46:47], v[46:47], v[138:139], v[154:155]
	v_pk_fma_f32 v[12:13], v[12:13], v[140:141], v[156:157]
	v_pk_fma_f32 v[14:15], v[14:15], v[142:143], v[158:159]
	global_store_dwordx4 v204, v[108:111], s[6:7] offset:0
	global_store_dwordx4 v204, v[76:79], s[6:7] offset:64
	global_store_dwordx4 v204, v[44:47], s[6:7] offset:512
	global_store_dwordx4 v204, v[12:15], s[6:7] offset:576
	v_add_u32_e32 v204, 0x20000, v204
	s_waitcnt vmcnt(20)
	v_pk_fma_f32 v[104:105], v[104:105], v[128:129], v[160:161]
	v_pk_fma_f32 v[106:107], v[106:107], v[130:131], v[162:163]
	v_pk_fma_f32 v[72:73], v[72:73], v[132:133], v[174:175]
	v_pk_fma_f32 v[74:75], v[74:75], v[134:135], v[176:177]
	v_pk_fma_f32 v[40:41], v[40:41], v[136:137], v[178:179]
	v_pk_fma_f32 v[42:43], v[42:43], v[138:139], v[180:181]
	v_pk_fma_f32 v[8:9], v[8:9], v[140:141], v[182:183]
	v_pk_fma_f32 v[10:11], v[10:11], v[142:143], v[184:185]
	global_store_dwordx4 v204, v[104:107], s[6:7] offset:0
	global_store_dwordx4 v204, v[72:75], s[6:7] offset:64
	global_store_dwordx4 v204, v[40:43], s[6:7] offset:512
	global_store_dwordx4 v204, v[8:11], s[6:7] offset:576
	v_add_u32_e32 v204, 0x20000, v204
	s_waitcnt vmcnt(16)
	v_pk_fma_f32 v[100:101], v[100:101], v[128:129], v[186:187]
	v_pk_fma_f32 v[102:103], v[102:103], v[130:131], v[188:189]
	v_pk_fma_f32 v[68:69], v[68:69], v[132:133], v[190:191]
	v_pk_fma_f32 v[70:71], v[70:71], v[134:135], v[192:193]
	v_pk_fma_f32 v[36:37], v[36:37], v[136:137], v[194:195]
	v_pk_fma_f32 v[38:39], v[38:39], v[138:139], v[196:197]
	v_pk_fma_f32 v[4:5], v[4:5], v[140:141], v[208:209]
	v_pk_fma_f32 v[6:7], v[6:7], v[142:143], v[210:211]
	global_store_dwordx4 v204, v[100:103], s[6:7] offset:0
	global_store_dwordx4 v204, v[68:71], s[6:7] offset:64
	global_store_dwordx4 v204, v[36:39], s[6:7] offset:512
	global_store_dwordx4 v204, v[4:7], s[6:7] offset:576
	v_add_u32_e32 v204, 0x20000, v204
	s_waitcnt vmcnt(12)
	v_pk_fma_f32 v[96:97], v[96:97], v[128:129], v[212:213]
	v_pk_fma_f32 v[98:99], v[98:99], v[130:131], v[214:215]
	v_pk_fma_f32 v[64:65], v[64:65], v[132:133], v[216:217]
	v_pk_fma_f32 v[66:67], v[66:67], v[134:135], v[218:219]
	v_pk_fma_f32 v[32:33], v[32:33], v[136:137], v[220:221]
	v_pk_fma_f32 v[34:35], v[34:35], v[138:139], v[222:223]
	v_pk_fma_f32 v[0:1], v[0:1], v[140:141], v[224:225]
	v_pk_fma_f32 v[2:3], v[2:3], v[142:143], v[226:227]
	global_store_dwordx4 v204, v[96:99], s[6:7] offset:0
	global_store_dwordx4 v204, v[64:67], s[6:7] offset:64
	global_store_dwordx4 v204, v[32:35], s[6:7] offset:512
	global_store_dwordx4 v204, v[0:3], s[6:7] offset:576
	s_branch .Lresid_latch_wout1

; #define WAIT_V(n) asm volatile("s_waitcnt vmcnt(" #n ")" ::: "memory")
; #define WAIT_L(n) asm volatile("s_waitcnt lgkmcnt(" #n ")" ::: "memory")
; #define BAR __builtin_amdgcn_s_barrier()
; #define SCHED __builtin_amdgcn_sched_barrier(0)
; template <class Get, class Epi>
; DI void gemm_stream(LAS unsigned char* lds, const int K, const int ld, Get get, Epi epi) {
;     ...
;             const bool last = (t == nt - 2);
;             const char* a1 = cA + (size_t)(t + 1) * kstep;
;             const char* a2 = last ? nA : cA + (size_t)(t + 2) * kstep;
;             const char* b2 = last ? nB : cB + (size_t)(t + 2) * kstep;
;             const char* a3 = a2 + kstep;
;             const char* b3 = b2 + kstep;
;             LDB(B0, 0, 0); SCHED; LDA(At, 0, 0); STAGE(SAo(1, 1), a1 + hstep);
;             WAIT_L(8); BAR; WAIT_L(0); MMA(0, 0, At, B0); BAR; SCHED;
;             LDB(B1, 0, 1); STAGE(SBo(0, 0), b2);
;             BAR; WAIT_L(0); MMA(0, 1, At, B1); BAR;
;             LDA(At, 0, 1); STAGE(SAo(0, 0), a2);
;             BAR; WAIT_L(0); MMA(1, 0, At, B0); BAR; SCHED;
;             STAGE(SBo(0, 1), b2 + hstep);
;             WAIT_V(6); BAR; MMA(1, 1, At, B1); BAR;
.LBB0_3046:
	ds_read_b128 v[148:151], v142
	ds_read_b128 v[152:155], v142 offset:1024
	ds_read_b128 v[156:159], v142 offset:2048
	ds_read_b128 v[160:163], v142 offset:3072
	s_add_u32 s14, s12, 0xfff80080
	s_addc_u32 s15, s13, -1
	s_cmp_eq_u32 s56, 28
	s_cselect_b32 s17, s9, s15
	s_cselect_b32 s16, s8, s14
	s_cselect_b32 s15, s11, s55
	s_cselect_b32 s14, s10, s0
	s_mov_b32 m0, s38
	v_lshl_add_u64 v[140:141], s[12:13], 0, v[134:135]
	ds_read_b128 v[164:167], v143
	ds_read_b128 v[168:171], v143 offset:1024
	ds_read_b128 v[172:175], v143 offset:2048
	ds_read_b128 v[176:179], v143 offset:3072
	ds_read_b128 v[180:183], v143 offset:4096
	ds_read_b128 v[184:187], v143 offset:5120
	ds_read_b128 v[188:191], v143 offset:6144
	ds_read_b128 v[192:195], v143 offset:7168
	global_load_lds_dwordx4 v[140:141], off
	v_lshl_add_u64 v[140:141], s[12:13], 0, v[136:137]
	s_mov_b32 m0, s39
	s_nop 0
	global_load_lds_dwordx4 v[140:141], off
	s_waitcnt lgkmcnt(8)
	s_barrier
	s_waitcnt lgkmcnt(0)
	v_mfma_f32_16x16x32_bf16 v[124:127], v[148:151], v[164:167], v[124:127]
	v_mfma_f32_16x16x32_bf16 v[116:119], v[156:159], v[164:167], v[116:119]
	v_mfma_f32_16x16x32_bf16 v[108:111], v[148:151], v[172:175], v[108:111]
	v_mfma_f32_16x16x32_bf16 v[100:103], v[156:159], v[172:175], v[100:103]
	v_mfma_f32_16x16x32_bf16 v[92:95], v[148:151], v[180:183], v[92:95]
	v_mfma_f32_16x16x32_bf16 v[84:87], v[156:159], v[180:183], v[84:87]
	v_mfma_f32_16x16x32_bf16 v[76:79], v[148:151], v[188:191], v[76:79]
	v_mfma_f32_16x16x32_bf16 v[68:71], v[156:159], v[188:191], v[68:71]
	v_mfma_f32_16x16x32_bf16 v[124:127], v[152:155], v[168:171], v[124:127]
	v_mfma_f32_16x16x32_bf16 v[116:119], v[160:163], v[168:171], v[116:119]
	v_mfma_f32_16x16x32_bf16 v[108:111], v[152:155], v[176:179], v[108:111]
	v_mfma_f32_16x16x32_bf16 v[100:103], v[160:163], v[176:179], v[100:103]
	v_mfma_f32_16x16x32_bf16 v[92:95], v[152:155], v[184:187], v[92:95]
	v_mfma_f32_16x16x32_bf16 v[84:87], v[160:163], v[184:187], v[84:87]
	v_mfma_f32_16x16x32_bf16 v[76:79], v[152:155], v[192:195], v[76:79]
	v_mfma_f32_16x16x32_bf16 v[68:71], v[160:163], v[192:195], v[68:71]
	s_barrier
	s_mov_b32 m0, s40
	v_lshl_add_u64 v[140:141], s[14:15], 0, v[130:131]
	ds_read_b128 v[196:199], v144
	ds_read_b128 v[200:203], v144 offset:1024
	ds_read_b128 v[208:211], v144 offset:2048
	ds_read_b128 v[212:215], v144 offset:3072
	global_load_lds_dwordx4 v[140:141], off
	v_lshl_add_u64 v[204:205], s[14:15], 0, v[128:129]
	s_mov_b32 m0, s41
	s_nop 0
	global_load_lds_dwordx4 v[204:205], off
	s_barrier
	s_waitcnt lgkmcnt(0)
	v_mfma_f32_16x16x32_bf16 v[120:123], v[196:199], v[164:167], v[120:123]
	v_mfma_f32_16x16x32_bf16 v[112:115], v[208:211], v[164:167], v[112:115]
	v_mfma_f32_16x16x32_bf16 v[104:107], v[196:199], v[172:175], v[104:107]
	v_mfma_f32_16x16x32_bf16 v[96:99], v[208:211], v[172:175], v[96:99]
	v_mfma_f32_16x16x32_bf16 v[88:91], v[196:199], v[180:183], v[88:91]
	v_mfma_f32_16x16x32_bf16 v[80:83], v[208:211], v[180:183], v[80:83]
	v_mfma_f32_16x16x32_bf16 v[72:75], v[196:199], v[188:191], v[72:75]
	v_mfma_f32_16x16x32_bf16 v[64:67], v[208:211], v[188:191], v[64:67]
	v_mfma_f32_16x16x32_bf16 v[120:123], v[200:203], v[168:171], v[120:123]
	v_mfma_f32_16x16x32_bf16 v[112:115], v[212:215], v[168:171], v[112:115]
	v_mfma_f32_16x16x32_bf16 v[104:107], v[200:203], v[176:179], v[104:107]
	v_mfma_f32_16x16x32_bf16 v[96:99], v[212:215], v[176:179], v[96:99]
	v_mfma_f32_16x16x32_bf16 v[88:91], v[200:203], v[184:187], v[88:91]
	v_mfma_f32_16x16x32_bf16 v[80:83], v[212:215], v[184:187], v[80:83]
	v_mfma_f32_16x16x32_bf16 v[72:75], v[200:203], v[192:195], v[72:75]
	v_mfma_f32_16x16x32_bf16 v[64:67], v[212:215], v[192:195], v[64:67]
	s_barrier
	s_mov_b32 m0, s19
	v_lshl_add_u64 v[216:217], s[16:17], 0, v[130:131]
	ds_read_b128 v[164:167], v143 offset:16384
	ds_read_b128 v[168:171], v143 offset:17408
	ds_read_b128 v[172:175], v143 offset:18432
	ds_read_b128 v[176:179], v143 offset:19456
	ds_read_b128 v[180:183], v143 offset:20480
	ds_read_b128 v[184:187], v143 offset:21504
	ds_read_b128 v[188:191], v143 offset:22528
	ds_read_b128 v[192:195], v143 offset:23552
	global_load_lds_dwordx4 v[216:217], off
	v_lshl_add_u64 v[218:219], s[16:17], 0, v[128:129]
	s_mov_b32 m0, s20
	s_nop 0
	global_load_lds_dwordx4 v[218:219], off
	s_barrier
	s_waitcnt lgkmcnt(0)
	v_mfma_f32_16x16x32_bf16 v[60:63], v[148:151], v[164:167], v[60:63]
	v_mfma_f32_16x16x32_bf16 v[52:55], v[156:159], v[164:167], v[52:55]
	v_mfma_f32_16x16x32_bf16 v[44:47], v[148:151], v[172:175], v[44:47]
	v_mfma_f32_16x16x32_bf16 v[36:39], v[156:159], v[172:175], v[36:39]
	v_mfma_f32_16x16x32_bf16 v[28:31], v[148:151], v[180:183], v[28:31]
	v_mfma_f32_16x16x32_bf16 v[20:23], v[156:159], v[180:183], v[20:23]
	v_mfma_f32_16x16x32_bf16 v[12:15], v[148:151], v[188:191], v[12:15]
	v_mfma_f32_16x16x32_bf16 v[4:7], v[156:159], v[188:191], v[4:7]
	v_mfma_f32_16x16x32_bf16 v[60:63], v[152:155], v[168:171], v[60:63]
	v_mfma_f32_16x16x32_bf16 v[52:55], v[160:163], v[168:171], v[52:55]
	v_mfma_f32_16x16x32_bf16 v[44:47], v[152:155], v[176:179], v[44:47]
	v_mfma_f32_16x16x32_bf16 v[36:39], v[160:163], v[176:179], v[36:39]
	v_mfma_f32_16x16x32_bf16 v[28:31], v[152:155], v[184:187], v[28:31]
	v_mfma_f32_16x16x32_bf16 v[20:23], v[160:163], v[184:187], v[20:23]
	v_mfma_f32_16x16x32_bf16 v[12:15], v[152:155], v[192:195], v[12:15]
	v_mfma_f32_16x16x32_bf16 v[4:7], v[160:163], v[192:195], v[4:7]
	s_barrier
	s_add_u32 s58, s14, 0x80000
	s_addc_u32 s59, s15, 0
	s_mov_b32 m0, s42
	v_lshl_add_u64 v[148:149], s[58:59], 0, v[130:131]
	global_load_lds_dwordx4 v[148:149], off
	v_lshl_add_u64 v[148:149], s[58:59], 0, v[128:129]
	s_mov_b32 m0, s43
	s_nop 0
	global_load_lds_dwordx4 v[148:149], off
	s_waitcnt vmcnt(6)
	s_barrier
; #define WAIT_V(n) asm volatile("s_waitcnt vmcnt(" #n ")" ::: "memory")
; #define WAIT_L(n) asm volatile("s_waitcnt lgkmcnt(" #n ")" ::: "memory")
; #define BAR __builtin_amdgcn_s_barrier()
; #define SCHED __builtin_amdgcn_sched_barrier(0)
; template <class Get, class Epi>
; DI void gemm_stream(LAS unsigned char* lds, const int K, const int ld, Get get, Epi epi) {
;     ...
;             WAIT_V(6); BAR; MMA(1, 1, At, B1); BAR;
;             LDB(B0, 1, 0); SCHED; LDA(At, 1, 0); STAGE(SAo(0, 1), a2 + hstep);
;             WAIT_L(8); BAR; WAIT_L(0); MMA(0, 0, At, B0); BAR; SCHED;
;             LDB(B1, 1, 1); STAGE(SBo(1, 0), b3);
;             BAR; WAIT_L(0); MMA(0, 1, At, B1); BAR;
;             LDA(At, 1, 1); STAGE(SAo(1, 0), a3);
;             BAR; WAIT_L(0); MMA(1, 0, At, B0); BAR; SCHED;
	v_mfma_f32_16x16x32_bf16 v[56:59], v[196:199], v[164:167], v[56:59]
	v_mfma_f32_16x16x32_bf16 v[48:51], v[208:211], v[164:167], v[48:51]
	v_mfma_f32_16x16x32_bf16 v[40:43], v[196:199], v[172:175], v[40:43]
	v_mfma_f32_16x16x32_bf16 v[32:35], v[208:211], v[172:175], v[32:35]
	v_mfma_f32_16x16x32_bf16 v[24:27], v[196:199], v[180:183], v[24:27]
	v_mfma_f32_16x16x32_bf16 v[16:19], v[208:211], v[180:183], v[16:19]
	v_mfma_f32_16x16x32_bf16 v[8:11], v[196:199], v[188:191], v[8:11]
	v_mfma_f32_16x16x32_bf16 v[0:3], v[208:211], v[188:191], v[0:3]
	v_mfma_f32_16x16x32_bf16 v[56:59], v[200:203], v[168:171], v[56:59]
	v_mfma_f32_16x16x32_bf16 v[48:51], v[212:215], v[168:171], v[48:51]
	v_mfma_f32_16x16x32_bf16 v[40:43], v[200:203], v[176:179], v[40:43]
	v_mfma_f32_16x16x32_bf16 v[32:35], v[212:215], v[176:179], v[32:35]
	v_mfma_f32_16x16x32_bf16 v[24:27], v[200:203], v[184:187], v[24:27]
	v_mfma_f32_16x16x32_bf16 v[16:19], v[212:215], v[184:187], v[16:19]
	v_mfma_f32_16x16x32_bf16 v[8:11], v[200:203], v[192:195], v[8:11]
	v_mfma_f32_16x16x32_bf16 v[0:3], v[212:215], v[192:195], v[0:3]
	s_barrier
	ds_read_b128 v[148:151], v145
	ds_read_b128 v[152:155], v145 offset:1024
	ds_read_b128 v[156:159], v145 offset:2048
	ds_read_b128 v[160:163], v145 offset:3072
	s_add_u32 s16, s16, 0x80000
	s_addc_u32 s17, s17, 0
	s_mov_b32 m0, s21
	v_lshl_add_u64 v[196:197], s[16:17], 0, v[130:131]
	ds_read_b128 v[164:167], v143 offset:32768
	ds_read_b128 v[168:171], v143 offset:33792
	ds_read_b128 v[172:175], v143 offset:34816
	ds_read_b128 v[176:179], v143 offset:35840
	ds_read_b128 v[180:183], v143 offset:36864
	ds_read_b128 v[184:187], v143 offset:37888
	ds_read_b128 v[188:191], v143 offset:38912
	ds_read_b128 v[192:195], v143 offset:39936
	global_load_lds_dwordx4 v[196:197], off
	v_lshl_add_u64 v[196:197], s[16:17], 0, v[128:129]
	s_mov_b32 m0, s28
	s_nop 0
	global_load_lds_dwordx4 v[196:197], off
	s_waitcnt lgkmcnt(8)
	s_barrier
	s_waitcnt lgkmcnt(0)
	v_mfma_f32_16x16x32_bf16 v[124:127], v[148:151], v[164:167], v[124:127]
	v_mfma_f32_16x16x32_bf16 v[116:119], v[156:159], v[164:167], v[116:119]
	v_mfma_f32_16x16x32_bf16 v[108:111], v[148:151], v[172:175], v[108:111]
	v_mfma_f32_16x16x32_bf16 v[100:103], v[156:159], v[172:175], v[100:103]
	v_mfma_f32_16x16x32_bf16 v[92:95], v[148:151], v[180:183], v[92:95]
	v_mfma_f32_16x16x32_bf16 v[84:87], v[156:159], v[180:183], v[84:87]
	v_mfma_f32_16x16x32_bf16 v[76:79], v[148:151], v[188:191], v[76:79]
	v_mfma_f32_16x16x32_bf16 v[68:71], v[156:159], v[188:191], v[68:71]
	v_mfma_f32_16x16x32_bf16 v[124:127], v[152:155], v[168:171], v[124:127]
	v_mfma_f32_16x16x32_bf16 v[116:119], v[160:163], v[168:171], v[116:119]
	v_mfma_f32_16x16x32_bf16 v[108:111], v[152:155], v[176:179], v[108:111]
	v_mfma_f32_16x16x32_bf16 v[100:103], v[160:163], v[176:179], v[100:103]
	v_mfma_f32_16x16x32_bf16 v[92:95], v[152:155], v[184:187], v[92:95]
	v_mfma_f32_16x16x32_bf16 v[84:87], v[160:163], v[184:187], v[84:87]
	v_mfma_f32_16x16x32_bf16 v[76:79], v[152:155], v[192:195], v[76:79]
	v_mfma_f32_16x16x32_bf16 v[68:71], v[160:163], v[192:195], v[68:71]
	s_barrier
	s_mov_b32 m0, s44
	v_lshl_add_u64 v[140:141], v[140:141], 0, s[6:7]
	ds_read_b128 v[196:199], v146
	ds_read_b128 v[200:203], v146 offset:1024
	ds_read_b128 v[208:211], v146 offset:2048
	ds_read_b128 v[212:215], v146 offset:3072
	global_load_lds_dwordx4 v[140:141], off
	v_lshl_add_u64 v[140:141], v[204:205], 0, s[6:7]
	s_mov_b32 m0, s45
	s_nop 0
	global_load_lds_dwordx4 v[140:141], off
	s_barrier
	s_waitcnt lgkmcnt(0)
	v_mfma_f32_16x16x32_bf16 v[120:123], v[196:199], v[164:167], v[120:123]
	v_mfma_f32_16x16x32_bf16 v[112:115], v[208:211], v[164:167], v[112:115]
	v_mfma_f32_16x16x32_bf16 v[104:107], v[196:199], v[172:175], v[104:107]
	v_mfma_f32_16x16x32_bf16 v[96:99], v[208:211], v[172:175], v[96:99]
	v_mfma_f32_16x16x32_bf16 v[88:91], v[196:199], v[180:183], v[88:91]
	v_mfma_f32_16x16x32_bf16 v[80:83], v[208:211], v[180:183], v[80:83]
	v_mfma_f32_16x16x32_bf16 v[72:75], v[196:199], v[188:191], v[72:75]
	v_mfma_f32_16x16x32_bf16 v[64:67], v[208:211], v[188:191], v[64:67]
	v_mfma_f32_16x16x32_bf16 v[120:123], v[200:203], v[168:171], v[120:123]
	v_mfma_f32_16x16x32_bf16 v[112:115], v[212:215], v[168:171], v[112:115]
	v_mfma_f32_16x16x32_bf16 v[104:107], v[200:203], v[176:179], v[104:107]
	v_mfma_f32_16x16x32_bf16 v[96:99], v[212:215], v[176:179], v[96:99]
	v_mfma_f32_16x16x32_bf16 v[88:91], v[200:203], v[184:187], v[88:91]
	v_mfma_f32_16x16x32_bf16 v[80:83], v[212:215], v[184:187], v[80:83]
	v_mfma_f32_16x16x32_bf16 v[72:75], v[200:203], v[192:195], v[72:75]
	v_mfma_f32_16x16x32_bf16 v[64:67], v[212:215], v[192:195], v[64:67]
	s_barrier
	s_mov_b32 m0, s29
	v_lshl_add_u64 v[140:141], v[216:217], 0, s[6:7]
	ds_read_b128 v[164:167], v143 offset:49152
	ds_read_b128 v[168:171], v143 offset:50176
	ds_read_b128 v[172:175], v143 offset:51200
	ds_read_b128 v[176:179], v143 offset:52224
	ds_read_b128 v[180:183], v143 offset:53248
	ds_read_b128 v[184:187], v143 offset:54272
	ds_read_b128 v[188:191], v143 offset:55296
	ds_read_b128 v[192:195], v143 offset:56320
	global_load_lds_dwordx4 v[140:141], off
	v_lshl_add_u64 v[140:141], v[218:219], 0, s[6:7]
	s_mov_b32 m0, s36
	s_nop 0
	global_load_lds_dwordx4 v[140:141], off
	s_barrier
; DI float silu_f(float g) { return g * __builtin_amdgcn_rcpf(1.f + __builtin_amdgcn_exp2f(-LOG2E * g)); }
; #define WAIT_V(n) asm volatile("s_waitcnt vmcnt(" #n ")" ::: "memory")
; #define WAIT_L(n) asm volatile("s_waitcnt lgkmcnt(" #n ")" ::: "memory")
; #define BAR __builtin_amdgcn_s_barrier()
; #define SCHED __builtin_amdgcn_sched_barrier(0)
; template <class Get, class Epi>
; DI void gemm_stream(LAS unsigned char* lds, const int K, const int ld, Get get, Epi epi) {
;     ...
;             BAR; WAIT_L(0); MMA(1, 0, At, B0); BAR; SCHED;
;             STAGE(SBo(1, 1), b3 + hstep);
;             WAIT_V(6); BAR; MMA(1, 1, At, B1); BAR;
;         }
; DI void epi_swiglu(const Acc& acc, int brow, int pn, bf16_t* hid) {
;     ...
;     for (int ai = 0; ai < 2; ++ai)
; #pragma unroll
;         for (int m = 0; m < 4; ++m) {
;             const int r = brow + ai * 128 + wr * 64 + m * 16 + fr;
;             bf16_t* rp = hid + (size_t)r * FF + pn * 128 + wc * 32 + fq * 4;
; #pragma unroll
;             for (int n = 0; n < 2; ++n) {
;                 const f32x4 g = acc[ai][0][m][n], u = acc[ai][1][m][n];
;                 float o[4];
; #pragma unroll
;                 for (int j = 0; j < 4; ++j) o[j] = silu_f(g[j]) * u[j];
;                 st4(rp + n * 16, o[0], o[1], o[2], o[3]);
;             }
	s_waitcnt lgkmcnt(0)
	v_mfma_f32_16x16x32_bf16 v[60:63], v[148:151], v[164:167], v[60:63]
	v_mfma_f32_16x16x32_bf16 v[52:55], v[156:159], v[164:167], v[52:55]
	v_mfma_f32_16x16x32_bf16 v[44:47], v[148:151], v[172:175], v[44:47]
	v_mfma_f32_16x16x32_bf16 v[36:39], v[156:159], v[172:175], v[36:39]
	v_mfma_f32_16x16x32_bf16 v[28:31], v[148:151], v[180:183], v[28:31]
	v_mfma_f32_16x16x32_bf16 v[20:23], v[156:159], v[180:183], v[20:23]
	v_mfma_f32_16x16x32_bf16 v[12:15], v[148:151], v[188:191], v[12:15]
	v_mfma_f32_16x16x32_bf16 v[4:7], v[156:159], v[188:191], v[4:7]
	v_mfma_f32_16x16x32_bf16 v[60:63], v[152:155], v[168:171], v[60:63]
	v_mfma_f32_16x16x32_bf16 v[52:55], v[160:163], v[168:171], v[52:55]
	v_mfma_f32_16x16x32_bf16 v[44:47], v[152:155], v[176:179], v[44:47]
	v_mfma_f32_16x16x32_bf16 v[36:39], v[160:163], v[176:179], v[36:39]
	v_mfma_f32_16x16x32_bf16 v[28:31], v[152:155], v[184:187], v[28:31]
	v_mfma_f32_16x16x32_bf16 v[20:23], v[160:163], v[184:187], v[20:23]
	v_mfma_f32_16x16x32_bf16 v[12:15], v[152:155], v[192:195], v[12:15]
	v_mfma_f32_16x16x32_bf16 v[4:7], v[160:163], v[192:195], v[4:7]
	s_barrier
	s_add_u32 s14, s14, 0x80080
	s_addc_u32 s15, s15, 0
	s_mov_b32 m0, s46
	v_lshl_add_u64 v[140:141], s[14:15], 0, v[130:131]
	global_load_lds_dwordx4 v[140:141], off
	v_lshl_add_u64 v[140:141], s[14:15], 0, v[128:129]
	s_mov_b32 m0, s47
	s_nop 0
	global_load_lds_dwordx4 v[140:141], off
	s_add_i32 s56, s56, 2
	s_add_u32 s12, s12, 0x100
	s_addc_u32 s13, s13, 0
	s_add_u32 s0, s0, 0x100
	s_addc_u32 s55, s55, 0
	s_cmp_gt_u32 s56, 29
	s_waitcnt vmcnt(6)
	s_barrier
	v_mfma_f32_16x16x32_bf16 v[56:59], v[196:199], v[164:167], v[56:59]
	v_mfma_f32_16x16x32_bf16 v[48:51], v[208:211], v[164:167], v[48:51]
	v_mfma_f32_16x16x32_bf16 v[40:43], v[196:199], v[172:175], v[40:43]
	v_mfma_f32_16x16x32_bf16 v[32:35], v[208:211], v[172:175], v[32:35]
	v_mfma_f32_16x16x32_bf16 v[24:27], v[196:199], v[180:183], v[24:27]
	v_mfma_f32_16x16x32_bf16 v[16:19], v[208:211], v[180:183], v[16:19]
	v_mfma_f32_16x16x32_bf16 v[8:11], v[196:199], v[188:191], v[8:11]
	v_mfma_f32_16x16x32_bf16 v[0:3], v[208:211], v[188:191], v[0:3]
	v_mfma_f32_16x16x32_bf16 v[56:59], v[200:203], v[168:171], v[56:59]
	v_mfma_f32_16x16x32_bf16 v[48:51], v[212:215], v[168:171], v[48:51]
	v_mfma_f32_16x16x32_bf16 v[40:43], v[200:203], v[176:179], v[40:43]
	v_mfma_f32_16x16x32_bf16 v[32:35], v[212:215], v[176:179], v[32:35]
	v_mfma_f32_16x16x32_bf16 v[24:27], v[200:203], v[184:187], v[24:27]
	v_mfma_f32_16x16x32_bf16 v[16:19], v[212:215], v[184:187], v[16:19]
	v_mfma_f32_16x16x32_bf16 v[8:11], v[200:203], v[192:195], v[8:11]
	v_mfma_f32_16x16x32_bf16 v[0:3], v[212:215], v[192:195], v[0:3]
	s_barrier
	s_cbranch_scc0 .LBB0_3046
	s_lshr_b32 s0, s53, 4
	s_lshl_b32 s12, s53, 8
	s_mulk_i32 s0, 0x1100
	s_and_b32 s12, s12, 0xf00
	s_add_i32 s0, s0, s12
	s_lshl_b32 s12, s54, 7
	s_ashr_i32 s13, s12, 31
	s_addk_i32 s0, 0x100
	v_mov_b32_e32 v132, v206
	s_lshl_b64 s[12:13], s[12:13], 1
	s_add_u32 s12, s23, s12
	v_ashrrev_i32_e32 v140, 2, v132
	v_and_b32_e32 v140, 0xffffffc0, v140
	v_and_or_b32 v141, v132, 15, s0
	s_addc_u32 s13, s35, s13
	v_lshrrev_b32_e32 v148, 1, v132
	v_and_b32_e32 v132, 0xc0, v132
	v_add_u32_e32 v147, v141, v140
	v_lshl_add_u64 v[140:141], s[12:13], 0, v[132:133]
	v_and_b32_e32 v132, 24, v148
	v_mul_f32_e32 v148, 0xbfb8aa3b, v124
	v_exp_f32_e32 v148, v148
	v_mul_f32_e32 v149, 0xbfb8aa3b, v125
	v_exp_f32_e32 v149, v149
	v_lshl_add_u64 v[140:141], v[140:141], 0, v[132:133]
	v_add_f32_e32 v132, 1.0, v148
	v_rcp_f32_e32 v148, v132
	v_add_f32_e32 v132, 1.0, v149
	v_mul_f32_e32 v149, 0xbfb8aa3b, v126
	v_exp_f32_e32 v150, v149
	v_mul_f32_e32 v149, 0xbfb8aa3b, v127
	v_exp_f32_e32 v151, v149
	v_rcp_f32_e32 v149, v132
	v_add_f32_e32 v132, 1.0, v150
	v_rcp_f32_e32 v150, v132
	v_add_f32_e32 v132, 1.0, v151
	v_rcp_f32_e32 v151, v132
	v_pk_mul_f32 v[124:125], v[124:125], v[148:149]
	v_mad_i64_i32 v[152:153], s[12:13], v147, s37, v[140:141]
	v_pk_mul_f32 v[120:121], v[124:125], v[120:121]
	v_pk_mul_f32 v[124:125], v[126:127], v[150:151]
	v_cvt_pk_bf16_f32 v120, v120, v121
	v_mul_f32_e32 v121, 0xbfb8aa3b, v116
	v_pk_mul_f32 v[122:123], v[124:125], v[122:123]
	v_exp_f32_e32 v124, v121
	v_mul_f32_e32 v121, 0xbfb8aa3b, v117
	v_exp_f32_e32 v125, v121
	v_cvt_pk_bf16_f32 v121, v122, v123
	v_add_f32_e32 v122, 1.0, v124
	v_mul_f32_e32 v124, 0xbfb8aa3b, v118
	v_add_f32_e32 v123, 1.0, v125
	v_mul_f32_e32 v125, 0xbfb8aa3b, v119
	v_exp_f32_e32 v124, v124
	v_exp_f32_e32 v125, v125
	v_rcp_f32_e32 v122, v122
	v_rcp_f32_e32 v123, v123
	v_add_f32_e32 v124, 1.0, v124
	v_add_f32_e32 v125, 1.0, v125
	v_rcp_f32_e32 v124, v124
	v_rcp_f32_e32 v125, v125
	v_pk_mul_f32 v[116:117], v[116:117], v[122:123]
	s_and_b64 vcc, exec, s[4:5]
	v_pk_mul_f32 v[112:113], v[116:117], v[112:113]
	v_pk_mul_f32 v[116:117], v[118:119], v[124:125]
	v_cvt_pk_bf16_f32 v112, v112, v113
	v_pk_mul_f32 v[114:115], v[116:117], v[114:115]
	v_or_b32_e32 v116, 16, v147
	v_cvt_pk_bf16_f32 v113, v114, v115
	global_store_dwordx2 v[152:153], v[112:113], off offset:32
	v_mul_f32_e32 v112, 0xbfb8aa3b, v108
	v_mul_f32_e32 v113, 0xbfb8aa3b, v109
	v_exp_f32_e32 v112, v112
	v_exp_f32_e32 v113, v113
	v_mul_f32_e32 v114, 0xbfb8aa3b, v110
	v_mul_f32_e32 v115, 0xbfb8aa3b, v111
	v_exp_f32_e32 v114, v114
	v_exp_f32_e32 v115, v115
	v_add_f32_e32 v112, 1.0, v112
	v_add_f32_e32 v113, 1.0, v113
	v_rcp_f32_e32 v112, v112
	v_rcp_f32_e32 v113, v113
	v_add_f32_e32 v114, 1.0, v114
	v_add_f32_e32 v115, 1.0, v115
	v_rcp_f32_e32 v114, v114
	v_rcp_f32_e32 v115, v115
	v_pk_mul_f32 v[108:109], v[108:109], v[112:113]
	v_mad_i64_i32 v[116:117], s[12:13], v116, s37, v[140:141]
; DI float silu_f(float g) { return g * __builtin_amdgcn_rcpf(1.f + __builtin_amdgcn_exp2f(-LOG2E * g)); }
; DI void epi_swiglu(const Acc& acc, int brow, int pn, bf16_t* hid) {
;     ...
;     for (int ai = 0; ai < 2; ++ai)
; #pragma unroll
;         for (int m = 0; m < 4; ++m) {
;             const int r = brow + ai * 128 + wr * 64 + m * 16 + fr;
;             bf16_t* rp = hid + (size_t)r * FF + pn * 128 + wc * 32 + fq * 4;
; #pragma unroll
;             for (int n = 0; n < 2; ++n) {
;                 const f32x4 g = acc[ai][0][m][n], u = acc[ai][1][m][n];
;                 float o[4];
; #pragma unroll
;                 for (int j = 0; j < 4; ++j) o[j] = silu_f(g[j]) * u[j];
;                 st4(rp + n * 16, o[0], o[1], o[2], o[3]);
;             }
	v_pk_mul_f32 v[104:105], v[108:109], v[104:105]
	v_pk_mul_f32 v[108:109], v[110:111], v[114:115]
	v_cvt_pk_bf16_f32 v104, v104, v105
	v_mul_f32_e32 v105, 0xbfb8aa3b, v100
	v_pk_mul_f32 v[106:107], v[108:109], v[106:107]
	v_exp_f32_e32 v108, v105
	v_mul_f32_e32 v105, 0xbfb8aa3b, v101
	v_exp_f32_e32 v109, v105
	v_cvt_pk_bf16_f32 v105, v106, v107
	v_add_f32_e32 v106, 1.0, v108
	v_mul_f32_e32 v108, 0xbfb8aa3b, v102
	v_add_f32_e32 v107, 1.0, v109
	v_mul_f32_e32 v109, 0xbfb8aa3b, v103
	v_exp_f32_e32 v108, v108
	v_exp_f32_e32 v109, v109
	v_rcp_f32_e32 v106, v106
	v_rcp_f32_e32 v107, v107
	v_add_f32_e32 v108, 1.0, v108
	v_add_f32_e32 v109, 1.0, v109
	v_rcp_f32_e32 v108, v108
	v_rcp_f32_e32 v109, v109
	v_pk_mul_f32 v[100:101], v[100:101], v[106:107]
	s_mov_b32 s54, s49
	v_pk_mul_f32 v[96:97], v[100:101], v[96:97]
	v_pk_mul_f32 v[100:101], v[102:103], v[108:109]
	v_cvt_pk_bf16_f32 v96, v96, v97
	v_pk_mul_f32 v[98:99], v[100:101], v[98:99]
	v_or_b32_e32 v100, 32, v147
	v_cvt_pk_bf16_f32 v97, v98, v99
	global_store_dwordx2 v[116:117], v[96:97], off offset:32
	v_mul_f32_e32 v96, 0xbfb8aa3b, v92
	v_mul_f32_e32 v97, 0xbfb8aa3b, v93
	v_exp_f32_e32 v96, v96
	v_exp_f32_e32 v97, v97
	v_mul_f32_e32 v98, 0xbfb8aa3b, v94
	v_mul_f32_e32 v99, 0xbfb8aa3b, v95
	v_exp_f32_e32 v98, v98
	v_exp_f32_e32 v99, v99
	v_add_f32_e32 v96, 1.0, v96
	v_add_f32_e32 v97, 1.0, v97
	v_rcp_f32_e32 v96, v96
	v_rcp_f32_e32 v97, v97
	v_add_f32_e32 v98, 1.0, v98
	v_add_f32_e32 v99, 1.0, v99
	v_rcp_f32_e32 v98, v98
	v_rcp_f32_e32 v99, v99
	v_pk_mul_f32 v[92:93], v[92:93], v[96:97]
	v_mad_i64_i32 v[100:101], s[12:13], v100, s37, v[140:141]
	v_pk_mul_f32 v[88:89], v[92:93], v[88:89]
	v_pk_mul_f32 v[92:93], v[94:95], v[98:99]
	v_cvt_pk_bf16_f32 v88, v88, v89
	v_mul_f32_e32 v89, 0xbfb8aa3b, v84
	v_pk_mul_f32 v[90:91], v[92:93], v[90:91]
	v_exp_f32_e32 v92, v89
	v_mul_f32_e32 v89, 0xbfb8aa3b, v85
	v_exp_f32_e32 v93, v89
	v_cvt_pk_bf16_f32 v89, v90, v91
	v_add_f32_e32 v90, 1.0, v92
	v_mul_f32_e32 v92, 0xbfb8aa3b, v86
	v_add_f32_e32 v91, 1.0, v93
	v_mul_f32_e32 v93, 0xbfb8aa3b, v87
	v_exp_f32_e32 v92, v92
	v_exp_f32_e32 v93, v93
	v_rcp_f32_e32 v90, v90
	v_rcp_f32_e32 v91, v91
	v_add_f32_e32 v92, 1.0, v92
	v_add_f32_e32 v93, 1.0, v93
	v_rcp_f32_e32 v92, v92
	v_rcp_f32_e32 v93, v93
	v_pk_mul_f32 v[84:85], v[84:85], v[90:91]
	s_mov_b32 s53, s52
	v_pk_mul_f32 v[80:81], v[84:85], v[80:81]
	v_pk_mul_f32 v[84:85], v[86:87], v[92:93]
	v_cvt_pk_bf16_f32 v80, v80, v81
	v_pk_mul_f32 v[82:83], v[84:85], v[82:83]
	v_or_b32_e32 v84, 48, v147
	v_cvt_pk_bf16_f32 v81, v82, v83
	global_store_dwordx2 v[100:101], v[80:81], off offset:32
	v_mul_f32_e32 v80, 0xbfb8aa3b, v76
	v_mul_f32_e32 v81, 0xbfb8aa3b, v77
	v_exp_f32_e32 v80, v80
	v_exp_f32_e32 v81, v81
	v_mul_f32_e32 v82, 0xbfb8aa3b, v78
	v_mul_f32_e32 v83, 0xbfb8aa3b, v79
	v_exp_f32_e32 v82, v82
	v_exp_f32_e32 v83, v83
	v_add_f32_e32 v80, 1.0, v80
	v_add_f32_e32 v81, 1.0, v81
	v_rcp_f32_e32 v80, v80
	v_rcp_f32_e32 v81, v81
	v_add_f32_e32 v82, 1.0, v82
	v_add_f32_e32 v83, 1.0, v83
	v_rcp_f32_e32 v82, v82
	v_rcp_f32_e32 v83, v83
	v_pk_mul_f32 v[76:77], v[76:77], v[80:81]
	v_mad_i64_i32 v[84:85], s[12:13], v84, s37, v[140:141]
	v_pk_mul_f32 v[72:73], v[76:77], v[72:73]
	v_pk_mul_f32 v[76:77], v[78:79], v[82:83]
	v_cvt_pk_bf16_f32 v72, v72, v73
	v_mul_f32_e32 v73, 0xbfb8aa3b, v68
	v_pk_mul_f32 v[74:75], v[76:77], v[74:75]
	v_exp_f32_e32 v76, v73
	v_mul_f32_e32 v73, 0xbfb8aa3b, v69
	v_exp_f32_e32 v77, v73
	v_cvt_pk_bf16_f32 v73, v74, v75
	v_add_f32_e32 v74, 1.0, v76
	v_mul_f32_e32 v76, 0xbfb8aa3b, v70
	v_add_f32_e32 v75, 1.0, v77
	v_mul_f32_e32 v77, 0xbfb8aa3b, v71
	v_exp_f32_e32 v76, v76
	v_exp_f32_e32 v77, v77
	v_rcp_f32_e32 v74, v74
	v_rcp_f32_e32 v75, v75
	v_add_f32_e32 v76, 1.0, v76
	v_add_f32_e32 v77, 1.0, v77
	v_rcp_f32_e32 v76, v76
	v_rcp_f32_e32 v77, v77
	v_pk_mul_f32 v[68:69], v[68:69], v[74:75]
	s_mov_b64 s[14:15], s[10:11]
	v_pk_mul_f32 v[64:65], v[68:69], v[64:65]
	v_pk_mul_f32 v[68:69], v[70:71], v[76:77]
	v_cvt_pk_bf16_f32 v64, v64, v65
	v_pk_mul_f32 v[66:67], v[68:69], v[66:67]
	v_add_u32_e32 v68, 0x80, v147
	v_cvt_pk_bf16_f32 v65, v66, v67
	global_store_dwordx2 v[84:85], v[64:65], off offset:32
	v_mul_f32_e32 v64, 0xbfb8aa3b, v60
	v_mul_f32_e32 v65, 0xbfb8aa3b, v61
	v_exp_f32_e32 v64, v64
	v_exp_f32_e32 v65, v65
	v_mul_f32_e32 v66, 0xbfb8aa3b, v62
	v_mul_f32_e32 v67, 0xbfb8aa3b, v63
	v_exp_f32_e32 v66, v66
	v_exp_f32_e32 v67, v67
	v_add_f32_e32 v64, 1.0, v64
	v_add_f32_e32 v65, 1.0, v65
	v_rcp_f32_e32 v64, v64
	v_rcp_f32_e32 v65, v65
	v_add_f32_e32 v66, 1.0, v66
	v_add_f32_e32 v67, 1.0, v67
	v_rcp_f32_e32 v66, v66
	v_rcp_f32_e32 v67, v67
	v_pk_mul_f32 v[60:61], v[60:61], v[64:65]
	v_mad_i64_i32 v[68:69], s[12:13], v68, s37, v[140:141]
	v_pk_mul_f32 v[56:57], v[60:61], v[56:57]
	v_pk_mul_f32 v[60:61], v[62:63], v[66:67]
	v_cvt_pk_bf16_f32 v56, v56, v57
	v_mul_f32_e32 v57, 0xbfb8aa3b, v52
	v_pk_mul_f32 v[58:59], v[60:61], v[58:59]
	v_exp_f32_e32 v60, v57
	v_mul_f32_e32 v57, 0xbfb8aa3b, v53
	v_exp_f32_e32 v61, v57
	v_cvt_pk_bf16_f32 v57, v58, v59
	v_add_f32_e32 v58, 1.0, v60
	v_mul_f32_e32 v60, 0xbfb8aa3b, v54
	v_add_f32_e32 v59, 1.0, v61
	v_mul_f32_e32 v61, 0xbfb8aa3b, v55
	v_exp_f32_e32 v60, v60
	v_exp_f32_e32 v61, v61
	v_rcp_f32_e32 v58, v58
	v_rcp_f32_e32 v59, v59
	v_add_f32_e32 v60, 1.0, v60
	v_add_f32_e32 v61, 1.0, v61
	v_rcp_f32_e32 v60, v60
; DI float silu_f(float g) { return g * __builtin_amdgcn_rcpf(1.f + __builtin_amdgcn_exp2f(-LOG2E * g)); }
; #define WAIT_V(n) asm volatile("s_waitcnt vmcnt(" #n ")" ::: "memory")
; #define BAR __builtin_amdgcn_s_barrier()
; template <class Get, class Epi>
; DI void gemm_stream(LAS unsigned char* lds, const int K, const int ld, Get get, Epi epi) {
;     ...
;         epi(acc, cur);
;         if (!has_next) break;
;         ZERO_ACC;
;         cur = nxt; cA = nA; cB = nB; ++ui;
;     }
;     WAIT_V(0);
;     if (wr == 0) BAR;
;     BAR;
; DI void epi_swiglu(const Acc& acc, int brow, int pn, bf16_t* hid) {
;     ...
;     for (int ai = 0; ai < 2; ++ai)
; #pragma unroll
;         for (int m = 0; m < 4; ++m) {
;             const int r = brow + ai * 128 + wr * 64 + m * 16 + fr;
;             bf16_t* rp = hid + (size_t)r * FF + pn * 128 + wc * 32 + fq * 4;
; #pragma unroll
;             for (int n = 0; n < 2; ++n) {
;                 const f32x4 g = acc[ai][0][m][n], u = acc[ai][1][m][n];
;                 float o[4];
; #pragma unroll
;                 for (int j = 0; j < 4; ++j) o[j] = silu_f(g[j]) * u[j];
;                 st4(rp + n * 16, o[0], o[1], o[2], o[3]);
;             }
	v_rcp_f32_e32 v61, v61
	v_pk_mul_f32 v[52:53], v[52:53], v[58:59]
	global_store_dwordx2 v[152:153], v[120:121], off
	v_pk_mul_f32 v[48:49], v[52:53], v[48:49]
	v_pk_mul_f32 v[52:53], v[54:55], v[60:61]
	v_cvt_pk_bf16_f32 v48, v48, v49
	v_pk_mul_f32 v[50:51], v[52:53], v[50:51]
	v_add_u32_e32 v52, 0x90, v147
	v_cvt_pk_bf16_f32 v49, v50, v51
	global_store_dwordx2 v[68:69], v[48:49], off offset:32
	v_mul_f32_e32 v48, 0xbfb8aa3b, v44
	v_mul_f32_e32 v49, 0xbfb8aa3b, v45
	v_exp_f32_e32 v48, v48
	v_exp_f32_e32 v49, v49
	v_mul_f32_e32 v50, 0xbfb8aa3b, v46
	v_mul_f32_e32 v51, 0xbfb8aa3b, v47
	v_exp_f32_e32 v50, v50
	v_exp_f32_e32 v51, v51
	v_add_f32_e32 v48, 1.0, v48
	v_add_f32_e32 v49, 1.0, v49
	v_rcp_f32_e32 v48, v48
	v_rcp_f32_e32 v49, v49
	v_add_f32_e32 v50, 1.0, v50
	v_add_f32_e32 v51, 1.0, v51
	v_rcp_f32_e32 v50, v50
	v_rcp_f32_e32 v51, v51
	v_pk_mul_f32 v[44:45], v[44:45], v[48:49]
	v_mad_i64_i32 v[52:53], s[12:13], v52, s37, v[140:141]
	v_pk_mul_f32 v[40:41], v[44:45], v[40:41]
	v_pk_mul_f32 v[44:45], v[46:47], v[50:51]
	v_cvt_pk_bf16_f32 v40, v40, v41
	v_mul_f32_e32 v41, 0xbfb8aa3b, v36
	v_pk_mul_f32 v[42:43], v[44:45], v[42:43]
	v_exp_f32_e32 v44, v41
	v_mul_f32_e32 v41, 0xbfb8aa3b, v37
	v_exp_f32_e32 v45, v41
	v_cvt_pk_bf16_f32 v41, v42, v43
	v_add_f32_e32 v42, 1.0, v44
	v_mul_f32_e32 v44, 0xbfb8aa3b, v38
	v_add_f32_e32 v43, 1.0, v45
	v_mul_f32_e32 v45, 0xbfb8aa3b, v39
	v_exp_f32_e32 v44, v44
	v_exp_f32_e32 v45, v45
	v_rcp_f32_e32 v42, v42
	v_rcp_f32_e32 v43, v43
	v_add_f32_e32 v44, 1.0, v44
	v_add_f32_e32 v45, 1.0, v45
	v_rcp_f32_e32 v44, v44
	v_rcp_f32_e32 v45, v45
	v_pk_mul_f32 v[36:37], v[36:37], v[42:43]
	global_store_dwordx2 v[116:117], v[104:105], off
	v_pk_mul_f32 v[32:33], v[36:37], v[32:33]
	v_pk_mul_f32 v[36:37], v[38:39], v[44:45]
	v_cvt_pk_bf16_f32 v32, v32, v33
	v_pk_mul_f32 v[34:35], v[36:37], v[34:35]
	v_add_u32_e32 v36, 0xa0, v147
	v_cvt_pk_bf16_f32 v33, v34, v35
	global_store_dwordx2 v[52:53], v[32:33], off offset:32
	v_mul_f32_e32 v32, 0xbfb8aa3b, v28
	v_mul_f32_e32 v33, 0xbfb8aa3b, v29
	v_exp_f32_e32 v32, v32
	v_exp_f32_e32 v33, v33
	v_mul_f32_e32 v34, 0xbfb8aa3b, v30
	v_mul_f32_e32 v35, 0xbfb8aa3b, v31
	v_exp_f32_e32 v34, v34
	v_exp_f32_e32 v35, v35
	v_add_f32_e32 v32, 1.0, v32
	v_add_f32_e32 v33, 1.0, v33
	v_rcp_f32_e32 v32, v32
	v_rcp_f32_e32 v33, v33
	v_add_f32_e32 v34, 1.0, v34
	v_add_f32_e32 v35, 1.0, v35
	v_rcp_f32_e32 v34, v34
	v_rcp_f32_e32 v35, v35
	v_pk_mul_f32 v[28:29], v[28:29], v[32:33]
	v_mad_i64_i32 v[36:37], s[12:13], v36, s37, v[140:141]
	v_pk_mul_f32 v[24:25], v[28:29], v[24:25]
	v_pk_mul_f32 v[28:29], v[30:31], v[34:35]
	v_cvt_pk_bf16_f32 v24, v24, v25
	v_mul_f32_e32 v25, 0xbfb8aa3b, v20
	v_pk_mul_f32 v[26:27], v[28:29], v[26:27]
	v_exp_f32_e32 v28, v25
	v_mul_f32_e32 v25, 0xbfb8aa3b, v21
	v_exp_f32_e32 v29, v25
	v_cvt_pk_bf16_f32 v25, v26, v27
	v_add_f32_e32 v26, 1.0, v28
	v_mul_f32_e32 v28, 0xbfb8aa3b, v22
	v_add_f32_e32 v27, 1.0, v29
	v_mul_f32_e32 v29, 0xbfb8aa3b, v23
	v_exp_f32_e32 v28, v28
	v_exp_f32_e32 v29, v29
	v_rcp_f32_e32 v26, v26
	v_rcp_f32_e32 v27, v27
	v_add_f32_e32 v28, 1.0, v28
	v_add_f32_e32 v29, 1.0, v29
	v_rcp_f32_e32 v28, v28
	v_rcp_f32_e32 v29, v29
	v_pk_mul_f32 v[20:21], v[20:21], v[26:27]
	global_store_dwordx2 v[100:101], v[88:89], off
	v_pk_mul_f32 v[16:17], v[20:21], v[16:17]
	v_pk_mul_f32 v[20:21], v[22:23], v[28:29]
	v_cvt_pk_bf16_f32 v16, v16, v17
	v_pk_mul_f32 v[18:19], v[20:21], v[18:19]
	v_add_u32_e32 v20, 0xb0, v147
	v_cvt_pk_bf16_f32 v17, v18, v19
	global_store_dwordx2 v[36:37], v[16:17], off offset:32
	v_mul_f32_e32 v16, 0xbfb8aa3b, v12
	v_mul_f32_e32 v17, 0xbfb8aa3b, v13
	v_exp_f32_e32 v16, v16
	v_exp_f32_e32 v17, v17
	v_mul_f32_e32 v18, 0xbfb8aa3b, v14
	v_mul_f32_e32 v19, 0xbfb8aa3b, v15
	v_exp_f32_e32 v18, v18
	v_exp_f32_e32 v19, v19
	v_add_f32_e32 v16, 1.0, v16
	v_add_f32_e32 v17, 1.0, v17
	v_rcp_f32_e32 v16, v16
	v_rcp_f32_e32 v17, v17
	v_add_f32_e32 v18, 1.0, v18
	v_add_f32_e32 v19, 1.0, v19
	v_rcp_f32_e32 v18, v18
	v_rcp_f32_e32 v19, v19
	v_pk_mul_f32 v[12:13], v[12:13], v[16:17]
	v_mad_i64_i32 v[20:21], s[12:13], v20, s37, v[140:141]
	v_pk_mul_f32 v[8:9], v[12:13], v[8:9]
	v_pk_mul_f32 v[12:13], v[14:15], v[18:19]
	v_cvt_pk_bf16_f32 v8, v8, v9
	v_mul_f32_e32 v9, 0xbfb8aa3b, v4
	v_pk_mul_f32 v[10:11], v[12:13], v[10:11]
	v_exp_f32_e32 v12, v9
	v_mul_f32_e32 v9, 0xbfb8aa3b, v5
	v_exp_f32_e32 v13, v9
	v_cvt_pk_bf16_f32 v9, v10, v11
	v_add_f32_e32 v10, 1.0, v12
	v_mul_f32_e32 v12, 0xbfb8aa3b, v6
	v_add_f32_e32 v11, 1.0, v13
	v_mul_f32_e32 v13, 0xbfb8aa3b, v7
	v_exp_f32_e32 v12, v12
	v_exp_f32_e32 v13, v13
	v_rcp_f32_e32 v10, v10
	v_rcp_f32_e32 v11, v11
	v_add_f32_e32 v12, 1.0, v12
	v_add_f32_e32 v13, 1.0, v13
	v_rcp_f32_e32 v12, v12
	v_rcp_f32_e32 v13, v13
	v_pk_mul_f32 v[4:5], v[4:5], v[10:11]
	s_mov_b64 s[12:13], s[8:9]
	v_pk_mul_f32 v[0:1], v[4:5], v[0:1]
	v_pk_mul_f32 v[4:5], v[6:7], v[12:13]
	v_cvt_pk_bf16_f32 v0, v0, v1
	v_pk_mul_f32 v[2:3], v[4:5], v[2:3]
	global_store_dwordx2 v[84:85], v[72:73], off
	v_cvt_pk_bf16_f32 v1, v2, v3
	global_store_dwordx2 v[68:69], v[56:57], off
	global_store_dwordx2 v[52:53], v[40:41], off
	global_store_dwordx2 v[36:37], v[24:25], off
	global_store_dwordx2 v[20:21], v[8:9], off
	global_store_dwordx2 v[20:21], v[0:1], off offset:32
	s_cbranch_vccz .LBB0_3043
	s_waitcnt vmcnt(0)
	s_cmpk_gt_u32 s2, 0xff
	s_cbranch_scc1 .LBB0_3050
	s_barrier

; #define WAIT_V(n) asm volatile("s_waitcnt vmcnt(" #n ")" ::: "memory")
; #define WAIT_L(n) asm volatile("s_waitcnt lgkmcnt(" #n ")" ::: "memory")
; #define BAR __builtin_amdgcn_s_barrier()
; #define SCHED __builtin_amdgcn_sched_barrier(0)
; template <class Get, class Epi>
; DI void gemm_stream(LAS unsigned char* lds, const int K, const int ld, Get get, Epi epi) {
;     ...
;             const bool last = (t == nt - 2);
;             const char* a1 = cA + (size_t)(t + 1) * kstep;
;             const char* a2 = last ? nA : cA + (size_t)(t + 2) * kstep;
;             const char* b2 = last ? nB : cB + (size_t)(t + 2) * kstep;
;             const char* a3 = a2 + kstep;
;             const char* b3 = b2 + kstep;
;             LDB(B0, 0, 0); SCHED; LDA(At, 0, 0); STAGE(SAo(1, 1), a1 + hstep);
;             WAIT_L(8); BAR; WAIT_L(0); MMA(0, 0, At, B0); BAR; SCHED;
;             LDB(B1, 0, 1); STAGE(SBo(0, 0), b2);
;             BAR; WAIT_L(0); MMA(0, 1, At, B1); BAR;
;             LDA(At, 0, 1); STAGE(SAo(0, 0), a2);
;             BAR; WAIT_L(0); MMA(1, 0, At, B0); BAR; SCHED;
;             STAGE(SBo(0, 1), b2 + hstep);
;             WAIT_V(6); BAR; MMA(1, 1, At, B1); BAR;
.LBB0_3113:
	ds_read_b128 v[128:131], v199
	ds_read_b128 v[132:135], v199 offset:1024
	ds_read_b128 v[136:139], v199 offset:2048
	ds_read_b128 v[140:143], v199 offset:3072
	s_add_u32 s6, s4, 0x100
	s_addc_u32 s7, s5, 0
	s_cmpk_eq_i32 s16, 0x54
	s_cselect_b32 s11, s37, s7
	s_cselect_b32 s10, s36, s6
	s_cselect_b32 s9, s39, s15
	s_cselect_b32 s8, s38, s14
	s_mov_b32 m0, s54
	v_lshl_add_u64 v[186:187], s[4:5], 0, v[168:169]
	ds_read_b128 v[144:147], v200
	ds_read_b128 v[148:151], v200 offset:1024
	ds_read_b128 v[152:155], v200 offset:2048
	ds_read_b128 v[156:159], v200 offset:3072
	ds_read_b128 v[160:163], v200 offset:4096
	ds_read_b128 v[174:177], v200 offset:5120
	ds_read_b128 v[178:181], v200 offset:6144
	ds_read_b128 v[182:185], v200 offset:7168
	global_load_lds_dwordx4 v[186:187], off
	v_lshl_add_u64 v[186:187], s[4:5], 0, v[170:171]
	s_mov_b32 m0, s55
	s_nop 0
	global_load_lds_dwordx4 v[186:187], off
	s_waitcnt lgkmcnt(8)
	s_barrier
	s_waitcnt lgkmcnt(0)
	v_mfma_f32_16x16x32_bf16 v[124:127], v[128:131], v[144:147], v[124:127]
	v_mfma_f32_16x16x32_bf16 v[92:95], v[136:139], v[144:147], v[92:95]
	v_mfma_f32_16x16x32_bf16 v[120:123], v[128:131], v[152:155], v[120:123]
	v_mfma_f32_16x16x32_bf16 v[88:91], v[136:139], v[152:155], v[88:91]
	v_mfma_f32_16x16x32_bf16 v[116:119], v[128:131], v[160:163], v[116:119]
	v_mfma_f32_16x16x32_bf16 v[84:87], v[136:139], v[160:163], v[84:87]
	v_mfma_f32_16x16x32_bf16 v[112:115], v[128:131], v[178:181], v[112:115]
	v_mfma_f32_16x16x32_bf16 v[80:83], v[136:139], v[178:181], v[80:83]
	v_mfma_f32_16x16x32_bf16 v[124:127], v[132:135], v[148:151], v[124:127]
	v_mfma_f32_16x16x32_bf16 v[92:95], v[140:143], v[148:151], v[92:95]
	v_mfma_f32_16x16x32_bf16 v[120:123], v[132:135], v[156:159], v[120:123]
	v_mfma_f32_16x16x32_bf16 v[88:91], v[140:143], v[156:159], v[88:91]
	v_mfma_f32_16x16x32_bf16 v[116:119], v[132:135], v[174:177], v[116:119]
	v_mfma_f32_16x16x32_bf16 v[84:87], v[140:143], v[174:177], v[84:87]
	v_mfma_f32_16x16x32_bf16 v[112:115], v[132:135], v[182:185], v[112:115]
	v_mfma_f32_16x16x32_bf16 v[80:83], v[140:143], v[182:185], v[80:83]
	s_barrier
	s_mov_b32 m0, s56
	v_lshl_add_u64 v[208:209], s[8:9], 0, v[164:165]
	ds_read_b128 v[186:189], v201
	ds_read_b128 v[190:193], v201 offset:1024
	ds_read_b128 v[194:197], v201 offset:2048
	ds_read_b128 v[202:205], v201 offset:3072
	global_load_lds_dwordx4 v[208:209], off
	v_lshl_add_u64 v[210:211], s[8:9], 0, v[166:167]
	s_mov_b32 m0, s57
	s_nop 0
	global_load_lds_dwordx4 v[210:211], off
	s_barrier
	s_waitcnt lgkmcnt(0)
	v_mfma_f32_16x16x32_bf16 v[60:63], v[186:189], v[144:147], v[60:63]
	v_mfma_f32_16x16x32_bf16 v[28:31], v[194:197], v[144:147], v[28:31]
	v_mfma_f32_16x16x32_bf16 v[56:59], v[186:189], v[152:155], v[56:59]
	v_mfma_f32_16x16x32_bf16 v[24:27], v[194:197], v[152:155], v[24:27]
	v_mfma_f32_16x16x32_bf16 v[52:55], v[186:189], v[160:163], v[52:55]
	v_mfma_f32_16x16x32_bf16 v[20:23], v[194:197], v[160:163], v[20:23]
	v_mfma_f32_16x16x32_bf16 v[48:51], v[186:189], v[178:181], v[48:51]
	v_mfma_f32_16x16x32_bf16 v[16:19], v[194:197], v[178:181], v[16:19]
	v_mfma_f32_16x16x32_bf16 v[60:63], v[190:193], v[148:151], v[60:63]
	v_mfma_f32_16x16x32_bf16 v[28:31], v[202:205], v[148:151], v[28:31]
	v_mfma_f32_16x16x32_bf16 v[56:59], v[190:193], v[156:159], v[56:59]
	v_mfma_f32_16x16x32_bf16 v[24:27], v[202:205], v[156:159], v[24:27]
	v_mfma_f32_16x16x32_bf16 v[52:55], v[190:193], v[174:177], v[52:55]
	v_mfma_f32_16x16x32_bf16 v[20:23], v[202:205], v[174:177], v[20:23]
	v_mfma_f32_16x16x32_bf16 v[48:51], v[190:193], v[182:185], v[48:51]
	v_mfma_f32_16x16x32_bf16 v[16:19], v[202:205], v[182:185], v[16:19]
	s_barrier
	s_mov_b32 m0, s33
	v_lshl_add_u64 v[212:213], s[10:11], 0, v[164:165]
	ds_read_b128 v[144:147], v200 offset:16384
	ds_read_b128 v[148:151], v200 offset:17408
	ds_read_b128 v[152:155], v200 offset:18432
	ds_read_b128 v[156:159], v200 offset:19456
	ds_read_b128 v[160:163], v200 offset:20480
	ds_read_b128 v[174:177], v200 offset:21504
	ds_read_b128 v[178:181], v200 offset:22528
	ds_read_b128 v[182:185], v200 offset:23552
	global_load_lds_dwordx4 v[212:213], off
	v_lshl_add_u64 v[214:215], s[10:11], 0, v[166:167]
	s_mov_b32 m0, s42
	s_nop 0
	global_load_lds_dwordx4 v[214:215], off
	s_barrier
	s_waitcnt lgkmcnt(0)
	v_mfma_f32_16x16x32_bf16 v[108:111], v[128:131], v[144:147], v[108:111]
	v_mfma_f32_16x16x32_bf16 v[76:79], v[136:139], v[144:147], v[76:79]
	v_mfma_f32_16x16x32_bf16 v[104:107], v[128:131], v[152:155], v[104:107]
	v_mfma_f32_16x16x32_bf16 v[72:75], v[136:139], v[152:155], v[72:75]
	v_mfma_f32_16x16x32_bf16 v[100:103], v[128:131], v[160:163], v[100:103]
	v_mfma_f32_16x16x32_bf16 v[68:71], v[136:139], v[160:163], v[68:71]
	v_mfma_f32_16x16x32_bf16 v[96:99], v[128:131], v[178:181], v[96:99]
	v_mfma_f32_16x16x32_bf16 v[64:67], v[136:139], v[178:181], v[64:67]
	v_mfma_f32_16x16x32_bf16 v[108:111], v[132:135], v[148:151], v[108:111]
	v_mfma_f32_16x16x32_bf16 v[76:79], v[140:143], v[148:151], v[76:79]
	v_mfma_f32_16x16x32_bf16 v[104:107], v[132:135], v[156:159], v[104:107]
	v_mfma_f32_16x16x32_bf16 v[72:75], v[140:143], v[156:159], v[72:75]
	v_mfma_f32_16x16x32_bf16 v[100:103], v[132:135], v[174:177], v[100:103]
	v_mfma_f32_16x16x32_bf16 v[68:71], v[140:143], v[174:177], v[68:71]
	v_mfma_f32_16x16x32_bf16 v[96:99], v[132:135], v[182:185], v[96:99]
	v_mfma_f32_16x16x32_bf16 v[64:67], v[140:143], v[182:185], v[64:67]
	s_barrier
	s_add_u32 s4, s8, 0x160000
	s_addc_u32 s5, s9, 0
	s_mov_b32 m0, s58
	v_lshl_add_u64 v[128:129], s[4:5], 0, v[164:165]
	global_load_lds_dwordx4 v[128:129], off
	v_lshl_add_u64 v[128:129], s[4:5], 0, v[166:167]
	s_mov_b32 m0, s59
	s_nop 0
	global_load_lds_dwordx4 v[128:129], off
	s_waitcnt vmcnt(6)
	s_barrier
; #define WAIT_V(n) asm volatile("s_waitcnt vmcnt(" #n ")" ::: "memory")
; #define WAIT_L(n) asm volatile("s_waitcnt lgkmcnt(" #n ")" ::: "memory")
; #define BAR __builtin_amdgcn_s_barrier()
; #define SCHED __builtin_amdgcn_sched_barrier(0)
; template <class Get, class Epi>
; DI void gemm_stream(LAS unsigned char* lds, const int K, const int ld, Get get, Epi epi) {
;     ...
;             WAIT_V(6); BAR; MMA(1, 1, At, B1); BAR;
;             LDB(B0, 1, 0); SCHED; LDA(At, 1, 0); STAGE(SAo(0, 1), a2 + hstep);
;             WAIT_L(8); BAR; WAIT_L(0); MMA(0, 0, At, B0); BAR; SCHED;
;             LDB(B1, 1, 1); STAGE(SBo(1, 0), b3);
;             BAR; WAIT_L(0); MMA(0, 1, At, B1); BAR;
;             LDA(At, 1, 1); STAGE(SAo(1, 0), a3);
;             BAR; WAIT_L(0); MMA(1, 0, At, B0); BAR; SCHED;
	v_mfma_f32_16x16x32_bf16 v[44:47], v[186:189], v[144:147], v[44:47]
	v_mfma_f32_16x16x32_bf16 v[12:15], v[194:197], v[144:147], v[12:15]
	v_mfma_f32_16x16x32_bf16 v[40:43], v[186:189], v[152:155], v[40:43]
	v_mfma_f32_16x16x32_bf16 v[8:11], v[194:197], v[152:155], v[8:11]
	v_mfma_f32_16x16x32_bf16 v[36:39], v[186:189], v[160:163], v[36:39]
	v_mfma_f32_16x16x32_bf16 v[4:7], v[194:197], v[160:163], v[4:7]
	v_mfma_f32_16x16x32_bf16 v[32:35], v[186:189], v[178:181], v[32:35]
	v_mfma_f32_16x16x32_bf16 v[0:3], v[194:197], v[178:181], v[0:3]
	v_mfma_f32_16x16x32_bf16 v[44:47], v[190:193], v[148:151], v[44:47]
	v_mfma_f32_16x16x32_bf16 v[12:15], v[202:205], v[148:151], v[12:15]
	v_mfma_f32_16x16x32_bf16 v[40:43], v[190:193], v[156:159], v[40:43]
	v_mfma_f32_16x16x32_bf16 v[8:11], v[202:205], v[156:159], v[8:11]
	v_mfma_f32_16x16x32_bf16 v[36:39], v[190:193], v[174:177], v[36:39]
	v_mfma_f32_16x16x32_bf16 v[4:7], v[202:205], v[174:177], v[4:7]
	v_mfma_f32_16x16x32_bf16 v[32:35], v[190:193], v[182:185], v[32:35]
	v_mfma_f32_16x16x32_bf16 v[0:3], v[202:205], v[182:185], v[0:3]
	s_add_i32 s17, 16, 0x18000
	v_add_u32_e32 v140, s17, v198
	s_barrier
	ds_read_b128 v[128:131], v140
	ds_read_b128 v[132:135], v140 offset:1024
	ds_read_b128 v[136:139], v140 offset:2048
	ds_read_b128 v[140:143], v140 offset:3072
	s_add_u32 s4, s10, 0x160000
	s_addc_u32 s5, s11, 0
	s_mov_b32 m0, s43
	v_lshl_add_u64 v[186:187], s[4:5], 0, v[164:165]
	ds_read_b128 v[144:147], v200 offset:32768
	ds_read_b128 v[148:151], v200 offset:33792
	ds_read_b128 v[152:155], v200 offset:34816
	ds_read_b128 v[156:159], v200 offset:35840
	ds_read_b128 v[160:163], v200 offset:36864
	ds_read_b128 v[174:177], v200 offset:37888
	ds_read_b128 v[178:181], v200 offset:38912
	ds_read_b128 v[182:185], v200 offset:39936
	global_load_lds_dwordx4 v[186:187], off
	v_lshl_add_u64 v[186:187], s[4:5], 0, v[166:167]
	s_mov_b32 m0, s44
	s_nop 0
	global_load_lds_dwordx4 v[186:187], off
	s_waitcnt lgkmcnt(8)
	s_barrier
	s_waitcnt lgkmcnt(0)
	v_mfma_f32_16x16x32_bf16 v[124:127], v[128:131], v[144:147], v[124:127]
	v_mfma_f32_16x16x32_bf16 v[92:95], v[136:139], v[144:147], v[92:95]
	v_mfma_f32_16x16x32_bf16 v[120:123], v[128:131], v[152:155], v[120:123]
	v_mfma_f32_16x16x32_bf16 v[88:91], v[136:139], v[152:155], v[88:91]
	v_mfma_f32_16x16x32_bf16 v[116:119], v[128:131], v[160:163], v[116:119]
	v_mfma_f32_16x16x32_bf16 v[84:87], v[136:139], v[160:163], v[84:87]
	v_mfma_f32_16x16x32_bf16 v[112:115], v[128:131], v[178:181], v[112:115]
	v_mfma_f32_16x16x32_bf16 v[80:83], v[136:139], v[178:181], v[80:83]
	v_mfma_f32_16x16x32_bf16 v[124:127], v[132:135], v[148:151], v[124:127]
	v_mfma_f32_16x16x32_bf16 v[92:95], v[140:143], v[148:151], v[92:95]
	v_mfma_f32_16x16x32_bf16 v[120:123], v[132:135], v[156:159], v[120:123]
	v_mfma_f32_16x16x32_bf16 v[88:91], v[140:143], v[156:159], v[88:91]
	v_mfma_f32_16x16x32_bf16 v[116:119], v[132:135], v[174:177], v[116:119]
	v_mfma_f32_16x16x32_bf16 v[84:87], v[140:143], v[174:177], v[84:87]
	v_mfma_f32_16x16x32_bf16 v[112:115], v[132:135], v[182:185], v[112:115]
	v_mfma_f32_16x16x32_bf16 v[80:83], v[140:143], v[182:185], v[80:83]
	s_barrier
	s_add_i32 s10, 16, 0x1c000
	s_add_i32 s4, s17, s21
	v_add_u32_e32 v202, s10, v198
	v_lshl_add_u64 v[208:209], v[208:209], 0, s[0:1]
	s_mov_b32 m0, s4
	ds_read_b128 v[186:189], v202
	ds_read_b128 v[190:193], v202 offset:1024
	ds_read_b128 v[194:197], v202 offset:2048
	ds_read_b128 v[202:205], v202 offset:3072
	global_load_lds_dwordx4 v[208:209], off
	v_lshl_add_u64 v[208:209], v[210:211], 0, s[0:1]
	s_add_i32 m0, s4, 0x2000
	s_nop 0
	global_load_lds_dwordx4 v[208:209], off
	s_barrier
	s_waitcnt lgkmcnt(0)
	v_mfma_f32_16x16x32_bf16 v[60:63], v[186:189], v[144:147], v[60:63]
	v_mfma_f32_16x16x32_bf16 v[28:31], v[194:197], v[144:147], v[28:31]
	v_mfma_f32_16x16x32_bf16 v[56:59], v[186:189], v[152:155], v[56:59]
	v_mfma_f32_16x16x32_bf16 v[24:27], v[194:197], v[152:155], v[24:27]
	v_mfma_f32_16x16x32_bf16 v[52:55], v[186:189], v[160:163], v[52:55]
	v_mfma_f32_16x16x32_bf16 v[20:23], v[194:197], v[160:163], v[20:23]
	v_mfma_f32_16x16x32_bf16 v[48:51], v[186:189], v[178:181], v[48:51]
	v_mfma_f32_16x16x32_bf16 v[16:19], v[194:197], v[178:181], v[16:19]
	v_mfma_f32_16x16x32_bf16 v[60:63], v[190:193], v[148:151], v[60:63]
	v_mfma_f32_16x16x32_bf16 v[28:31], v[202:205], v[148:151], v[28:31]
	v_mfma_f32_16x16x32_bf16 v[56:59], v[190:193], v[156:159], v[56:59]
	v_mfma_f32_16x16x32_bf16 v[24:27], v[202:205], v[156:159], v[24:27]
	v_mfma_f32_16x16x32_bf16 v[52:55], v[190:193], v[174:177], v[52:55]
	v_mfma_f32_16x16x32_bf16 v[20:23], v[202:205], v[174:177], v[20:23]
	v_mfma_f32_16x16x32_bf16 v[48:51], v[190:193], v[182:185], v[48:51]
	v_mfma_f32_16x16x32_bf16 v[16:19], v[202:205], v[182:185], v[16:19]
	s_barrier
	s_mov_b32 m0, s45
	v_lshl_add_u64 v[208:209], v[212:213], 0, s[0:1]
	ds_read_b128 v[144:147], v200 offset:49152
	ds_read_b128 v[148:151], v200 offset:50176
	ds_read_b128 v[152:155], v200 offset:51200
	ds_read_b128 v[156:159], v200 offset:52224
	ds_read_b128 v[160:163], v200 offset:53248
	ds_read_b128 v[174:177], v200 offset:54272
	ds_read_b128 v[178:181], v200 offset:55296
	ds_read_b128 v[182:185], v200 offset:56320
	global_load_lds_dwordx4 v[208:209], off
	v_lshl_add_u64 v[208:209], v[214:215], 0, s[0:1]
	s_mov_b32 m0, s46
	s_nop 0
	global_load_lds_dwordx4 v[208:209], off
	s_barrier
; #define WAIT_V(n) asm volatile("s_waitcnt vmcnt(" #n ")" ::: "memory")
; #define WAIT_L(n) asm volatile("s_waitcnt lgkmcnt(" #n ")" ::: "memory")
; #define BAR __builtin_amdgcn_s_barrier()
; #define SCHED __builtin_amdgcn_sched_barrier(0)
; template <class Get, class Epi>
; DI void gemm_stream(LAS unsigned char* lds, const int K, const int ld, Get get, Epi epi) {
;     ...
;             BAR; WAIT_L(0); MMA(1, 0, At, B0); BAR; SCHED;
;             STAGE(SBo(1, 1), b3 + hstep);
;             WAIT_V(6); BAR; MMA(1, 1, At, B1); BAR;
;         }
; DI void epi_resid(const Acc& acc, const P& p, int brow, int bcol, int layer, int gch, bool from_input) {
;     ...
; #pragma unroll
;     for (int bj = 0; bj < 2; ++bj)
; #pragma unroll
;         for (int n = 0; n < 2; ++n) {
;             const int c0 = bcol + bj * 128 + wc * 32 + n * 16 + fq * 4;
;             const f32x4 g = *(const f32x4*)(gate + c0);
;             f32x4 xv[2][4];
; #pragma unroll
;             for (int ai = 0; ai < 2; ++ai)
; #pragma unroll
;                 for (int m = 0; m < 4; ++m) {
;                     const int r = brow + ai * 128 + wr * 64 + m * 16 + fr;
;                     const float* sp = (from_input ? inrow(p, r) : xrow(p, r)) + c0;
;                     xv[ai][m] = *(const f32x4*)sp;
;                 }
;             __builtin_amdgcn_sched_barrier(0);
; #pragma unroll
;             for (int ai = 0; ai < 2; ++ai)
; #pragma unroll
;                 for (int m = 0; m < 4; ++m) {
;                     const int r = brow + ai * 128 + wr * 64 + m * 16 + fr;
;                     *(f32x4*)(xrow(p, r) + c0) = xv[ai][m] + g * acc[ai][bj][m][n];
;                 }
;             __builtin_amdgcn_sched_barrier(0);
;         }
	s_waitcnt lgkmcnt(0)
	v_mfma_f32_16x16x32_bf16 v[108:111], v[128:131], v[144:147], v[108:111]
	v_mfma_f32_16x16x32_bf16 v[76:79], v[136:139], v[144:147], v[76:79]
	v_mfma_f32_16x16x32_bf16 v[104:107], v[128:131], v[152:155], v[104:107]
	v_mfma_f32_16x16x32_bf16 v[72:75], v[136:139], v[152:155], v[72:75]
	v_mfma_f32_16x16x32_bf16 v[100:103], v[128:131], v[160:163], v[100:103]
	v_mfma_f32_16x16x32_bf16 v[68:71], v[136:139], v[160:163], v[68:71]
	v_mfma_f32_16x16x32_bf16 v[96:99], v[128:131], v[178:181], v[96:99]
	v_mfma_f32_16x16x32_bf16 v[64:67], v[136:139], v[178:181], v[64:67]
	v_mfma_f32_16x16x32_bf16 v[108:111], v[132:135], v[148:151], v[108:111]
	v_mfma_f32_16x16x32_bf16 v[76:79], v[140:143], v[148:151], v[76:79]
	v_mfma_f32_16x16x32_bf16 v[104:107], v[132:135], v[156:159], v[104:107]
	v_mfma_f32_16x16x32_bf16 v[72:75], v[140:143], v[156:159], v[72:75]
	v_mfma_f32_16x16x32_bf16 v[100:103], v[132:135], v[174:177], v[100:103]
	v_mfma_f32_16x16x32_bf16 v[68:71], v[140:143], v[174:177], v[68:71]
	v_mfma_f32_16x16x32_bf16 v[96:99], v[132:135], v[182:185], v[96:99]
	v_mfma_f32_16x16x32_bf16 v[64:67], v[140:143], v[182:185], v[64:67]
	s_barrier
	s_add_u32 s4, s8, 0x160080
	s_addc_u32 s5, s9, 0
	s_add_i32 s8, s10, s21
	v_lshl_add_u64 v[128:129], s[4:5], 0, v[164:165]
	s_mov_b32 m0, s8
	s_nop 0
	global_load_lds_dwordx4 v[128:129], off
	v_lshl_add_u64 v[128:129], s[4:5], 0, v[166:167]
	s_add_i32 m0, s8, 0x2000
	s_nop 0
	global_load_lds_dwordx4 v[128:129], off
	s_add_i32 s16, s16, 2
	s_add_u32 s14, s14, 0x100
	s_addc_u32 s15, s15, 0
	s_cmpk_gt_u32 s16, 0x55
	s_mov_b64 s[4:5], s[6:7]
	s_waitcnt vmcnt(6)
	s_barrier
	v_mfma_f32_16x16x32_bf16 v[44:47], v[186:189], v[144:147], v[44:47]
	v_mfma_f32_16x16x32_bf16 v[12:15], v[194:197], v[144:147], v[12:15]
	v_mfma_f32_16x16x32_bf16 v[40:43], v[186:189], v[152:155], v[40:43]
	v_mfma_f32_16x16x32_bf16 v[8:11], v[194:197], v[152:155], v[8:11]
	v_mfma_f32_16x16x32_bf16 v[36:39], v[186:189], v[160:163], v[36:39]
	v_mfma_f32_16x16x32_bf16 v[4:7], v[194:197], v[160:163], v[4:7]
	v_mfma_f32_16x16x32_bf16 v[32:35], v[186:189], v[178:181], v[32:35]
	v_mfma_f32_16x16x32_bf16 v[0:3], v[194:197], v[178:181], v[0:3]
	v_mfma_f32_16x16x32_bf16 v[44:47], v[190:193], v[148:151], v[44:47]
	v_mfma_f32_16x16x32_bf16 v[12:15], v[202:205], v[148:151], v[12:15]
	v_mfma_f32_16x16x32_bf16 v[40:43], v[190:193], v[156:159], v[40:43]
	v_mfma_f32_16x16x32_bf16 v[8:11], v[202:205], v[156:159], v[8:11]
	v_mfma_f32_16x16x32_bf16 v[36:39], v[190:193], v[174:177], v[36:39]
	v_mfma_f32_16x16x32_bf16 v[4:7], v[202:205], v[174:177], v[4:7]
	v_mfma_f32_16x16x32_bf16 v[32:35], v[190:193], v[182:185], v[32:35]
	v_mfma_f32_16x16x32_bf16 v[0:3], v[202:205], v[182:185], v[0:3]
	s_barrier
	s_cbranch_scc0 .LBB0_3113
	s_lshl_b32 s8, s13, 21
	s_lshl_b32 s9, s12, 10
	s_lshr_b32 s16, s13, 4
	s_add_u32 s8, s8, s9
	s_mul_i32 s16, s16, 6
	s_add_i32 s16, s16, 35
	s_lshl_b32 s16, s16, 13
	s_add_u32 s16, s16, s9
	s_add_u32 s10, s26, s16
	s_addc_u32 s11, s27, 0
	s_add_u32 s6, s24, s8
	s_addc_u32 s7, s25, 0
	v_lshrrev_b32_e32 v224, 6, v206
	v_and_b32_e32 v225, 3, v224
	v_lshrrev_b32_e32 v224, 2, v224
	v_and_b32_e32 v205, 15, v206
	v_bfe_u32 v226, v206, 4, 2
	v_lshl_add_u32 v225, v225, 3, v226
	v_lshl_add_u32 v224, v224, 6, v205
	v_lshlrev_b32_e32 v205, 4, v225
	v_lshl_add_u32 v203, v224, 13, v205
	v_mov_b32_e32 v204, v203
	global_load_dwordx4 v[128:131], v205, s[10:11] offset:0
	global_load_dwordx4 v[132:135], v205, s[10:11] offset:64
	global_load_dwordx4 v[136:139], v205, s[10:11] offset:512
	global_load_dwordx4 v[140:143], v205, s[10:11] offset:576
	global_load_dwordx4 v[144:147], v203, s[6:7] offset:0
	global_load_dwordx4 v[148:151], v203, s[6:7] offset:64
	global_load_dwordx4 v[152:155], v203, s[6:7] offset:512
	global_load_dwordx4 v[156:159], v203, s[6:7] offset:576
	v_add_u32_e32 v203, 0x20000, v203
	global_load_dwordx4 v[160:163], v203, s[6:7] offset:0
	global_load_dwordx4 v[174:177], v203, s[6:7] offset:64
	global_load_dwordx4 v[178:181], v203, s[6:7] offset:512
	global_load_dwordx4 v[182:185], v203, s[6:7] offset:576
	v_add_u32_e32 v203, 0x20000, v203
	global_load_dwordx4 v[186:189], v203, s[6:7] offset:0
	global_load_dwordx4 v[190:193], v203, s[6:7] offset:64
	global_load_dwordx4 v[194:197], v203, s[6:7] offset:512
	global_load_dwordx4 v[208:211], v203, s[6:7] offset:576
	v_add_u32_e32 v203, 0x20000, v203
	global_load_dwordx4 v[212:215], v203, s[6:7] offset:0
	global_load_dwordx4 v[216:219], v203, s[6:7] offset:64
	global_load_dwordx4 v[220:223], v203, s[6:7] offset:512
	global_load_dwordx4 v[224:227], v203, s[6:7] offset:576
	v_add_u32_e32 v203, 0xa0000, v203
	s_waitcnt vmcnt(12)
	v_pk_fma_f32 v[124:125], v[124:125], v[128:129], v[144:145]
	v_pk_fma_f32 v[126:127], v[126:127], v[130:131], v[146:147]
	v_pk_fma_f32 v[92:93], v[92:93], v[132:133], v[148:149]
	v_pk_fma_f32 v[94:95], v[94:95], v[134:135], v[150:151]
	v_pk_fma_f32 v[60:61], v[60:61], v[136:137], v[152:153]
	v_pk_fma_f32 v[62:63], v[62:63], v[138:139], v[154:155]
	v_pk_fma_f32 v[28:29], v[28:29], v[140:141], v[156:157]
	v_pk_fma_f32 v[30:31], v[30:31], v[142:143], v[158:159]
	global_store_dwordx4 v204, v[124:127], s[6:7] offset:0
	global_store_dwordx4 v204, v[92:95], s[6:7] offset:64
	global_store_dwordx4 v204, v[60:63], s[6:7] offset:512
	global_store_dwordx4 v204, v[28:31], s[6:7] offset:576
	v_add_u32_e32 v204, 0x20000, v204
	global_load_dwordx4 v[144:147], v203, s[6:7] offset:0
	global_load_dwordx4 v[148:151], v203, s[6:7] offset:64
	global_load_dwordx4 v[152:155], v203, s[6:7] offset:512
	global_load_dwordx4 v[156:159], v203, s[6:7] offset:576
	v_add_u32_e32 v203, 0x20000, v203
	s_waitcnt vmcnt(16)
; DI void epi_resid(const Acc& acc, const P& p, int brow, int bcol, int layer, int gch, bool from_input) {
;     ...
; #pragma unroll
;     for (int bj = 0; bj < 2; ++bj)
; #pragma unroll
;         for (int n = 0; n < 2; ++n) {
;             const int c0 = bcol + bj * 128 + wc * 32 + n * 16 + fq * 4;
;             const f32x4 g = *(const f32x4*)(gate + c0);
;             f32x4 xv[2][4];
; #pragma unroll
;             for (int ai = 0; ai < 2; ++ai)
; #pragma unroll
;                 for (int m = 0; m < 4; ++m) {
;                     const int r = brow + ai * 128 + wr * 64 + m * 16 + fr;
;                     const float* sp = (from_input ? inrow(p, r) : xrow(p, r)) + c0;
;                     xv[ai][m] = *(const f32x4*)sp;
;                 }
;             __builtin_amdgcn_sched_barrier(0);
; #pragma unroll
;             for (int ai = 0; ai < 2; ++ai)
; #pragma unroll
;                 for (int m = 0; m < 4; ++m) {
;                     const int r = brow + ai * 128 + wr * 64 + m * 16 + fr;
;                     *(f32x4*)(xrow(p, r) + c0) = xv[ai][m] + g * acc[ai][bj][m][n];
;                 }
;             __builtin_amdgcn_sched_barrier(0);
;         }
	v_pk_fma_f32 v[120:121], v[120:121], v[128:129], v[160:161]
	v_pk_fma_f32 v[122:123], v[122:123], v[130:131], v[162:163]
	v_pk_fma_f32 v[88:89], v[88:89], v[132:133], v[174:175]
	v_pk_fma_f32 v[90:91], v[90:91], v[134:135], v[176:177]
	v_pk_fma_f32 v[56:57], v[56:57], v[136:137], v[178:179]
	v_pk_fma_f32 v[58:59], v[58:59], v[138:139], v[180:181]
	v_pk_fma_f32 v[24:25], v[24:25], v[140:141], v[182:183]
	v_pk_fma_f32 v[26:27], v[26:27], v[142:143], v[184:185]
	global_store_dwordx4 v204, v[120:123], s[6:7] offset:0
	global_store_dwordx4 v204, v[88:91], s[6:7] offset:64
	global_store_dwordx4 v204, v[56:59], s[6:7] offset:512
	global_store_dwordx4 v204, v[24:27], s[6:7] offset:576
	v_add_u32_e32 v204, 0x20000, v204
	global_load_dwordx4 v[160:163], v203, s[6:7] offset:0
	global_load_dwordx4 v[174:177], v203, s[6:7] offset:64
	global_load_dwordx4 v[178:181], v203, s[6:7] offset:512
	global_load_dwordx4 v[182:185], v203, s[6:7] offset:576
	v_add_u32_e32 v203, 0x20000, v203
	s_waitcnt vmcnt(20)
	v_pk_fma_f32 v[116:117], v[116:117], v[128:129], v[186:187]
	v_pk_fma_f32 v[118:119], v[118:119], v[130:131], v[188:189]
	v_pk_fma_f32 v[84:85], v[84:85], v[132:133], v[190:191]
	v_pk_fma_f32 v[86:87], v[86:87], v[134:135], v[192:193]
	v_pk_fma_f32 v[52:53], v[52:53], v[136:137], v[194:195]
	v_pk_fma_f32 v[54:55], v[54:55], v[138:139], v[196:197]
	v_pk_fma_f32 v[20:21], v[20:21], v[140:141], v[208:209]
	v_pk_fma_f32 v[22:23], v[22:23], v[142:143], v[210:211]
	global_store_dwordx4 v204, v[116:119], s[6:7] offset:0
	global_store_dwordx4 v204, v[84:87], s[6:7] offset:64
	global_store_dwordx4 v204, v[52:55], s[6:7] offset:512
	global_store_dwordx4 v204, v[20:23], s[6:7] offset:576
	v_add_u32_e32 v204, 0x20000, v204
	global_load_dwordx4 v[186:189], v203, s[6:7] offset:0
	global_load_dwordx4 v[190:193], v203, s[6:7] offset:64
	global_load_dwordx4 v[194:197], v203, s[6:7] offset:512
	global_load_dwordx4 v[208:211], v203, s[6:7] offset:576
	v_add_u32_e32 v203, 0x20000, v203
	s_waitcnt vmcnt(24)
	v_pk_fma_f32 v[112:113], v[112:113], v[128:129], v[212:213]
	v_pk_fma_f32 v[114:115], v[114:115], v[130:131], v[214:215]
	v_pk_fma_f32 v[80:81], v[80:81], v[132:133], v[216:217]
	v_pk_fma_f32 v[82:83], v[82:83], v[134:135], v[218:219]
	v_pk_fma_f32 v[48:49], v[48:49], v[136:137], v[220:221]
	v_pk_fma_f32 v[50:51], v[50:51], v[138:139], v[222:223]
	v_pk_fma_f32 v[16:17], v[16:17], v[140:141], v[224:225]
	v_pk_fma_f32 v[18:19], v[18:19], v[142:143], v[226:227]
	global_store_dwordx4 v204, v[112:115], s[6:7] offset:0
	global_store_dwordx4 v204, v[80:83], s[6:7] offset:64
	global_store_dwordx4 v204, v[48:51], s[6:7] offset:512
	global_store_dwordx4 v204, v[16:19], s[6:7] offset:576
	v_add_u32_e32 v204, 0xa0000, v204
	global_load_dwordx4 v[212:215], v203, s[6:7] offset:0
	global_load_dwordx4 v[216:219], v203, s[6:7] offset:64
	global_load_dwordx4 v[220:223], v203, s[6:7] offset:512
	global_load_dwordx4 v[224:227], v203, s[6:7] offset:576
	s_waitcnt vmcnt(24)
	v_pk_fma_f32 v[108:109], v[108:109], v[128:129], v[144:145]
	v_pk_fma_f32 v[110:111], v[110:111], v[130:131], v[146:147]
	v_pk_fma_f32 v[76:77], v[76:77], v[132:133], v[148:149]
	v_pk_fma_f32 v[78:79], v[78:79], v[134:135], v[150:151]
	v_pk_fma_f32 v[44:45], v[44:45], v[136:137], v[152:153]
	v_pk_fma_f32 v[46:47], v[46:47], v[138:139], v[154:155]
	v_pk_fma_f32 v[12:13], v[12:13], v[140:141], v[156:157]
	v_pk_fma_f32 v[14:15], v[14:15], v[142:143], v[158:159]
	global_store_dwordx4 v204, v[108:111], s[6:7] offset:0
	global_store_dwordx4 v204, v[76:79], s[6:7] offset:64
	global_store_dwordx4 v204, v[44:47], s[6:7] offset:512
	global_store_dwordx4 v204, v[12:15], s[6:7] offset:576
	v_add_u32_e32 v204, 0x20000, v204
	s_waitcnt vmcnt(20)
	v_pk_fma_f32 v[104:105], v[104:105], v[128:129], v[160:161]
	v_pk_fma_f32 v[106:107], v[106:107], v[130:131], v[162:163]
	v_pk_fma_f32 v[72:73], v[72:73], v[132:133], v[174:175]
	v_pk_fma_f32 v[74:75], v[74:75], v[134:135], v[176:177]
	v_pk_fma_f32 v[40:41], v[40:41], v[136:137], v[178:179]
	v_pk_fma_f32 v[42:43], v[42:43], v[138:139], v[180:181]
	v_pk_fma_f32 v[8:9], v[8:9], v[140:141], v[182:183]
	v_pk_fma_f32 v[10:11], v[10:11], v[142:143], v[184:185]
	global_store_dwordx4 v204, v[104:107], s[6:7] offset:0
	global_store_dwordx4 v204, v[72:75], s[6:7] offset:64
	global_store_dwordx4 v204, v[40:43], s[6:7] offset:512
	global_store_dwordx4 v204, v[8:11], s[6:7] offset:576
	v_add_u32_e32 v204, 0x20000, v204
	s_waitcnt vmcnt(16)
	v_pk_fma_f32 v[100:101], v[100:101], v[128:129], v[186:187]
	v_pk_fma_f32 v[102:103], v[102:103], v[130:131], v[188:189]
	v_pk_fma_f32 v[68:69], v[68:69], v[132:133], v[190:191]
	v_pk_fma_f32 v[70:71], v[70:71], v[134:135], v[192:193]
	v_pk_fma_f32 v[36:37], v[36:37], v[136:137], v[194:195]
	v_pk_fma_f32 v[38:39], v[38:39], v[138:139], v[196:197]
	v_pk_fma_f32 v[4:5], v[4:5], v[140:141], v[208:209]
	v_pk_fma_f32 v[6:7], v[6:7], v[142:143], v[210:211]
	global_store_dwordx4 v204, v[100:103], s[6:7] offset:0
	global_store_dwordx4 v204, v[68:71], s[6:7] offset:64
	global_store_dwordx4 v204, v[36:39], s[6:7] offset:512
	global_store_dwordx4 v204, v[4:7], s[6:7] offset:576
	v_add_u32_e32 v204, 0x20000, v204
	s_waitcnt vmcnt(12)
	v_pk_fma_f32 v[96:97], v[96:97], v[128:129], v[212:213]
	v_pk_fma_f32 v[98:99], v[98:99], v[130:131], v[214:215]
	v_pk_fma_f32 v[64:65], v[64:65], v[132:133], v[216:217]
	v_pk_fma_f32 v[66:67], v[66:67], v[134:135], v[218:219]
	v_pk_fma_f32 v[32:33], v[32:33], v[136:137], v[220:221]
	v_pk_fma_f32 v[34:35], v[34:35], v[138:139], v[222:223]
	v_pk_fma_f32 v[0:1], v[0:1], v[140:141], v[224:225]
	v_pk_fma_f32 v[2:3], v[2:3], v[142:143], v[226:227]
	global_store_dwordx4 v204, v[96:99], s[6:7] offset:0
	global_store_dwordx4 v204, v[64:67], s[6:7] offset:64
	global_store_dwordx4 v204, v[32:35], s[6:7] offset:512
	global_store_dwordx4 v204, v[0:3], s[6:7] offset:576
	s_branch .Lresid_latch_ffndL1
